# GEMM epilogue 16-byte stores non-temporal (nt)
# speedup vs baseline: 1.0117x; 1.0117x over previous
; #define LAS __attribute__((address_space(3)))
; __device__ __forceinline__ unsigned cvt_pk2(float lo, float hi) { f32x2c v = {lo, hi}; bf16x2c q = __builtin_convertvector(v, bf16x2c); return __builtin_bit_cast(unsigned, q); }
;     __device__ __forceinline__ void operator()(const f32x4 (&acc)[2][2][4][2], const pg8::Unit& u, int wr, int wc, int fr, int fq) const {
;         const int row0 = u.pm * 256 + wr * 64 + fr, col0 = u.pn * 128 + wc * 32 + 8 * fq;
;         const LAS float* rt = rt_.of(u.pm) + wr * 64 + fr;
; #pragma unroll
;         for (int ai = 0; ai < 2; ++ai)
; #pragma unroll
;             for (int m = 0; m < 4; ++m) { bf16_t* rowp = O + (size_t)(row0 + ai * 128 + m * 16) * FF + col0; const float r = rt[ai * 128 + m * 16];
;                 const float rl = -r * LOG2E, r2 = r * r; unsigned w[4];
; #pragma unroll
;                 for (int n = 0; n < 2; ++n)
; #pragma unroll
;                     for (int h = 0; h < 2; ++h) { const f32x2v g = {acc[ai][0][m][n][2 * h], acc[ai][0][m][n][2 * h + 1]}, uu = {acc[ai][1][m][n][2 * h], acc[ai][1][m][n][2 * h + 1]};
;                         const f32x2v t = g * rl; f32x2v d = {__builtin_amdgcn_exp2f(t.x), __builtin_amdgcn_exp2f(t.y)}; d = d + 1.0f;
;                         const f32x2v q = {__builtin_amdgcn_rcpf(d.x), __builtin_amdgcn_rcpf(d.y)}; const f32x2v o = ((g * uu) * r2) * q;
;                         w[2 * n + h] = cvt_pk2(o.x, o.y); }
;                 u32x4 wv; wv.x = w[0]; wv.y = w[1]; wv.z = w[2]; wv.w = w[3];
;                 *(u32x4*)rowp = wv; }
.LBB0_227:
	s_cmp_eq_u32 s34, s51
	s_cselect_b32 s13, s65, 0x300
	s_cmp_lg_u32 s34, s52
	s_cselect_b32 s13, s13, 0x100
	s_cmp_lg_u32 s34, s50
	s_cselect_b32 s13, s13, 0
	v_lshl_add_u32 v154, s13, 2, v148
	ds_read2_b32 v[200:201], v154 offset1:16
	ds_read2_b32 v[202:203], v154 offset0:32 offset1:48
	ds_read2_b32 v[204:205], v154 offset0:128 offset1:144
	ds_read2_b32 v[206:207], v154 offset0:160 offset1:176
	v_lshl_add_u32 v153, s34, 8, v146
	v_lshl_or_b32 v158, s67, 7, v149
	v_mov_b64_e32 v[178:179], s[40:41]
	s_mov_b32 s98, 0x1600
	v_lshlrev_b32_e32 v158, 1, v158
	v_mov_b32_e32 v159, 0
	v_mad_i64_i32 v[178:179], s[20:21], v153, s98, v[178:179]
	s_mov_b32 s98, 0x16000
	s_mov_b32 s99, 0
	s_mov_b32 s100, 0x6e000
	s_mov_b32 s101, 0
	v_lshl_add_u64 v[178:179], v[178:179], 0, v[158:159]
	s_waitcnt lgkmcnt(0)
	v_mul_f32_e32 v208, 0xbfb8aa3b, v200
	v_mul_f32_e32 v228, v200, v200
	v_mul_f32_e32 v210, 0xbfb8aa3b, v201
	v_mul_f32_e32 v230, v201, v201
	v_mul_f32_e32 v212, 0xbfb8aa3b, v202
	v_mul_f32_e32 v232, v202, v202
	v_mul_f32_e32 v214, 0xbfb8aa3b, v203
	v_mul_f32_e32 v234, v203, v203
	v_mul_f32_e32 v216, 0xbfb8aa3b, v204
	v_mul_f32_e32 v236, v204, v204
	v_mul_f32_e32 v218, 0xbfb8aa3b, v205
	v_mul_f32_e32 v238, v205, v205
	v_mul_f32_e32 v220, 0xbfb8aa3b, v206
	v_mul_f32_e32 v240, v206, v206
	v_mul_f32_e32 v222, 0xbfb8aa3b, v207
	v_mul_f32_e32 v242, v207, v207
	v_rcp_f32_e32 v228, v228
	v_rcp_f32_e32 v230, v230
	v_rcp_f32_e32 v232, v232
	v_rcp_f32_e32 v234, v234
	v_rcp_f32_e32 v236, v236
	v_rcp_f32_e32 v238, v238
	v_rcp_f32_e32 v240, v240
	v_rcp_f32_e32 v242, v242
	v_pk_mul_f32 v[154:155], v[124:125], v[208:209] op_sel_hi:[1,0]
	v_pk_mul_f32 v[156:157], v[126:127], v[208:209] op_sel_hi:[1,0]
	v_pk_mul_f32 v[158:159], v[116:117], v[208:209] op_sel_hi:[1,0]
	v_pk_mul_f32 v[160:161], v[118:119], v[208:209] op_sel_hi:[1,0]
	v_exp_f32_e32 v154, v154
	v_exp_f32_e32 v155, v155
	v_exp_f32_e32 v156, v156
	v_exp_f32_e32 v157, v157
	v_exp_f32_e32 v158, v158
	v_exp_f32_e32 v159, v159
	v_exp_f32_e32 v160, v160
	v_exp_f32_e32 v161, v161
	v_pk_mul_f32 v[162:163], v[108:109], v[210:211] op_sel_hi:[1,0]
	v_pk_mul_f32 v[164:165], v[110:111], v[210:211] op_sel_hi:[1,0]
	v_pk_mul_f32 v[166:167], v[100:101], v[210:211] op_sel_hi:[1,0]
	v_pk_mul_f32 v[168:169], v[102:103], v[210:211] op_sel_hi:[1,0]
	v_exp_f32_e32 v162, v162
	v_exp_f32_e32 v163, v163
	v_exp_f32_e32 v164, v164
	v_exp_f32_e32 v165, v165
	v_exp_f32_e32 v166, v166
	v_exp_f32_e32 v167, v167
	v_exp_f32_e32 v168, v168
	v_exp_f32_e32 v169, v169
	v_pk_mul_f32 v[120:121], v[124:125], v[120:121]
	v_pk_mul_f32 v[122:123], v[126:127], v[122:123]
	v_pk_mul_f32 v[112:113], v[116:117], v[112:113]
	v_pk_mul_f32 v[114:115], v[118:119], v[114:115]
	v_pk_fma_f32 v[154:155], v[154:155], v[228:229], v[228:229] op_sel_hi:[1,0,0]
	v_pk_fma_f32 v[156:157], v[156:157], v[228:229], v[228:229] op_sel_hi:[1,0,0]
	v_pk_fma_f32 v[158:159], v[158:159], v[228:229], v[228:229] op_sel_hi:[1,0,0]
	v_pk_fma_f32 v[160:161], v[160:161], v[228:229], v[228:229] op_sel_hi:[1,0,0]
	v_rcp_f32_e32 v154, v154
	v_rcp_f32_e32 v155, v155
	v_rcp_f32_e32 v156, v156
	v_rcp_f32_e32 v157, v157
	v_rcp_f32_e32 v158, v158
	v_rcp_f32_e32 v159, v159
	v_rcp_f32_e32 v160, v160
	v_rcp_f32_e32 v161, v161
	v_pk_mul_f32 v[170:171], v[92:93], v[212:213] op_sel_hi:[1,0]
	v_pk_mul_f32 v[172:173], v[94:95], v[212:213] op_sel_hi:[1,0]
	v_pk_mul_f32 v[174:175], v[84:85], v[212:213] op_sel_hi:[1,0]
	v_pk_mul_f32 v[176:177], v[86:87], v[212:213] op_sel_hi:[1,0]
	v_exp_f32_e32 v170, v170
	v_exp_f32_e32 v171, v171
	v_exp_f32_e32 v172, v172
	v_exp_f32_e32 v173, v173
	v_exp_f32_e32 v174, v174
	v_exp_f32_e32 v175, v175
	v_exp_f32_e32 v176, v176
	v_exp_f32_e32 v177, v177
	v_pk_mul_f32 v[104:105], v[108:109], v[104:105]
	v_pk_mul_f32 v[106:107], v[110:111], v[106:107]
	v_pk_mul_f32 v[96:97], v[100:101], v[96:97]
	v_pk_mul_f32 v[98:99], v[102:103], v[98:99]
	v_pk_fma_f32 v[162:163], v[162:163], v[230:231], v[230:231] op_sel_hi:[1,0,0]
	v_pk_fma_f32 v[164:165], v[164:165], v[230:231], v[230:231] op_sel_hi:[1,0,0]
	v_pk_fma_f32 v[166:167], v[166:167], v[230:231], v[230:231] op_sel_hi:[1,0,0]
	v_pk_fma_f32 v[168:169], v[168:169], v[230:231], v[230:231] op_sel_hi:[1,0,0]
	v_rcp_f32_e32 v162, v162
	v_rcp_f32_e32 v163, v163
	v_rcp_f32_e32 v164, v164
	v_rcp_f32_e32 v165, v165
	v_rcp_f32_e32 v166, v166
	v_rcp_f32_e32 v167, v167
	v_rcp_f32_e32 v168, v168
	v_rcp_f32_e32 v169, v169
	v_pk_mul_f32 v[120:121], v[120:121], v[154:155]
	v_pk_mul_f32 v[122:123], v[122:123], v[156:157]
	v_pk_mul_f32 v[112:113], v[112:113], v[158:159]
	v_pk_mul_f32 v[114:115], v[114:115], v[160:161]
	v_cvt_pk_bf16_f32 v154, v120, v121
	v_cvt_pk_bf16_f32 v155, v122, v123
	v_cvt_pk_bf16_f32 v156, v112, v113
	v_cvt_pk_bf16_f32 v157, v114, v115
	global_store_dwordx4 v[178:179], v[154:157], off nt
	v_lshl_add_u64 v[178:179], v[178:179], 0, s[98:99]
	s_nop 1
	v_pk_mul_f32 v[154:155], v[76:77], v[214:215] op_sel_hi:[1,0]
	v_pk_mul_f32 v[156:157], v[78:79], v[214:215] op_sel_hi:[1,0]
	v_pk_mul_f32 v[158:159], v[68:69], v[214:215] op_sel_hi:[1,0]
	v_pk_mul_f32 v[160:161], v[70:71], v[214:215] op_sel_hi:[1,0]
	v_exp_f32_e32 v154, v154
	v_exp_f32_e32 v155, v155
	v_exp_f32_e32 v156, v156
	v_exp_f32_e32 v157, v157
	v_exp_f32_e32 v158, v158
	v_exp_f32_e32 v159, v159
	v_exp_f32_e32 v160, v160
	v_exp_f32_e32 v161, v161
	v_pk_mul_f32 v[88:89], v[92:93], v[88:89]
	v_pk_mul_f32 v[90:91], v[94:95], v[90:91]
	v_pk_mul_f32 v[80:81], v[84:85], v[80:81]
	v_pk_mul_f32 v[82:83], v[86:87], v[82:83]
	v_pk_fma_f32 v[170:171], v[170:171], v[232:233], v[232:233] op_sel_hi:[1,0,0]
	v_pk_fma_f32 v[172:173], v[172:173], v[232:233], v[232:233] op_sel_hi:[1,0,0]
; __device__ __forceinline__ unsigned cvt_pk2(float lo, float hi) { f32x2c v = {lo, hi}; bf16x2c q = __builtin_convertvector(v, bf16x2c); return __builtin_bit_cast(unsigned, q); }
;     __device__ __forceinline__ void operator()(const f32x4 (&acc)[2][2][4][2], const pg8::Unit& u, int wr, int wc, int fr, int fq) const {
;     ...
;             for (int m = 0; m < 4; ++m) { bf16_t* rowp = O + (size_t)(row0 + ai * 128 + m * 16) * FF + col0; const float r = rt[ai * 128 + m * 16];
;                 const float rl = -r * LOG2E, r2 = r * r; unsigned w[4];
; #pragma unroll
;                 for (int n = 0; n < 2; ++n)
; #pragma unroll
;                     for (int h = 0; h < 2; ++h) { const f32x2v g = {acc[ai][0][m][n][2 * h], acc[ai][0][m][n][2 * h + 1]}, uu = {acc[ai][1][m][n][2 * h], acc[ai][1][m][n][2 * h + 1]};
;                         const f32x2v t = g * rl; f32x2v d = {__builtin_amdgcn_exp2f(t.x), __builtin_amdgcn_exp2f(t.y)}; d = d + 1.0f;
;                         const f32x2v q = {__builtin_amdgcn_rcpf(d.x), __builtin_amdgcn_rcpf(d.y)}; const f32x2v o = ((g * uu) * r2) * q;
;                         w[2 * n + h] = cvt_pk2(o.x, o.y); }
;                 u32x4 wv; wv.x = w[0]; wv.y = w[1]; wv.z = w[2]; wv.w = w[3];
;                 *(u32x4*)rowp = wv; }
	v_pk_fma_f32 v[174:175], v[174:175], v[232:233], v[232:233] op_sel_hi:[1,0,0]
	v_pk_fma_f32 v[176:177], v[176:177], v[232:233], v[232:233] op_sel_hi:[1,0,0]
	v_rcp_f32_e32 v170, v170
	v_rcp_f32_e32 v171, v171
	v_rcp_f32_e32 v172, v172
	v_rcp_f32_e32 v173, v173
	v_rcp_f32_e32 v174, v174
	v_rcp_f32_e32 v175, v175
	v_rcp_f32_e32 v176, v176
	v_rcp_f32_e32 v177, v177
	v_pk_mul_f32 v[104:105], v[104:105], v[162:163]
	v_pk_mul_f32 v[106:107], v[106:107], v[164:165]
	v_pk_mul_f32 v[96:97], v[96:97], v[166:167]
	v_pk_mul_f32 v[98:99], v[98:99], v[168:169]
	v_cvt_pk_bf16_f32 v162, v104, v105
	v_cvt_pk_bf16_f32 v163, v106, v107
	v_cvt_pk_bf16_f32 v164, v96, v97
	v_cvt_pk_bf16_f32 v165, v98, v99
	global_store_dwordx4 v[178:179], v[162:165], off nt
	v_lshl_add_u64 v[178:179], v[178:179], 0, s[98:99]
	s_nop 1
	v_pk_mul_f32 v[162:163], v[60:61], v[216:217] op_sel_hi:[1,0]
	v_pk_mul_f32 v[164:165], v[62:63], v[216:217] op_sel_hi:[1,0]
	v_pk_mul_f32 v[166:167], v[52:53], v[216:217] op_sel_hi:[1,0]
	v_pk_mul_f32 v[168:169], v[54:55], v[216:217] op_sel_hi:[1,0]
	v_exp_f32_e32 v162, v162
	v_exp_f32_e32 v163, v163
	v_exp_f32_e32 v164, v164
	v_exp_f32_e32 v165, v165
	v_exp_f32_e32 v166, v166
	v_exp_f32_e32 v167, v167
	v_exp_f32_e32 v168, v168
	v_exp_f32_e32 v169, v169
	v_pk_mul_f32 v[72:73], v[76:77], v[72:73]
	v_pk_mul_f32 v[74:75], v[78:79], v[74:75]
	v_pk_mul_f32 v[64:65], v[68:69], v[64:65]
	v_pk_mul_f32 v[66:67], v[70:71], v[66:67]
	v_pk_fma_f32 v[154:155], v[154:155], v[234:235], v[234:235] op_sel_hi:[1,0,0]
	v_pk_fma_f32 v[156:157], v[156:157], v[234:235], v[234:235] op_sel_hi:[1,0,0]
	v_pk_fma_f32 v[158:159], v[158:159], v[234:235], v[234:235] op_sel_hi:[1,0,0]
	v_pk_fma_f32 v[160:161], v[160:161], v[234:235], v[234:235] op_sel_hi:[1,0,0]
	v_rcp_f32_e32 v154, v154
	v_rcp_f32_e32 v155, v155
	v_rcp_f32_e32 v156, v156
	v_rcp_f32_e32 v157, v157
	v_rcp_f32_e32 v158, v158
	v_rcp_f32_e32 v159, v159
	v_rcp_f32_e32 v160, v160
	v_rcp_f32_e32 v161, v161
	v_pk_mul_f32 v[88:89], v[88:89], v[170:171]
	v_pk_mul_f32 v[90:91], v[90:91], v[172:173]
	v_pk_mul_f32 v[80:81], v[80:81], v[174:175]
	v_pk_mul_f32 v[82:83], v[82:83], v[176:177]
	v_cvt_pk_bf16_f32 v170, v88, v89
	v_cvt_pk_bf16_f32 v171, v90, v91
	v_cvt_pk_bf16_f32 v172, v80, v81
	v_cvt_pk_bf16_f32 v173, v82, v83
	global_store_dwordx4 v[178:179], v[170:173], off nt
	v_lshl_add_u64 v[178:179], v[178:179], 0, s[98:99]
	s_nop 1
	v_pk_mul_f32 v[170:171], v[44:45], v[218:219] op_sel_hi:[1,0]
	v_pk_mul_f32 v[172:173], v[46:47], v[218:219] op_sel_hi:[1,0]
	v_pk_mul_f32 v[174:175], v[36:37], v[218:219] op_sel_hi:[1,0]
	v_pk_mul_f32 v[176:177], v[38:39], v[218:219] op_sel_hi:[1,0]
	v_exp_f32_e32 v170, v170
	v_exp_f32_e32 v171, v171
	v_exp_f32_e32 v172, v172
	v_exp_f32_e32 v173, v173
	v_exp_f32_e32 v174, v174
	v_exp_f32_e32 v175, v175
	v_exp_f32_e32 v176, v176
	v_exp_f32_e32 v177, v177
	v_pk_mul_f32 v[56:57], v[60:61], v[56:57]
	v_pk_mul_f32 v[58:59], v[62:63], v[58:59]
	v_pk_mul_f32 v[48:49], v[52:53], v[48:49]
	v_pk_mul_f32 v[50:51], v[54:55], v[50:51]
	v_pk_fma_f32 v[162:163], v[162:163], v[236:237], v[236:237] op_sel_hi:[1,0,0]
	v_pk_fma_f32 v[164:165], v[164:165], v[236:237], v[236:237] op_sel_hi:[1,0,0]
	v_pk_fma_f32 v[166:167], v[166:167], v[236:237], v[236:237] op_sel_hi:[1,0,0]
	v_pk_fma_f32 v[168:169], v[168:169], v[236:237], v[236:237] op_sel_hi:[1,0,0]
	v_rcp_f32_e32 v162, v162
	v_rcp_f32_e32 v163, v163
	v_rcp_f32_e32 v164, v164
	v_rcp_f32_e32 v165, v165
	v_rcp_f32_e32 v166, v166
	v_rcp_f32_e32 v167, v167
	v_rcp_f32_e32 v168, v168
	v_rcp_f32_e32 v169, v169
	v_pk_mul_f32 v[72:73], v[72:73], v[154:155]
	v_pk_mul_f32 v[74:75], v[74:75], v[156:157]
	v_pk_mul_f32 v[64:65], v[64:65], v[158:159]
	v_pk_mul_f32 v[66:67], v[66:67], v[160:161]
	v_cvt_pk_bf16_f32 v154, v72, v73
	v_cvt_pk_bf16_f32 v155, v74, v75
	v_cvt_pk_bf16_f32 v156, v64, v65
	v_cvt_pk_bf16_f32 v157, v66, v67
	global_store_dwordx4 v[178:179], v[154:157], off nt
	v_lshl_add_u64 v[178:179], v[178:179], 0, s[100:101]
	s_nop 1
	v_pk_mul_f32 v[154:155], v[28:29], v[220:221] op_sel_hi:[1,0]
	v_pk_mul_f32 v[156:157], v[30:31], v[220:221] op_sel_hi:[1,0]
	v_pk_mul_f32 v[158:159], v[20:21], v[220:221] op_sel_hi:[1,0]
	v_pk_mul_f32 v[160:161], v[22:23], v[220:221] op_sel_hi:[1,0]
	v_exp_f32_e32 v154, v154
	v_exp_f32_e32 v155, v155
	v_exp_f32_e32 v156, v156
	v_exp_f32_e32 v157, v157
	v_exp_f32_e32 v158, v158
	v_exp_f32_e32 v159, v159
; #define PG8_BAR __builtin_amdgcn_s_barrier()
; __device__ __forceinline__ unsigned cvt_pk2(float lo, float hi) { f32x2c v = {lo, hi}; bf16x2c q = __builtin_convertvector(v, bf16x2c); return __builtin_bit_cast(unsigned, q); }
; template <class Epi, class Sched, bool ALIGN_EPI = false, bool SP2 = false>
; __device__ __forceinline__ void gemm_phase(PG8_LAS unsigned char* lds, const Gemm g, const Sched& S, const Epi& E) {
;     ...
;         if constexpr (ALIGN_EPI) { if (wr == 0) PG8_BAR; }
;         if constexpr (!Epi::AFTER_DRAIN) { E(acc, cur, wr, wc, fr, fq); S.done(cur); }
;         if (!has_next) break;
; #pragma unroll
;         for (int a = 0; a < 2; ++a)
; #pragma unroll
;             for (int b = 0; b < 2; ++b)
; #pragma unroll
;                 for (int m = 0; m < 4; ++m)
; #pragma unroll
;                     for (int n = 0; n < 2; ++n) acc[a][b][m][n] = (f32x4){0.f, 0.f, 0.f, 0.f};
;         cur = nxt; cA = nA; cB = nB; ++ui;
;         if constexpr (ALIGN_EPI) { if (wr == 1) PG8_BAR; }
;     __device__ __forceinline__ void operator()(const f32x4 (&acc)[2][2][4][2], const pg8::Unit& u, int wr, int wc, int fr, int fq) const {
;     ...
;             for (int m = 0; m < 4; ++m) { bf16_t* rowp = O + (size_t)(row0 + ai * 128 + m * 16) * FF + col0; const float r = rt[ai * 128 + m * 16];
;                 const float rl = -r * LOG2E, r2 = r * r; unsigned w[4];
; #pragma unroll
;                 for (int n = 0; n < 2; ++n)
; #pragma unroll
;                     for (int h = 0; h < 2; ++h) { const f32x2v g = {acc[ai][0][m][n][2 * h], acc[ai][0][m][n][2 * h + 1]}, uu = {acc[ai][1][m][n][2 * h], acc[ai][1][m][n][2 * h + 1]};
;                         const f32x2v t = g * rl; f32x2v d = {__builtin_amdgcn_exp2f(t.x), __builtin_amdgcn_exp2f(t.y)}; d = d + 1.0f;
;                         const f32x2v q = {__builtin_amdgcn_rcpf(d.x), __builtin_amdgcn_rcpf(d.y)}; const f32x2v o = ((g * uu) * r2) * q;
;                         w[2 * n + h] = cvt_pk2(o.x, o.y); }
;                 u32x4 wv; wv.x = w[0]; wv.y = w[1]; wv.z = w[2]; wv.w = w[3];
;                 *(u32x4*)rowp = wv; }
	v_exp_f32_e32 v160, v160
	v_exp_f32_e32 v161, v161
	v_pk_mul_f32 v[40:41], v[44:45], v[40:41]
	v_pk_mul_f32 v[42:43], v[46:47], v[42:43]
	v_pk_mul_f32 v[32:33], v[36:37], v[32:33]
	v_pk_mul_f32 v[34:35], v[38:39], v[34:35]
	v_pk_fma_f32 v[170:171], v[170:171], v[238:239], v[238:239] op_sel_hi:[1,0,0]
	v_pk_fma_f32 v[172:173], v[172:173], v[238:239], v[238:239] op_sel_hi:[1,0,0]
	v_pk_fma_f32 v[174:175], v[174:175], v[238:239], v[238:239] op_sel_hi:[1,0,0]
	v_pk_fma_f32 v[176:177], v[176:177], v[238:239], v[238:239] op_sel_hi:[1,0,0]
	v_rcp_f32_e32 v170, v170
	v_rcp_f32_e32 v171, v171
	v_rcp_f32_e32 v172, v172
	v_rcp_f32_e32 v173, v173
	v_rcp_f32_e32 v174, v174
	v_rcp_f32_e32 v175, v175
	v_rcp_f32_e32 v176, v176
	v_rcp_f32_e32 v177, v177
	v_pk_mul_f32 v[56:57], v[56:57], v[162:163]
	v_pk_mul_f32 v[58:59], v[58:59], v[164:165]
	v_pk_mul_f32 v[48:49], v[48:49], v[166:167]
	v_pk_mul_f32 v[50:51], v[50:51], v[168:169]
	v_cvt_pk_bf16_f32 v162, v56, v57
	v_cvt_pk_bf16_f32 v163, v58, v59
	v_cvt_pk_bf16_f32 v164, v48, v49
	v_cvt_pk_bf16_f32 v165, v50, v51
	global_store_dwordx4 v[178:179], v[162:165], off nt
	v_lshl_add_u64 v[178:179], v[178:179], 0, s[98:99]
	s_nop 1
	v_pk_mul_f32 v[162:163], v[12:13], v[222:223] op_sel_hi:[1,0]
	v_pk_mul_f32 v[164:165], v[14:15], v[222:223] op_sel_hi:[1,0]
	v_pk_mul_f32 v[166:167], v[4:5], v[222:223] op_sel_hi:[1,0]
	v_pk_mul_f32 v[168:169], v[6:7], v[222:223] op_sel_hi:[1,0]
	v_exp_f32_e32 v162, v162
	v_exp_f32_e32 v163, v163
	v_exp_f32_e32 v164, v164
	v_exp_f32_e32 v165, v165
	v_exp_f32_e32 v166, v166
	v_exp_f32_e32 v167, v167
	v_exp_f32_e32 v168, v168
	v_exp_f32_e32 v169, v169
	v_pk_mul_f32 v[24:25], v[28:29], v[24:25]
	v_pk_mul_f32 v[26:27], v[30:31], v[26:27]
	v_pk_mul_f32 v[16:17], v[20:21], v[16:17]
	v_pk_mul_f32 v[18:19], v[22:23], v[18:19]
	v_pk_fma_f32 v[154:155], v[154:155], v[240:241], v[240:241] op_sel_hi:[1,0,0]
	v_pk_fma_f32 v[156:157], v[156:157], v[240:241], v[240:241] op_sel_hi:[1,0,0]
	v_pk_fma_f32 v[158:159], v[158:159], v[240:241], v[240:241] op_sel_hi:[1,0,0]
	v_pk_fma_f32 v[160:161], v[160:161], v[240:241], v[240:241] op_sel_hi:[1,0,0]
	v_rcp_f32_e32 v154, v154
	v_rcp_f32_e32 v155, v155
	v_rcp_f32_e32 v156, v156
	v_rcp_f32_e32 v157, v157
	v_rcp_f32_e32 v158, v158
	v_rcp_f32_e32 v159, v159
	v_rcp_f32_e32 v160, v160
	v_rcp_f32_e32 v161, v161
	v_pk_mul_f32 v[40:41], v[40:41], v[170:171]
	v_pk_mul_f32 v[42:43], v[42:43], v[172:173]
	v_pk_mul_f32 v[32:33], v[32:33], v[174:175]
	v_pk_mul_f32 v[34:35], v[34:35], v[176:177]
	v_cvt_pk_bf16_f32 v170, v40, v41
	v_cvt_pk_bf16_f32 v171, v42, v43
	v_cvt_pk_bf16_f32 v172, v32, v33
	v_cvt_pk_bf16_f32 v173, v34, v35
	global_store_dwordx4 v[178:179], v[170:173], off nt
	v_lshl_add_u64 v[178:179], v[178:179], 0, s[98:99]
	s_nop 1
	v_pk_mul_f32 v[8:9], v[12:13], v[8:9]
	v_pk_mul_f32 v[10:11], v[14:15], v[10:11]
	v_pk_mul_f32 v[0:1], v[4:5], v[0:1]
	v_pk_mul_f32 v[2:3], v[6:7], v[2:3]
	v_pk_fma_f32 v[162:163], v[162:163], v[242:243], v[242:243] op_sel_hi:[1,0,0]
	v_pk_fma_f32 v[164:165], v[164:165], v[242:243], v[242:243] op_sel_hi:[1,0,0]
	v_pk_fma_f32 v[166:167], v[166:167], v[242:243], v[242:243] op_sel_hi:[1,0,0]
	v_pk_fma_f32 v[168:169], v[168:169], v[242:243], v[242:243] op_sel_hi:[1,0,0]
	v_rcp_f32_e32 v162, v162
	v_rcp_f32_e32 v163, v163
	v_rcp_f32_e32 v164, v164
	v_rcp_f32_e32 v165, v165
	v_rcp_f32_e32 v166, v166
	v_rcp_f32_e32 v167, v167
	v_rcp_f32_e32 v168, v168
	v_rcp_f32_e32 v169, v169
	v_pk_mul_f32 v[24:25], v[24:25], v[154:155]
	v_pk_mul_f32 v[26:27], v[26:27], v[156:157]
	v_pk_mul_f32 v[16:17], v[16:17], v[158:159]
	v_pk_mul_f32 v[18:19], v[18:19], v[160:161]
	v_cvt_pk_bf16_f32 v154, v24, v25
	v_cvt_pk_bf16_f32 v155, v26, v27
	v_cvt_pk_bf16_f32 v156, v16, v17
	v_cvt_pk_bf16_f32 v157, v18, v19
	global_store_dwordx4 v[178:179], v[154:157], off nt
	v_lshl_add_u64 v[178:179], v[178:179], 0, s[98:99]
	s_nop 1
	v_pk_mul_f32 v[8:9], v[8:9], v[162:163]
	v_pk_mul_f32 v[10:11], v[10:11], v[164:165]
	v_pk_mul_f32 v[0:1], v[0:1], v[166:167]
	v_pk_mul_f32 v[2:3], v[2:3], v[168:169]
	v_cvt_pk_bf16_f32 v162, v8, v9
	v_cvt_pk_bf16_f32 v163, v10, v11
	v_cvt_pk_bf16_f32 v164, v0, v1
	v_cvt_pk_bf16_f32 v165, v2, v3
	global_store_dwordx4 v[178:179], v[162:165], off nt
	s_andn2_b64 vcc, exec, s[4:5]
	s_mov_b64 s[4:5], -1
	s_cbranch_vccnz .LBB0_220
	s_andn2_b64 vcc, exec, s[0:1]
	s_cbranch_vccnz .LBB0_219
	s_barrier
	s_branch .LBB0_219

; __device__ __forceinline__ unsigned cvt_pk_bf16(float lo, float hi) { unsigned r; asm volatile("v_cvt_pk_bf16_f32 %0, %1, %2" : "=v"(r) : "v"(lo), "v"(hi)); return r; }
;     __device__ __forceinline__ void operator()(const f32x4 (&acc)[2][2][4][2], const pg8::Unit& u, int wr, int wc, int fr, int fq) const {
;         const int row0 = u.pm * 256 + wr * 64 + fr, col0 = u.pn * 256 + wc * 32 + 8 * fq;
;         u32x4 xin[2][4][2];
; #pragma unroll
;         for (int ai = 0; ai < 2; ++ai)
; #pragma unroll
;             for (int m = 0; m < 4; ++m)
; #pragma unroll
;                 for (int bj = 0; bj < 2; ++bj) xin[ai][m][bj] = *(const u32x4*)(XB + (size_t)(row0 + ai * 128 + m * 16) * D + col0 + bj * 128);
; #pragma unroll
;         for (int ai = 0; ai < 2; ++ai)
; #pragma unroll
;             for (int m = 0; m < 4; ++m) { const size_t ro = (size_t)(row0 + ai * 128 + m * 16) * D + col0; float sq = 0.f;
; #pragma unroll
;                 for (int bj = 0; bj < 2; ++bj) { const u32x4 xb = xin[ai][m][bj];
;                     const f32x4 x0 = (f32x4){bf_lo(xb.x), bf_hi(xb.x), bf_lo(xb.y), bf_hi(xb.y)} + acc[ai][bj][m][0] * s, x1 = (f32x4){bf_lo(xb.z), bf_hi(xb.z), bf_lo(xb.w), bf_hi(xb.w)} + acc[ai][bj][m][1] * s;
;                     sq += (x0[0] * x0[0] + x0[1] * x0[1]) + (x0[2] * x0[2] + x0[3] * x0[3]) + (x1[0] * x1[0] + x1[1] * x1[1]) + (x1[2] * x1[2] + x1[3] * x1[3]);
;                     u32x4 w; w.x = cvt_pk_bf16(x0[0], x0[1]); w.y = cvt_pk_bf16(x0[2], x0[3]); w.z = cvt_pk_bf16(x1[0], x1[1]); w.w = cvt_pk_bf16(x1[2], x1[3]);
;                     *(u32x4*)(XB + ro + bj * 128) = w; }
;                 sq += __shfl_xor(sq, 16); sq += __shfl_xor(sq, 32);
;                 if (fq == 0) SSo[(size_t)(u.pn * 4 + wc) * T + row0 + ai * 128 + m * 16] = sq; }
.LBB0_312:
	v_lshl_or_b32 v204, s71, 8, v222
	v_lshl_add_u32 v202, s72, 8, v220
	v_ashrrev_i32_e32 v205, 31, v204
	v_lshlrev_b64 v[236:237], 1, v[204:205]
	v_ashrrev_i32_e32 v203, 31, v202
	v_lshl_add_u64 v[96:97], s[36:37], 0, v[236:237]
	v_lshlrev_b64 v[238:239], 11, v[202:203]
	v_lshl_add_u64 v[98:99], v[96:97], 0, v[238:239]
	global_load_dwordx4 v[228:231], v[98:99], off
	global_load_dwordx4 v[232:235], v[98:99], off offset:256
	v_or_b32_e32 v98, 16, v202
	v_or_b32_e32 v108, 32, v202
	v_or_b32_e32 v110, 48, v202
	v_ashrrev_i32_e32 v99, 31, v98
	v_ashrrev_i32_e32 v109, 31, v108
	v_ashrrev_i32_e32 v111, 31, v110
	v_lshlrev_b64 v[218:219], 11, v[98:99]
	v_lshlrev_b64 v[216:217], 11, v[108:109]
	v_lshlrev_b64 v[214:215], 11, v[110:111]
	v_lshl_add_u64 v[212:213], v[238:239], 0, s[16:17]
	v_lshl_add_u64 v[210:211], v[238:239], 0, s[18:19]
	v_lshl_add_u64 v[208:209], v[238:239], 0, s[42:43]
	v_lshl_add_u64 v[206:207], v[238:239], 0, s[46:47]
	v_lshl_add_u64 v[98:99], v[96:97], 0, v[218:219]
	v_lshl_add_u64 v[108:109], v[96:97], 0, v[216:217]
	v_lshl_add_u64 v[110:111], v[96:97], 0, v[214:215]
	v_lshl_add_u64 v[120:121], v[96:97], 0, v[212:213]
	v_lshl_add_u64 v[122:123], v[96:97], 0, v[210:211]
	v_lshl_add_u64 v[240:241], v[96:97], 0, v[208:209]
	v_lshl_add_u64 v[96:97], v[96:97], 0, v[206:207]
	global_load_dwordx4 v[180:183], v[98:99], off
	global_load_dwordx4 v[176:179], v[98:99], off offset:256
	global_load_dwordx4 v[172:175], v[108:109], off
	global_load_dwordx4 v[168:171], v[108:109], off offset:256
	global_load_dwordx4 v[164:167], v[110:111], off
	global_load_dwordx4 v[160:163], v[110:111], off offset:256
	global_load_dwordx4 v[156:159], v[120:121], off
	global_load_dwordx4 v[152:155], v[120:121], off offset:256
	global_load_dwordx4 v[148:151], v[122:123], off
	global_load_dwordx4 v[144:147], v[122:123], off offset:256
	global_load_dwordx4 v[128:131], v[240:241], off
	s_nop 0
	global_load_dwordx4 v[120:123], v[240:241], off offset:256
	global_load_dwordx4 v[108:111], v[96:97], off
	s_nop 0
	global_load_dwordx4 v[96:99], v[96:97], off offset:256
	s_lshl_b32 s20, s71, 2
	s_or_b32 s20, s20, s61
	s_ashr_i32 s21, s20, 31
	s_lshl_b64 s[20:21], s[20:21], 17
	s_waitcnt vmcnt(0)
	v_lshlrev_b32_e32 v240, 16, v228
	v_and_b32_e32 v241, 0xffff0000, v228
	v_lshlrev_b32_e32 v228, 16, v229
	v_and_b32_e32 v229, 0xffff0000, v229
	v_lshlrev_b32_e32 v242, 16, v230
	v_and_b32_e32 v243, 0xffff0000, v230
	v_lshlrev_b32_e32 v244, 16, v232
	v_and_b32_e32 v245, 0xffff0000, v232
	v_lshlrev_b32_e32 v232, 16, v233
	v_and_b32_e32 v233, 0xffff0000, v233
	v_lshlrev_b32_e32 v246, 16, v234
	v_and_b32_e32 v247, 0xffff0000, v234
	v_lshlrev_b32_e32 v234, 16, v235
	v_and_b32_e32 v235, 0xffff0000, v235
	v_pk_fma_f32 v[142:143], v[142:143], 0.5, v[228:229] op_sel_hi:[1,0,1]
	v_pk_fma_f32 v[140:141], v[140:141], 0.5, v[240:241] op_sel_hi:[1,0,1]
	v_lshlrev_b32_e32 v230, 16, v231
	v_and_b32_e32 v231, 0xffff0000, v231
	v_pk_fma_f32 v[136:137], v[136:137], 0.5, v[242:243] op_sel_hi:[1,0,1]
	v_pk_fma_f32 v[228:229], v[134:135], 0.5, v[232:233] op_sel_hi:[1,0,1]
	v_pk_fma_f32 v[232:233], v[126:127], 0.5, v[234:235] op_sel_hi:[1,0,1]
	v_pk_fma_f32 v[234:235], v[124:125], 0.5, v[246:247] op_sel_hi:[1,0,1]
	v_mul_f32_e32 v124, v141, v141
	v_mul_f32_e32 v125, v143, v143
	v_pk_fma_f32 v[138:139], v[138:139], 0.5, v[230:231] op_sel_hi:[1,0,1]
	v_pk_fma_f32 v[230:231], v[132:133], 0.5, v[244:245] op_sel_hi:[1,0,1]
	v_mul_f32_e32 v126, v137, v137
	v_fmac_f32_e32 v124, v140, v140
	v_fmac_f32_e32 v125, v142, v142
	v_mul_f32_e32 v127, v139, v139
	v_cvt_pk_bf16_f32 v132, v140, v141
	v_cvt_pk_bf16_f32 v133, v142, v143
	v_cvt_pk_bf16_f32 v134, v136, v137
	v_cvt_pk_bf16_f32 v135, v138, v139
	v_mul_f32_e32 v137, v231, v231
	v_mul_f32_e32 v139, v229, v229
	v_fmac_f32_e32 v126, v136, v136
	v_add_f32_e32 v124, v124, v125
	v_fmac_f32_e32 v137, v230, v230
	v_fmac_f32_e32 v139, v228, v228
	v_add_f32_e32 v124, v126, v124
	v_mul_f32_e32 v126, v235, v235
	v_add_f32_e32 v125, v137, v139
	v_fmac_f32_e32 v126, v234, v234
	v_add_f32_e32 v125, v126, v125
	v_mul_f32_e32 v126, v233, v233
	v_fmac_f32_e32 v127, v138, v138
	v_fmac_f32_e32 v126, v232, v232
	v_add_f32_e32 v124, v127, v124
	v_add_f32_e32 v125, v126, v125
	v_and_b32_e32 v126, 64, v226
	v_add_f32_e32 v125, v124, v125
	v_add_u32_e32 v138, 64, v126
	v_lshl_add_u64 v[126:127], s[36:37], 0, v[238:239]
	v_lshl_add_u64 v[136:137], v[126:127], 0, v[236:237]
	v_mov_b32_e32 v139, v125
	s_nop 1
	v_permlane16_swap_b32_e32 v139, v125
	global_store_dwordx4 v[136:137], v[132:135], off nt
	s_waitcnt lgkmcnt(0)
	v_add_f32_e32 v126, v125, v139
	v_cvt_pk_bf16_f32 v132, v230, v231
	v_cvt_pk_bf16_f32 v133, v228, v229
	v_cvt_pk_bf16_f32 v134, v234, v235
	v_cvt_pk_bf16_f32 v135, v232, v233
	global_store_dwordx4 v[136:137], v[132:135], off offset:256 nt
	s_nop 0
	v_mov_b32_e32 v127, v126
	s_nop 1
	v_permlane32_swap_b32_e32 v127, v126
	s_and_saveexec_b64 s[34:35], s[4:5]
	s_cbranch_execz .LBB0_314
	s_add_u32 s50, s59, s20
	s_addc_u32 s51, s60, s21
	v_lshl_add_u64 v[132:133], v[202:203], 2, s[50:51]
	s_waitcnt lgkmcnt(0)
	v_add_f32_e32 v126, v126, v127
	global_store_dword v[132:133], v126, off
; __device__ __forceinline__ unsigned cvt_pk_bf16(float lo, float hi) { unsigned r; asm volatile("v_cvt_pk_bf16_f32 %0, %1, %2" : "=v"(r) : "v"(lo), "v"(hi)); return r; }
;     __device__ __forceinline__ void operator()(const f32x4 (&acc)[2][2][4][2], const pg8::Unit& u, int wr, int wc, int fr, int fq) const {
;     ...
;             for (int m = 0; m < 4; ++m) { const size_t ro = (size_t)(row0 + ai * 128 + m * 16) * D + col0; float sq = 0.f;
; #pragma unroll
;                 for (int bj = 0; bj < 2; ++bj) { const u32x4 xb = xin[ai][m][bj];
;                     const f32x4 x0 = (f32x4){bf_lo(xb.x), bf_hi(xb.x), bf_lo(xb.y), bf_hi(xb.y)} + acc[ai][bj][m][0] * s, x1 = (f32x4){bf_lo(xb.z), bf_hi(xb.z), bf_lo(xb.w), bf_hi(xb.w)} + acc[ai][bj][m][1] * s;
;                     sq += (x0[0] * x0[0] + x0[1] * x0[1]) + (x0[2] * x0[2] + x0[3] * x0[3]) + (x1[0] * x1[0] + x1[1] * x1[1]) + (x1[2] * x1[2] + x1[3] * x1[3]);
;                     u32x4 w; w.x = cvt_pk_bf16(x0[0], x0[1]); w.y = cvt_pk_bf16(x0[2], x0[3]); w.z = cvt_pk_bf16(x1[0], x1[1]); w.w = cvt_pk_bf16(x1[2], x1[3]);
;                     *(u32x4*)(XB + ro + bj * 128) = w; }
;                 sq += __shfl_xor(sq, 16); sq += __shfl_xor(sq, 32);
;                 if (fq == 0) SSo[(size_t)(u.pn * 4 + wc) * T + row0 + ai * 128 + m * 16] = sq; }
.LBB0_314:
	s_or_b64 exec, exec, s[34:35]
	v_lshlrev_b32_e32 v126, 16, v180
	s_waitcnt lgkmcnt(0)
	v_and_b32_e32 v127, 0xffff0000, v180
	v_lshlrev_b32_e32 v132, 16, v181
	v_and_b32_e32 v133, 0xffff0000, v181
	v_pk_fma_f32 v[118:119], v[118:119], 0.5, v[132:133] op_sel_hi:[1,0,1]
	v_pk_fma_f32 v[116:117], v[116:117], 0.5, v[126:127] op_sel_hi:[1,0,1]
	v_lshlrev_b32_e32 v126, 16, v182
	v_and_b32_e32 v127, 0xffff0000, v182
	v_lshlrev_b32_e32 v132, 16, v183
	v_and_b32_e32 v133, 0xffff0000, v183
	v_pk_fma_f32 v[132:133], v[114:115], 0.5, v[132:133] op_sel_hi:[1,0,1]
	v_pk_fma_f32 v[114:115], v[112:113], 0.5, v[126:127] op_sel_hi:[1,0,1]
	v_mul_f32_e32 v112, v117, v117
	v_mul_f32_e32 v113, v119, v119
	v_fmac_f32_e32 v112, v116, v116
	v_fmac_f32_e32 v113, v118, v118
	v_add_f32_e32 v112, v112, v113
	v_mul_f32_e32 v113, v115, v115
	v_fmac_f32_e32 v113, v114, v114
	v_add_f32_e32 v112, v113, v112
	v_mul_f32_e32 v113, v133, v133
	v_fmac_f32_e32 v113, v132, v132
	v_add_f32_e32 v126, v113, v112
	v_cvt_pk_bf16_f32 v112, v116, v117
	v_cvt_pk_bf16_f32 v113, v118, v119
	v_lshlrev_b32_e32 v116, 16, v176
	v_and_b32_e32 v117, 0xffff0000, v176
	v_lshlrev_b32_e32 v118, 16, v177
	v_and_b32_e32 v119, 0xffff0000, v177
	v_pk_fma_f32 v[106:107], v[106:107], 0.5, v[118:119] op_sel_hi:[1,0,1]
	v_pk_fma_f32 v[104:105], v[104:105], 0.5, v[116:117] op_sel_hi:[1,0,1]
	v_lshlrev_b32_e32 v116, 16, v178
	v_and_b32_e32 v117, 0xffff0000, v178
	v_pk_fma_f32 v[116:117], v[100:101], 0.5, v[116:117] op_sel_hi:[1,0,1]
	v_mul_f32_e32 v100, v105, v105
	v_mul_f32_e32 v101, v107, v107
	v_fmac_f32_e32 v100, v104, v104
	v_fmac_f32_e32 v101, v106, v106
	v_lshlrev_b32_e32 v118, 16, v179
	v_and_b32_e32 v119, 0xffff0000, v179
	v_add_f32_e32 v100, v100, v101
	v_mul_f32_e32 v101, v117, v117
	v_pk_fma_f32 v[118:119], v[102:103], 0.5, v[118:119] op_sel_hi:[1,0,1]
	v_fmac_f32_e32 v101, v116, v116
	v_add_f32_e32 v100, v101, v100
	v_mul_f32_e32 v101, v119, v119
	v_fmac_f32_e32 v101, v118, v118
	v_add_f32_e32 v100, v101, v100
	v_add_f32_e32 v103, v126, v100
	v_cvt_pk_bf16_f32 v114, v114, v115
	v_cvt_pk_bf16_f32 v115, v132, v133
	v_mov_b32_e32 v132, v103
	s_nop 1
	v_permlane16_swap_b32_e32 v132, v103
	v_lshl_add_u64 v[100:101], s[36:37], 0, v[218:219]
	v_lshl_add_u64 v[126:127], v[204:205], 1, v[100:101]
	global_store_dwordx4 v[126:127], v[112:115], off nt
	v_cvt_pk_bf16_f32 v102, v104, v105
	s_waitcnt lgkmcnt(0)
	v_add_f32_e32 v100, v103, v132
	v_mov_b32_e32 v101, v100
	s_nop 1
	v_permlane32_swap_b32_e32 v101, v100
	v_cvt_pk_bf16_f32 v103, v106, v107
	v_cvt_pk_bf16_f32 v104, v116, v117
	v_cvt_pk_bf16_f32 v105, v118, v119
	global_store_dwordx4 v[126:127], v[102:105], off offset:256 nt
	s_and_saveexec_b64 s[34:35], s[4:5]
	s_cbranch_execz .LBB0_316
	s_add_u32 s50, s59, s20
	s_addc_u32 s51, s60, s21
	v_lshl_add_u64 v[102:103], v[202:203], 2, s[50:51]
	s_waitcnt lgkmcnt(0)
	v_add_f32_e32 v100, v100, v101
	global_store_dword v[102:103], v100, off offset:64
.LBB0_316:
	s_or_b64 exec, exec, s[34:35]
	v_lshlrev_b32_e32 v100, 16, v172
	s_waitcnt lgkmcnt(0)
	v_and_b32_e32 v101, 0xffff0000, v172
	v_lshlrev_b32_e32 v102, 16, v173
	v_and_b32_e32 v103, 0xffff0000, v173
	v_pk_fma_f32 v[94:95], v[94:95], 0.5, v[102:103] op_sel_hi:[1,0,1]
	v_pk_fma_f32 v[92:93], v[92:93], 0.5, v[100:101] op_sel_hi:[1,0,1]
	v_lshlrev_b32_e32 v100, 16, v174
	v_and_b32_e32 v101, 0xffff0000, v174
	v_lshlrev_b32_e32 v102, 16, v175
	v_and_b32_e32 v103, 0xffff0000, v175
	v_pk_fma_f32 v[102:103], v[90:91], 0.5, v[102:103] op_sel_hi:[1,0,1]
	v_pk_fma_f32 v[90:91], v[88:89], 0.5, v[100:101] op_sel_hi:[1,0,1]
	v_mul_f32_e32 v88, v93, v93
	v_mul_f32_e32 v89, v95, v95
	v_fmac_f32_e32 v88, v92, v92
	v_fmac_f32_e32 v89, v94, v94
	v_add_f32_e32 v88, v88, v89
	v_mul_f32_e32 v89, v91, v91
	v_fmac_f32_e32 v89, v90, v90
	v_add_f32_e32 v88, v89, v88
	v_mul_f32_e32 v89, v103, v103
	v_fmac_f32_e32 v89, v102, v102
	v_add_f32_e32 v100, v89, v88
	v_cvt_pk_bf16_f32 v88, v92, v93
	v_cvt_pk_bf16_f32 v89, v94, v95
	v_lshlrev_b32_e32 v92, 16, v168
	v_and_b32_e32 v93, 0xffff0000, v168
	v_lshlrev_b32_e32 v94, 16, v169
	v_and_b32_e32 v95, 0xffff0000, v169
	v_pk_fma_f32 v[86:87], v[86:87], 0.5, v[94:95] op_sel_hi:[1,0,1]
	v_pk_fma_f32 v[84:85], v[84:85], 0.5, v[92:93] op_sel_hi:[1,0,1]
	v_lshlrev_b32_e32 v92, 16, v170
	v_and_b32_e32 v93, 0xffff0000, v170
	v_pk_fma_f32 v[92:93], v[80:81], 0.5, v[92:93] op_sel_hi:[1,0,1]
	v_mul_f32_e32 v80, v85, v85
	v_mul_f32_e32 v81, v87, v87
	v_fmac_f32_e32 v80, v84, v84
	v_fmac_f32_e32 v81, v86, v86
	v_lshlrev_b32_e32 v94, 16, v171
	v_and_b32_e32 v95, 0xffff0000, v171
	v_add_f32_e32 v80, v80, v81
	v_mul_f32_e32 v81, v93, v93
	v_pk_fma_f32 v[94:95], v[82:83], 0.5, v[94:95] op_sel_hi:[1,0,1]
	v_fmac_f32_e32 v81, v92, v92
	v_add_f32_e32 v80, v81, v80
	v_mul_f32_e32 v81, v95, v95
	v_fmac_f32_e32 v81, v94, v94
	v_add_f32_e32 v80, v81, v80
	v_add_f32_e32 v83, v100, v80
	v_cvt_pk_bf16_f32 v90, v90, v91
	v_cvt_pk_bf16_f32 v91, v102, v103
	v_mov_b32_e32 v102, v83
	s_nop 1
	v_permlane16_swap_b32_e32 v102, v83
	v_lshl_add_u64 v[80:81], s[36:37], 0, v[216:217]
	v_lshl_add_u64 v[100:101], v[204:205], 1, v[80:81]
	global_store_dwordx4 v[100:101], v[88:91], off nt
	v_cvt_pk_bf16_f32 v82, v84, v85
	s_waitcnt lgkmcnt(0)
	v_add_f32_e32 v80, v83, v102
	v_mov_b32_e32 v81, v80
	s_nop 1
	v_permlane32_swap_b32_e32 v81, v80
	v_cvt_pk_bf16_f32 v83, v86, v87
	v_cvt_pk_bf16_f32 v84, v92, v93
	v_cvt_pk_bf16_f32 v85, v94, v95
	global_store_dwordx4 v[100:101], v[82:85], off offset:256 nt
	s_and_saveexec_b64 s[34:35], s[4:5]
	s_cbranch_execz .LBB0_318
	s_add_u32 s50, s59, s20
	s_addc_u32 s51, s60, s21
	v_lshl_add_u64 v[82:83], v[202:203], 2, s[50:51]
	s_waitcnt lgkmcnt(0)
	v_add_f32_e32 v80, v80, v81
	global_store_dword v[82:83], v80, off offset:128
; __device__ __forceinline__ unsigned cvt_pk_bf16(float lo, float hi) { unsigned r; asm volatile("v_cvt_pk_bf16_f32 %0, %1, %2" : "=v"(r) : "v"(lo), "v"(hi)); return r; }
;     __device__ __forceinline__ void operator()(const f32x4 (&acc)[2][2][4][2], const pg8::Unit& u, int wr, int wc, int fr, int fq) const {
;     ...
;             for (int m = 0; m < 4; ++m) { const size_t ro = (size_t)(row0 + ai * 128 + m * 16) * D + col0; float sq = 0.f;
; #pragma unroll
;                 for (int bj = 0; bj < 2; ++bj) { const u32x4 xb = xin[ai][m][bj];
;                     const f32x4 x0 = (f32x4){bf_lo(xb.x), bf_hi(xb.x), bf_lo(xb.y), bf_hi(xb.y)} + acc[ai][bj][m][0] * s, x1 = (f32x4){bf_lo(xb.z), bf_hi(xb.z), bf_lo(xb.w), bf_hi(xb.w)} + acc[ai][bj][m][1] * s;
;                     sq += (x0[0] * x0[0] + x0[1] * x0[1]) + (x0[2] * x0[2] + x0[3] * x0[3]) + (x1[0] * x1[0] + x1[1] * x1[1]) + (x1[2] * x1[2] + x1[3] * x1[3]);
;                     u32x4 w; w.x = cvt_pk_bf16(x0[0], x0[1]); w.y = cvt_pk_bf16(x0[2], x0[3]); w.z = cvt_pk_bf16(x1[0], x1[1]); w.w = cvt_pk_bf16(x1[2], x1[3]);
;                     *(u32x4*)(XB + ro + bj * 128) = w; }
;                 sq += __shfl_xor(sq, 16); sq += __shfl_xor(sq, 32);
;                 if (fq == 0) SSo[(size_t)(u.pn * 4 + wc) * T + row0 + ai * 128 + m * 16] = sq; }
.LBB0_318:
	s_or_b64 exec, exec, s[34:35]
	v_lshlrev_b32_e32 v80, 16, v164
	s_waitcnt lgkmcnt(0)
	v_and_b32_e32 v81, 0xffff0000, v164
	v_lshlrev_b32_e32 v82, 16, v165
	v_and_b32_e32 v83, 0xffff0000, v165
	v_pk_fma_f32 v[78:79], v[78:79], 0.5, v[82:83] op_sel_hi:[1,0,1]
	v_pk_fma_f32 v[76:77], v[76:77], 0.5, v[80:81] op_sel_hi:[1,0,1]
	v_lshlrev_b32_e32 v80, 16, v166
	v_and_b32_e32 v81, 0xffff0000, v166
	v_lshlrev_b32_e32 v82, 16, v167
	v_and_b32_e32 v83, 0xffff0000, v167
	v_pk_fma_f32 v[82:83], v[74:75], 0.5, v[82:83] op_sel_hi:[1,0,1]
	v_pk_fma_f32 v[74:75], v[72:73], 0.5, v[80:81] op_sel_hi:[1,0,1]
	v_mul_f32_e32 v72, v77, v77
	v_mul_f32_e32 v73, v79, v79
	v_fmac_f32_e32 v72, v76, v76
	v_fmac_f32_e32 v73, v78, v78
	v_add_f32_e32 v72, v72, v73
	v_mul_f32_e32 v73, v75, v75
	v_fmac_f32_e32 v73, v74, v74
	v_add_f32_e32 v72, v73, v72
	v_mul_f32_e32 v73, v83, v83
	v_fmac_f32_e32 v73, v82, v82
	v_add_f32_e32 v80, v73, v72
	v_cvt_pk_bf16_f32 v72, v76, v77
	v_cvt_pk_bf16_f32 v73, v78, v79
	v_lshlrev_b32_e32 v76, 16, v160
	v_and_b32_e32 v77, 0xffff0000, v160
	v_lshlrev_b32_e32 v78, 16, v161
	v_and_b32_e32 v79, 0xffff0000, v161
	v_pk_fma_f32 v[70:71], v[70:71], 0.5, v[78:79] op_sel_hi:[1,0,1]
	v_pk_fma_f32 v[68:69], v[68:69], 0.5, v[76:77] op_sel_hi:[1,0,1]
	v_lshlrev_b32_e32 v76, 16, v162
	v_and_b32_e32 v77, 0xffff0000, v162
	v_pk_fma_f32 v[76:77], v[64:65], 0.5, v[76:77] op_sel_hi:[1,0,1]
	v_mul_f32_e32 v64, v69, v69
	v_mul_f32_e32 v65, v71, v71
	v_fmac_f32_e32 v64, v68, v68
	v_fmac_f32_e32 v65, v70, v70
	v_lshlrev_b32_e32 v78, 16, v163
	v_and_b32_e32 v79, 0xffff0000, v163
	v_add_f32_e32 v64, v64, v65
	v_mul_f32_e32 v65, v77, v77
	v_pk_fma_f32 v[78:79], v[66:67], 0.5, v[78:79] op_sel_hi:[1,0,1]
	v_fmac_f32_e32 v65, v76, v76
	v_add_f32_e32 v64, v65, v64
	v_mul_f32_e32 v65, v79, v79
	v_fmac_f32_e32 v65, v78, v78
	v_add_f32_e32 v64, v65, v64
	v_add_f32_e32 v67, v80, v64
	v_cvt_pk_bf16_f32 v74, v74, v75
	v_cvt_pk_bf16_f32 v75, v82, v83
	v_mov_b32_e32 v82, v67
	s_nop 1
	v_permlane16_swap_b32_e32 v82, v67
	v_lshl_add_u64 v[64:65], s[36:37], 0, v[214:215]
	v_lshl_add_u64 v[80:81], v[204:205], 1, v[64:65]
	global_store_dwordx4 v[80:81], v[72:75], off nt
	v_cvt_pk_bf16_f32 v66, v68, v69
	s_waitcnt lgkmcnt(0)
	v_add_f32_e32 v64, v67, v82
	v_mov_b32_e32 v65, v64
	s_nop 1
	v_permlane32_swap_b32_e32 v65, v64
	v_cvt_pk_bf16_f32 v67, v70, v71
	v_cvt_pk_bf16_f32 v68, v76, v77
	v_cvt_pk_bf16_f32 v69, v78, v79
	global_store_dwordx4 v[80:81], v[66:69], off offset:256 nt
	s_and_saveexec_b64 s[34:35], s[4:5]
	s_cbranch_execz .LBB0_320
	s_add_u32 s50, s59, s20
	s_addc_u32 s51, s60, s21
	v_lshl_add_u64 v[66:67], v[202:203], 2, s[50:51]
	s_waitcnt lgkmcnt(0)
	v_add_f32_e32 v64, v64, v65
	global_store_dword v[66:67], v64, off offset:192
.LBB0_320:
	s_or_b64 exec, exec, s[34:35]
	v_lshlrev_b32_e32 v64, 16, v156
	s_waitcnt lgkmcnt(0)
	v_and_b32_e32 v65, 0xffff0000, v156
	v_lshlrev_b32_e32 v66, 16, v157
	v_and_b32_e32 v67, 0xffff0000, v157
	v_pk_fma_f32 v[62:63], v[62:63], 0.5, v[66:67] op_sel_hi:[1,0,1]
	v_pk_fma_f32 v[60:61], v[60:61], 0.5, v[64:65] op_sel_hi:[1,0,1]
	v_lshlrev_b32_e32 v64, 16, v158
	v_and_b32_e32 v65, 0xffff0000, v158
	v_lshlrev_b32_e32 v66, 16, v159
	v_and_b32_e32 v67, 0xffff0000, v159
	v_pk_fma_f32 v[66:67], v[58:59], 0.5, v[66:67] op_sel_hi:[1,0,1]
	v_pk_fma_f32 v[58:59], v[56:57], 0.5, v[64:65] op_sel_hi:[1,0,1]
	v_mul_f32_e32 v56, v61, v61
	v_mul_f32_e32 v57, v63, v63
	v_fmac_f32_e32 v56, v60, v60
	v_fmac_f32_e32 v57, v62, v62
	v_add_f32_e32 v56, v56, v57
	v_mul_f32_e32 v57, v59, v59
	v_fmac_f32_e32 v57, v58, v58
	v_add_f32_e32 v56, v57, v56
	v_mul_f32_e32 v57, v67, v67
	v_fmac_f32_e32 v57, v66, v66
	v_add_f32_e32 v64, v57, v56
	v_cvt_pk_bf16_f32 v56, v60, v61
	v_cvt_pk_bf16_f32 v57, v62, v63
	v_lshlrev_b32_e32 v60, 16, v152
	v_and_b32_e32 v61, 0xffff0000, v152
	v_lshlrev_b32_e32 v62, 16, v153
	v_and_b32_e32 v63, 0xffff0000, v153
	v_pk_fma_f32 v[54:55], v[54:55], 0.5, v[62:63] op_sel_hi:[1,0,1]
	v_pk_fma_f32 v[52:53], v[52:53], 0.5, v[60:61] op_sel_hi:[1,0,1]
	v_lshlrev_b32_e32 v60, 16, v154
	v_and_b32_e32 v61, 0xffff0000, v154
	v_pk_fma_f32 v[60:61], v[48:49], 0.5, v[60:61] op_sel_hi:[1,0,1]
	v_mul_f32_e32 v48, v53, v53
	v_mul_f32_e32 v49, v55, v55
	v_fmac_f32_e32 v48, v52, v52
	v_fmac_f32_e32 v49, v54, v54
	v_lshlrev_b32_e32 v62, 16, v155
	v_and_b32_e32 v63, 0xffff0000, v155
	v_add_f32_e32 v48, v48, v49
	v_mul_f32_e32 v49, v61, v61
	v_pk_fma_f32 v[62:63], v[50:51], 0.5, v[62:63] op_sel_hi:[1,0,1]
	v_fmac_f32_e32 v49, v60, v60
	v_add_f32_e32 v48, v49, v48
	v_mul_f32_e32 v49, v63, v63
	v_fmac_f32_e32 v49, v62, v62
	v_add_f32_e32 v48, v49, v48
	v_add_f32_e32 v51, v64, v48
	v_cvt_pk_bf16_f32 v58, v58, v59
	v_cvt_pk_bf16_f32 v59, v66, v67
	v_mov_b32_e32 v66, v51
	s_nop 1
	v_permlane16_swap_b32_e32 v66, v51
	v_lshl_add_u64 v[48:49], s[36:37], 0, v[212:213]
	v_lshl_add_u64 v[64:65], v[204:205], 1, v[48:49]
	global_store_dwordx4 v[64:65], v[56:59], off nt
	v_cvt_pk_bf16_f32 v50, v52, v53
	s_waitcnt lgkmcnt(0)
	v_add_f32_e32 v48, v51, v66
	v_mov_b32_e32 v49, v48
	s_nop 1
	v_permlane32_swap_b32_e32 v49, v48
	v_cvt_pk_bf16_f32 v51, v54, v55
	v_cvt_pk_bf16_f32 v52, v60, v61
	v_cvt_pk_bf16_f32 v53, v62, v63
	global_store_dwordx4 v[64:65], v[50:53], off offset:256 nt
	s_and_saveexec_b64 s[34:35], s[4:5]
	s_cbranch_execz .LBB0_322
	s_add_u32 s50, s59, s20
	s_addc_u32 s51, s60, s21
	v_lshl_add_u64 v[50:51], v[202:203], 2, s[50:51]
	s_waitcnt lgkmcnt(0)
	v_add_f32_e32 v48, v48, v49
	global_store_dword v[50:51], v48, off offset:512
; __device__ __forceinline__ unsigned cvt_pk_bf16(float lo, float hi) { unsigned r; asm volatile("v_cvt_pk_bf16_f32 %0, %1, %2" : "=v"(r) : "v"(lo), "v"(hi)); return r; }
;     __device__ __forceinline__ void operator()(const f32x4 (&acc)[2][2][4][2], const pg8::Unit& u, int wr, int wc, int fr, int fq) const {
;     ...
;             for (int m = 0; m < 4; ++m) { const size_t ro = (size_t)(row0 + ai * 128 + m * 16) * D + col0; float sq = 0.f;
; #pragma unroll
;                 for (int bj = 0; bj < 2; ++bj) { const u32x4 xb = xin[ai][m][bj];
;                     const f32x4 x0 = (f32x4){bf_lo(xb.x), bf_hi(xb.x), bf_lo(xb.y), bf_hi(xb.y)} + acc[ai][bj][m][0] * s, x1 = (f32x4){bf_lo(xb.z), bf_hi(xb.z), bf_lo(xb.w), bf_hi(xb.w)} + acc[ai][bj][m][1] * s;
;                     sq += (x0[0] * x0[0] + x0[1] * x0[1]) + (x0[2] * x0[2] + x0[3] * x0[3]) + (x1[0] * x1[0] + x1[1] * x1[1]) + (x1[2] * x1[2] + x1[3] * x1[3]);
;                     u32x4 w; w.x = cvt_pk_bf16(x0[0], x0[1]); w.y = cvt_pk_bf16(x0[2], x0[3]); w.z = cvt_pk_bf16(x1[0], x1[1]); w.w = cvt_pk_bf16(x1[2], x1[3]);
;                     *(u32x4*)(XB + ro + bj * 128) = w; }
;                 sq += __shfl_xor(sq, 16); sq += __shfl_xor(sq, 32);
;                 if (fq == 0) SSo[(size_t)(u.pn * 4 + wc) * T + row0 + ai * 128 + m * 16] = sq; }
.LBB0_322:
	s_or_b64 exec, exec, s[34:35]
	v_lshlrev_b32_e32 v48, 16, v148
	s_waitcnt lgkmcnt(0)
	v_and_b32_e32 v49, 0xffff0000, v148
	v_lshlrev_b32_e32 v50, 16, v149
	v_and_b32_e32 v51, 0xffff0000, v149
	v_pk_fma_f32 v[46:47], v[46:47], 0.5, v[50:51] op_sel_hi:[1,0,1]
	v_pk_fma_f32 v[44:45], v[44:45], 0.5, v[48:49] op_sel_hi:[1,0,1]
	v_lshlrev_b32_e32 v48, 16, v150
	v_and_b32_e32 v49, 0xffff0000, v150
	v_lshlrev_b32_e32 v50, 16, v151
	v_and_b32_e32 v51, 0xffff0000, v151
	v_pk_fma_f32 v[50:51], v[42:43], 0.5, v[50:51] op_sel_hi:[1,0,1]
	v_pk_fma_f32 v[42:43], v[40:41], 0.5, v[48:49] op_sel_hi:[1,0,1]
	v_mul_f32_e32 v40, v45, v45
	v_mul_f32_e32 v41, v47, v47
	v_fmac_f32_e32 v40, v44, v44
	v_fmac_f32_e32 v41, v46, v46
	v_add_f32_e32 v40, v40, v41
	v_mul_f32_e32 v41, v43, v43
	v_fmac_f32_e32 v41, v42, v42
	v_add_f32_e32 v40, v41, v40
	v_mul_f32_e32 v41, v51, v51
	v_fmac_f32_e32 v41, v50, v50
	v_add_f32_e32 v48, v41, v40
	v_cvt_pk_bf16_f32 v40, v44, v45
	v_cvt_pk_bf16_f32 v41, v46, v47
	v_lshlrev_b32_e32 v44, 16, v144
	v_and_b32_e32 v45, 0xffff0000, v144
	v_lshlrev_b32_e32 v46, 16, v145
	v_and_b32_e32 v47, 0xffff0000, v145
	v_pk_fma_f32 v[38:39], v[38:39], 0.5, v[46:47] op_sel_hi:[1,0,1]
	v_pk_fma_f32 v[36:37], v[36:37], 0.5, v[44:45] op_sel_hi:[1,0,1]
	v_lshlrev_b32_e32 v44, 16, v146
	v_and_b32_e32 v45, 0xffff0000, v146
	v_pk_fma_f32 v[44:45], v[32:33], 0.5, v[44:45] op_sel_hi:[1,0,1]
	v_mul_f32_e32 v32, v37, v37
	v_mul_f32_e32 v33, v39, v39
	v_fmac_f32_e32 v32, v36, v36
	v_fmac_f32_e32 v33, v38, v38
	v_lshlrev_b32_e32 v46, 16, v147
	v_and_b32_e32 v47, 0xffff0000, v147
	v_add_f32_e32 v32, v32, v33
	v_mul_f32_e32 v33, v45, v45
	v_pk_fma_f32 v[46:47], v[34:35], 0.5, v[46:47] op_sel_hi:[1,0,1]
	v_fmac_f32_e32 v33, v44, v44
	v_add_f32_e32 v32, v33, v32
	v_mul_f32_e32 v33, v47, v47
	v_fmac_f32_e32 v33, v46, v46
	v_add_f32_e32 v32, v33, v32
	v_add_f32_e32 v35, v48, v32
	v_cvt_pk_bf16_f32 v42, v42, v43
	v_cvt_pk_bf16_f32 v43, v50, v51
	v_mov_b32_e32 v50, v35
	s_nop 1
	v_permlane16_swap_b32_e32 v50, v35
	v_lshl_add_u64 v[32:33], s[36:37], 0, v[210:211]
	v_lshl_add_u64 v[48:49], v[204:205], 1, v[32:33]
	global_store_dwordx4 v[48:49], v[40:43], off nt
	v_cvt_pk_bf16_f32 v34, v36, v37
	s_waitcnt lgkmcnt(0)
	v_add_f32_e32 v32, v35, v50
	v_mov_b32_e32 v33, v32
	s_nop 1
	v_permlane32_swap_b32_e32 v33, v32
	v_cvt_pk_bf16_f32 v35, v38, v39
	v_cvt_pk_bf16_f32 v36, v44, v45
	v_cvt_pk_bf16_f32 v37, v46, v47
	global_store_dwordx4 v[48:49], v[34:37], off offset:256 nt
	s_and_saveexec_b64 s[34:35], s[4:5]
	s_cbranch_execz .LBB0_324
	s_add_u32 s50, s59, s20
	s_addc_u32 s51, s60, s21
	v_lshl_add_u64 v[34:35], v[202:203], 2, s[50:51]
	s_waitcnt lgkmcnt(0)
	v_add_f32_e32 v32, v32, v33
	global_store_dword v[34:35], v32, off offset:576
; __device__ __forceinline__ unsigned cvt_pk_bf16(float lo, float hi) { unsigned r; asm volatile("v_cvt_pk_bf16_f32 %0, %1, %2" : "=v"(r) : "v"(lo), "v"(hi)); return r; }
;     __device__ __forceinline__ void operator()(const f32x4 (&acc)[2][2][4][2], const pg8::Unit& u, int wr, int wc, int fr, int fq) const {
;     ...
;             for (int m = 0; m < 4; ++m) { const size_t ro = (size_t)(row0 + ai * 128 + m * 16) * D + col0; float sq = 0.f;
; #pragma unroll
;                 for (int bj = 0; bj < 2; ++bj) { const u32x4 xb = xin[ai][m][bj];
;                     const f32x4 x0 = (f32x4){bf_lo(xb.x), bf_hi(xb.x), bf_lo(xb.y), bf_hi(xb.y)} + acc[ai][bj][m][0] * s, x1 = (f32x4){bf_lo(xb.z), bf_hi(xb.z), bf_lo(xb.w), bf_hi(xb.w)} + acc[ai][bj][m][1] * s;
;                     sq += (x0[0] * x0[0] + x0[1] * x0[1]) + (x0[2] * x0[2] + x0[3] * x0[3]) + (x1[0] * x1[0] + x1[1] * x1[1]) + (x1[2] * x1[2] + x1[3] * x1[3]);
;                     u32x4 w; w.x = cvt_pk_bf16(x0[0], x0[1]); w.y = cvt_pk_bf16(x0[2], x0[3]); w.z = cvt_pk_bf16(x1[0], x1[1]); w.w = cvt_pk_bf16(x1[2], x1[3]);
;                     *(u32x4*)(XB + ro + bj * 128) = w; }
;                 sq += __shfl_xor(sq, 16); sq += __shfl_xor(sq, 32);
;                 if (fq == 0) SSo[(size_t)(u.pn * 4 + wc) * T + row0 + ai * 128 + m * 16] = sq; }
.LBB0_324:
	s_or_b64 exec, exec, s[34:35]
	v_lshlrev_b32_e32 v32, 16, v128
	s_waitcnt lgkmcnt(0)
	v_and_b32_e32 v33, 0xffff0000, v128
	v_lshlrev_b32_e32 v34, 16, v129
	v_and_b32_e32 v35, 0xffff0000, v129
	v_pk_fma_f32 v[30:31], v[30:31], 0.5, v[34:35] op_sel_hi:[1,0,1]
	v_pk_fma_f32 v[28:29], v[28:29], 0.5, v[32:33] op_sel_hi:[1,0,1]
	v_lshlrev_b32_e32 v32, 16, v130
	v_and_b32_e32 v33, 0xffff0000, v130
	v_lshlrev_b32_e32 v34, 16, v131
	v_and_b32_e32 v35, 0xffff0000, v131
	v_pk_fma_f32 v[34:35], v[26:27], 0.5, v[34:35] op_sel_hi:[1,0,1]
	v_pk_fma_f32 v[26:27], v[24:25], 0.5, v[32:33] op_sel_hi:[1,0,1]
	v_mul_f32_e32 v24, v29, v29
	v_mul_f32_e32 v25, v31, v31
	v_fmac_f32_e32 v24, v28, v28
	v_fmac_f32_e32 v25, v30, v30
	v_add_f32_e32 v24, v24, v25
	v_mul_f32_e32 v25, v27, v27
	v_fmac_f32_e32 v25, v26, v26
	v_add_f32_e32 v24, v25, v24
	v_mul_f32_e32 v25, v35, v35
	v_fmac_f32_e32 v25, v34, v34
	v_add_f32_e32 v32, v25, v24
	v_cvt_pk_bf16_f32 v24, v28, v29
	v_cvt_pk_bf16_f32 v25, v30, v31
	v_lshlrev_b32_e32 v28, 16, v120
	v_and_b32_e32 v29, 0xffff0000, v120
	v_lshlrev_b32_e32 v30, 16, v121
	v_and_b32_e32 v31, 0xffff0000, v121
	v_pk_fma_f32 v[22:23], v[22:23], 0.5, v[30:31] op_sel_hi:[1,0,1]
	v_pk_fma_f32 v[20:21], v[20:21], 0.5, v[28:29] op_sel_hi:[1,0,1]
	v_lshlrev_b32_e32 v28, 16, v122
	v_and_b32_e32 v29, 0xffff0000, v122
	v_pk_fma_f32 v[28:29], v[16:17], 0.5, v[28:29] op_sel_hi:[1,0,1]
	v_mul_f32_e32 v16, v21, v21
	v_mul_f32_e32 v17, v23, v23
	v_fmac_f32_e32 v16, v20, v20
	v_fmac_f32_e32 v17, v22, v22
	v_lshlrev_b32_e32 v30, 16, v123
	v_and_b32_e32 v31, 0xffff0000, v123
	v_add_f32_e32 v16, v16, v17
	v_mul_f32_e32 v17, v29, v29
	v_pk_fma_f32 v[30:31], v[18:19], 0.5, v[30:31] op_sel_hi:[1,0,1]
	v_fmac_f32_e32 v17, v28, v28
	v_add_f32_e32 v16, v17, v16
	v_mul_f32_e32 v17, v31, v31
	v_fmac_f32_e32 v17, v30, v30
	v_add_f32_e32 v16, v17, v16
	v_add_f32_e32 v19, v32, v16
	v_cvt_pk_bf16_f32 v26, v26, v27
	v_cvt_pk_bf16_f32 v27, v34, v35
	v_mov_b32_e32 v34, v19
	s_nop 1
	v_permlane16_swap_b32_e32 v34, v19
	v_lshl_add_u64 v[16:17], s[36:37], 0, v[208:209]
	v_lshl_add_u64 v[32:33], v[204:205], 1, v[16:17]
	global_store_dwordx4 v[32:33], v[24:27], off nt
	v_cvt_pk_bf16_f32 v18, v20, v21
	s_waitcnt lgkmcnt(0)
	v_add_f32_e32 v16, v19, v34
	v_mov_b32_e32 v17, v16
	s_nop 1
	v_permlane32_swap_b32_e32 v17, v16
	v_cvt_pk_bf16_f32 v19, v22, v23
	v_cvt_pk_bf16_f32 v20, v28, v29
	v_cvt_pk_bf16_f32 v21, v30, v31
	global_store_dwordx4 v[32:33], v[18:21], off offset:256 nt
	s_and_saveexec_b64 s[34:35], s[4:5]
	s_cbranch_execz .LBB0_326
	s_add_u32 s50, s59, s20
	s_addc_u32 s51, s60, s21
	v_lshl_add_u64 v[18:19], v[202:203], 2, s[50:51]
	s_waitcnt lgkmcnt(0)
	v_add_f32_e32 v16, v16, v17
	global_store_dword v[18:19], v16, off offset:640
.LBB0_326:
	s_or_b64 exec, exec, s[34:35]
	v_lshlrev_b32_e32 v16, 16, v108
	s_waitcnt lgkmcnt(0)
	v_and_b32_e32 v17, 0xffff0000, v108
	v_lshlrev_b32_e32 v18, 16, v109
	v_and_b32_e32 v19, 0xffff0000, v109
	v_pk_fma_f32 v[14:15], v[14:15], 0.5, v[18:19] op_sel_hi:[1,0,1]
	v_pk_fma_f32 v[12:13], v[12:13], 0.5, v[16:17] op_sel_hi:[1,0,1]
	v_lshlrev_b32_e32 v16, 16, v110
	v_and_b32_e32 v17, 0xffff0000, v110
	v_lshlrev_b32_e32 v18, 16, v111
	v_and_b32_e32 v19, 0xffff0000, v111
	v_pk_fma_f32 v[18:19], v[10:11], 0.5, v[18:19] op_sel_hi:[1,0,1]
	v_pk_fma_f32 v[10:11], v[8:9], 0.5, v[16:17] op_sel_hi:[1,0,1]
	v_mul_f32_e32 v8, v13, v13
	v_mul_f32_e32 v9, v15, v15
	v_fmac_f32_e32 v8, v12, v12
	v_fmac_f32_e32 v9, v14, v14
	v_add_f32_e32 v8, v8, v9
	v_mul_f32_e32 v9, v11, v11
	v_fmac_f32_e32 v9, v10, v10
	v_add_f32_e32 v8, v9, v8
	v_mul_f32_e32 v9, v19, v19
	v_fmac_f32_e32 v9, v18, v18
	v_add_f32_e32 v16, v9, v8
	v_cvt_pk_bf16_f32 v8, v12, v13
	v_cvt_pk_bf16_f32 v9, v14, v15
	v_lshlrev_b32_e32 v12, 16, v96
	v_and_b32_e32 v13, 0xffff0000, v96
	v_lshlrev_b32_e32 v14, 16, v97
	v_and_b32_e32 v15, 0xffff0000, v97
	v_pk_fma_f32 v[6:7], v[6:7], 0.5, v[14:15] op_sel_hi:[1,0,1]
	v_pk_fma_f32 v[4:5], v[4:5], 0.5, v[12:13] op_sel_hi:[1,0,1]
	v_lshlrev_b32_e32 v12, 16, v98
	v_and_b32_e32 v13, 0xffff0000, v98
	v_pk_fma_f32 v[12:13], v[0:1], 0.5, v[12:13] op_sel_hi:[1,0,1]
	v_mul_f32_e32 v0, v5, v5
	v_mul_f32_e32 v1, v7, v7
	v_fmac_f32_e32 v0, v4, v4
	v_fmac_f32_e32 v1, v6, v6
	v_lshlrev_b32_e32 v14, 16, v99
	v_and_b32_e32 v15, 0xffff0000, v99
	v_add_f32_e32 v0, v0, v1
	v_mul_f32_e32 v1, v13, v13
	v_pk_fma_f32 v[14:15], v[2:3], 0.5, v[14:15] op_sel_hi:[1,0,1]
	v_fmac_f32_e32 v1, v12, v12
	v_add_f32_e32 v0, v1, v0
	v_mul_f32_e32 v1, v15, v15
	v_fmac_f32_e32 v1, v14, v14
	v_add_f32_e32 v0, v1, v0
	v_add_f32_e32 v3, v16, v0
	v_cvt_pk_bf16_f32 v10, v10, v11
	v_cvt_pk_bf16_f32 v11, v18, v19
	v_mov_b32_e32 v18, v3
	s_nop 1
	v_permlane16_swap_b32_e32 v18, v3
	v_lshl_add_u64 v[0:1], s[36:37], 0, v[206:207]
	v_lshl_add_u64 v[16:17], v[204:205], 1, v[0:1]
	global_store_dwordx4 v[16:17], v[8:11], off nt
	v_cvt_pk_bf16_f32 v2, v4, v5
	s_waitcnt lgkmcnt(0)
	v_add_f32_e32 v0, v3, v18
	v_mov_b32_e32 v1, v0
	s_nop 1
	v_permlane32_swap_b32_e32 v1, v0
	v_cvt_pk_bf16_f32 v3, v6, v7
	v_cvt_pk_bf16_f32 v4, v12, v13
	v_cvt_pk_bf16_f32 v5, v14, v15
	global_store_dwordx4 v[16:17], v[2:5], off offset:256 nt
	s_and_saveexec_b64 s[34:35], s[4:5]
	s_cbranch_execz .LBB0_328
	s_add_u32 s20, s59, s20
	s_addc_u32 s21, s60, s21
	v_lshl_add_u64 v[2:3], v[202:203], 2, s[20:21]
	s_waitcnt lgkmcnt(0)
	v_add_f32_e32 v0, v0, v1
	global_store_dword v[2:3], v0, off offset:704

; __device__ __forceinline__ unsigned cvt_pk_bf16(float lo, float hi) { unsigned r; asm volatile("v_cvt_pk_bf16_f32 %0, %1, %2" : "=v"(r) : "v"(lo), "v"(hi)); return r; }
; #define LAS __attribute__((address_space(3)))
; __device__ __forceinline__ float fast_sigmoid(float x) { return __builtin_amdgcn_rcpf(1.f + __builtin_amdgcn_exp2f(-x * LOG2E)); }
;     __device__ __forceinline__ void operator()(const f32x4 (&acc)[2][2][4][2], const pg8::Unit& u, int wr, int wc, int fr, int fq) const {
;         const int row0 = u.pm * 256 + wr * 64 + fr; const LAS float* rt = rt_.of(u.pm) + wr * 64 + fr;
;         if (u.pn < 4) { const int col0 = u.pn * 128 + wc * 32 + 8 * fq;
; #pragma unroll
;             for (int ai = 0; ai < 2; ++ai)
; #pragma unroll
;                 for (int m = 0; m < 4; ++m) { bf16_t* rowp = VC + (size_t)(row0 + ai * 128 + m * 16) * CONVC + col0; const float r = rt[ai * 128 + m * 16];
;                     const f32x4 a0 = acc[ai][0][m][0] * r, a1 = acc[ai][0][m][1] * r, g0 = acc[ai][1][m][0] * r, g1 = acc[ai][1][m][1] * r;
;                     u32x4 w; w.x = cvt_pk_bf16(a0[0] * fast_sigmoid(g0[0]), a0[1] * fast_sigmoid(g0[1])); w.y = cvt_pk_bf16(a0[2] * fast_sigmoid(g0[2]), a0[3] * fast_sigmoid(g0[3]));
;                     w.z = cvt_pk_bf16(a1[0] * fast_sigmoid(g1[0]), a1[1] * fast_sigmoid(g1[1])); w.w = cvt_pk_bf16(a1[2] * fast_sigmoid(g1[2]), a1[3] * fast_sigmoid(g1[3]));
;                     *(u32x4*)rowp = w; }
;         } else { const int col0 = (u.pn - 4) * 256 + wc * 32 + 8 * fq;
; #pragma unroll
;             for (int ai = 0; ai < 2; ++ai)
; #pragma unroll
;                 for (int m = 0; m < 4; ++m) { bf16_t* rowp = US + (size_t)(row0 + ai * 128 + m * 16) * SSMW + col0; const float r = rt[ai * 128 + m * 16];
; #pragma unroll
;                     for (int bj = 0; bj < 2; ++bj) { const f32x4 v0 = acc[ai][bj][m][0] * r, v1 = acc[ai][bj][m][1] * r;
;                         u32x4 w; w.x = cvt_pk_bf16(v0[0], v0[1]); w.y = cvt_pk_bf16(v0[2], v0[3]); w.z = cvt_pk_bf16(v1[0], v1[1]); w.w = cvt_pk_bf16(v1[2], v1[3]);
;                         *(u32x4*)(rowp + bj * 128) = w; } }
.LBB0_417:
	s_cmp_eq_u32 s34, s59
	s_movk_i32 s19, 0x200
	s_cselect_b32 s19, s19, 0x300
	s_cmp_lg_u32 s34, s60
	s_cselect_b32 s19, s19, 0x100
	s_cmp_lg_u32 s34, s58
	s_cselect_b32 s19, s19, 0
	v_lshl_add_u32 v168, s19, 2, v164
	ds_read_b32 v154, v168
	v_lshl_add_u32 v146, s34, 8, v160
	v_ashrrev_i32_e32 v147, 31, v146
	s_cmp_gt_i32 s77, 3
	v_lshlrev_b64 v[148:149], 10, v[146:147]
	s_waitcnt lgkmcnt(0)
	v_mov_b32_e32 v155, v154
	v_pk_mul_f32 v[152:153], v[126:127], v[154:155] op_sel_hi:[1,0]
	v_pk_mul_f32 v[156:157], v[124:125], v[154:155] op_sel_hi:[1,0]
	v_pk_mul_f32 v[126:127], v[122:123], v[154:155] op_sel_hi:[1,0]
	v_pk_mul_f32 v[150:151], v[120:121], v[154:155] op_sel_hi:[1,0]
	v_or_b32_e32 v124, 16, v146
	v_or_b32_e32 v122, 32, v146
	v_or_b32_e32 v120, 48, v146
	s_mov_b64 s[20:21], -1
	v_pk_mul_f32 v[116:117], v[116:117], v[154:155]
	v_pk_mul_f32 v[112:113], v[112:113], v[154:155]
	v_ashrrev_i32_e32 v125, 31, v124
	v_ashrrev_i32_e32 v123, 31, v122
	v_ashrrev_i32_e32 v121, 31, v120
	s_cbranch_scc0 .LBB0_420
	v_lshl_add_u32 v136, s77, 8, v163
	v_lshl_add_u64 v[158:159], s[46:47], 0, v[148:149]
	v_lshlrev_b64 v[174:175], 1, v[136:137]
	v_lshl_add_u64 v[158:159], v[158:159], 0, v[174:175]
	v_cvt_pk_bf16_f32 v170, v156, v157
	v_cvt_pk_bf16_f32 v171, v152, v153
	v_cvt_pk_bf16_f32 v172, v150, v151
	v_cvt_pk_bf16_f32 v173, v126, v127
	v_mov_b32_e32 v155, v154
	global_store_dwordx4 v[158:159], v[170:173], off nt
	v_pk_mul_f32 v[176:177], v[114:115], v[154:155]
	s_mov_b64 s[20:21], 0x20000
	v_pk_mul_f32 v[172:173], v[118:119], v[154:155]
	v_cvt_pk_bf16_f32 v170, v116, v117
	s_nop 0
	v_cvt_pk_bf16_f32 v171, v172, v173
	v_cvt_pk_bf16_f32 v172, v112, v113
	v_cvt_pk_bf16_f32 v173, v176, v177
	ds_read_b32 v136, v168 offset:64
	global_store_dwordx4 v[158:159], v[170:173], off offset:256 nt
	s_waitcnt lgkmcnt(0)
	v_pk_mul_f32 v[178:179], v[106:107], v[136:137] op_sel_hi:[1,0]
	v_lshlrev_b64 v[170:171], 10, v[124:125]
	v_lshl_add_u64 v[170:171], s[46:47], 0, v[170:171]
	v_lshl_add_u64 v[176:177], v[170:171], 0, v[174:175]
	v_pk_mul_f32 v[172:173], v[110:111], v[136:137] op_sel_hi:[1,0]
	v_pk_mul_f32 v[170:171], v[108:109], v[136:137] op_sel_hi:[1,0]
	v_pk_mul_f32 v[180:181], v[104:105], v[136:137] op_sel_hi:[1,0]
	v_cvt_pk_bf16_f32 v170, v170, v171
	v_cvt_pk_bf16_f32 v171, v172, v173
	s_nop 0
	v_cvt_pk_bf16_f32 v172, v180, v181
	v_cvt_pk_bf16_f32 v173, v178, v179
	global_store_dwordx4 v[176:177], v[170:173], off nt
	v_pk_mul_f32 v[178:179], v[98:99], v[136:137] op_sel_hi:[1,0]
	v_pk_mul_f32 v[180:181], v[96:97], v[136:137] op_sel_hi:[1,0]
	v_pk_mul_f32 v[172:173], v[102:103], v[136:137] op_sel_hi:[1,0]
	v_pk_mul_f32 v[170:171], v[100:101], v[136:137] op_sel_hi:[1,0]
	s_nop 0
	v_cvt_pk_bf16_f32 v170, v170, v171
	v_cvt_pk_bf16_f32 v171, v172, v173
	v_cvt_pk_bf16_f32 v172, v180, v181
	v_cvt_pk_bf16_f32 v173, v178, v179
	ds_read_b32 v136, v168 offset:128
	global_store_dwordx4 v[176:177], v[170:173], off offset:256 nt
	s_waitcnt lgkmcnt(0)
	v_pk_mul_f32 v[178:179], v[90:91], v[136:137] op_sel_hi:[1,0]
	v_lshlrev_b64 v[170:171], 10, v[122:123]
	v_lshl_add_u64 v[170:171], s[46:47], 0, v[170:171]
	v_lshl_add_u64 v[176:177], v[170:171], 0, v[174:175]
	v_pk_mul_f32 v[172:173], v[94:95], v[136:137] op_sel_hi:[1,0]
	v_pk_mul_f32 v[170:171], v[92:93], v[136:137] op_sel_hi:[1,0]
	v_pk_mul_f32 v[180:181], v[88:89], v[136:137] op_sel_hi:[1,0]
	v_cvt_pk_bf16_f32 v170, v170, v171
	v_cvt_pk_bf16_f32 v171, v172, v173
	s_nop 0
	v_cvt_pk_bf16_f32 v172, v180, v181
	v_cvt_pk_bf16_f32 v173, v178, v179
	global_store_dwordx4 v[176:177], v[170:173], off nt
	v_pk_mul_f32 v[178:179], v[82:83], v[136:137] op_sel_hi:[1,0]
	v_pk_mul_f32 v[180:181], v[80:81], v[136:137] op_sel_hi:[1,0]
	v_pk_mul_f32 v[172:173], v[86:87], v[136:137] op_sel_hi:[1,0]
	v_pk_mul_f32 v[170:171], v[84:85], v[136:137] op_sel_hi:[1,0]
	s_nop 0
	v_cvt_pk_bf16_f32 v170, v170, v171
	v_cvt_pk_bf16_f32 v171, v172, v173
	v_cvt_pk_bf16_f32 v172, v180, v181
	v_cvt_pk_bf16_f32 v173, v178, v179
	ds_read_b32 v136, v168 offset:192
	global_store_dwordx4 v[176:177], v[170:173], off offset:256 nt
	s_waitcnt lgkmcnt(0)
	v_pk_mul_f32 v[176:177], v[74:75], v[136:137] op_sel_hi:[1,0]
	v_lshlrev_b64 v[170:171], 10, v[120:121]
	v_lshl_add_u64 v[170:171], s[46:47], 0, v[170:171]
	v_lshl_add_u64 v[174:175], v[170:171], 0, v[174:175]
	v_pk_mul_f32 v[172:173], v[78:79], v[136:137] op_sel_hi:[1,0]
	v_pk_mul_f32 v[170:171], v[76:77], v[136:137] op_sel_hi:[1,0]
	v_pk_mul_f32 v[178:179], v[72:73], v[136:137] op_sel_hi:[1,0]
	v_cvt_pk_bf16_f32 v170, v170, v171
	v_cvt_pk_bf16_f32 v171, v172, v173
	s_nop 0
	v_cvt_pk_bf16_f32 v172, v178, v179
	v_cvt_pk_bf16_f32 v173, v176, v177
	global_store_dwordx4 v[174:175], v[170:173], off nt
	v_pk_mul_f32 v[176:177], v[66:67], v[136:137] op_sel_hi:[1,0]
	v_pk_mul_f32 v[178:179], v[64:65], v[136:137] op_sel_hi:[1,0]
	v_pk_mul_f32 v[172:173], v[70:71], v[136:137] op_sel_hi:[1,0]
	v_pk_mul_f32 v[170:171], v[68:69], v[136:137] op_sel_hi:[1,0]
	s_nop 0
	v_cvt_pk_bf16_f32 v170, v170, v171
	v_cvt_pk_bf16_f32 v171, v172, v173
	v_cvt_pk_bf16_f32 v172, v178, v179
	v_cvt_pk_bf16_f32 v173, v176, v177
	ds_read_b32 v136, v168 offset:512
	global_store_dwordx4 v[174:175], v[170:173], off offset:256 nt
	s_waitcnt lgkmcnt(0)
; __device__ __forceinline__ unsigned cvt_pk_bf16(float lo, float hi) { unsigned r; asm volatile("v_cvt_pk_bf16_f32 %0, %1, %2" : "=v"(r) : "v"(lo), "v"(hi)); return r; }
;     __device__ __forceinline__ void operator()(const f32x4 (&acc)[2][2][4][2], const pg8::Unit& u, int wr, int wc, int fr, int fq) const {
;     ...
;             for (int ai = 0; ai < 2; ++ai)
; #pragma unroll
;                 for (int m = 0; m < 4; ++m) { bf16_t* rowp = US + (size_t)(row0 + ai * 128 + m * 16) * SSMW + col0; const float r = rt[ai * 128 + m * 16];
; #pragma unroll
;                     for (int bj = 0; bj < 2; ++bj) { const f32x4 v0 = acc[ai][bj][m][0] * r, v1 = acc[ai][bj][m][1] * r;
;                         u32x4 w; w.x = cvt_pk_bf16(v0[0], v0[1]); w.y = cvt_pk_bf16(v0[2], v0[3]); w.z = cvt_pk_bf16(v1[0], v1[1]); w.w = cvt_pk_bf16(v1[2], v1[3]);
;                         *(u32x4*)(rowp + bj * 128) = w; } }
	v_pk_mul_f32 v[174:175], v[58:59], v[136:137] op_sel_hi:[1,0]
	v_pk_mul_f32 v[172:173], v[62:63], v[136:137] op_sel_hi:[1,0]
	v_pk_mul_f32 v[170:171], v[60:61], v[136:137] op_sel_hi:[1,0]
	v_pk_mul_f32 v[176:177], v[56:57], v[136:137] op_sel_hi:[1,0]
	v_cvt_pk_bf16_f32 v170, v170, v171
	v_cvt_pk_bf16_f32 v171, v172, v173
	s_nop 0
	v_cvt_pk_bf16_f32 v172, v176, v177
	v_cvt_pk_bf16_f32 v173, v174, v175
	v_add_co_u32_e32 v174, vcc, s71, v158
	v_pk_mul_f32 v[176:177], v[48:49], v[136:137] op_sel_hi:[1,0]
	s_nop 0
	v_addc_co_u32_e32 v175, vcc, 0, v159, vcc
	global_store_dwordx4 v[174:175], v[170:173], off nt
	v_pk_mul_f32 v[174:175], v[50:51], v[136:137] op_sel_hi:[1,0]
	s_nop 0
	v_pk_mul_f32 v[172:173], v[54:55], v[136:137] op_sel_hi:[1,0]
	v_pk_mul_f32 v[170:171], v[52:53], v[136:137] op_sel_hi:[1,0]
	s_nop 0
	v_cvt_pk_bf16_f32 v170, v170, v171
	v_cvt_pk_bf16_f32 v171, v172, v173
	v_cvt_pk_bf16_f32 v172, v176, v177
	v_cvt_pk_bf16_f32 v173, v174, v175
	ds_read_b32 v136, v168 offset:576
	v_lshl_add_u64 v[174:175], v[158:159], 0, s[20:21]
	global_store_dwordx4 v[174:175], v[170:173], off offset:256 nt
	s_waitcnt lgkmcnt(0)
	v_pk_mul_f32 v[174:175], v[42:43], v[136:137] op_sel_hi:[1,0]
	v_pk_mul_f32 v[172:173], v[46:47], v[136:137] op_sel_hi:[1,0]
	v_pk_mul_f32 v[170:171], v[44:45], v[136:137] op_sel_hi:[1,0]
	v_pk_mul_f32 v[176:177], v[40:41], v[136:137] op_sel_hi:[1,0]
	v_cvt_pk_bf16_f32 v170, v170, v171
	v_cvt_pk_bf16_f32 v171, v172, v173
	s_nop 0
	v_cvt_pk_bf16_f32 v172, v176, v177
	v_cvt_pk_bf16_f32 v173, v174, v175
	v_add_co_u32_e32 v174, vcc, s74, v158
	v_pk_mul_f32 v[176:177], v[32:33], v[136:137] op_sel_hi:[1,0]
	s_nop 0
	v_addc_co_u32_e32 v175, vcc, 0, v159, vcc
	global_store_dwordx4 v[174:175], v[170:173], off nt
	v_pk_mul_f32 v[174:175], v[34:35], v[136:137] op_sel_hi:[1,0]
	s_nop 0
	v_pk_mul_f32 v[172:173], v[38:39], v[136:137] op_sel_hi:[1,0]
	v_pk_mul_f32 v[170:171], v[36:37], v[136:137] op_sel_hi:[1,0]
	s_nop 0
	v_cvt_pk_bf16_f32 v170, v170, v171
	v_cvt_pk_bf16_f32 v171, v172, v173
	v_cvt_pk_bf16_f32 v172, v176, v177
	v_cvt_pk_bf16_f32 v173, v174, v175
	ds_read_b32 v136, v168 offset:640
	v_lshl_add_u64 v[174:175], v[158:159], 0, s[12:13]
	global_store_dwordx4 v[174:175], v[170:173], off offset:256 nt
	s_waitcnt lgkmcnt(0)
	v_pk_mul_f32 v[174:175], v[26:27], v[136:137] op_sel_hi:[1,0]
	v_pk_mul_f32 v[172:173], v[30:31], v[136:137] op_sel_hi:[1,0]
	v_pk_mul_f32 v[170:171], v[28:29], v[136:137] op_sel_hi:[1,0]
	v_pk_mul_f32 v[176:177], v[24:25], v[136:137] op_sel_hi:[1,0]
	v_cvt_pk_bf16_f32 v170, v170, v171
	v_cvt_pk_bf16_f32 v171, v172, v173
	s_nop 0
	v_cvt_pk_bf16_f32 v172, v176, v177
	v_cvt_pk_bf16_f32 v173, v174, v175
	v_add_co_u32_e32 v174, vcc, s75, v158
	v_pk_mul_f32 v[176:177], v[16:17], v[136:137] op_sel_hi:[1,0]
	s_nop 0
	v_addc_co_u32_e32 v175, vcc, 0, v159, vcc
	global_store_dwordx4 v[174:175], v[170:173], off nt
	v_pk_mul_f32 v[174:175], v[18:19], v[136:137] op_sel_hi:[1,0]
	s_nop 0
	v_pk_mul_f32 v[172:173], v[22:23], v[136:137] op_sel_hi:[1,0]
	v_pk_mul_f32 v[170:171], v[20:21], v[136:137] op_sel_hi:[1,0]
	s_nop 0
	v_cvt_pk_bf16_f32 v170, v170, v171
	v_cvt_pk_bf16_f32 v171, v172, v173
	v_cvt_pk_bf16_f32 v172, v176, v177
	v_cvt_pk_bf16_f32 v173, v174, v175
	ds_read_b32 v136, v168 offset:704
	v_lshl_add_u64 v[174:175], v[158:159], 0, s[14:15]
	global_store_dwordx4 v[174:175], v[170:173], off offset:256 nt
	v_lshl_add_u64 v[174:175], v[158:159], 0, s[16:17]
	v_add_co_u32_e32 v158, vcc, s76, v158
	s_waitcnt lgkmcnt(0)
	v_pk_mul_f32 v[172:173], v[14:15], v[136:137] op_sel_hi:[1,0]
	v_pk_mul_f32 v[170:171], v[12:13], v[136:137] op_sel_hi:[1,0]
	v_pk_mul_f32 v[176:177], v[10:11], v[136:137] op_sel_hi:[1,0]
	v_pk_mul_f32 v[178:179], v[8:9], v[136:137] op_sel_hi:[1,0]
	v_cvt_pk_bf16_f32 v170, v170, v171
	v_cvt_pk_bf16_f32 v171, v172, v173
	v_addc_co_u32_e32 v159, vcc, 0, v159, vcc
	v_cvt_pk_bf16_f32 v172, v178, v179
	v_cvt_pk_bf16_f32 v173, v176, v177
	global_store_dwordx4 v[158:159], v[170:173], off nt
	v_pk_mul_f32 v[158:159], v[6:7], v[136:137] op_sel_hi:[1,0]
	v_pk_mul_f32 v[176:177], v[2:3], v[136:137] op_sel_hi:[1,0]
	v_pk_mul_f32 v[170:171], v[4:5], v[136:137] op_sel_hi:[1,0]
	v_pk_mul_f32 v[172:173], v[0:1], v[136:137] op_sel_hi:[1,0]
	v_cvt_pk_bf16_f32 v170, v170, v171
	v_cvt_pk_bf16_f32 v171, v158, v159
	s_nop 0
	v_cvt_pk_bf16_f32 v172, v172, v173
	v_cvt_pk_bf16_f32 v173, v176, v177
	global_store_dwordx4 v[174:175], v[170:173], off offset:256 nt
	s_cbranch_execz .LBB0_421

; __device__ __forceinline__ unsigned cvt_pk_bf16(float lo, float hi) { unsigned r; asm volatile("v_cvt_pk_bf16_f32 %0, %1, %2" : "=v"(r) : "v"(lo), "v"(hi)); return r; }
; __device__ __forceinline__ float fast_sigmoid(float x) { return __builtin_amdgcn_rcpf(1.f + __builtin_amdgcn_exp2f(-x * LOG2E)); }
;     __device__ __forceinline__ void operator()(const f32x4 (&acc)[2][2][4][2], const pg8::Unit& u, int wr, int wc, int fr, int fq) const {
;     ...
;         if (u.pn < 4) { const int col0 = u.pn * 128 + wc * 32 + 8 * fq;
; #pragma unroll
;             for (int ai = 0; ai < 2; ++ai)
; #pragma unroll
;                 for (int m = 0; m < 4; ++m) { bf16_t* rowp = VC + (size_t)(row0 + ai * 128 + m * 16) * CONVC + col0; const float r = rt[ai * 128 + m * 16];
;                     const f32x4 a0 = acc[ai][0][m][0] * r, a1 = acc[ai][0][m][1] * r, g0 = acc[ai][1][m][0] * r, g1 = acc[ai][1][m][1] * r;
;                     u32x4 w; w.x = cvt_pk_bf16(a0[0] * fast_sigmoid(g0[0]), a0[1] * fast_sigmoid(g0[1])); w.y = cvt_pk_bf16(a0[2] * fast_sigmoid(g0[2]), a0[3] * fast_sigmoid(g0[3]));
;                     w.z = cvt_pk_bf16(a1[0] * fast_sigmoid(g1[0]), a1[1] * fast_sigmoid(g1[1])); w.w = cvt_pk_bf16(a1[2] * fast_sigmoid(g1[2]), a1[3] * fast_sigmoid(g1[3]));
;                     *(u32x4*)rowp = w; }
.LBB0_421:
	v_mul_f32_e32 v116, 0xbfb8aa3b, v116
	v_exp_f32_e32 v136, v116
	v_mul_f32_e32 v116, 0xbfb8aa3b, v117
	v_exp_f32_e32 v169, v116
	v_mov_b32_e32 v155, v154
	v_pk_mul_f32 v[118:119], v[118:119], v[154:155]
	v_pk_mul_f32 v[116:117], v[114:115], v[154:155]
	v_add_f32_e32 v114, 1.0, v136
	v_add_f32_e32 v115, 1.0, v169
	v_rcp_f32_e32 v114, v114
	v_rcp_f32_e32 v115, v115
	v_mul_f32_e32 v118, 0xbfb8aa3b, v118
	v_exp_f32_e32 v118, v118
	v_mul_f32_e32 v114, v156, v114
	v_mul_f32_e32 v115, v157, v115
	v_cvt_pk_bf16_f32 v114, v114, v115
	v_add_f32_e32 v115, 1.0, v118
	v_mul_f32_e32 v118, 0xbfb8aa3b, v119
	v_exp_f32_e32 v118, v118
	v_mul_f32_e32 v112, 0xbfb8aa3b, v112
	v_mul_f32_e32 v113, 0xbfb8aa3b, v113
	v_mul_f32_e32 v116, 0xbfb8aa3b, v116
	v_add_f32_e32 v118, 1.0, v118
	v_rcp_f32_e32 v115, v115
	v_exp_f32_e32 v112, v112
	v_rcp_f32_e32 v118, v118
	v_exp_f32_e32 v113, v113
	v_exp_f32_e32 v116, v116
	v_mul_f32_e32 v117, 0xbfb8aa3b, v117
	v_exp_f32_e32 v117, v117
	v_mul_f32_e32 v115, v152, v115
	v_add_f32_e32 v112, 1.0, v112
	v_mul_f32_e32 v118, v153, v118
	v_add_f32_e32 v113, 1.0, v113
	v_add_f32_e32 v116, 1.0, v116
	v_rcp_f32_e32 v112, v112
	v_cvt_pk_bf16_f32 v115, v115, v118
	v_rcp_f32_e32 v113, v113
	v_rcp_f32_e32 v118, v116
	v_add_f32_e32 v116, 1.0, v117
	v_rcp_f32_e32 v117, v116
	v_mul_f32_e32 v112, v150, v112
	v_mul_f32_e32 v113, v151, v113
	v_cvt_pk_bf16_f32 v116, v112, v113
	v_mul_f32_e32 v112, v126, v118
	v_mul_f32_e32 v113, v127, v117
	v_cvt_pk_bf16_f32 v117, v112, v113
	ds_read_b32 v118, v168 offset:64
	v_lshl_or_b32 v158, s77, 7, v162
	v_ashrrev_i32_e32 v159, 31, v158
	v_lshl_add_u64 v[126:127], s[40:41], 0, v[148:149]
	v_lshlrev_b64 v[112:113], 1, v[158:159]
	s_waitcnt lgkmcnt(0)
	v_pk_mul_f32 v[100:101], v[100:101], v[118:119] op_sel_hi:[1,0]
	v_lshl_add_u64 v[126:127], v[126:127], 0, v[112:113]
	v_mul_f32_e32 v100, 0xbfb8aa3b, v100
	global_store_dwordx4 v[126:127], v[114:117], off nt
	v_pk_mul_f32 v[102:103], v[102:103], v[118:119] op_sel_hi:[1,0]
	v_pk_mul_f32 v[108:109], v[108:109], v[118:119] op_sel_hi:[1,0]
	v_exp_f32_e32 v114, v100
	v_mul_f32_e32 v100, 0xbfb8aa3b, v101
	v_exp_f32_e32 v115, v100
	v_pk_mul_f32 v[100:101], v[96:97], v[118:119] op_sel_hi:[1,0]
	v_add_f32_e32 v96, 1.0, v114
	v_rcp_f32_e32 v96, v96
	v_add_f32_e32 v97, 1.0, v115
	v_rcp_f32_e32 v97, v97
	v_mul_f32_e32 v102, 0xbfb8aa3b, v102
	v_exp_f32_e32 v102, v102
	v_mul_f32_e32 v96, v108, v96
	v_mul_f32_e32 v97, v109, v97
	v_cvt_pk_bf16_f32 v96, v96, v97
	v_add_f32_e32 v97, 1.0, v102
	v_mul_f32_e32 v102, 0xbfb8aa3b, v103
	v_exp_f32_e32 v102, v102
	v_pk_mul_f32 v[98:99], v[98:99], v[118:119] op_sel_hi:[1,0]
	v_mul_f32_e32 v100, 0xbfb8aa3b, v100
	v_mul_f32_e32 v101, 0xbfb8aa3b, v101
	v_add_f32_e32 v102, 1.0, v102
	v_mul_f32_e32 v98, 0xbfb8aa3b, v98
	v_rcp_f32_e32 v97, v97
	v_exp_f32_e32 v100, v100
	v_rcp_f32_e32 v102, v102
	v_exp_f32_e32 v101, v101
	v_exp_f32_e32 v98, v98
	v_mul_f32_e32 v99, 0xbfb8aa3b, v99
	v_exp_f32_e32 v99, v99
	v_pk_mul_f32 v[110:111], v[110:111], v[118:119] op_sel_hi:[1,0]
	v_add_f32_e32 v100, 1.0, v100
	v_mul_f32_e32 v97, v110, v97
	v_mul_f32_e32 v102, v111, v102
	v_add_f32_e32 v101, 1.0, v101
	v_add_f32_e32 v98, 1.0, v98
	v_rcp_f32_e32 v100, v100
	v_cvt_pk_bf16_f32 v97, v97, v102
	v_rcp_f32_e32 v101, v101
	v_rcp_f32_e32 v102, v98
	v_add_f32_e32 v98, 1.0, v99
	v_rcp_f32_e32 v99, v98
	v_pk_mul_f32 v[104:105], v[104:105], v[118:119] op_sel_hi:[1,0]
	v_pk_mul_f32 v[106:107], v[106:107], v[118:119] op_sel_hi:[1,0]
	v_mul_f32_e32 v100, v104, v100
	v_mul_f32_e32 v98, v105, v101
	v_cvt_pk_bf16_f32 v98, v100, v98
	v_mul_f32_e32 v100, v106, v102
	v_mul_f32_e32 v99, v107, v99
	v_cvt_pk_bf16_f32 v99, v100, v99
	ds_read_b32 v100, v168 offset:128
	v_lshlrev_b64 v[102:103], 10, v[124:125]
	v_lshl_add_u64 v[102:103], s[40:41], 0, v[102:103]
	v_lshl_add_u64 v[102:103], v[102:103], 0, v[112:113]
	global_store_dwordx4 v[102:103], v[96:99], off nt
	s_waitcnt lgkmcnt(0)
	v_pk_mul_f32 v[84:85], v[84:85], v[100:101] op_sel_hi:[1,0]
	v_pk_mul_f32 v[86:87], v[86:87], v[100:101] op_sel_hi:[1,0]
	v_mul_f32_e32 v84, 0xbfb8aa3b, v84
	v_exp_f32_e32 v96, v84
	v_mul_f32_e32 v84, 0xbfb8aa3b, v85
	v_exp_f32_e32 v97, v84
	v_pk_mul_f32 v[84:85], v[80:81], v[100:101] op_sel_hi:[1,0]
	v_add_f32_e32 v80, 1.0, v96
	v_rcp_f32_e32 v80, v80
	v_add_f32_e32 v81, 1.0, v97
	v_rcp_f32_e32 v81, v81
	v_mul_f32_e32 v86, 0xbfb8aa3b, v86
	v_exp_f32_e32 v86, v86
	v_pk_mul_f32 v[92:93], v[92:93], v[100:101] op_sel_hi:[1,0]
	v_pk_mul_f32 v[82:83], v[82:83], v[100:101] op_sel_hi:[1,0]
	v_mul_f32_e32 v80, v92, v80
	v_mul_f32_e32 v81, v93, v81
	v_cvt_pk_bf16_f32 v80, v80, v81
	v_add_f32_e32 v81, 1.0, v86
	v_mul_f32_e32 v86, 0xbfb8aa3b, v87
	v_exp_f32_e32 v86, v86
	v_mul_f32_e32 v84, 0xbfb8aa3b, v84
	v_mul_f32_e32 v85, 0xbfb8aa3b, v85
	v_mul_f32_e32 v82, 0xbfb8aa3b, v82
	v_add_f32_e32 v86, 1.0, v86
	v_rcp_f32_e32 v81, v81
	v_exp_f32_e32 v84, v84
	v_rcp_f32_e32 v86, v86
	v_exp_f32_e32 v85, v85
	v_exp_f32_e32 v82, v82
	v_mul_f32_e32 v83, 0xbfb8aa3b, v83
	v_exp_f32_e32 v83, v83
	v_pk_mul_f32 v[94:95], v[94:95], v[100:101] op_sel_hi:[1,0]
	v_add_f32_e32 v84, 1.0, v84
	v_mul_f32_e32 v81, v94, v81
	v_mul_f32_e32 v86, v95, v86
	v_add_f32_e32 v85, 1.0, v85
	v_add_f32_e32 v82, 1.0, v82
	v_rcp_f32_e32 v84, v84
	v_cvt_pk_bf16_f32 v81, v81, v86
	v_rcp_f32_e32 v85, v85
	v_rcp_f32_e32 v86, v82
	v_add_f32_e32 v82, 1.0, v83
	v_rcp_f32_e32 v83, v82
	v_pk_mul_f32 v[88:89], v[88:89], v[100:101] op_sel_hi:[1,0]
	v_pk_mul_f32 v[90:91], v[90:91], v[100:101] op_sel_hi:[1,0]
	v_mul_f32_e32 v84, v88, v84
	v_mul_f32_e32 v82, v89, v85
	v_cvt_pk_bf16_f32 v82, v84, v82
	v_mul_f32_e32 v84, v90, v86
	v_mul_f32_e32 v83, v91, v83
	v_cvt_pk_bf16_f32 v83, v84, v83
	ds_read_b32 v84, v168 offset:192
	v_lshlrev_b64 v[86:87], 10, v[122:123]
	v_lshl_add_u64 v[86:87], s[40:41], 0, v[86:87]
	v_lshl_add_u64 v[86:87], v[86:87], 0, v[112:113]
	global_store_dwordx4 v[86:87], v[80:83], off nt
	s_waitcnt lgkmcnt(0)
; __device__ __forceinline__ unsigned cvt_pk_bf16(float lo, float hi) { unsigned r; asm volatile("v_cvt_pk_bf16_f32 %0, %1, %2" : "=v"(r) : "v"(lo), "v"(hi)); return r; }
; __device__ __forceinline__ float fast_sigmoid(float x) { return __builtin_amdgcn_rcpf(1.f + __builtin_amdgcn_exp2f(-x * LOG2E)); }
;     __device__ __forceinline__ void operator()(const f32x4 (&acc)[2][2][4][2], const pg8::Unit& u, int wr, int wc, int fr, int fq) const {
;     ...
;                 for (int m = 0; m < 4; ++m) { bf16_t* rowp = VC + (size_t)(row0 + ai * 128 + m * 16) * CONVC + col0; const float r = rt[ai * 128 + m * 16];
;                     const f32x4 a0 = acc[ai][0][m][0] * r, a1 = acc[ai][0][m][1] * r, g0 = acc[ai][1][m][0] * r, g1 = acc[ai][1][m][1] * r;
;                     u32x4 w; w.x = cvt_pk_bf16(a0[0] * fast_sigmoid(g0[0]), a0[1] * fast_sigmoid(g0[1])); w.y = cvt_pk_bf16(a0[2] * fast_sigmoid(g0[2]), a0[3] * fast_sigmoid(g0[3]));
;                     w.z = cvt_pk_bf16(a1[0] * fast_sigmoid(g1[0]), a1[1] * fast_sigmoid(g1[1])); w.w = cvt_pk_bf16(a1[2] * fast_sigmoid(g1[2]), a1[3] * fast_sigmoid(g1[3]));
;                     *(u32x4*)rowp = w; }
	v_pk_mul_f32 v[68:69], v[68:69], v[84:85] op_sel_hi:[1,0]
	v_pk_mul_f32 v[70:71], v[70:71], v[84:85] op_sel_hi:[1,0]
	v_mul_f32_e32 v68, 0xbfb8aa3b, v68
	v_exp_f32_e32 v80, v68
	v_mul_f32_e32 v68, 0xbfb8aa3b, v69
	v_exp_f32_e32 v81, v68
	v_pk_mul_f32 v[68:69], v[64:65], v[84:85] op_sel_hi:[1,0]
	v_add_f32_e32 v64, 1.0, v80
	v_rcp_f32_e32 v64, v64
	v_add_f32_e32 v65, 1.0, v81
	v_rcp_f32_e32 v65, v65
	v_mul_f32_e32 v70, 0xbfb8aa3b, v70
	v_exp_f32_e32 v70, v70
	v_pk_mul_f32 v[76:77], v[76:77], v[84:85] op_sel_hi:[1,0]
	v_pk_mul_f32 v[66:67], v[66:67], v[84:85] op_sel_hi:[1,0]
	v_mul_f32_e32 v64, v76, v64
	v_mul_f32_e32 v65, v77, v65
	v_cvt_pk_bf16_f32 v64, v64, v65
	v_add_f32_e32 v65, 1.0, v70
	v_mul_f32_e32 v70, 0xbfb8aa3b, v71
	v_exp_f32_e32 v70, v70
	v_mul_f32_e32 v68, 0xbfb8aa3b, v68
	v_mul_f32_e32 v69, 0xbfb8aa3b, v69
	v_mul_f32_e32 v66, 0xbfb8aa3b, v66
	v_add_f32_e32 v70, 1.0, v70
	v_rcp_f32_e32 v65, v65
	v_exp_f32_e32 v68, v68
	v_rcp_f32_e32 v70, v70
	v_exp_f32_e32 v69, v69
	v_exp_f32_e32 v66, v66
	v_mul_f32_e32 v67, 0xbfb8aa3b, v67
	v_exp_f32_e32 v67, v67
	v_pk_mul_f32 v[78:79], v[78:79], v[84:85] op_sel_hi:[1,0]
	v_add_f32_e32 v68, 1.0, v68
	v_mul_f32_e32 v65, v78, v65
	v_mul_f32_e32 v70, v79, v70
	v_add_f32_e32 v69, 1.0, v69
	v_add_f32_e32 v66, 1.0, v66
	v_rcp_f32_e32 v68, v68
	v_cvt_pk_bf16_f32 v65, v65, v70
	v_rcp_f32_e32 v69, v69
	v_rcp_f32_e32 v70, v66
	v_add_f32_e32 v66, 1.0, v67
	v_rcp_f32_e32 v67, v66
	v_pk_mul_f32 v[72:73], v[72:73], v[84:85] op_sel_hi:[1,0]
	v_pk_mul_f32 v[74:75], v[74:75], v[84:85] op_sel_hi:[1,0]
	v_mul_f32_e32 v68, v72, v68
	v_mul_f32_e32 v66, v73, v69
	v_cvt_pk_bf16_f32 v66, v68, v66
	v_mul_f32_e32 v68, v74, v70
	v_mul_f32_e32 v67, v75, v67
	v_cvt_pk_bf16_f32 v67, v68, v67
	ds_read_b32 v68, v168 offset:512
	v_lshlrev_b64 v[70:71], 10, v[120:121]
	v_lshl_add_u64 v[70:71], s[40:41], 0, v[70:71]
	v_lshl_add_u64 v[70:71], v[70:71], 0, v[112:113]
	global_store_dwordx4 v[70:71], v[64:67], off nt
	s_waitcnt lgkmcnt(0)
	v_pk_mul_f32 v[52:53], v[52:53], v[68:69] op_sel_hi:[1,0]
	v_pk_mul_f32 v[54:55], v[54:55], v[68:69] op_sel_hi:[1,0]
	v_pk_mul_f32 v[64:65], v[50:51], v[68:69] op_sel_hi:[1,0]
	v_mul_f32_e32 v50, 0xbfb8aa3b, v52
	v_mul_f32_e32 v51, 0xbfb8aa3b, v53
	v_exp_f32_e32 v50, v50
	v_exp_f32_e32 v51, v51
	v_mul_f32_e32 v52, 0xbfb8aa3b, v54
	v_exp_f32_e32 v52, v52
	v_add_f32_e32 v50, 1.0, v50
	v_add_f32_e32 v51, 1.0, v51
	v_rcp_f32_e32 v50, v50
	v_rcp_f32_e32 v51, v51
	v_pk_mul_f32 v[60:61], v[60:61], v[68:69] op_sel_hi:[1,0]
	v_pk_mul_f32 v[62:63], v[62:63], v[68:69] op_sel_hi:[1,0]
	v_mul_f32_e32 v50, v60, v50
	v_mul_f32_e32 v51, v61, v51
	v_cvt_pk_bf16_f32 v50, v50, v51
	v_add_f32_e32 v51, 1.0, v52
	v_mul_f32_e32 v52, 0xbfb8aa3b, v55
	v_exp_f32_e32 v52, v52
	v_rcp_f32_e32 v51, v51
	v_pk_mul_f32 v[48:49], v[48:49], v[68:69] op_sel_hi:[1,0]
	v_mul_f32_e32 v53, 0xbfb8aa3b, v65
	v_add_f32_e32 v52, 1.0, v52
	v_rcp_f32_e32 v52, v52
	v_mul_f32_e32 v51, v62, v51
	v_mul_f32_e32 v48, 0xbfb8aa3b, v48
	v_mul_f32_e32 v49, 0xbfb8aa3b, v49
	v_mul_f32_e32 v52, v63, v52
	v_cvt_pk_bf16_f32 v51, v51, v52
	v_mul_f32_e32 v52, 0xbfb8aa3b, v64
	v_exp_f32_e32 v48, v48
	v_exp_f32_e32 v49, v49
	v_exp_f32_e32 v52, v52
	v_exp_f32_e32 v53, v53
	v_add_f32_e32 v48, 1.0, v48
	v_add_f32_e32 v49, 1.0, v49
	v_add_f32_e32 v52, 1.0, v52
	v_rcp_f32_e32 v48, v48
	v_rcp_f32_e32 v49, v49
	v_rcp_f32_e32 v54, v52
	v_add_f32_e32 v52, 1.0, v53
	v_rcp_f32_e32 v53, v52
	v_pk_mul_f32 v[56:57], v[56:57], v[68:69] op_sel_hi:[1,0]
	v_pk_mul_f32 v[58:59], v[58:59], v[68:69] op_sel_hi:[1,0]
	v_mul_f32_e32 v48, v56, v48
	v_mul_f32_e32 v49, v57, v49
	v_cvt_pk_bf16_f32 v52, v48, v49
	v_mul_f32_e32 v48, v58, v54
	v_mul_f32_e32 v49, v59, v53
	v_cvt_pk_bf16_f32 v53, v48, v49
	ds_read_b32 v54, v168 offset:576
	v_lshlrev_b64 v[48:49], 10, v[146:147]
	v_lshl_add_u64 v[48:49], s[40:41], 0, v[48:49]
	v_lshl_add_u64 v[48:49], v[48:49], 0, v[112:113]
	v_add_co_u32_e32 v56, vcc, s71, v48
	s_waitcnt lgkmcnt(0)
; __device__ __forceinline__ unsigned cvt_pk_bf16(float lo, float hi) { unsigned r; asm volatile("v_cvt_pk_bf16_f32 %0, %1, %2" : "=v"(r) : "v"(lo), "v"(hi)); return r; }
; __device__ __forceinline__ float fast_sigmoid(float x) { return __builtin_amdgcn_rcpf(1.f + __builtin_amdgcn_exp2f(-x * LOG2E)); }
;     __device__ __forceinline__ void operator()(const f32x4 (&acc)[2][2][4][2], const pg8::Unit& u, int wr, int wc, int fr, int fq) const {
;     ...
;                 for (int m = 0; m < 4; ++m) { bf16_t* rowp = VC + (size_t)(row0 + ai * 128 + m * 16) * CONVC + col0; const float r = rt[ai * 128 + m * 16];
;                     const f32x4 a0 = acc[ai][0][m][0] * r, a1 = acc[ai][0][m][1] * r, g0 = acc[ai][1][m][0] * r, g1 = acc[ai][1][m][1] * r;
;                     u32x4 w; w.x = cvt_pk_bf16(a0[0] * fast_sigmoid(g0[0]), a0[1] * fast_sigmoid(g0[1])); w.y = cvt_pk_bf16(a0[2] * fast_sigmoid(g0[2]), a0[3] * fast_sigmoid(g0[3]));
;                     w.z = cvt_pk_bf16(a1[0] * fast_sigmoid(g1[0]), a1[1] * fast_sigmoid(g1[1])); w.w = cvt_pk_bf16(a1[2] * fast_sigmoid(g1[2]), a1[3] * fast_sigmoid(g1[3]));
;                     *(u32x4*)rowp = w; }
	v_pk_mul_f32 v[36:37], v[36:37], v[54:55] op_sel_hi:[1,0]
	v_addc_co_u32_e32 v57, vcc, 0, v49, vcc
	v_mul_f32_e32 v36, 0xbfb8aa3b, v36
	global_store_dwordx4 v[56:57], v[50:53], off nt
	v_pk_mul_f32 v[38:39], v[38:39], v[54:55] op_sel_hi:[1,0]
	v_pk_mul_f32 v[44:45], v[44:45], v[54:55] op_sel_hi:[1,0]
	v_exp_f32_e32 v50, v36
	v_mul_f32_e32 v36, 0xbfb8aa3b, v37
	v_exp_f32_e32 v51, v36
	v_pk_mul_f32 v[36:37], v[32:33], v[54:55] op_sel_hi:[1,0]
	v_add_f32_e32 v32, 1.0, v50
	v_rcp_f32_e32 v32, v32
	v_add_f32_e32 v33, 1.0, v51
	v_rcp_f32_e32 v33, v33
	v_mul_f32_e32 v38, 0xbfb8aa3b, v38
	v_exp_f32_e32 v38, v38
	v_mul_f32_e32 v32, v44, v32
	v_mul_f32_e32 v33, v45, v33
	v_cvt_pk_bf16_f32 v32, v32, v33
	v_add_f32_e32 v33, 1.0, v38
	v_mul_f32_e32 v38, 0xbfb8aa3b, v39
	v_exp_f32_e32 v38, v38
	v_pk_mul_f32 v[34:35], v[34:35], v[54:55] op_sel_hi:[1,0]
	v_mul_f32_e32 v36, 0xbfb8aa3b, v36
	v_mul_f32_e32 v37, 0xbfb8aa3b, v37
	v_add_f32_e32 v38, 1.0, v38
	v_mul_f32_e32 v34, 0xbfb8aa3b, v34
	v_rcp_f32_e32 v33, v33
	v_exp_f32_e32 v36, v36
	v_rcp_f32_e32 v38, v38
	v_exp_f32_e32 v37, v37
	v_exp_f32_e32 v34, v34
	v_mul_f32_e32 v35, 0xbfb8aa3b, v35
	v_exp_f32_e32 v35, v35
	v_pk_mul_f32 v[46:47], v[46:47], v[54:55] op_sel_hi:[1,0]
	v_add_f32_e32 v36, 1.0, v36
	v_mul_f32_e32 v33, v46, v33
	v_mul_f32_e32 v38, v47, v38
	v_add_f32_e32 v37, 1.0, v37
	v_add_f32_e32 v34, 1.0, v34
	v_rcp_f32_e32 v36, v36
	v_cvt_pk_bf16_f32 v33, v33, v38
	v_rcp_f32_e32 v37, v37
	v_rcp_f32_e32 v38, v34
	v_add_f32_e32 v34, 1.0, v35
	v_rcp_f32_e32 v35, v34
	v_pk_mul_f32 v[40:41], v[40:41], v[54:55] op_sel_hi:[1,0]
	v_pk_mul_f32 v[42:43], v[42:43], v[54:55] op_sel_hi:[1,0]
	v_mul_f32_e32 v36, v40, v36
	v_mul_f32_e32 v34, v41, v37
	v_cvt_pk_bf16_f32 v34, v36, v34
	v_mul_f32_e32 v36, v42, v38
	v_mul_f32_e32 v35, v43, v35
	v_cvt_pk_bf16_f32 v35, v36, v35
	ds_read_b32 v36, v168 offset:640
	v_add_co_u32_e32 v38, vcc, s74, v48
	s_waitcnt lgkmcnt(0)
	v_pk_mul_f32 v[20:21], v[20:21], v[36:37] op_sel_hi:[1,0]
	v_addc_co_u32_e32 v39, vcc, 0, v49, vcc
	v_mul_f32_e32 v20, 0xbfb8aa3b, v20
	global_store_dwordx4 v[38:39], v[32:35], off nt
	v_pk_mul_f32 v[22:23], v[22:23], v[36:37] op_sel_hi:[1,0]
	v_pk_mul_f32 v[28:29], v[28:29], v[36:37] op_sel_hi:[1,0]
	v_exp_f32_e32 v32, v20
	v_mul_f32_e32 v20, 0xbfb8aa3b, v21
	v_exp_f32_e32 v33, v20
	v_pk_mul_f32 v[20:21], v[16:17], v[36:37] op_sel_hi:[1,0]
	v_add_f32_e32 v16, 1.0, v32
	v_rcp_f32_e32 v16, v16
	v_add_f32_e32 v17, 1.0, v33
	v_rcp_f32_e32 v17, v17
	v_mul_f32_e32 v22, 0xbfb8aa3b, v22
	v_exp_f32_e32 v22, v22
	v_mul_f32_e32 v16, v28, v16
	v_mul_f32_e32 v17, v29, v17
	v_cvt_pk_bf16_f32 v16, v16, v17
	v_add_f32_e32 v17, 1.0, v22
	v_mul_f32_e32 v22, 0xbfb8aa3b, v23
	v_exp_f32_e32 v22, v22
	v_pk_mul_f32 v[18:19], v[18:19], v[36:37] op_sel_hi:[1,0]
	v_mul_f32_e32 v20, 0xbfb8aa3b, v20
	v_mul_f32_e32 v21, 0xbfb8aa3b, v21
	v_add_f32_e32 v22, 1.0, v22
	v_mul_f32_e32 v18, 0xbfb8aa3b, v18
	v_rcp_f32_e32 v17, v17
	v_exp_f32_e32 v20, v20
	v_rcp_f32_e32 v22, v22
	v_exp_f32_e32 v21, v21
	v_exp_f32_e32 v18, v18
	v_mul_f32_e32 v19, 0xbfb8aa3b, v19
	v_exp_f32_e32 v19, v19
	v_pk_mul_f32 v[30:31], v[30:31], v[36:37] op_sel_hi:[1,0]
	v_add_f32_e32 v20, 1.0, v20
	v_mul_f32_e32 v17, v30, v17
	v_mul_f32_e32 v22, v31, v22
	v_add_f32_e32 v21, 1.0, v21
	v_add_f32_e32 v18, 1.0, v18
	v_rcp_f32_e32 v20, v20
	v_cvt_pk_bf16_f32 v17, v17, v22
	v_rcp_f32_e32 v21, v21
	v_rcp_f32_e32 v22, v18
	v_add_f32_e32 v18, 1.0, v19
	v_rcp_f32_e32 v19, v18
	v_pk_mul_f32 v[24:25], v[24:25], v[36:37] op_sel_hi:[1,0]
	v_pk_mul_f32 v[26:27], v[26:27], v[36:37] op_sel_hi:[1,0]
	v_mul_f32_e32 v20, v24, v20
	v_mul_f32_e32 v18, v25, v21
	v_cvt_pk_bf16_f32 v18, v20, v18
	v_mul_f32_e32 v20, v26, v22
	v_mul_f32_e32 v19, v27, v19
	v_cvt_pk_bf16_f32 v19, v20, v19
	ds_read_b32 v20, v168 offset:704
	v_add_co_u32_e32 v22, vcc, s75, v48
	s_waitcnt lgkmcnt(0)
	v_pk_mul_f32 v[4:5], v[4:5], v[20:21] op_sel_hi:[1,0]
	v_addc_co_u32_e32 v23, vcc, 0, v49, vcc
	v_mul_f32_e32 v4, 0xbfb8aa3b, v4
	global_store_dwordx4 v[22:23], v[16:19], off nt
	v_pk_mul_f32 v[6:7], v[6:7], v[20:21] op_sel_hi:[1,0]
	v_pk_mul_f32 v[12:13], v[12:13], v[20:21] op_sel_hi:[1,0]
	v_exp_f32_e32 v16, v4
	v_mul_f32_e32 v4, 0xbfb8aa3b, v5
	v_exp_f32_e32 v17, v4
	v_pk_mul_f32 v[4:5], v[0:1], v[20:21] op_sel_hi:[1,0]
	v_add_f32_e32 v0, 1.0, v16
	v_rcp_f32_e32 v0, v0
	v_add_f32_e32 v1, 1.0, v17
	v_rcp_f32_e32 v1, v1
	v_mul_f32_e32 v6, 0xbfb8aa3b, v6
	v_exp_f32_e32 v6, v6
	v_mul_f32_e32 v0, v12, v0
	v_mul_f32_e32 v1, v13, v1
	v_cvt_pk_bf16_f32 v0, v0, v1
	v_add_f32_e32 v1, 1.0, v6
	v_mul_f32_e32 v6, 0xbfb8aa3b, v7
	v_exp_f32_e32 v6, v6
	v_pk_mul_f32 v[2:3], v[2:3], v[20:21] op_sel_hi:[1,0]
	v_mul_f32_e32 v4, 0xbfb8aa3b, v4
	v_mul_f32_e32 v5, 0xbfb8aa3b, v5
	v_add_f32_e32 v6, 1.0, v6
	v_mul_f32_e32 v2, 0xbfb8aa3b, v2
	v_rcp_f32_e32 v1, v1
	v_exp_f32_e32 v4, v4
	v_rcp_f32_e32 v6, v6
	v_exp_f32_e32 v5, v5
	v_exp_f32_e32 v2, v2
	v_mul_f32_e32 v3, 0xbfb8aa3b, v3
	v_exp_f32_e32 v3, v3
	v_pk_mul_f32 v[14:15], v[14:15], v[20:21] op_sel_hi:[1,0]
	v_add_f32_e32 v4, 1.0, v4
	v_mul_f32_e32 v1, v14, v1
	v_mul_f32_e32 v6, v15, v6
	v_add_f32_e32 v5, 1.0, v5
	v_add_f32_e32 v2, 1.0, v2
	v_rcp_f32_e32 v4, v4
	v_cvt_pk_bf16_f32 v1, v1, v6
	v_rcp_f32_e32 v5, v5
	v_rcp_f32_e32 v6, v2
	v_add_f32_e32 v2, 1.0, v3
	v_rcp_f32_e32 v3, v2
	v_pk_mul_f32 v[8:9], v[8:9], v[20:21] op_sel_hi:[1,0]
	v_pk_mul_f32 v[10:11], v[10:11], v[20:21] op_sel_hi:[1,0]
	v_mul_f32_e32 v4, v8, v4
	v_mul_f32_e32 v2, v9, v5
	v_cvt_pk_bf16_f32 v2, v4, v2
	v_mul_f32_e32 v4, v10, v6
	v_mul_f32_e32 v3, v11, v3
	v_cvt_pk_bf16_f32 v3, v4, v3
	v_add_co_u32_e32 v4, vcc, 0x2c000, v48
	s_nop 1
	v_addc_co_u32_e32 v5, vcc, 0, v49, vcc
	global_store_dwordx4 v[4:5], v[0:3], off nt
	s_andn2_b64 vcc, exec, s[4:5]
	s_mov_b64 s[4:5], -1
	s_cbranch_vccnz .LBB0_410

; __device__ __forceinline__ unsigned cvt_pk_bf16(float lo, float hi) { unsigned r; asm volatile("v_cvt_pk_bf16_f32 %0, %1, %2" : "=v"(r) : "v"(lo), "v"(hi)); return r; }
; __device__ __forceinline__ float fast_sigmoid(float x) { return __builtin_amdgcn_rcpf(1.f + __builtin_amdgcn_exp2f(-x * LOG2E)); }
;     __device__ __forceinline__ void operator()(const f32x4 (&acc)[2][2][4][2], const pg8::Unit& u, int wr, int wc, int fr, int fq) const {
;         const int row0 = u.pm * 256 + wr * 64 + fr, col0 = u.pn * 256 + wc * 32 + 8 * fq;
; #pragma unroll
;         for (int bj = 0; bj < 2; ++bj) { const int c = col0 + bj * 128; const f32x4 b0 = *(const f32x4*)(bias + c), b1 = *(const f32x4*)(bias + c + 4);
; #pragma unroll
;             for (int ai = 0; ai < 2; ++ai)
; #pragma unroll
;                 for (int m = 0; m < 4; ++m) { const size_t r = (size_t)(row0 + ai * 128 + m * 16);
;                     const u32x4 y = *(const u32x4*)(YB + r * SSMW + c); const f32x4 v0 = acc[ai][bj][m][0] + b0, v1 = acc[ai][bj][m][1] + b1;
;                     u32x4 w; w.x = cvt_pk_bf16(bf_lo(y.x) * fast_sigmoid(v0[0]), bf_hi(y.x) * fast_sigmoid(v0[1])); w.y = cvt_pk_bf16(bf_lo(y.y) * fast_sigmoid(v0[2]), bf_hi(y.y) * fast_sigmoid(v0[3]));
;                     w.z = cvt_pk_bf16(bf_lo(y.z) * fast_sigmoid(v1[0]), bf_hi(y.z) * fast_sigmoid(v1[1])); w.w = cvt_pk_bf16(bf_lo(y.w) * fast_sigmoid(v1[2]), bf_hi(y.w) * fast_sigmoid(v1[3]));
;                     *(u32x4*)(CAT + r * D + 512 + c) = w; } }
.LBB0_627:
	v_lshl_or_b32 v152, s62, 8, v166
	v_ashrrev_i32_e32 v153, 31, v152
	v_lshl_add_u64 v[156:157], v[152:153], 2, s[44:45]
	global_load_dwordx4 v[116:119], v[156:157], off
	global_load_dwordx4 v[112:115], v[156:157], off offset:16
	v_lshl_add_u32 v162, s34, 8, v164
	v_ashrrev_i32_e32 v163, 31, v162
	v_lshlrev_b64 v[154:155], 10, v[162:163]
	v_lshlrev_b64 v[158:159], 1, v[152:153]
	v_lshl_add_u64 v[152:153], s[0:1], 0, v[154:155]
	v_lshl_add_u64 v[160:161], v[152:153], 0, v[158:159]
	global_load_dwordx4 v[170:173], v[160:161], off
	v_or_b32_e32 v174, 16, v162
	v_lshlrev_b64 v[152:153], 11, v[162:163]
	v_ashrrev_i32_e32 v175, 31, v174
	v_lshl_add_u64 v[152:153], s[42:43], 0, v[152:153]
	v_lshlrev_b64 v[154:155], 10, v[174:175]
	v_lshl_add_u64 v[152:153], v[152:153], 0, v[158:159]
	v_lshl_add_u64 v[154:155], s[0:1], 0, v[154:155]
	v_lshl_add_u64 v[154:155], v[154:155], 0, v[158:159]
	s_andn2_b64 vcc, exec, s[4:5]
	s_mov_b64 s[4:5], -1
	s_waitcnt vmcnt(0)
	v_pk_add_f32 v[134:135], v[134:135], v[118:119]
	v_pk_add_f32 v[130:131], v[130:131], v[114:115]
	v_pk_add_f32 v[132:133], v[132:133], v[116:117]
	v_pk_add_f32 v[128:129], v[128:129], v[112:113]
	v_mul_f32_e32 v131, 0xbfb8aa3b, v131
	v_mul_f32_e32 v132, 0xbfb8aa3b, v132
	v_mul_f32_e32 v133, 0xbfb8aa3b, v133
	v_mul_f32_e32 v134, 0xbfb8aa3b, v134
	v_mul_f32_e32 v135, 0xbfb8aa3b, v135
	v_mul_f32_e32 v128, 0xbfb8aa3b, v128
	v_mul_f32_e32 v129, 0xbfb8aa3b, v129
	v_mul_f32_e32 v130, 0xbfb8aa3b, v130
	v_exp_f32_e32 v131, v131
	v_exp_f32_e32 v132, v132
	v_exp_f32_e32 v133, v133
	v_exp_f32_e32 v134, v134
	v_exp_f32_e32 v135, v135
	v_exp_f32_e32 v128, v128
	v_exp_f32_e32 v129, v129
	v_exp_f32_e32 v130, v130
	v_add_f32_e32 v131, 1.0, v131
	v_add_f32_e32 v132, 1.0, v132
	v_add_f32_e32 v133, 1.0, v133
	v_add_f32_e32 v134, 1.0, v134
	v_add_f32_e32 v135, 1.0, v135
	v_add_f32_e32 v128, 1.0, v128
	v_add_f32_e32 v129, 1.0, v129
	v_add_f32_e32 v130, 1.0, v130
	v_rcp_f32_e32 v131, v131
	v_rcp_f32_e32 v132, v132
	v_rcp_f32_e32 v133, v133
	v_rcp_f32_e32 v134, v134
	v_rcp_f32_e32 v135, v135
	v_rcp_f32_e32 v128, v128
	v_rcp_f32_e32 v129, v129
	v_rcp_f32_e32 v130, v130
	v_lshlrev_b32_e32 v178, 16, v173
	v_and_b32_e32 v173, 0xffff0000, v173
	v_lshlrev_b32_e32 v163, 16, v170
	v_and_b32_e32 v170, 0xffff0000, v170
	v_lshlrev_b32_e32 v176, 16, v171
	v_and_b32_e32 v171, 0xffff0000, v171
	v_lshlrev_b32_e32 v177, 16, v172
	v_and_b32_e32 v172, 0xffff0000, v172
	v_mul_f32_e32 v131, v131, v173
	v_mul_f32_e32 v132, v132, v163
	v_mul_f32_e32 v133, v133, v170
	v_mul_f32_e32 v134, v134, v176
	v_mul_f32_e32 v135, v135, v171
	v_mul_f32_e32 v163, v128, v177
	v_mul_f32_e32 v170, v129, v172
	v_mul_f32_e32 v171, v130, v178
	v_cvt_pk_bf16_f32 v128, v132, v133
	v_cvt_pk_bf16_f32 v129, v134, v135
	v_cvt_pk_bf16_f32 v130, v163, v170
	v_cvt_pk_bf16_f32 v131, v171, v131
	global_store_dwordx4 v[152:153], v[128:131], off offset:1024 nt
	global_load_dwordx4 v[132:135], v[154:155], off
	v_pk_add_f32 v[122:123], v[122:123], v[114:115]
	v_pk_add_f32 v[126:127], v[126:127], v[118:119]
	v_pk_add_f32 v[124:125], v[124:125], v[116:117]
	v_pk_add_f32 v[120:121], v[120:121], v[112:113]
	v_mul_f32_e32 v123, 0xbfb8aa3b, v123
	v_mul_f32_e32 v124, 0xbfb8aa3b, v124
	v_mul_f32_e32 v125, 0xbfb8aa3b, v125
	v_mul_f32_e32 v126, 0xbfb8aa3b, v126
	v_mul_f32_e32 v127, 0xbfb8aa3b, v127
	v_mul_f32_e32 v120, 0xbfb8aa3b, v120
	v_mul_f32_e32 v121, 0xbfb8aa3b, v121
	v_mul_f32_e32 v122, 0xbfb8aa3b, v122
	v_exp_f32_e32 v123, v123
	v_exp_f32_e32 v124, v124
	v_exp_f32_e32 v125, v125
	v_exp_f32_e32 v126, v126
	v_exp_f32_e32 v127, v127
	v_exp_f32_e32 v120, v120
	v_exp_f32_e32 v121, v121
	v_exp_f32_e32 v122, v122
	v_add_f32_e32 v123, 1.0, v123
	v_add_f32_e32 v124, 1.0, v124
	v_add_f32_e32 v125, 1.0, v125
	v_add_f32_e32 v126, 1.0, v126
	v_add_f32_e32 v127, 1.0, v127
	v_add_f32_e32 v120, 1.0, v120
	v_add_f32_e32 v121, 1.0, v121
	v_add_f32_e32 v122, 1.0, v122
	v_rcp_f32_e32 v123, v123
	v_or_b32_e32 v170, 32, v162
	v_rcp_f32_e32 v124, v124
	v_rcp_f32_e32 v125, v125
	v_rcp_f32_e32 v126, v126
	v_rcp_f32_e32 v127, v127
	v_rcp_f32_e32 v120, v120
	v_rcp_f32_e32 v121, v121
	v_rcp_f32_e32 v122, v122
	v_ashrrev_i32_e32 v171, 31, v170
	v_lshlrev_b64 v[128:129], 11, v[174:175]
	v_lshlrev_b64 v[130:131], 10, v[170:171]
	v_lshl_add_u64 v[128:129], s[42:43], 0, v[128:129]
	v_lshl_add_u64 v[130:131], s[0:1], 0, v[130:131]
	v_lshl_add_u64 v[128:129], v[128:129], 0, v[158:159]
	v_lshl_add_u64 v[130:131], v[130:131], 0, v[158:159]
	v_pk_add_f32 v[106:107], v[106:107], v[114:115]
	v_pk_add_f32 v[110:111], v[110:111], v[118:119]
	v_pk_add_f32 v[108:109], v[108:109], v[116:117]
	v_pk_add_f32 v[104:105], v[104:105], v[112:113]
	v_mul_f32_e32 v107, 0xbfb8aa3b, v107
	v_mul_f32_e32 v108, 0xbfb8aa3b, v108
	v_mul_f32_e32 v109, 0xbfb8aa3b, v109
	v_mul_f32_e32 v110, 0xbfb8aa3b, v110
	v_mul_f32_e32 v111, 0xbfb8aa3b, v111
	v_mul_f32_e32 v104, 0xbfb8aa3b, v104
	v_mul_f32_e32 v105, 0xbfb8aa3b, v105
	v_mul_f32_e32 v106, 0xbfb8aa3b, v106
	v_exp_f32_e32 v107, v107
	v_exp_f32_e32 v108, v108
	v_exp_f32_e32 v109, v109
	v_exp_f32_e32 v110, v110
	v_exp_f32_e32 v111, v111
	v_exp_f32_e32 v104, v104
	v_exp_f32_e32 v105, v105
	v_exp_f32_e32 v106, v106
	v_add_f32_e32 v107, 1.0, v107
	v_add_f32_e32 v108, 1.0, v108
	v_add_f32_e32 v109, 1.0, v109
	v_add_f32_e32 v110, 1.0, v110
	v_add_f32_e32 v111, 1.0, v111
	v_add_f32_e32 v104, 1.0, v104
	v_add_f32_e32 v105, 1.0, v105
	v_add_f32_e32 v106, 1.0, v106
	v_rcp_f32_e32 v107, v107
	v_rcp_f32_e32 v108, v108
	v_rcp_f32_e32 v109, v109
	v_rcp_f32_e32 v110, v110
	v_rcp_f32_e32 v111, v111
	v_rcp_f32_e32 v104, v104
	v_rcp_f32_e32 v105, v105
	s_waitcnt vmcnt(0)
; __device__ __forceinline__ unsigned cvt_pk_bf16(float lo, float hi) { unsigned r; asm volatile("v_cvt_pk_bf16_f32 %0, %1, %2" : "=v"(r) : "v"(lo), "v"(hi)); return r; }
; __device__ __forceinline__ float fast_sigmoid(float x) { return __builtin_amdgcn_rcpf(1.f + __builtin_amdgcn_exp2f(-x * LOG2E)); }
;     __device__ __forceinline__ void operator()(const f32x4 (&acc)[2][2][4][2], const pg8::Unit& u, int wr, int wc, int fr, int fq) const {
;     ...
; #pragma unroll
;         for (int bj = 0; bj < 2; ++bj) { const int c = col0 + bj * 128; const f32x4 b0 = *(const f32x4*)(bias + c), b1 = *(const f32x4*)(bias + c + 4);
; #pragma unroll
;             for (int ai = 0; ai < 2; ++ai)
; #pragma unroll
;                 for (int m = 0; m < 4; ++m) { const size_t r = (size_t)(row0 + ai * 128 + m * 16);
;                     const u32x4 y = *(const u32x4*)(YB + r * SSMW + c); const f32x4 v0 = acc[ai][bj][m][0] + b0, v1 = acc[ai][bj][m][1] + b1;
;                     u32x4 w; w.x = cvt_pk_bf16(bf_lo(y.x) * fast_sigmoid(v0[0]), bf_hi(y.x) * fast_sigmoid(v0[1])); w.y = cvt_pk_bf16(bf_lo(y.y) * fast_sigmoid(v0[2]), bf_hi(y.y) * fast_sigmoid(v0[3]));
;                     w.z = cvt_pk_bf16(bf_lo(y.z) * fast_sigmoid(v1[0]), bf_hi(y.z) * fast_sigmoid(v1[1])); w.w = cvt_pk_bf16(bf_lo(y.w) * fast_sigmoid(v1[2]), bf_hi(y.w) * fast_sigmoid(v1[3]));
;                     *(u32x4*)(CAT + r * D + 512 + c) = w; } }
	v_lshlrev_b32_e32 v174, 16, v135
	v_and_b32_e32 v135, 0xffff0000, v135
	v_lshlrev_b32_e32 v163, 16, v132
	v_and_b32_e32 v132, 0xffff0000, v132
	v_lshlrev_b32_e32 v172, 16, v133
	v_and_b32_e32 v133, 0xffff0000, v133
	v_lshlrev_b32_e32 v173, 16, v134
	v_and_b32_e32 v134, 0xffff0000, v134
	v_mul_f32_e32 v123, v123, v135
	v_mul_f32_e32 v124, v124, v163
	v_mul_f32_e32 v125, v125, v132
	v_mul_f32_e32 v126, v126, v172
	v_mul_f32_e32 v127, v127, v133
	v_mul_f32_e32 v132, v120, v173
	v_mul_f32_e32 v133, v121, v134
	v_mul_f32_e32 v134, v122, v174
	v_cvt_pk_bf16_f32 v120, v124, v125
	v_cvt_pk_bf16_f32 v121, v126, v127
	v_cvt_pk_bf16_f32 v122, v132, v133
	v_cvt_pk_bf16_f32 v123, v134, v123
	global_store_dwordx4 v[128:129], v[120:123], off offset:1024 nt
	global_load_dwordx4 v[124:127], v[130:131], off
	v_or_b32_e32 v132, 48, v162
	v_rcp_f32_e32 v106, v106
	v_ashrrev_i32_e32 v133, 31, v132
	v_lshlrev_b64 v[120:121], 11, v[170:171]
	v_lshlrev_b64 v[122:123], 10, v[132:133]
	v_lshl_add_u64 v[120:121], s[42:43], 0, v[120:121]
	v_lshl_add_u64 v[122:123], s[0:1], 0, v[122:123]
	v_lshl_add_u64 v[120:121], v[120:121], 0, v[158:159]
	v_lshl_add_u64 v[122:123], v[122:123], 0, v[158:159]
	v_pk_add_f32 v[98:99], v[98:99], v[114:115]
	v_pk_add_f32 v[102:103], v[102:103], v[118:119]
	v_pk_add_f32 v[100:101], v[100:101], v[116:117]
	v_pk_add_f32 v[96:97], v[96:97], v[112:113]
	v_mul_f32_e32 v99, 0xbfb8aa3b, v99
	v_mul_f32_e32 v100, 0xbfb8aa3b, v100
	v_mul_f32_e32 v101, 0xbfb8aa3b, v101
	v_mul_f32_e32 v102, 0xbfb8aa3b, v102
	v_mul_f32_e32 v103, 0xbfb8aa3b, v103
	v_mul_f32_e32 v96, 0xbfb8aa3b, v96
	v_mul_f32_e32 v97, 0xbfb8aa3b, v97
	v_mul_f32_e32 v98, 0xbfb8aa3b, v98
	v_exp_f32_e32 v99, v99
	v_exp_f32_e32 v100, v100
	v_exp_f32_e32 v101, v101
	v_exp_f32_e32 v102, v102
	v_exp_f32_e32 v103, v103
	v_exp_f32_e32 v96, v96
	v_exp_f32_e32 v97, v97
	v_exp_f32_e32 v98, v98
	v_add_f32_e32 v99, 1.0, v99
	v_add_f32_e32 v100, 1.0, v100
	v_add_f32_e32 v101, 1.0, v101
	v_add_f32_e32 v102, 1.0, v102
	v_add_f32_e32 v103, 1.0, v103
	v_add_f32_e32 v96, 1.0, v96
	v_add_f32_e32 v97, 1.0, v97
	v_add_f32_e32 v98, 1.0, v98
	v_rcp_f32_e32 v99, v99
	v_rcp_f32_e32 v100, v100
	v_rcp_f32_e32 v101, v101
	v_rcp_f32_e32 v102, v102
	v_rcp_f32_e32 v103, v103
	v_rcp_f32_e32 v96, v96
	v_rcp_f32_e32 v97, v97
	v_rcp_f32_e32 v98, v98
	v_pk_add_f32 v[90:91], v[90:91], v[114:115]
	v_pk_add_f32 v[94:95], v[94:95], v[118:119]
	v_pk_add_f32 v[92:93], v[92:93], v[116:117]
	v_pk_add_f32 v[88:89], v[88:89], v[112:113]
	v_mul_f32_e32 v91, 0xbfb8aa3b, v91
	v_mul_f32_e32 v92, 0xbfb8aa3b, v92
	v_mul_f32_e32 v93, 0xbfb8aa3b, v93
	v_mul_f32_e32 v94, 0xbfb8aa3b, v94
	v_mul_f32_e32 v95, 0xbfb8aa3b, v95
	v_mul_f32_e32 v88, 0xbfb8aa3b, v88
	v_mul_f32_e32 v89, 0xbfb8aa3b, v89
	v_mul_f32_e32 v90, 0xbfb8aa3b, v90
	v_exp_f32_e32 v91, v91
	v_exp_f32_e32 v92, v92
	v_exp_f32_e32 v93, v93
	v_exp_f32_e32 v94, v94
	v_exp_f32_e32 v95, v95
	v_exp_f32_e32 v88, v88
	v_exp_f32_e32 v89, v89
	v_exp_f32_e32 v90, v90
	v_add_f32_e32 v91, 1.0, v91
	v_add_f32_e32 v92, 1.0, v92
	v_add_f32_e32 v93, 1.0, v93
	v_add_f32_e32 v94, 1.0, v94
	v_add_f32_e32 v95, 1.0, v95
	v_add_f32_e32 v88, 1.0, v88
	v_add_f32_e32 v89, 1.0, v89
	v_add_f32_e32 v90, 1.0, v90
	v_rcp_f32_e32 v91, v91
	v_rcp_f32_e32 v92, v92
	v_rcp_f32_e32 v93, v93
	v_rcp_f32_e32 v94, v94
	v_rcp_f32_e32 v95, v95
	v_rcp_f32_e32 v88, v88
	s_waitcnt vmcnt(0)
	v_lshlrev_b32_e32 v170, 16, v127
	v_and_b32_e32 v127, 0xffff0000, v127
	v_lshlrev_b32_e32 v134, 16, v124
	v_and_b32_e32 v124, 0xffff0000, v124
	v_lshlrev_b32_e32 v135, 16, v125
	v_and_b32_e32 v125, 0xffff0000, v125
	v_lshlrev_b32_e32 v163, 16, v126
	v_and_b32_e32 v126, 0xffff0000, v126
	v_mul_f32_e32 v107, v107, v127
	v_mul_f32_e32 v108, v108, v134
	v_mul_f32_e32 v109, v109, v124
	v_mul_f32_e32 v110, v110, v135
	v_mul_f32_e32 v111, v111, v125
	v_mul_f32_e32 v124, v104, v163
	v_mul_f32_e32 v125, v105, v126
	v_mul_f32_e32 v126, v106, v170
	v_cvt_pk_bf16_f32 v104, v108, v109
	v_cvt_pk_bf16_f32 v105, v110, v111
	v_cvt_pk_bf16_f32 v106, v124, v125
	v_cvt_pk_bf16_f32 v107, v126, v107
	global_store_dwordx4 v[120:121], v[104:107], off offset:1024 nt
	global_load_dwordx4 v[108:111], v[122:123], off
	v_add_u32_e32 v124, 0x80, v162
	v_ashrrev_i32_e32 v125, 31, v124
	v_lshlrev_b64 v[104:105], 11, v[132:133]
	v_lshlrev_b64 v[106:107], 10, v[124:125]
	v_lshl_add_u64 v[104:105], s[42:43], 0, v[104:105]
	v_lshl_add_u64 v[106:107], s[0:1], 0, v[106:107]
	v_lshl_add_u64 v[104:105], v[104:105], 0, v[158:159]
	v_lshl_add_u64 v[106:107], v[106:107], 0, v[158:159]
	v_rcp_f32_e32 v89, v89
	v_rcp_f32_e32 v90, v90
	v_pk_add_f32 v[82:83], v[82:83], v[114:115]
	v_pk_add_f32 v[86:87], v[86:87], v[118:119]
	v_pk_add_f32 v[84:85], v[84:85], v[116:117]
	v_pk_add_f32 v[80:81], v[80:81], v[112:113]
	v_mul_f32_e32 v83, 0xbfb8aa3b, v83
	v_mul_f32_e32 v84, 0xbfb8aa3b, v84
	v_mul_f32_e32 v85, 0xbfb8aa3b, v85
	v_mul_f32_e32 v86, 0xbfb8aa3b, v86
	v_mul_f32_e32 v87, 0xbfb8aa3b, v87
	v_mul_f32_e32 v80, 0xbfb8aa3b, v80
	v_mul_f32_e32 v81, 0xbfb8aa3b, v81
	v_mul_f32_e32 v82, 0xbfb8aa3b, v82
	v_exp_f32_e32 v83, v83
	v_exp_f32_e32 v84, v84
	v_exp_f32_e32 v85, v85
	v_exp_f32_e32 v86, v86
	v_exp_f32_e32 v87, v87
	v_exp_f32_e32 v80, v80
	v_exp_f32_e32 v81, v81
	v_exp_f32_e32 v82, v82
	v_add_f32_e32 v83, 1.0, v83
	v_add_f32_e32 v84, 1.0, v84
	v_add_f32_e32 v85, 1.0, v85
	v_add_f32_e32 v86, 1.0, v86
	v_add_f32_e32 v87, 1.0, v87
	v_add_f32_e32 v80, 1.0, v80
	v_add_f32_e32 v81, 1.0, v81
	v_add_f32_e32 v82, 1.0, v82
	v_rcp_f32_e32 v83, v83
	v_rcp_f32_e32 v84, v84
	v_rcp_f32_e32 v85, v85
	v_rcp_f32_e32 v86, v86
	v_rcp_f32_e32 v87, v87
	v_rcp_f32_e32 v80, v80
	v_rcp_f32_e32 v81, v81
	v_rcp_f32_e32 v82, v82
	v_pk_add_f32 v[74:75], v[74:75], v[114:115]
	v_pk_add_f32 v[78:79], v[78:79], v[118:119]
	v_pk_add_f32 v[76:77], v[76:77], v[116:117]
	v_pk_add_f32 v[72:73], v[72:73], v[112:113]
	v_mul_f32_e32 v75, 0xbfb8aa3b, v75
	v_mul_f32_e32 v76, 0xbfb8aa3b, v76
	v_mul_f32_e32 v77, 0xbfb8aa3b, v77
	v_mul_f32_e32 v78, 0xbfb8aa3b, v78
	v_mul_f32_e32 v79, 0xbfb8aa3b, v79
	v_mul_f32_e32 v72, 0xbfb8aa3b, v72
	v_mul_f32_e32 v73, 0xbfb8aa3b, v73
	v_mul_f32_e32 v74, 0xbfb8aa3b, v74
	v_exp_f32_e32 v75, v75
	v_exp_f32_e32 v76, v76
	v_exp_f32_e32 v77, v77
	v_exp_f32_e32 v78, v78
	v_exp_f32_e32 v79, v79
	v_exp_f32_e32 v72, v72
	v_exp_f32_e32 v73, v73
	v_exp_f32_e32 v74, v74
	v_add_f32_e32 v75, 1.0, v75
	v_add_f32_e32 v76, 1.0, v76
	v_add_f32_e32 v77, 1.0, v77
	v_add_f32_e32 v78, 1.0, v78
	v_add_f32_e32 v79, 1.0, v79
	v_add_f32_e32 v72, 1.0, v72
	v_add_f32_e32 v73, 1.0, v73
	v_add_f32_e32 v74, 1.0, v74
	v_rcp_f32_e32 v75, v75
	v_rcp_f32_e32 v76, v76
	v_rcp_f32_e32 v77, v77
	v_rcp_f32_e32 v78, v78
	v_rcp_f32_e32 v79, v79
	s_waitcnt vmcnt(0)
; __device__ __forceinline__ unsigned cvt_pk_bf16(float lo, float hi) { unsigned r; asm volatile("v_cvt_pk_bf16_f32 %0, %1, %2" : "=v"(r) : "v"(lo), "v"(hi)); return r; }
; __device__ __forceinline__ float fast_sigmoid(float x) { return __builtin_amdgcn_rcpf(1.f + __builtin_amdgcn_exp2f(-x * LOG2E)); }
;     __device__ __forceinline__ void operator()(const f32x4 (&acc)[2][2][4][2], const pg8::Unit& u, int wr, int wc, int fr, int fq) const {
;     ...
; #pragma unroll
;         for (int bj = 0; bj < 2; ++bj) { const int c = col0 + bj * 128; const f32x4 b0 = *(const f32x4*)(bias + c), b1 = *(const f32x4*)(bias + c + 4);
; #pragma unroll
;             for (int ai = 0; ai < 2; ++ai)
; #pragma unroll
;                 for (int m = 0; m < 4; ++m) { const size_t r = (size_t)(row0 + ai * 128 + m * 16);
;                     const u32x4 y = *(const u32x4*)(YB + r * SSMW + c); const f32x4 v0 = acc[ai][bj][m][0] + b0, v1 = acc[ai][bj][m][1] + b1;
;                     u32x4 w; w.x = cvt_pk_bf16(bf_lo(y.x) * fast_sigmoid(v0[0]), bf_hi(y.x) * fast_sigmoid(v0[1])); w.y = cvt_pk_bf16(bf_lo(y.y) * fast_sigmoid(v0[2]), bf_hi(y.y) * fast_sigmoid(v0[3]));
;                     w.z = cvt_pk_bf16(bf_lo(y.z) * fast_sigmoid(v1[0]), bf_hi(y.z) * fast_sigmoid(v1[1])); w.w = cvt_pk_bf16(bf_lo(y.w) * fast_sigmoid(v1[2]), bf_hi(y.w) * fast_sigmoid(v1[3]));
;                     *(u32x4*)(CAT + r * D + 512 + c) = w; } }
	v_lshlrev_b32_e32 v133, 16, v111
	v_and_b32_e32 v111, 0xffff0000, v111
	v_lshlrev_b32_e32 v126, 16, v108
	v_and_b32_e32 v108, 0xffff0000, v108
	v_lshlrev_b32_e32 v127, 16, v109
	v_and_b32_e32 v109, 0xffff0000, v109
	v_lshlrev_b32_e32 v132, 16, v110
	v_and_b32_e32 v110, 0xffff0000, v110
	v_mul_f32_e32 v99, v99, v111
	v_mul_f32_e32 v100, v100, v126
	v_mul_f32_e32 v101, v101, v108
	v_mul_f32_e32 v102, v102, v127
	v_mul_f32_e32 v103, v103, v109
	v_mul_f32_e32 v108, v96, v132
	v_mul_f32_e32 v109, v97, v110
	v_mul_f32_e32 v110, v98, v133
	v_cvt_pk_bf16_f32 v96, v100, v101
	v_cvt_pk_bf16_f32 v97, v102, v103
	v_cvt_pk_bf16_f32 v98, v108, v109
	v_cvt_pk_bf16_f32 v99, v110, v99
	global_store_dwordx4 v[104:105], v[96:99], off offset:1024 nt
	global_load_dwordx4 v[100:103], v[106:107], off
	v_add_u32_e32 v108, 0x90, v162
	v_ashrrev_i32_e32 v109, 31, v108
	v_lshlrev_b64 v[96:97], 11, v[124:125]
	v_lshlrev_b64 v[98:99], 10, v[108:109]
	v_lshl_add_u64 v[96:97], s[42:43], 0, v[96:97]
	v_lshl_add_u64 v[98:99], s[0:1], 0, v[98:99]
	v_lshl_add_u64 v[96:97], v[96:97], 0, v[158:159]
	v_lshl_add_u64 v[98:99], v[98:99], 0, v[158:159]
	v_rcp_f32_e32 v72, v72
	v_rcp_f32_e32 v73, v73
	v_rcp_f32_e32 v74, v74
	v_pk_add_f32 v[68:69], v[68:69], v[116:117]
	v_pk_add_f32 v[64:65], v[64:65], v[112:113]
	v_mul_f32_e32 v68, 0xbfb8aa3b, v68
	v_mul_f32_e32 v69, 0xbfb8aa3b, v69
	v_pk_add_f32 v[70:71], v[70:71], v[118:119]
	v_mul_f32_e32 v64, 0xbfb8aa3b, v64
	v_exp_f32_e32 v68, v68
	v_exp_f32_e32 v69, v69
	v_pk_add_f32 v[66:67], v[66:67], v[114:115]
	v_mul_f32_e32 v71, 0xbfb8aa3b, v71
	v_mul_f32_e32 v65, 0xbfb8aa3b, v65
	v_exp_f32_e32 v64, v64
	v_mul_f32_e32 v70, 0xbfb8aa3b, v70
	v_mul_f32_e32 v66, 0xbfb8aa3b, v66
	v_mul_f32_e32 v67, 0xbfb8aa3b, v67
	v_exp_f32_e32 v71, v71
	v_exp_f32_e32 v65, v65
	v_exp_f32_e32 v70, v70
	v_exp_f32_e32 v66, v66
	v_exp_f32_e32 v67, v67
	v_add_f32_e32 v68, 1.0, v68
	v_add_f32_e32 v69, 1.0, v69
	v_add_f32_e32 v64, 1.0, v64
	v_rcp_f32_e32 v68, v68
	v_rcp_f32_e32 v69, v69
	v_add_f32_e32 v71, 1.0, v71
	v_add_f32_e32 v65, 1.0, v65
	v_rcp_f32_e32 v64, v64
	v_add_f32_e32 v70, 1.0, v70
	v_add_f32_e32 v66, 1.0, v66
	v_add_f32_e32 v67, 1.0, v67
	v_rcp_f32_e32 v71, v71
	v_rcp_f32_e32 v65, v65
	v_rcp_f32_e32 v70, v70
	v_rcp_f32_e32 v66, v66
	v_rcp_f32_e32 v67, v67
	s_waitcnt vmcnt(0)
	v_lshlrev_b32_e32 v125, 16, v103
	v_and_b32_e32 v103, 0xffff0000, v103
	v_lshlrev_b32_e32 v110, 16, v100
	v_and_b32_e32 v100, 0xffff0000, v100
	v_lshlrev_b32_e32 v111, 16, v101
	v_and_b32_e32 v101, 0xffff0000, v101
	v_lshlrev_b32_e32 v124, 16, v102
	v_and_b32_e32 v102, 0xffff0000, v102
	v_mul_f32_e32 v91, v91, v103
	v_mul_f32_e32 v92, v92, v110
	v_mul_f32_e32 v93, v93, v100
	v_mul_f32_e32 v94, v94, v111
	v_mul_f32_e32 v95, v95, v101
	v_mul_f32_e32 v100, v88, v124
	v_mul_f32_e32 v101, v89, v102
	v_mul_f32_e32 v102, v90, v125
	v_cvt_pk_bf16_f32 v88, v92, v93
	v_cvt_pk_bf16_f32 v89, v94, v95
	v_cvt_pk_bf16_f32 v90, v100, v101
	v_cvt_pk_bf16_f32 v91, v102, v91
	global_store_dwordx4 v[96:97], v[88:91], off offset:1024 nt
	global_load_dwordx4 v[92:95], v[98:99], off
	v_add_u32_e32 v100, 0xa0, v162
	v_ashrrev_i32_e32 v101, 31, v100
	v_lshlrev_b64 v[88:89], 11, v[108:109]
	v_lshlrev_b64 v[90:91], 10, v[100:101]
	v_lshl_add_u64 v[88:89], s[42:43], 0, v[88:89]
	v_lshl_add_u64 v[90:91], s[0:1], 0, v[90:91]
	v_lshl_add_u64 v[88:89], v[88:89], 0, v[158:159]
	v_lshl_add_u64 v[90:91], v[90:91], 0, v[158:159]
	s_waitcnt vmcnt(0)
	v_lshlrev_b32_e32 v109, 16, v95
	v_and_b32_e32 v95, 0xffff0000, v95
	v_lshlrev_b32_e32 v102, 16, v92
	v_and_b32_e32 v92, 0xffff0000, v92
	v_lshlrev_b32_e32 v103, 16, v93
	v_and_b32_e32 v93, 0xffff0000, v93
	v_lshlrev_b32_e32 v108, 16, v94
	v_and_b32_e32 v94, 0xffff0000, v94
	v_mul_f32_e32 v83, v83, v95
	v_mul_f32_e32 v84, v84, v102
	v_mul_f32_e32 v85, v85, v92
	v_mul_f32_e32 v86, v86, v103
	v_mul_f32_e32 v87, v87, v93
	v_mul_f32_e32 v92, v80, v108
	v_mul_f32_e32 v93, v81, v94
	v_mul_f32_e32 v94, v82, v109
	v_cvt_pk_bf16_f32 v80, v84, v85
	v_cvt_pk_bf16_f32 v81, v86, v87
	v_cvt_pk_bf16_f32 v82, v92, v93
	v_cvt_pk_bf16_f32 v83, v94, v83
	global_store_dwordx4 v[88:89], v[80:83], off offset:1024 nt
	global_load_dwordx4 v[84:87], v[90:91], off
	v_add_u32_e32 v92, 0xb0, v162
	v_ashrrev_i32_e32 v93, 31, v92
	v_lshlrev_b64 v[80:81], 11, v[100:101]
	v_lshlrev_b64 v[82:83], 10, v[92:93]
	v_lshl_add_u64 v[80:81], s[42:43], 0, v[80:81]
	v_lshl_add_u64 v[82:83], s[0:1], 0, v[82:83]
	v_lshl_add_u64 v[80:81], v[80:81], 0, v[158:159]
	v_lshl_add_u64 v[82:83], v[82:83], 0, v[158:159]
	s_waitcnt vmcnt(0)
	v_lshlrev_b32_e32 v101, 16, v87
	v_and_b32_e32 v87, 0xffff0000, v87
	v_lshlrev_b32_e32 v94, 16, v84
	v_and_b32_e32 v84, 0xffff0000, v84
	v_lshlrev_b32_e32 v95, 16, v85
	v_and_b32_e32 v85, 0xffff0000, v85
	v_lshlrev_b32_e32 v100, 16, v86
	v_and_b32_e32 v86, 0xffff0000, v86
	v_mul_f32_e32 v75, v75, v87
	v_mul_f32_e32 v76, v76, v94
	v_mul_f32_e32 v77, v77, v84
	v_mul_f32_e32 v78, v78, v95
	v_mul_f32_e32 v79, v79, v85
	v_mul_f32_e32 v84, v72, v100
	v_mul_f32_e32 v85, v73, v86
	v_mul_f32_e32 v86, v74, v101
	v_cvt_pk_bf16_f32 v72, v76, v77
	v_cvt_pk_bf16_f32 v73, v78, v79
	v_cvt_pk_bf16_f32 v74, v84, v85
	v_cvt_pk_bf16_f32 v75, v86, v75
	global_store_dwordx4 v[80:81], v[72:75], off offset:1024 nt
	global_load_dwordx4 v[72:75], v[82:83], off
	s_waitcnt vmcnt(0)
; __device__ __forceinline__ unsigned cvt_pk_bf16(float lo, float hi) { unsigned r; asm volatile("v_cvt_pk_bf16_f32 %0, %1, %2" : "=v"(r) : "v"(lo), "v"(hi)); return r; }
; __device__ __forceinline__ float fast_sigmoid(float x) { return __builtin_amdgcn_rcpf(1.f + __builtin_amdgcn_exp2f(-x * LOG2E)); }
;     __device__ __forceinline__ void operator()(const f32x4 (&acc)[2][2][4][2], const pg8::Unit& u, int wr, int wc, int fr, int fq) const {
;     ...
; #pragma unroll
;         for (int bj = 0; bj < 2; ++bj) { const int c = col0 + bj * 128; const f32x4 b0 = *(const f32x4*)(bias + c), b1 = *(const f32x4*)(bias + c + 4);
; #pragma unroll
;             for (int ai = 0; ai < 2; ++ai)
; #pragma unroll
;                 for (int m = 0; m < 4; ++m) { const size_t r = (size_t)(row0 + ai * 128 + m * 16);
;                     const u32x4 y = *(const u32x4*)(YB + r * SSMW + c); const f32x4 v0 = acc[ai][bj][m][0] + b0, v1 = acc[ai][bj][m][1] + b1;
;                     u32x4 w; w.x = cvt_pk_bf16(bf_lo(y.x) * fast_sigmoid(v0[0]), bf_hi(y.x) * fast_sigmoid(v0[1])); w.y = cvt_pk_bf16(bf_lo(y.y) * fast_sigmoid(v0[2]), bf_hi(y.y) * fast_sigmoid(v0[3]));
;                     w.z = cvt_pk_bf16(bf_lo(y.z) * fast_sigmoid(v1[0]), bf_hi(y.z) * fast_sigmoid(v1[1])); w.w = cvt_pk_bf16(bf_lo(y.w) * fast_sigmoid(v1[2]), bf_hi(y.w) * fast_sigmoid(v1[3]));
;                     *(u32x4*)(CAT + r * D + 512 + c) = w; } }
	v_lshlrev_b32_e32 v76, 16, v72
	v_and_b32_e32 v72, 0xffff0000, v72
	v_lshlrev_b32_e32 v78, 16, v74
	v_mul_f32_e32 v68, v68, v76
	v_mul_f32_e32 v69, v69, v72
	v_lshlrev_b32_e32 v77, 16, v73
	v_and_b32_e32 v73, 0xffff0000, v73
	v_and_b32_e32 v74, 0xffff0000, v74
	v_mul_f32_e32 v72, v64, v78
	v_cvt_pk_bf16_f32 v64, v68, v69
	v_lshlrev_b64 v[68:69], 11, v[92:93]
	v_lshlrev_b32_e32 v79, 16, v75
	v_and_b32_e32 v75, 0xffff0000, v75
	v_mul_f32_e32 v71, v71, v73
	v_mul_f32_e32 v73, v65, v74
	v_lshl_add_u64 v[68:69], s[42:43], 0, v[68:69]
	v_mul_f32_e32 v70, v70, v77
	v_mul_f32_e32 v74, v66, v79
	v_mul_f32_e32 v67, v67, v75
	v_cvt_pk_bf16_f32 v65, v70, v71
	v_cvt_pk_bf16_f32 v66, v72, v73
	v_lshl_add_u64 v[72:73], v[68:69], 0, v[158:159]
	v_cvt_pk_bf16_f32 v67, v74, v67
	global_store_dwordx4 v[72:73], v[64:67], off offset:1024 nt
	global_load_dwordx4 v[74:77], v[160:161], off offset:256
	global_load_dwordx4 v[68:71], v[156:157], off offset:512
	s_nop 0
	global_load_dwordx4 v[64:67], v[156:157], off offset:528
	s_waitcnt vmcnt(1)
	v_pk_add_f32 v[62:63], v[62:63], v[70:71]
	s_waitcnt vmcnt(0)
	v_pk_add_f32 v[58:59], v[58:59], v[66:67]
	v_pk_add_f32 v[60:61], v[60:61], v[68:69]
	v_pk_add_f32 v[56:57], v[56:57], v[64:65]
	v_mul_f32_e32 v59, 0xbfb8aa3b, v59
	v_mul_f32_e32 v60, 0xbfb8aa3b, v60
	v_mul_f32_e32 v61, 0xbfb8aa3b, v61
	v_mul_f32_e32 v62, 0xbfb8aa3b, v62
	v_mul_f32_e32 v63, 0xbfb8aa3b, v63
	v_mul_f32_e32 v56, 0xbfb8aa3b, v56
	v_mul_f32_e32 v57, 0xbfb8aa3b, v57
	v_mul_f32_e32 v58, 0xbfb8aa3b, v58
	v_exp_f32_e32 v59, v59
	v_exp_f32_e32 v60, v60
	v_exp_f32_e32 v61, v61
	v_exp_f32_e32 v62, v62
	v_exp_f32_e32 v63, v63
	v_exp_f32_e32 v56, v56
	v_exp_f32_e32 v57, v57
	v_exp_f32_e32 v58, v58
	v_add_f32_e32 v59, 1.0, v59
	v_add_f32_e32 v60, 1.0, v60
	v_add_f32_e32 v61, 1.0, v61
	v_add_f32_e32 v62, 1.0, v62
	v_add_f32_e32 v63, 1.0, v63
	v_add_f32_e32 v56, 1.0, v56
	v_add_f32_e32 v57, 1.0, v57
	v_add_f32_e32 v58, 1.0, v58
	v_rcp_f32_e32 v59, v59
	v_rcp_f32_e32 v60, v60
	v_rcp_f32_e32 v61, v61
	v_rcp_f32_e32 v62, v62
	v_rcp_f32_e32 v63, v63
	v_rcp_f32_e32 v56, v56
	v_rcp_f32_e32 v57, v57
	v_rcp_f32_e32 v58, v58
	v_lshlrev_b32_e32 v85, 16, v77
	v_and_b32_e32 v77, 0xffff0000, v77
	v_lshlrev_b32_e32 v78, 16, v74
	v_and_b32_e32 v74, 0xffff0000, v74
	v_lshlrev_b32_e32 v79, 16, v75
	v_and_b32_e32 v75, 0xffff0000, v75
	v_lshlrev_b32_e32 v84, 16, v76
	v_and_b32_e32 v76, 0xffff0000, v76
	v_mul_f32_e32 v59, v59, v77
	v_mul_f32_e32 v60, v60, v78
	v_mul_f32_e32 v61, v61, v74
	v_mul_f32_e32 v62, v62, v79
	v_mul_f32_e32 v63, v63, v75
	v_mul_f32_e32 v74, v56, v84
	v_mul_f32_e32 v75, v57, v76
	v_mul_f32_e32 v76, v58, v85
	v_cvt_pk_bf16_f32 v56, v60, v61
	v_cvt_pk_bf16_f32 v57, v62, v63
	v_cvt_pk_bf16_f32 v58, v74, v75
	v_cvt_pk_bf16_f32 v59, v76, v59
	global_store_dwordx4 v[152:153], v[56:59], off offset:1280 nt
	global_load_dwordx4 v[56:59], v[154:155], off offset:256
	v_pk_add_f32 v[50:51], v[50:51], v[66:67]
	v_pk_add_f32 v[54:55], v[54:55], v[70:71]
	v_pk_add_f32 v[52:53], v[52:53], v[68:69]
	v_pk_add_f32 v[48:49], v[48:49], v[64:65]
	v_mul_f32_e32 v51, 0xbfb8aa3b, v51
	v_mul_f32_e32 v52, 0xbfb8aa3b, v52
	v_mul_f32_e32 v53, 0xbfb8aa3b, v53
	v_mul_f32_e32 v54, 0xbfb8aa3b, v54
	v_mul_f32_e32 v55, 0xbfb8aa3b, v55
	v_mul_f32_e32 v48, 0xbfb8aa3b, v48
	v_mul_f32_e32 v49, 0xbfb8aa3b, v49
	v_mul_f32_e32 v50, 0xbfb8aa3b, v50
	v_exp_f32_e32 v51, v51
	v_exp_f32_e32 v52, v52
	v_exp_f32_e32 v53, v53
	v_exp_f32_e32 v54, v54
	v_exp_f32_e32 v55, v55
	v_exp_f32_e32 v48, v48
	v_exp_f32_e32 v49, v49
	v_exp_f32_e32 v50, v50
	v_add_f32_e32 v51, 1.0, v51
	v_add_f32_e32 v52, 1.0, v52
	v_add_f32_e32 v53, 1.0, v53
	v_add_f32_e32 v54, 1.0, v54
	v_add_f32_e32 v55, 1.0, v55
	v_add_f32_e32 v48, 1.0, v48
	v_add_f32_e32 v49, 1.0, v49
	v_add_f32_e32 v50, 1.0, v50
	v_rcp_f32_e32 v51, v51
	v_rcp_f32_e32 v52, v52
	v_rcp_f32_e32 v53, v53
	v_rcp_f32_e32 v54, v54
	v_rcp_f32_e32 v55, v55
	v_rcp_f32_e32 v48, v48
	v_rcp_f32_e32 v49, v49
	v_rcp_f32_e32 v50, v50
	v_pk_add_f32 v[42:43], v[42:43], v[66:67]
	v_pk_add_f32 v[46:47], v[46:47], v[70:71]
	v_pk_add_f32 v[44:45], v[44:45], v[68:69]
	v_pk_add_f32 v[40:41], v[40:41], v[64:65]
	v_mul_f32_e32 v43, 0xbfb8aa3b, v43
	v_mul_f32_e32 v44, 0xbfb8aa3b, v44
	v_mul_f32_e32 v45, 0xbfb8aa3b, v45
	v_mul_f32_e32 v46, 0xbfb8aa3b, v46
	v_mul_f32_e32 v47, 0xbfb8aa3b, v47
	v_mul_f32_e32 v40, 0xbfb8aa3b, v40
	v_mul_f32_e32 v41, 0xbfb8aa3b, v41
	v_mul_f32_e32 v42, 0xbfb8aa3b, v42
	v_exp_f32_e32 v43, v43
	v_exp_f32_e32 v44, v44
	v_exp_f32_e32 v45, v45
	v_exp_f32_e32 v46, v46
	v_exp_f32_e32 v47, v47
	v_exp_f32_e32 v40, v40
	v_exp_f32_e32 v41, v41
	v_exp_f32_e32 v42, v42
	v_add_f32_e32 v43, 1.0, v43
	v_add_f32_e32 v44, 1.0, v44
	v_add_f32_e32 v45, 1.0, v45
	v_add_f32_e32 v46, 1.0, v46
	v_add_f32_e32 v47, 1.0, v47
	v_add_f32_e32 v40, 1.0, v40
	v_add_f32_e32 v41, 1.0, v41
	v_add_f32_e32 v42, 1.0, v42
	v_rcp_f32_e32 v43, v43
	v_rcp_f32_e32 v44, v44
	v_rcp_f32_e32 v45, v45
	v_rcp_f32_e32 v46, v46
	v_rcp_f32_e32 v47, v47
	v_rcp_f32_e32 v40, v40
	v_rcp_f32_e32 v41, v41
	v_rcp_f32_e32 v42, v42
	v_pk_add_f32 v[34:35], v[34:35], v[66:67]
	v_pk_add_f32 v[38:39], v[38:39], v[70:71]
	v_pk_add_f32 v[36:37], v[36:37], v[68:69]
	v_pk_add_f32 v[32:33], v[32:33], v[64:65]
	v_mul_f32_e32 v35, 0xbfb8aa3b, v35
	v_mul_f32_e32 v36, 0xbfb8aa3b, v36
	v_mul_f32_e32 v37, 0xbfb8aa3b, v37
	s_waitcnt vmcnt(0)
; __device__ __forceinline__ unsigned cvt_pk_bf16(float lo, float hi) { unsigned r; asm volatile("v_cvt_pk_bf16_f32 %0, %1, %2" : "=v"(r) : "v"(lo), "v"(hi)); return r; }
; __device__ __forceinline__ float fast_sigmoid(float x) { return __builtin_amdgcn_rcpf(1.f + __builtin_amdgcn_exp2f(-x * LOG2E)); }
;     __device__ __forceinline__ void operator()(const f32x4 (&acc)[2][2][4][2], const pg8::Unit& u, int wr, int wc, int fr, int fq) const {
;     ...
; #pragma unroll
;         for (int bj = 0; bj < 2; ++bj) { const int c = col0 + bj * 128; const f32x4 b0 = *(const f32x4*)(bias + c), b1 = *(const f32x4*)(bias + c + 4);
; #pragma unroll
;             for (int ai = 0; ai < 2; ++ai)
; #pragma unroll
;                 for (int m = 0; m < 4; ++m) { const size_t r = (size_t)(row0 + ai * 128 + m * 16);
;                     const u32x4 y = *(const u32x4*)(YB + r * SSMW + c); const f32x4 v0 = acc[ai][bj][m][0] + b0, v1 = acc[ai][bj][m][1] + b1;
;                     u32x4 w; w.x = cvt_pk_bf16(bf_lo(y.x) * fast_sigmoid(v0[0]), bf_hi(y.x) * fast_sigmoid(v0[1])); w.y = cvt_pk_bf16(bf_lo(y.y) * fast_sigmoid(v0[2]), bf_hi(y.y) * fast_sigmoid(v0[3]));
;                     w.z = cvt_pk_bf16(bf_lo(y.z) * fast_sigmoid(v1[0]), bf_hi(y.z) * fast_sigmoid(v1[1])); w.w = cvt_pk_bf16(bf_lo(y.w) * fast_sigmoid(v1[2]), bf_hi(y.w) * fast_sigmoid(v1[3]));
;                     *(u32x4*)(CAT + r * D + 512 + c) = w; } }
	v_lshlrev_b32_e32 v63, 16, v59
	v_and_b32_e32 v59, 0xffff0000, v59
	v_lshlrev_b32_e32 v60, 16, v56
	v_and_b32_e32 v56, 0xffff0000, v56
	v_lshlrev_b32_e32 v61, 16, v57
	v_and_b32_e32 v57, 0xffff0000, v57
	v_lshlrev_b32_e32 v62, 16, v58
	v_and_b32_e32 v58, 0xffff0000, v58
	v_mul_f32_e32 v51, v51, v59
	v_mul_f32_e32 v52, v52, v60
	v_mul_f32_e32 v53, v53, v56
	v_mul_f32_e32 v54, v54, v61
	v_mul_f32_e32 v55, v55, v57
	v_mul_f32_e32 v56, v48, v62
	v_mul_f32_e32 v57, v49, v58
	v_mul_f32_e32 v58, v50, v63
	v_cvt_pk_bf16_f32 v48, v52, v53
	v_cvt_pk_bf16_f32 v49, v54, v55
	v_cvt_pk_bf16_f32 v50, v56, v57
	v_cvt_pk_bf16_f32 v51, v58, v51
	global_store_dwordx4 v[128:129], v[48:51], off offset:1280 nt
	global_load_dwordx4 v[48:51], v[130:131], off offset:256
	v_mul_f32_e32 v38, 0xbfb8aa3b, v38
	v_mul_f32_e32 v39, 0xbfb8aa3b, v39
	v_mul_f32_e32 v32, 0xbfb8aa3b, v32
	v_mul_f32_e32 v33, 0xbfb8aa3b, v33
	v_mul_f32_e32 v34, 0xbfb8aa3b, v34
	v_exp_f32_e32 v35, v35
	v_exp_f32_e32 v36, v36
	v_exp_f32_e32 v37, v37
	v_exp_f32_e32 v38, v38
	v_exp_f32_e32 v39, v39
	v_exp_f32_e32 v32, v32
	v_exp_f32_e32 v33, v33
	v_exp_f32_e32 v34, v34
	v_add_f32_e32 v35, 1.0, v35
	v_add_f32_e32 v36, 1.0, v36
	v_add_f32_e32 v37, 1.0, v37
	v_add_f32_e32 v38, 1.0, v38
	v_add_f32_e32 v39, 1.0, v39
	v_add_f32_e32 v32, 1.0, v32
	v_add_f32_e32 v33, 1.0, v33
	v_add_f32_e32 v34, 1.0, v34
	v_rcp_f32_e32 v35, v35
	v_rcp_f32_e32 v36, v36
	v_rcp_f32_e32 v37, v37
	v_rcp_f32_e32 v38, v38
	v_rcp_f32_e32 v39, v39
	v_rcp_f32_e32 v32, v32
	v_rcp_f32_e32 v33, v33
	v_rcp_f32_e32 v34, v34
	v_pk_add_f32 v[26:27], v[26:27], v[66:67]
	v_pk_add_f32 v[30:31], v[30:31], v[70:71]
	v_pk_add_f32 v[28:29], v[28:29], v[68:69]
	v_pk_add_f32 v[24:25], v[24:25], v[64:65]
	v_mul_f32_e32 v27, 0xbfb8aa3b, v27
	v_mul_f32_e32 v28, 0xbfb8aa3b, v28
	v_mul_f32_e32 v29, 0xbfb8aa3b, v29
	v_mul_f32_e32 v30, 0xbfb8aa3b, v30
	v_mul_f32_e32 v31, 0xbfb8aa3b, v31
	v_mul_f32_e32 v24, 0xbfb8aa3b, v24
	v_mul_f32_e32 v25, 0xbfb8aa3b, v25
	v_mul_f32_e32 v26, 0xbfb8aa3b, v26
	v_exp_f32_e32 v27, v27
	v_exp_f32_e32 v28, v28
	v_exp_f32_e32 v29, v29
	v_exp_f32_e32 v30, v30
	v_exp_f32_e32 v31, v31
	v_exp_f32_e32 v24, v24
	v_exp_f32_e32 v25, v25
	v_exp_f32_e32 v26, v26
	v_add_f32_e32 v27, 1.0, v27
	v_add_f32_e32 v28, 1.0, v28
	v_add_f32_e32 v29, 1.0, v29
	v_add_f32_e32 v30, 1.0, v30
	v_add_f32_e32 v31, 1.0, v31
	v_add_f32_e32 v24, 1.0, v24
	v_add_f32_e32 v25, 1.0, v25
	v_add_f32_e32 v26, 1.0, v26
	v_rcp_f32_e32 v27, v27
	v_rcp_f32_e32 v28, v28
	v_rcp_f32_e32 v29, v29
	v_rcp_f32_e32 v30, v30
	v_rcp_f32_e32 v31, v31
	v_rcp_f32_e32 v24, v24
	v_rcp_f32_e32 v25, v25
	v_rcp_f32_e32 v26, v26
	v_pk_add_f32 v[18:19], v[18:19], v[66:67]
	v_pk_add_f32 v[22:23], v[22:23], v[70:71]
	v_pk_add_f32 v[20:21], v[20:21], v[68:69]
	v_pk_add_f32 v[16:17], v[16:17], v[64:65]
	v_mul_f32_e32 v19, 0xbfb8aa3b, v19
	v_mul_f32_e32 v20, 0xbfb8aa3b, v20
	v_mul_f32_e32 v21, 0xbfb8aa3b, v21
	v_mul_f32_e32 v22, 0xbfb8aa3b, v22
	v_mul_f32_e32 v23, 0xbfb8aa3b, v23
	v_mul_f32_e32 v16, 0xbfb8aa3b, v16
	v_mul_f32_e32 v17, 0xbfb8aa3b, v17
	v_mul_f32_e32 v18, 0xbfb8aa3b, v18
	v_exp_f32_e32 v19, v19
	v_exp_f32_e32 v20, v20
	s_waitcnt vmcnt(0)
	v_lshlrev_b32_e32 v55, 16, v51
	v_and_b32_e32 v51, 0xffff0000, v51
	v_lshlrev_b32_e32 v52, 16, v48
	v_and_b32_e32 v48, 0xffff0000, v48
	v_lshlrev_b32_e32 v53, 16, v49
	v_and_b32_e32 v49, 0xffff0000, v49
	v_lshlrev_b32_e32 v54, 16, v50
	v_and_b32_e32 v50, 0xffff0000, v50
	v_mul_f32_e32 v43, v43, v51
	v_mul_f32_e32 v44, v44, v52
	v_mul_f32_e32 v45, v45, v48
	v_mul_f32_e32 v46, v46, v53
	v_mul_f32_e32 v47, v47, v49
	v_mul_f32_e32 v48, v40, v54
	v_mul_f32_e32 v49, v41, v50
	v_mul_f32_e32 v50, v42, v55
	v_cvt_pk_bf16_f32 v40, v44, v45
	v_cvt_pk_bf16_f32 v41, v46, v47
	v_cvt_pk_bf16_f32 v42, v48, v49
	v_cvt_pk_bf16_f32 v43, v50, v43
	global_store_dwordx4 v[120:121], v[40:43], off offset:1280 nt
	global_load_dwordx4 v[40:43], v[122:123], off offset:256
	v_exp_f32_e32 v21, v21
	v_exp_f32_e32 v22, v22
	v_exp_f32_e32 v23, v23
	v_exp_f32_e32 v16, v16
	v_exp_f32_e32 v17, v17
	v_exp_f32_e32 v18, v18
	v_add_f32_e32 v19, 1.0, v19
	v_add_f32_e32 v20, 1.0, v20
	v_add_f32_e32 v21, 1.0, v21
	v_add_f32_e32 v22, 1.0, v22
	v_add_f32_e32 v23, 1.0, v23
	v_add_f32_e32 v16, 1.0, v16
	v_add_f32_e32 v17, 1.0, v17
	v_add_f32_e32 v18, 1.0, v18
	v_rcp_f32_e32 v19, v19
	v_rcp_f32_e32 v20, v20
	v_rcp_f32_e32 v21, v21
	v_rcp_f32_e32 v22, v22
	v_rcp_f32_e32 v23, v23
	v_rcp_f32_e32 v16, v16
	v_rcp_f32_e32 v17, v17
	v_rcp_f32_e32 v18, v18
	v_pk_add_f32 v[10:11], v[10:11], v[66:67]
	v_pk_add_f32 v[14:15], v[14:15], v[70:71]
	v_pk_add_f32 v[12:13], v[12:13], v[68:69]
	v_pk_add_f32 v[8:9], v[8:9], v[64:65]
	v_mul_f32_e32 v11, 0xbfb8aa3b, v11
	v_mul_f32_e32 v12, 0xbfb8aa3b, v12
	v_mul_f32_e32 v13, 0xbfb8aa3b, v13
	v_mul_f32_e32 v14, 0xbfb8aa3b, v14
	v_mul_f32_e32 v15, 0xbfb8aa3b, v15
	v_mul_f32_e32 v8, 0xbfb8aa3b, v8
	v_mul_f32_e32 v9, 0xbfb8aa3b, v9
	v_mul_f32_e32 v10, 0xbfb8aa3b, v10
	v_exp_f32_e32 v11, v11
	v_exp_f32_e32 v12, v12
	v_exp_f32_e32 v13, v13
	v_exp_f32_e32 v14, v14
	v_exp_f32_e32 v15, v15
	v_exp_f32_e32 v8, v8
	v_exp_f32_e32 v9, v9
	v_exp_f32_e32 v10, v10
	v_add_f32_e32 v11, 1.0, v11
	v_add_f32_e32 v12, 1.0, v12
	v_add_f32_e32 v13, 1.0, v13
	v_add_f32_e32 v14, 1.0, v14
	v_add_f32_e32 v15, 1.0, v15
	v_add_f32_e32 v8, 1.0, v8
	v_add_f32_e32 v9, 1.0, v9
	v_add_f32_e32 v10, 1.0, v10
	v_rcp_f32_e32 v11, v11
	v_rcp_f32_e32 v12, v12
	v_rcp_f32_e32 v13, v13
	v_rcp_f32_e32 v14, v14
	v_rcp_f32_e32 v15, v15
	v_rcp_f32_e32 v8, v8
	v_rcp_f32_e32 v9, v9
	v_rcp_f32_e32 v10, v10
	v_pk_add_f32 v[2:3], v[2:3], v[66:67]
	v_pk_add_f32 v[6:7], v[6:7], v[70:71]
	v_pk_add_f32 v[4:5], v[4:5], v[68:69]
	v_pk_add_f32 v[0:1], v[0:1], v[64:65]
	v_mul_f32_e32 v3, 0xbfb8aa3b, v3
	v_mul_f32_e32 v4, 0xbfb8aa3b, v4
	v_mul_f32_e32 v5, 0xbfb8aa3b, v5
	v_mul_f32_e32 v6, 0xbfb8aa3b, v6
	v_mul_f32_e32 v7, 0xbfb8aa3b, v7
	v_mul_f32_e32 v0, 0xbfb8aa3b, v0
	v_mul_f32_e32 v1, 0xbfb8aa3b, v1
	v_mul_f32_e32 v2, 0xbfb8aa3b, v2
	v_exp_f32_e32 v3, v3
	v_exp_f32_e32 v4, v4
	v_exp_f32_e32 v5, v5
	v_exp_f32_e32 v6, v6
	v_exp_f32_e32 v7, v7
	v_exp_f32_e32 v0, v0
	v_exp_f32_e32 v1, v1
	v_exp_f32_e32 v2, v2
	v_add_f32_e32 v3, 1.0, v3
	s_waitcnt vmcnt(0)
; __device__ __forceinline__ unsigned cvt_pk_bf16(float lo, float hi) { unsigned r; asm volatile("v_cvt_pk_bf16_f32 %0, %1, %2" : "=v"(r) : "v"(lo), "v"(hi)); return r; }
; #define PG8_BAR __builtin_amdgcn_s_barrier()
; __device__ __forceinline__ float fast_sigmoid(float x) { return __builtin_amdgcn_rcpf(1.f + __builtin_amdgcn_exp2f(-x * LOG2E)); }
; template <class Epi, class Sched, bool ALIGN_EPI = false, bool SP2 = false>
; __device__ __forceinline__ void gemm_phase(PG8_LAS unsigned char* lds, const Gemm g, const Sched& S, const Epi& E) {
;     ...
;         if constexpr (ALIGN_EPI) { if (wr == 0) PG8_BAR; }
;         if constexpr (!Epi::AFTER_DRAIN) { E(acc, cur, wr, wc, fr, fq); S.done(cur); }
;         if (!has_next) break;
; #pragma unroll
;         for (int a = 0; a < 2; ++a)
; #pragma unroll
;             for (int b = 0; b < 2; ++b)
; #pragma unroll
;                 for (int m = 0; m < 4; ++m)
; #pragma unroll
;                     for (int n = 0; n < 2; ++n) acc[a][b][m][n] = (f32x4){0.f, 0.f, 0.f, 0.f};
;         cur = nxt; cA = nA; cB = nB; ++ui;
;         if constexpr (ALIGN_EPI) { if (wr == 1) PG8_BAR; }
;     __device__ __forceinline__ void operator()(const f32x4 (&acc)[2][2][4][2], const pg8::Unit& u, int wr, int wc, int fr, int fq) const {
;     ...
; #pragma unroll
;         for (int bj = 0; bj < 2; ++bj) { const int c = col0 + bj * 128; const f32x4 b0 = *(const f32x4*)(bias + c), b1 = *(const f32x4*)(bias + c + 4);
; #pragma unroll
;             for (int ai = 0; ai < 2; ++ai)
; #pragma unroll
;                 for (int m = 0; m < 4; ++m) { const size_t r = (size_t)(row0 + ai * 128 + m * 16);
;                     const u32x4 y = *(const u32x4*)(YB + r * SSMW + c); const f32x4 v0 = acc[ai][bj][m][0] + b0, v1 = acc[ai][bj][m][1] + b1;
;                     u32x4 w; w.x = cvt_pk_bf16(bf_lo(y.x) * fast_sigmoid(v0[0]), bf_hi(y.x) * fast_sigmoid(v0[1])); w.y = cvt_pk_bf16(bf_lo(y.y) * fast_sigmoid(v0[2]), bf_hi(y.y) * fast_sigmoid(v0[3]));
;                     w.z = cvt_pk_bf16(bf_lo(y.z) * fast_sigmoid(v1[0]), bf_hi(y.z) * fast_sigmoid(v1[1])); w.w = cvt_pk_bf16(bf_lo(y.w) * fast_sigmoid(v1[2]), bf_hi(y.w) * fast_sigmoid(v1[3]));
;                     *(u32x4*)(CAT + r * D + 512 + c) = w; } }
	v_lshlrev_b32_e32 v47, 16, v43
	v_and_b32_e32 v43, 0xffff0000, v43
	v_lshlrev_b32_e32 v44, 16, v40
	v_and_b32_e32 v40, 0xffff0000, v40
	v_lshlrev_b32_e32 v45, 16, v41
	v_and_b32_e32 v41, 0xffff0000, v41
	v_lshlrev_b32_e32 v46, 16, v42
	v_and_b32_e32 v42, 0xffff0000, v42
	v_mul_f32_e32 v35, v35, v43
	v_mul_f32_e32 v36, v36, v44
	v_mul_f32_e32 v37, v37, v40
	v_mul_f32_e32 v38, v38, v45
	v_mul_f32_e32 v39, v39, v41
	v_mul_f32_e32 v40, v32, v46
	v_mul_f32_e32 v41, v33, v42
	v_mul_f32_e32 v42, v34, v47
	v_cvt_pk_bf16_f32 v32, v36, v37
	v_cvt_pk_bf16_f32 v33, v38, v39
	v_cvt_pk_bf16_f32 v34, v40, v41
	v_cvt_pk_bf16_f32 v35, v42, v35
	global_store_dwordx4 v[104:105], v[32:35], off offset:1280 nt
	global_load_dwordx4 v[32:35], v[106:107], off offset:256
	v_add_f32_e32 v4, 1.0, v4
	v_add_f32_e32 v5, 1.0, v5
	v_add_f32_e32 v6, 1.0, v6
	v_add_f32_e32 v7, 1.0, v7
	v_add_f32_e32 v0, 1.0, v0
	v_add_f32_e32 v1, 1.0, v1
	v_add_f32_e32 v2, 1.0, v2
	v_rcp_f32_e32 v3, v3
	v_rcp_f32_e32 v4, v4
	v_rcp_f32_e32 v5, v5
	v_rcp_f32_e32 v6, v6
	v_rcp_f32_e32 v7, v7
	v_rcp_f32_e32 v0, v0
	v_rcp_f32_e32 v1, v1
	v_rcp_f32_e32 v2, v2
	s_waitcnt vmcnt(0)
	v_lshlrev_b32_e32 v39, 16, v35
	v_and_b32_e32 v35, 0xffff0000, v35
	v_lshlrev_b32_e32 v36, 16, v32
	v_and_b32_e32 v32, 0xffff0000, v32
	v_lshlrev_b32_e32 v37, 16, v33
	v_and_b32_e32 v33, 0xffff0000, v33
	v_lshlrev_b32_e32 v38, 16, v34
	v_and_b32_e32 v34, 0xffff0000, v34
	v_mul_f32_e32 v27, v27, v35
	v_mul_f32_e32 v28, v28, v36
	v_mul_f32_e32 v29, v29, v32
	v_mul_f32_e32 v30, v30, v37
	v_mul_f32_e32 v31, v31, v33
	v_mul_f32_e32 v32, v24, v38
	v_mul_f32_e32 v33, v25, v34
	v_mul_f32_e32 v34, v26, v39
	v_cvt_pk_bf16_f32 v24, v28, v29
	v_cvt_pk_bf16_f32 v25, v30, v31
	v_cvt_pk_bf16_f32 v26, v32, v33
	v_cvt_pk_bf16_f32 v27, v34, v27
	global_store_dwordx4 v[96:97], v[24:27], off offset:1280 nt
	global_load_dwordx4 v[24:27], v[98:99], off offset:256
	s_waitcnt vmcnt(0)
	v_lshlrev_b32_e32 v31, 16, v27
	v_and_b32_e32 v27, 0xffff0000, v27
	v_lshlrev_b32_e32 v28, 16, v24
	v_and_b32_e32 v24, 0xffff0000, v24
	v_lshlrev_b32_e32 v29, 16, v25
	v_and_b32_e32 v25, 0xffff0000, v25
	v_lshlrev_b32_e32 v30, 16, v26
	v_and_b32_e32 v26, 0xffff0000, v26
	v_mul_f32_e32 v19, v19, v27
	v_mul_f32_e32 v20, v20, v28
	v_mul_f32_e32 v21, v21, v24
	v_mul_f32_e32 v22, v22, v29
	v_mul_f32_e32 v23, v23, v25
	v_mul_f32_e32 v24, v16, v30
	v_mul_f32_e32 v25, v17, v26
	v_mul_f32_e32 v26, v18, v31
	v_cvt_pk_bf16_f32 v16, v20, v21
	v_cvt_pk_bf16_f32 v17, v22, v23
	v_cvt_pk_bf16_f32 v18, v24, v25
	v_cvt_pk_bf16_f32 v19, v26, v19
	global_store_dwordx4 v[88:89], v[16:19], off offset:1280 nt
	global_load_dwordx4 v[16:19], v[90:91], off offset:256
	s_waitcnt vmcnt(0)
	v_lshlrev_b32_e32 v23, 16, v19
	v_and_b32_e32 v19, 0xffff0000, v19
	v_lshlrev_b32_e32 v20, 16, v16
	v_and_b32_e32 v16, 0xffff0000, v16
	v_lshlrev_b32_e32 v21, 16, v17
	v_and_b32_e32 v17, 0xffff0000, v17
	v_lshlrev_b32_e32 v22, 16, v18
	v_and_b32_e32 v18, 0xffff0000, v18
	v_mul_f32_e32 v11, v11, v19
	v_mul_f32_e32 v12, v12, v20
	v_mul_f32_e32 v13, v13, v16
	v_mul_f32_e32 v14, v14, v21
	v_mul_f32_e32 v15, v15, v17
	v_mul_f32_e32 v16, v8, v22
	v_mul_f32_e32 v17, v9, v18
	v_mul_f32_e32 v18, v10, v23
	v_cvt_pk_bf16_f32 v8, v12, v13
	v_cvt_pk_bf16_f32 v9, v14, v15
	v_cvt_pk_bf16_f32 v10, v16, v17
	v_cvt_pk_bf16_f32 v11, v18, v11
	global_store_dwordx4 v[80:81], v[8:11], off offset:1280 nt
	global_load_dwordx4 v[8:11], v[82:83], off offset:256
	s_waitcnt vmcnt(0)
	v_lshlrev_b32_e32 v15, 16, v11
	v_and_b32_e32 v11, 0xffff0000, v11
	v_lshlrev_b32_e32 v12, 16, v8
	v_and_b32_e32 v8, 0xffff0000, v8
	v_lshlrev_b32_e32 v13, 16, v9
	v_and_b32_e32 v9, 0xffff0000, v9
	v_lshlrev_b32_e32 v14, 16, v10
	v_and_b32_e32 v10, 0xffff0000, v10
	v_mul_f32_e32 v3, v3, v11
	v_mul_f32_e32 v4, v4, v12
	v_mul_f32_e32 v5, v5, v8
	v_mul_f32_e32 v6, v6, v13
	v_mul_f32_e32 v7, v7, v9
	v_mul_f32_e32 v8, v0, v14
	v_mul_f32_e32 v9, v1, v10
	v_mul_f32_e32 v10, v2, v15
	v_cvt_pk_bf16_f32 v0, v4, v5
	v_cvt_pk_bf16_f32 v1, v6, v7
	v_cvt_pk_bf16_f32 v2, v8, v9
	v_cvt_pk_bf16_f32 v3, v10, v3
	global_store_dwordx4 v[72:73], v[0:3], off offset:1280 nt
	s_cbranch_vccnz .LBB0_616
	s_andn2_b64 vcc, exec, s[8:9]
	s_cbranch_vccnz .LBB0_615
	s_barrier
	s_branch .LBB0_615

; __device__ __forceinline__ unsigned cvt_pk_bf16(float lo, float hi) { unsigned r; asm volatile("v_cvt_pk_bf16_f32 %0, %1, %2" : "=v"(r) : "v"(lo), "v"(hi)); return r; }
;     __device__ __forceinline__ void operator()(const f32x4 (&acc)[2][2][4][2], const pg8::Unit& u, int wr, int wc, int fr, int fq) const {
;         const int row0 = u.pm * 256 + wr * 64 + fr, col0 = u.pn * 256 + wc * 32 + 8 * fq;
;         u32x4 xin[2][4][2];
; #pragma unroll
;         for (int ai = 0; ai < 2; ++ai)
; #pragma unroll
;             for (int m = 0; m < 4; ++m)
; #pragma unroll
;                 for (int bj = 0; bj < 2; ++bj) xin[ai][m][bj] = *(const u32x4*)(XB + (size_t)(row0 + ai * 128 + m * 16) * D + col0 + bj * 128);
; #pragma unroll
;         for (int ai = 0; ai < 2; ++ai)
; #pragma unroll
;             for (int m = 0; m < 4; ++m) { const size_t ro = (size_t)(row0 + ai * 128 + m * 16) * D + col0; float sq = 0.f;
; #pragma unroll
;                 for (int bj = 0; bj < 2; ++bj) { const u32x4 xb = xin[ai][m][bj];
;                     const f32x4 x0 = (f32x4){bf_lo(xb.x), bf_hi(xb.x), bf_lo(xb.y), bf_hi(xb.y)} + acc[ai][bj][m][0] * s, x1 = (f32x4){bf_lo(xb.z), bf_hi(xb.z), bf_lo(xb.w), bf_hi(xb.w)} + acc[ai][bj][m][1] * s;
;                     sq += (x0[0] * x0[0] + x0[1] * x0[1]) + (x0[2] * x0[2] + x0[3] * x0[3]) + (x1[0] * x1[0] + x1[1] * x1[1]) + (x1[2] * x1[2] + x1[3] * x1[3]);
;                     u32x4 w; w.x = cvt_pk_bf16(x0[0], x0[1]); w.y = cvt_pk_bf16(x0[2], x0[3]); w.z = cvt_pk_bf16(x1[0], x1[1]); w.w = cvt_pk_bf16(x1[2], x1[3]);
;                     *(u32x4*)(XB + ro + bj * 128) = w; }
;                 sq += __shfl_xor(sq, 16); sq += __shfl_xor(sq, 32);
;                 if (fq == 0) SSo[(size_t)(u.pn * 4 + wc) * T + row0 + ai * 128 + m * 16] = sq; }
.LBB0_708:
	v_lshl_or_b32 v204, s34, 8, v222
	v_lshl_add_u32 v202, s52, 8, v220
	v_ashrrev_i32_e32 v205, 31, v204
	v_lshlrev_b64 v[236:237], 1, v[204:205]
	v_ashrrev_i32_e32 v203, 31, v202
	v_lshl_add_u64 v[96:97], s[36:37], 0, v[236:237]
	v_lshlrev_b64 v[238:239], 11, v[202:203]
	v_lshl_add_u64 v[98:99], v[96:97], 0, v[238:239]
	global_load_dwordx4 v[228:231], v[98:99], off
	global_load_dwordx4 v[232:235], v[98:99], off offset:256
	v_or_b32_e32 v98, 16, v202
	v_or_b32_e32 v108, 32, v202
	v_or_b32_e32 v110, 48, v202
	v_ashrrev_i32_e32 v99, 31, v98
	v_ashrrev_i32_e32 v109, 31, v108
	v_ashrrev_i32_e32 v111, 31, v110
	v_lshlrev_b64 v[218:219], 11, v[98:99]
	v_lshlrev_b64 v[216:217], 11, v[108:109]
	v_lshlrev_b64 v[214:215], 11, v[110:111]
	v_lshl_add_u64 v[212:213], v[238:239], 0, s[8:9]
	v_lshl_add_u64 v[210:211], v[238:239], 0, s[16:17]
	v_lshl_add_u64 v[208:209], v[238:239], 0, s[18:19]
	v_lshl_add_u64 v[206:207], v[238:239], 0, s[38:39]
	v_lshl_add_u64 v[98:99], v[96:97], 0, v[218:219]
	v_lshl_add_u64 v[108:109], v[96:97], 0, v[216:217]
	v_lshl_add_u64 v[110:111], v[96:97], 0, v[214:215]
	v_lshl_add_u64 v[120:121], v[96:97], 0, v[212:213]
	v_lshl_add_u64 v[122:123], v[96:97], 0, v[210:211]
	v_lshl_add_u64 v[240:241], v[96:97], 0, v[208:209]
	v_lshl_add_u64 v[96:97], v[96:97], 0, v[206:207]
	global_load_dwordx4 v[180:183], v[98:99], off
	global_load_dwordx4 v[176:179], v[98:99], off offset:256
	global_load_dwordx4 v[172:175], v[108:109], off
	global_load_dwordx4 v[168:171], v[108:109], off offset:256
	global_load_dwordx4 v[164:167], v[110:111], off
	global_load_dwordx4 v[160:163], v[110:111], off offset:256
	global_load_dwordx4 v[156:159], v[120:121], off
	global_load_dwordx4 v[152:155], v[120:121], off offset:256
	global_load_dwordx4 v[148:151], v[122:123], off
	global_load_dwordx4 v[144:147], v[122:123], off offset:256
	global_load_dwordx4 v[128:131], v[240:241], off
	s_nop 0
	global_load_dwordx4 v[120:123], v[240:241], off offset:256
	global_load_dwordx4 v[108:111], v[96:97], off
	s_nop 0
	global_load_dwordx4 v[96:99], v[96:97], off offset:256
	s_lshl_b32 s20, s34, 2
	s_or_b32 s20, s20, s65
	s_ashr_i32 s21, s20, 31
	s_lshl_b64 s[20:21], s[20:21], 17
	s_waitcnt vmcnt(0)
	v_lshlrev_b32_e32 v240, 16, v228
	v_and_b32_e32 v241, 0xffff0000, v228
	v_lshlrev_b32_e32 v228, 16, v229
	v_and_b32_e32 v229, 0xffff0000, v229
	v_lshlrev_b32_e32 v242, 16, v230
	v_and_b32_e32 v243, 0xffff0000, v230
	v_lshlrev_b32_e32 v244, 16, v232
	v_and_b32_e32 v245, 0xffff0000, v232
	v_lshlrev_b32_e32 v232, 16, v233
	v_and_b32_e32 v233, 0xffff0000, v233
	v_lshlrev_b32_e32 v246, 16, v234
	v_and_b32_e32 v247, 0xffff0000, v234
	v_lshlrev_b32_e32 v234, 16, v235
	v_and_b32_e32 v235, 0xffff0000, v235
	v_pk_add_f32 v[142:143], v[142:143], v[228:229]
	v_pk_add_f32 v[140:141], v[140:141], v[240:241]
	v_lshlrev_b32_e32 v230, 16, v231
	v_and_b32_e32 v231, 0xffff0000, v231
	v_pk_add_f32 v[136:137], v[136:137], v[242:243]
	v_pk_add_f32 v[228:229], v[134:135], v[232:233]
	v_pk_add_f32 v[232:233], v[126:127], v[234:235]
	v_pk_add_f32 v[234:235], v[124:125], v[246:247]
	v_mul_f32_e32 v124, v141, v141
	v_mul_f32_e32 v125, v143, v143
	v_pk_add_f32 v[138:139], v[138:139], v[230:231]
	v_pk_add_f32 v[230:231], v[132:133], v[244:245]
	v_mul_f32_e32 v126, v137, v137
	v_fmac_f32_e32 v124, v140, v140
	v_fmac_f32_e32 v125, v142, v142
	v_mul_f32_e32 v127, v139, v139
	v_cvt_pk_bf16_f32 v132, v140, v141
	v_cvt_pk_bf16_f32 v133, v142, v143
	v_cvt_pk_bf16_f32 v134, v136, v137
	v_cvt_pk_bf16_f32 v135, v138, v139
	v_mul_f32_e32 v137, v231, v231
	v_mul_f32_e32 v139, v229, v229
	v_fmac_f32_e32 v126, v136, v136
	v_add_f32_e32 v124, v124, v125
	v_fmac_f32_e32 v137, v230, v230
	v_fmac_f32_e32 v139, v228, v228
	v_add_f32_e32 v124, v126, v124
	v_mul_f32_e32 v126, v235, v235
	v_add_f32_e32 v125, v137, v139
	v_fmac_f32_e32 v126, v234, v234
	v_add_f32_e32 v125, v126, v125
	v_mul_f32_e32 v126, v233, v233
	v_fmac_f32_e32 v127, v138, v138
	v_fmac_f32_e32 v126, v232, v232
	v_add_f32_e32 v124, v127, v124
	v_add_f32_e32 v125, v126, v125
	v_and_b32_e32 v126, 64, v226
	v_add_f32_e32 v125, v124, v125
	v_add_u32_e32 v138, 64, v126
	v_lshl_add_u64 v[126:127], s[36:37], 0, v[238:239]
	v_lshl_add_u64 v[136:137], v[126:127], 0, v[236:237]
	v_mov_b32_e32 v139, v125
	s_nop 1
	v_permlane16_swap_b32_e32 v139, v125
	global_store_dwordx4 v[136:137], v[132:135], off nt
	s_waitcnt lgkmcnt(0)
	v_add_f32_e32 v126, v125, v139
	v_cvt_pk_bf16_f32 v132, v230, v231
	v_cvt_pk_bf16_f32 v133, v228, v229
	v_cvt_pk_bf16_f32 v134, v234, v235
	v_cvt_pk_bf16_f32 v135, v232, v233
	global_store_dwordx4 v[136:137], v[132:135], off offset:256 nt
	s_nop 0
	v_mov_b32_e32 v127, v126
	s_nop 1
	v_permlane32_swap_b32_e32 v127, v126
	s_and_saveexec_b64 s[34:35], s[4:5]
	s_cbranch_execz .LBB0_710
	s_add_u32 s54, s63, s20
	s_addc_u32 s55, s64, s21
	v_lshl_add_u64 v[132:133], v[202:203], 2, s[54:55]
	s_waitcnt lgkmcnt(0)
	v_add_f32_e32 v126, v126, v127
	global_store_dword v[132:133], v126, off
; __device__ __forceinline__ unsigned cvt_pk_bf16(float lo, float hi) { unsigned r; asm volatile("v_cvt_pk_bf16_f32 %0, %1, %2" : "=v"(r) : "v"(lo), "v"(hi)); return r; }
;     __device__ __forceinline__ void operator()(const f32x4 (&acc)[2][2][4][2], const pg8::Unit& u, int wr, int wc, int fr, int fq) const {
;     ...
;             for (int m = 0; m < 4; ++m) { const size_t ro = (size_t)(row0 + ai * 128 + m * 16) * D + col0; float sq = 0.f;
; #pragma unroll
;                 for (int bj = 0; bj < 2; ++bj) { const u32x4 xb = xin[ai][m][bj];
;                     const f32x4 x0 = (f32x4){bf_lo(xb.x), bf_hi(xb.x), bf_lo(xb.y), bf_hi(xb.y)} + acc[ai][bj][m][0] * s, x1 = (f32x4){bf_lo(xb.z), bf_hi(xb.z), bf_lo(xb.w), bf_hi(xb.w)} + acc[ai][bj][m][1] * s;
;                     sq += (x0[0] * x0[0] + x0[1] * x0[1]) + (x0[2] * x0[2] + x0[3] * x0[3]) + (x1[0] * x1[0] + x1[1] * x1[1]) + (x1[2] * x1[2] + x1[3] * x1[3]);
;                     u32x4 w; w.x = cvt_pk_bf16(x0[0], x0[1]); w.y = cvt_pk_bf16(x0[2], x0[3]); w.z = cvt_pk_bf16(x1[0], x1[1]); w.w = cvt_pk_bf16(x1[2], x1[3]);
;                     *(u32x4*)(XB + ro + bj * 128) = w; }
;                 sq += __shfl_xor(sq, 16); sq += __shfl_xor(sq, 32);
;                 if (fq == 0) SSo[(size_t)(u.pn * 4 + wc) * T + row0 + ai * 128 + m * 16] = sq; }
.LBB0_710:
	s_or_b64 exec, exec, s[34:35]
	v_lshlrev_b32_e32 v126, 16, v180
	s_waitcnt lgkmcnt(0)
	v_and_b32_e32 v127, 0xffff0000, v180
	v_lshlrev_b32_e32 v132, 16, v181
	v_and_b32_e32 v133, 0xffff0000, v181
	v_pk_add_f32 v[118:119], v[118:119], v[132:133]
	v_pk_add_f32 v[116:117], v[116:117], v[126:127]
	v_lshlrev_b32_e32 v126, 16, v182
	v_and_b32_e32 v127, 0xffff0000, v182
	v_lshlrev_b32_e32 v132, 16, v183
	v_and_b32_e32 v133, 0xffff0000, v183
	v_pk_add_f32 v[132:133], v[114:115], v[132:133]
	v_pk_add_f32 v[114:115], v[112:113], v[126:127]
	v_mul_f32_e32 v112, v117, v117
	v_mul_f32_e32 v113, v119, v119
	v_fmac_f32_e32 v112, v116, v116
	v_fmac_f32_e32 v113, v118, v118
	v_add_f32_e32 v112, v112, v113
	v_mul_f32_e32 v113, v115, v115
	v_fmac_f32_e32 v113, v114, v114
	v_add_f32_e32 v112, v113, v112
	v_mul_f32_e32 v113, v133, v133
	v_fmac_f32_e32 v113, v132, v132
	v_add_f32_e32 v126, v113, v112
	v_cvt_pk_bf16_f32 v112, v116, v117
	v_cvt_pk_bf16_f32 v113, v118, v119
	v_lshlrev_b32_e32 v116, 16, v176
	v_and_b32_e32 v117, 0xffff0000, v176
	v_lshlrev_b32_e32 v118, 16, v177
	v_and_b32_e32 v119, 0xffff0000, v177
	v_pk_add_f32 v[106:107], v[106:107], v[118:119]
	v_pk_add_f32 v[104:105], v[104:105], v[116:117]
	v_lshlrev_b32_e32 v116, 16, v178
	v_and_b32_e32 v117, 0xffff0000, v178
	v_pk_add_f32 v[116:117], v[100:101], v[116:117]
	v_mul_f32_e32 v100, v105, v105
	v_mul_f32_e32 v101, v107, v107
	v_fmac_f32_e32 v100, v104, v104
	v_fmac_f32_e32 v101, v106, v106
	v_lshlrev_b32_e32 v118, 16, v179
	v_and_b32_e32 v119, 0xffff0000, v179
	v_add_f32_e32 v100, v100, v101
	v_mul_f32_e32 v101, v117, v117
	v_pk_add_f32 v[118:119], v[102:103], v[118:119]
	v_fmac_f32_e32 v101, v116, v116
	v_add_f32_e32 v100, v101, v100
	v_mul_f32_e32 v101, v119, v119
	v_fmac_f32_e32 v101, v118, v118
	v_add_f32_e32 v100, v101, v100
	v_add_f32_e32 v103, v126, v100
	v_cvt_pk_bf16_f32 v114, v114, v115
	v_cvt_pk_bf16_f32 v115, v132, v133
	v_mov_b32_e32 v132, v103
	s_nop 1
	v_permlane16_swap_b32_e32 v132, v103
	v_lshl_add_u64 v[100:101], s[36:37], 0, v[218:219]
	v_lshl_add_u64 v[126:127], v[204:205], 1, v[100:101]
	global_store_dwordx4 v[126:127], v[112:115], off nt
	v_cvt_pk_bf16_f32 v102, v104, v105
	s_waitcnt lgkmcnt(0)
	v_add_f32_e32 v100, v103, v132
	v_mov_b32_e32 v101, v100
	s_nop 1
	v_permlane32_swap_b32_e32 v101, v100
	v_cvt_pk_bf16_f32 v103, v106, v107
	v_cvt_pk_bf16_f32 v104, v116, v117
	v_cvt_pk_bf16_f32 v105, v118, v119
	global_store_dwordx4 v[126:127], v[102:105], off offset:256 nt
	s_and_saveexec_b64 s[34:35], s[4:5]
	s_cbranch_execz .LBB0_712
	s_add_u32 s54, s63, s20
	s_addc_u32 s55, s64, s21
	v_lshl_add_u64 v[102:103], v[202:203], 2, s[54:55]
	s_waitcnt lgkmcnt(0)
	v_add_f32_e32 v100, v100, v101
	global_store_dword v[102:103], v100, off offset:64
.LBB0_712:
	s_or_b64 exec, exec, s[34:35]
	v_lshlrev_b32_e32 v100, 16, v172
	s_waitcnt lgkmcnt(0)
	v_and_b32_e32 v101, 0xffff0000, v172
	v_lshlrev_b32_e32 v102, 16, v173
	v_and_b32_e32 v103, 0xffff0000, v173
	v_pk_add_f32 v[94:95], v[94:95], v[102:103]
	v_pk_add_f32 v[92:93], v[92:93], v[100:101]
	v_lshlrev_b32_e32 v100, 16, v174
	v_and_b32_e32 v101, 0xffff0000, v174
	v_lshlrev_b32_e32 v102, 16, v175
	v_and_b32_e32 v103, 0xffff0000, v175
	v_pk_add_f32 v[102:103], v[90:91], v[102:103]
	v_pk_add_f32 v[90:91], v[88:89], v[100:101]
	v_mul_f32_e32 v88, v93, v93
	v_mul_f32_e32 v89, v95, v95
	v_fmac_f32_e32 v88, v92, v92
	v_fmac_f32_e32 v89, v94, v94
	v_add_f32_e32 v88, v88, v89
	v_mul_f32_e32 v89, v91, v91
	v_fmac_f32_e32 v89, v90, v90
	v_add_f32_e32 v88, v89, v88
	v_mul_f32_e32 v89, v103, v103
	v_fmac_f32_e32 v89, v102, v102
	v_add_f32_e32 v100, v89, v88
	v_cvt_pk_bf16_f32 v88, v92, v93
	v_cvt_pk_bf16_f32 v89, v94, v95
	v_lshlrev_b32_e32 v92, 16, v168
	v_and_b32_e32 v93, 0xffff0000, v168
	v_lshlrev_b32_e32 v94, 16, v169
	v_and_b32_e32 v95, 0xffff0000, v169
	v_pk_add_f32 v[86:87], v[86:87], v[94:95]
	v_pk_add_f32 v[84:85], v[84:85], v[92:93]
	v_lshlrev_b32_e32 v92, 16, v170
	v_and_b32_e32 v93, 0xffff0000, v170
	v_pk_add_f32 v[92:93], v[80:81], v[92:93]
	v_mul_f32_e32 v80, v85, v85
	v_mul_f32_e32 v81, v87, v87
	v_fmac_f32_e32 v80, v84, v84
	v_fmac_f32_e32 v81, v86, v86
	v_lshlrev_b32_e32 v94, 16, v171
	v_and_b32_e32 v95, 0xffff0000, v171
	v_add_f32_e32 v80, v80, v81
	v_mul_f32_e32 v81, v93, v93
	v_pk_add_f32 v[94:95], v[82:83], v[94:95]
	v_fmac_f32_e32 v81, v92, v92
	v_add_f32_e32 v80, v81, v80
	v_mul_f32_e32 v81, v95, v95
	v_fmac_f32_e32 v81, v94, v94
	v_add_f32_e32 v80, v81, v80
	v_add_f32_e32 v83, v100, v80
	v_cvt_pk_bf16_f32 v90, v90, v91
	v_cvt_pk_bf16_f32 v91, v102, v103
	v_mov_b32_e32 v102, v83
	s_nop 1
	v_permlane16_swap_b32_e32 v102, v83
	v_lshl_add_u64 v[80:81], s[36:37], 0, v[216:217]
	v_lshl_add_u64 v[100:101], v[204:205], 1, v[80:81]
	global_store_dwordx4 v[100:101], v[88:91], off nt
	v_cvt_pk_bf16_f32 v82, v84, v85
	s_waitcnt lgkmcnt(0)
	v_add_f32_e32 v80, v83, v102
	v_mov_b32_e32 v81, v80
	s_nop 1
	v_permlane32_swap_b32_e32 v81, v80
	v_cvt_pk_bf16_f32 v83, v86, v87
	v_cvt_pk_bf16_f32 v84, v92, v93
	v_cvt_pk_bf16_f32 v85, v94, v95
	global_store_dwordx4 v[100:101], v[82:85], off offset:256 nt
	s_and_saveexec_b64 s[34:35], s[4:5]
	s_cbranch_execz .LBB0_714
	s_add_u32 s54, s63, s20
	s_addc_u32 s55, s64, s21
	v_lshl_add_u64 v[82:83], v[202:203], 2, s[54:55]
	s_waitcnt lgkmcnt(0)
	v_add_f32_e32 v80, v80, v81
	global_store_dword v[82:83], v80, off offset:128
; __device__ __forceinline__ unsigned cvt_pk_bf16(float lo, float hi) { unsigned r; asm volatile("v_cvt_pk_bf16_f32 %0, %1, %2" : "=v"(r) : "v"(lo), "v"(hi)); return r; }
;     __device__ __forceinline__ void operator()(const f32x4 (&acc)[2][2][4][2], const pg8::Unit& u, int wr, int wc, int fr, int fq) const {
;     ...
;             for (int m = 0; m < 4; ++m) { const size_t ro = (size_t)(row0 + ai * 128 + m * 16) * D + col0; float sq = 0.f;
; #pragma unroll
;                 for (int bj = 0; bj < 2; ++bj) { const u32x4 xb = xin[ai][m][bj];
;                     const f32x4 x0 = (f32x4){bf_lo(xb.x), bf_hi(xb.x), bf_lo(xb.y), bf_hi(xb.y)} + acc[ai][bj][m][0] * s, x1 = (f32x4){bf_lo(xb.z), bf_hi(xb.z), bf_lo(xb.w), bf_hi(xb.w)} + acc[ai][bj][m][1] * s;
;                     sq += (x0[0] * x0[0] + x0[1] * x0[1]) + (x0[2] * x0[2] + x0[3] * x0[3]) + (x1[0] * x1[0] + x1[1] * x1[1]) + (x1[2] * x1[2] + x1[3] * x1[3]);
;                     u32x4 w; w.x = cvt_pk_bf16(x0[0], x0[1]); w.y = cvt_pk_bf16(x0[2], x0[3]); w.z = cvt_pk_bf16(x1[0], x1[1]); w.w = cvt_pk_bf16(x1[2], x1[3]);
;                     *(u32x4*)(XB + ro + bj * 128) = w; }
;                 sq += __shfl_xor(sq, 16); sq += __shfl_xor(sq, 32);
;                 if (fq == 0) SSo[(size_t)(u.pn * 4 + wc) * T + row0 + ai * 128 + m * 16] = sq; }
.LBB0_714:
	s_or_b64 exec, exec, s[34:35]
	v_lshlrev_b32_e32 v80, 16, v164
	s_waitcnt lgkmcnt(0)
	v_and_b32_e32 v81, 0xffff0000, v164
	v_lshlrev_b32_e32 v82, 16, v165
	v_and_b32_e32 v83, 0xffff0000, v165
	v_pk_add_f32 v[78:79], v[78:79], v[82:83]
	v_pk_add_f32 v[76:77], v[76:77], v[80:81]
	v_lshlrev_b32_e32 v80, 16, v166
	v_and_b32_e32 v81, 0xffff0000, v166
	v_lshlrev_b32_e32 v82, 16, v167
	v_and_b32_e32 v83, 0xffff0000, v167
	v_pk_add_f32 v[82:83], v[74:75], v[82:83]
	v_pk_add_f32 v[74:75], v[72:73], v[80:81]
	v_mul_f32_e32 v72, v77, v77
	v_mul_f32_e32 v73, v79, v79
	v_fmac_f32_e32 v72, v76, v76
	v_fmac_f32_e32 v73, v78, v78
	v_add_f32_e32 v72, v72, v73
	v_mul_f32_e32 v73, v75, v75
	v_fmac_f32_e32 v73, v74, v74
	v_add_f32_e32 v72, v73, v72
	v_mul_f32_e32 v73, v83, v83
	v_fmac_f32_e32 v73, v82, v82
	v_add_f32_e32 v80, v73, v72
	v_cvt_pk_bf16_f32 v72, v76, v77
	v_cvt_pk_bf16_f32 v73, v78, v79
	v_lshlrev_b32_e32 v76, 16, v160
	v_and_b32_e32 v77, 0xffff0000, v160
	v_lshlrev_b32_e32 v78, 16, v161
	v_and_b32_e32 v79, 0xffff0000, v161
	v_pk_add_f32 v[70:71], v[70:71], v[78:79]
	v_pk_add_f32 v[68:69], v[68:69], v[76:77]
	v_lshlrev_b32_e32 v76, 16, v162
	v_and_b32_e32 v77, 0xffff0000, v162
	v_pk_add_f32 v[76:77], v[64:65], v[76:77]
	v_mul_f32_e32 v64, v69, v69
	v_mul_f32_e32 v65, v71, v71
	v_fmac_f32_e32 v64, v68, v68
	v_fmac_f32_e32 v65, v70, v70
	v_lshlrev_b32_e32 v78, 16, v163
	v_and_b32_e32 v79, 0xffff0000, v163
	v_add_f32_e32 v64, v64, v65
	v_mul_f32_e32 v65, v77, v77
	v_pk_add_f32 v[78:79], v[66:67], v[78:79]
	v_fmac_f32_e32 v65, v76, v76
	v_add_f32_e32 v64, v65, v64
	v_mul_f32_e32 v65, v79, v79
	v_fmac_f32_e32 v65, v78, v78
	v_add_f32_e32 v64, v65, v64
	v_add_f32_e32 v67, v80, v64
	v_cvt_pk_bf16_f32 v74, v74, v75
	v_cvt_pk_bf16_f32 v75, v82, v83
	v_mov_b32_e32 v82, v67
	s_nop 1
	v_permlane16_swap_b32_e32 v82, v67
	v_lshl_add_u64 v[64:65], s[36:37], 0, v[214:215]
	v_lshl_add_u64 v[80:81], v[204:205], 1, v[64:65]
	global_store_dwordx4 v[80:81], v[72:75], off nt
	v_cvt_pk_bf16_f32 v66, v68, v69
	s_waitcnt lgkmcnt(0)
	v_add_f32_e32 v64, v67, v82
	v_mov_b32_e32 v65, v64
	s_nop 1
	v_permlane32_swap_b32_e32 v65, v64
	v_cvt_pk_bf16_f32 v67, v70, v71
	v_cvt_pk_bf16_f32 v68, v76, v77
	v_cvt_pk_bf16_f32 v69, v78, v79
	global_store_dwordx4 v[80:81], v[66:69], off offset:256 nt
	s_and_saveexec_b64 s[34:35], s[4:5]
	s_cbranch_execz .LBB0_716
	s_add_u32 s54, s63, s20
	s_addc_u32 s55, s64, s21
	v_lshl_add_u64 v[66:67], v[202:203], 2, s[54:55]
	s_waitcnt lgkmcnt(0)
	v_add_f32_e32 v64, v64, v65
	global_store_dword v[66:67], v64, off offset:192
.LBB0_716:
	s_or_b64 exec, exec, s[34:35]
	v_lshlrev_b32_e32 v64, 16, v156
	s_waitcnt lgkmcnt(0)
	v_and_b32_e32 v65, 0xffff0000, v156
	v_lshlrev_b32_e32 v66, 16, v157
	v_and_b32_e32 v67, 0xffff0000, v157
	v_pk_add_f32 v[62:63], v[62:63], v[66:67]
	v_pk_add_f32 v[60:61], v[60:61], v[64:65]
	v_lshlrev_b32_e32 v64, 16, v158
	v_and_b32_e32 v65, 0xffff0000, v158
	v_lshlrev_b32_e32 v66, 16, v159
	v_and_b32_e32 v67, 0xffff0000, v159
	v_pk_add_f32 v[66:67], v[58:59], v[66:67]
	v_pk_add_f32 v[58:59], v[56:57], v[64:65]
	v_mul_f32_e32 v56, v61, v61
	v_mul_f32_e32 v57, v63, v63
	v_fmac_f32_e32 v56, v60, v60
	v_fmac_f32_e32 v57, v62, v62
	v_add_f32_e32 v56, v56, v57
	v_mul_f32_e32 v57, v59, v59
	v_fmac_f32_e32 v57, v58, v58
	v_add_f32_e32 v56, v57, v56
	v_mul_f32_e32 v57, v67, v67
	v_fmac_f32_e32 v57, v66, v66
	v_add_f32_e32 v64, v57, v56
	v_cvt_pk_bf16_f32 v56, v60, v61
	v_cvt_pk_bf16_f32 v57, v62, v63
	v_lshlrev_b32_e32 v60, 16, v152
	v_and_b32_e32 v61, 0xffff0000, v152
	v_lshlrev_b32_e32 v62, 16, v153
	v_and_b32_e32 v63, 0xffff0000, v153
	v_pk_add_f32 v[54:55], v[54:55], v[62:63]
	v_pk_add_f32 v[52:53], v[52:53], v[60:61]
	v_lshlrev_b32_e32 v60, 16, v154
	v_and_b32_e32 v61, 0xffff0000, v154
	v_pk_add_f32 v[60:61], v[48:49], v[60:61]
	v_mul_f32_e32 v48, v53, v53
	v_mul_f32_e32 v49, v55, v55
	v_fmac_f32_e32 v48, v52, v52
	v_fmac_f32_e32 v49, v54, v54
	v_lshlrev_b32_e32 v62, 16, v155
	v_and_b32_e32 v63, 0xffff0000, v155
	v_add_f32_e32 v48, v48, v49
	v_mul_f32_e32 v49, v61, v61
	v_pk_add_f32 v[62:63], v[50:51], v[62:63]
	v_fmac_f32_e32 v49, v60, v60
	v_add_f32_e32 v48, v49, v48
	v_mul_f32_e32 v49, v63, v63
	v_fmac_f32_e32 v49, v62, v62
	v_add_f32_e32 v48, v49, v48
	v_add_f32_e32 v51, v64, v48
	v_cvt_pk_bf16_f32 v58, v58, v59
	v_cvt_pk_bf16_f32 v59, v66, v67
	v_mov_b32_e32 v66, v51
	s_nop 1
	v_permlane16_swap_b32_e32 v66, v51
	v_lshl_add_u64 v[48:49], s[36:37], 0, v[212:213]
	v_lshl_add_u64 v[64:65], v[204:205], 1, v[48:49]
	global_store_dwordx4 v[64:65], v[56:59], off nt
	v_cvt_pk_bf16_f32 v50, v52, v53
	s_waitcnt lgkmcnt(0)
	v_add_f32_e32 v48, v51, v66
	v_mov_b32_e32 v49, v48
	s_nop 1
	v_permlane32_swap_b32_e32 v49, v48
	v_cvt_pk_bf16_f32 v51, v54, v55
	v_cvt_pk_bf16_f32 v52, v60, v61
	v_cvt_pk_bf16_f32 v53, v62, v63
	global_store_dwordx4 v[64:65], v[50:53], off offset:256 nt
	s_and_saveexec_b64 s[34:35], s[4:5]
	s_cbranch_execz .LBB0_718
	s_add_u32 s54, s63, s20
	s_addc_u32 s55, s64, s21
	v_lshl_add_u64 v[50:51], v[202:203], 2, s[54:55]
	s_waitcnt lgkmcnt(0)
	v_add_f32_e32 v48, v48, v49
	global_store_dword v[50:51], v48, off offset:512
; __device__ __forceinline__ unsigned cvt_pk_bf16(float lo, float hi) { unsigned r; asm volatile("v_cvt_pk_bf16_f32 %0, %1, %2" : "=v"(r) : "v"(lo), "v"(hi)); return r; }
;     __device__ __forceinline__ void operator()(const f32x4 (&acc)[2][2][4][2], const pg8::Unit& u, int wr, int wc, int fr, int fq) const {
;     ...
;             for (int m = 0; m < 4; ++m) { const size_t ro = (size_t)(row0 + ai * 128 + m * 16) * D + col0; float sq = 0.f;
; #pragma unroll
;                 for (int bj = 0; bj < 2; ++bj) { const u32x4 xb = xin[ai][m][bj];
;                     const f32x4 x0 = (f32x4){bf_lo(xb.x), bf_hi(xb.x), bf_lo(xb.y), bf_hi(xb.y)} + acc[ai][bj][m][0] * s, x1 = (f32x4){bf_lo(xb.z), bf_hi(xb.z), bf_lo(xb.w), bf_hi(xb.w)} + acc[ai][bj][m][1] * s;
;                     sq += (x0[0] * x0[0] + x0[1] * x0[1]) + (x0[2] * x0[2] + x0[3] * x0[3]) + (x1[0] * x1[0] + x1[1] * x1[1]) + (x1[2] * x1[2] + x1[3] * x1[3]);
;                     u32x4 w; w.x = cvt_pk_bf16(x0[0], x0[1]); w.y = cvt_pk_bf16(x0[2], x0[3]); w.z = cvt_pk_bf16(x1[0], x1[1]); w.w = cvt_pk_bf16(x1[2], x1[3]);
;                     *(u32x4*)(XB + ro + bj * 128) = w; }
;                 sq += __shfl_xor(sq, 16); sq += __shfl_xor(sq, 32);
;                 if (fq == 0) SSo[(size_t)(u.pn * 4 + wc) * T + row0 + ai * 128 + m * 16] = sq; }
.LBB0_718:
	s_or_b64 exec, exec, s[34:35]
	v_lshlrev_b32_e32 v48, 16, v148
	s_waitcnt lgkmcnt(0)
	v_and_b32_e32 v49, 0xffff0000, v148
	v_lshlrev_b32_e32 v50, 16, v149
	v_and_b32_e32 v51, 0xffff0000, v149
	v_pk_add_f32 v[46:47], v[46:47], v[50:51]
	v_pk_add_f32 v[44:45], v[44:45], v[48:49]
	v_lshlrev_b32_e32 v48, 16, v150
	v_and_b32_e32 v49, 0xffff0000, v150
	v_lshlrev_b32_e32 v50, 16, v151
	v_and_b32_e32 v51, 0xffff0000, v151
	v_pk_add_f32 v[50:51], v[42:43], v[50:51]
	v_pk_add_f32 v[42:43], v[40:41], v[48:49]
	v_mul_f32_e32 v40, v45, v45
	v_mul_f32_e32 v41, v47, v47
	v_fmac_f32_e32 v40, v44, v44
	v_fmac_f32_e32 v41, v46, v46
	v_add_f32_e32 v40, v40, v41
	v_mul_f32_e32 v41, v43, v43
	v_fmac_f32_e32 v41, v42, v42
	v_add_f32_e32 v40, v41, v40
	v_mul_f32_e32 v41, v51, v51
	v_fmac_f32_e32 v41, v50, v50
	v_add_f32_e32 v48, v41, v40
	v_cvt_pk_bf16_f32 v40, v44, v45
	v_cvt_pk_bf16_f32 v41, v46, v47
	v_lshlrev_b32_e32 v44, 16, v144
	v_and_b32_e32 v45, 0xffff0000, v144
	v_lshlrev_b32_e32 v46, 16, v145
	v_and_b32_e32 v47, 0xffff0000, v145
	v_pk_add_f32 v[38:39], v[38:39], v[46:47]
	v_pk_add_f32 v[36:37], v[36:37], v[44:45]
	v_lshlrev_b32_e32 v44, 16, v146
	v_and_b32_e32 v45, 0xffff0000, v146
	v_pk_add_f32 v[44:45], v[32:33], v[44:45]
	v_mul_f32_e32 v32, v37, v37
	v_mul_f32_e32 v33, v39, v39
	v_fmac_f32_e32 v32, v36, v36
	v_fmac_f32_e32 v33, v38, v38
	v_lshlrev_b32_e32 v46, 16, v147
	v_and_b32_e32 v47, 0xffff0000, v147
	v_add_f32_e32 v32, v32, v33
	v_mul_f32_e32 v33, v45, v45
	v_pk_add_f32 v[46:47], v[34:35], v[46:47]
	v_fmac_f32_e32 v33, v44, v44
	v_add_f32_e32 v32, v33, v32
	v_mul_f32_e32 v33, v47, v47
	v_fmac_f32_e32 v33, v46, v46
	v_add_f32_e32 v32, v33, v32
	v_add_f32_e32 v35, v48, v32
	v_cvt_pk_bf16_f32 v42, v42, v43
	v_cvt_pk_bf16_f32 v43, v50, v51
	v_mov_b32_e32 v50, v35
	s_nop 1
	v_permlane16_swap_b32_e32 v50, v35
	v_lshl_add_u64 v[32:33], s[36:37], 0, v[210:211]
	v_lshl_add_u64 v[48:49], v[204:205], 1, v[32:33]
	global_store_dwordx4 v[48:49], v[40:43], off nt
	v_cvt_pk_bf16_f32 v34, v36, v37
	s_waitcnt lgkmcnt(0)
	v_add_f32_e32 v32, v35, v50
	v_mov_b32_e32 v33, v32
	s_nop 1
	v_permlane32_swap_b32_e32 v33, v32
	v_cvt_pk_bf16_f32 v35, v38, v39
	v_cvt_pk_bf16_f32 v36, v44, v45
	v_cvt_pk_bf16_f32 v37, v46, v47
	global_store_dwordx4 v[48:49], v[34:37], off offset:256 nt
	s_and_saveexec_b64 s[34:35], s[4:5]
	s_cbranch_execz .LBB0_720
	s_add_u32 s54, s63, s20
	s_addc_u32 s55, s64, s21
	v_lshl_add_u64 v[34:35], v[202:203], 2, s[54:55]
	s_waitcnt lgkmcnt(0)
	v_add_f32_e32 v32, v32, v33
	global_store_dword v[34:35], v32, off offset:576
; __device__ __forceinline__ unsigned cvt_pk_bf16(float lo, float hi) { unsigned r; asm volatile("v_cvt_pk_bf16_f32 %0, %1, %2" : "=v"(r) : "v"(lo), "v"(hi)); return r; }
;     __device__ __forceinline__ void operator()(const f32x4 (&acc)[2][2][4][2], const pg8::Unit& u, int wr, int wc, int fr, int fq) const {
;     ...
;             for (int m = 0; m < 4; ++m) { const size_t ro = (size_t)(row0 + ai * 128 + m * 16) * D + col0; float sq = 0.f;
; #pragma unroll
;                 for (int bj = 0; bj < 2; ++bj) { const u32x4 xb = xin[ai][m][bj];
;                     const f32x4 x0 = (f32x4){bf_lo(xb.x), bf_hi(xb.x), bf_lo(xb.y), bf_hi(xb.y)} + acc[ai][bj][m][0] * s, x1 = (f32x4){bf_lo(xb.z), bf_hi(xb.z), bf_lo(xb.w), bf_hi(xb.w)} + acc[ai][bj][m][1] * s;
;                     sq += (x0[0] * x0[0] + x0[1] * x0[1]) + (x0[2] * x0[2] + x0[3] * x0[3]) + (x1[0] * x1[0] + x1[1] * x1[1]) + (x1[2] * x1[2] + x1[3] * x1[3]);
;                     u32x4 w; w.x = cvt_pk_bf16(x0[0], x0[1]); w.y = cvt_pk_bf16(x0[2], x0[3]); w.z = cvt_pk_bf16(x1[0], x1[1]); w.w = cvt_pk_bf16(x1[2], x1[3]);
;                     *(u32x4*)(XB + ro + bj * 128) = w; }
;                 sq += __shfl_xor(sq, 16); sq += __shfl_xor(sq, 32);
;                 if (fq == 0) SSo[(size_t)(u.pn * 4 + wc) * T + row0 + ai * 128 + m * 16] = sq; }
.LBB0_720:
	s_or_b64 exec, exec, s[34:35]
	v_lshlrev_b32_e32 v32, 16, v128
	s_waitcnt lgkmcnt(0)
	v_and_b32_e32 v33, 0xffff0000, v128
	v_lshlrev_b32_e32 v34, 16, v129
	v_and_b32_e32 v35, 0xffff0000, v129
	v_pk_add_f32 v[30:31], v[30:31], v[34:35]
	v_pk_add_f32 v[28:29], v[28:29], v[32:33]
	v_lshlrev_b32_e32 v32, 16, v130
	v_and_b32_e32 v33, 0xffff0000, v130
	v_lshlrev_b32_e32 v34, 16, v131
	v_and_b32_e32 v35, 0xffff0000, v131
	v_pk_add_f32 v[34:35], v[26:27], v[34:35]
	v_pk_add_f32 v[26:27], v[24:25], v[32:33]
	v_mul_f32_e32 v24, v29, v29
	v_mul_f32_e32 v25, v31, v31
	v_fmac_f32_e32 v24, v28, v28
	v_fmac_f32_e32 v25, v30, v30
	v_add_f32_e32 v24, v24, v25
	v_mul_f32_e32 v25, v27, v27
	v_fmac_f32_e32 v25, v26, v26
	v_add_f32_e32 v24, v25, v24
	v_mul_f32_e32 v25, v35, v35
	v_fmac_f32_e32 v25, v34, v34
	v_add_f32_e32 v32, v25, v24
	v_cvt_pk_bf16_f32 v24, v28, v29
	v_cvt_pk_bf16_f32 v25, v30, v31
	v_lshlrev_b32_e32 v28, 16, v120
	v_and_b32_e32 v29, 0xffff0000, v120
	v_lshlrev_b32_e32 v30, 16, v121
	v_and_b32_e32 v31, 0xffff0000, v121
	v_pk_add_f32 v[22:23], v[22:23], v[30:31]
	v_pk_add_f32 v[20:21], v[20:21], v[28:29]
	v_lshlrev_b32_e32 v28, 16, v122
	v_and_b32_e32 v29, 0xffff0000, v122
	v_pk_add_f32 v[28:29], v[16:17], v[28:29]
	v_mul_f32_e32 v16, v21, v21
	v_mul_f32_e32 v17, v23, v23
	v_fmac_f32_e32 v16, v20, v20
	v_fmac_f32_e32 v17, v22, v22
	v_lshlrev_b32_e32 v30, 16, v123
	v_and_b32_e32 v31, 0xffff0000, v123
	v_add_f32_e32 v16, v16, v17
	v_mul_f32_e32 v17, v29, v29
	v_pk_add_f32 v[30:31], v[18:19], v[30:31]
	v_fmac_f32_e32 v17, v28, v28
	v_add_f32_e32 v16, v17, v16
	v_mul_f32_e32 v17, v31, v31
	v_fmac_f32_e32 v17, v30, v30
	v_add_f32_e32 v16, v17, v16
	v_add_f32_e32 v19, v32, v16
	v_cvt_pk_bf16_f32 v26, v26, v27
	v_cvt_pk_bf16_f32 v27, v34, v35
	v_mov_b32_e32 v34, v19
	s_nop 1
	v_permlane16_swap_b32_e32 v34, v19
	v_lshl_add_u64 v[16:17], s[36:37], 0, v[208:209]
	v_lshl_add_u64 v[32:33], v[204:205], 1, v[16:17]
	global_store_dwordx4 v[32:33], v[24:27], off nt
	v_cvt_pk_bf16_f32 v18, v20, v21
	s_waitcnt lgkmcnt(0)
	v_add_f32_e32 v16, v19, v34
	v_mov_b32_e32 v17, v16
	s_nop 1
	v_permlane32_swap_b32_e32 v17, v16
	v_cvt_pk_bf16_f32 v19, v22, v23
	v_cvt_pk_bf16_f32 v20, v28, v29
	v_cvt_pk_bf16_f32 v21, v30, v31
	global_store_dwordx4 v[32:33], v[18:21], off offset:256 nt
	s_and_saveexec_b64 s[34:35], s[4:5]
	s_cbranch_execz .LBB0_722
	s_add_u32 s54, s63, s20
	s_addc_u32 s55, s64, s21
	v_lshl_add_u64 v[18:19], v[202:203], 2, s[54:55]
	s_waitcnt lgkmcnt(0)
	v_add_f32_e32 v16, v16, v17
	global_store_dword v[18:19], v16, off offset:640
.LBB0_722:
	s_or_b64 exec, exec, s[34:35]
	v_lshlrev_b32_e32 v16, 16, v108
	s_waitcnt lgkmcnt(0)
	v_and_b32_e32 v17, 0xffff0000, v108
	v_lshlrev_b32_e32 v18, 16, v109
	v_and_b32_e32 v19, 0xffff0000, v109
	v_pk_add_f32 v[14:15], v[14:15], v[18:19]
	v_pk_add_f32 v[12:13], v[12:13], v[16:17]
	v_lshlrev_b32_e32 v16, 16, v110
	v_and_b32_e32 v17, 0xffff0000, v110
	v_lshlrev_b32_e32 v18, 16, v111
	v_and_b32_e32 v19, 0xffff0000, v111
	v_pk_add_f32 v[18:19], v[10:11], v[18:19]
	v_pk_add_f32 v[10:11], v[8:9], v[16:17]
	v_mul_f32_e32 v8, v13, v13
	v_mul_f32_e32 v9, v15, v15
	v_fmac_f32_e32 v8, v12, v12
	v_fmac_f32_e32 v9, v14, v14
	v_add_f32_e32 v8, v8, v9
	v_mul_f32_e32 v9, v11, v11
	v_fmac_f32_e32 v9, v10, v10
	v_add_f32_e32 v8, v9, v8
	v_mul_f32_e32 v9, v19, v19
	v_fmac_f32_e32 v9, v18, v18
	v_add_f32_e32 v16, v9, v8
	v_cvt_pk_bf16_f32 v8, v12, v13
	v_cvt_pk_bf16_f32 v9, v14, v15
	v_lshlrev_b32_e32 v12, 16, v96
	v_and_b32_e32 v13, 0xffff0000, v96
	v_lshlrev_b32_e32 v14, 16, v97
	v_and_b32_e32 v15, 0xffff0000, v97
	v_pk_add_f32 v[6:7], v[6:7], v[14:15]
	v_pk_add_f32 v[4:5], v[4:5], v[12:13]
	v_lshlrev_b32_e32 v12, 16, v98
	v_and_b32_e32 v13, 0xffff0000, v98
	v_pk_add_f32 v[12:13], v[0:1], v[12:13]
	v_mul_f32_e32 v0, v5, v5
	v_mul_f32_e32 v1, v7, v7
	v_fmac_f32_e32 v0, v4, v4
	v_fmac_f32_e32 v1, v6, v6
	v_lshlrev_b32_e32 v14, 16, v99
	v_and_b32_e32 v15, 0xffff0000, v99
	v_add_f32_e32 v0, v0, v1
	v_mul_f32_e32 v1, v13, v13
	v_pk_add_f32 v[14:15], v[2:3], v[14:15]
	v_fmac_f32_e32 v1, v12, v12
	v_add_f32_e32 v0, v1, v0
	v_mul_f32_e32 v1, v15, v15
	v_fmac_f32_e32 v1, v14, v14
	v_add_f32_e32 v0, v1, v0
	v_add_f32_e32 v3, v16, v0
	v_cvt_pk_bf16_f32 v10, v10, v11
	v_cvt_pk_bf16_f32 v11, v18, v19
	v_mov_b32_e32 v18, v3
	s_nop 1
	v_permlane16_swap_b32_e32 v18, v3
	v_lshl_add_u64 v[0:1], s[36:37], 0, v[206:207]
	v_lshl_add_u64 v[16:17], v[204:205], 1, v[0:1]
	global_store_dwordx4 v[16:17], v[8:11], off nt
	v_cvt_pk_bf16_f32 v2, v4, v5
	s_waitcnt lgkmcnt(0)
	v_add_f32_e32 v0, v3, v18
	v_mov_b32_e32 v1, v0
	s_nop 1
	v_permlane32_swap_b32_e32 v1, v0
	v_cvt_pk_bf16_f32 v3, v6, v7
	v_cvt_pk_bf16_f32 v4, v12, v13
	v_cvt_pk_bf16_f32 v5, v14, v15
	global_store_dwordx4 v[16:17], v[2:5], off offset:256 nt
	s_and_saveexec_b64 s[34:35], s[4:5]
	s_cbranch_execz .LBB0_724
	s_add_u32 s20, s63, s20
	s_addc_u32 s21, s64, s21
	v_lshl_add_u64 v[2:3], v[202:203], 2, s[20:21]
	s_waitcnt lgkmcnt(0)
	v_add_f32_e32 v0, v0, v1
	global_store_dword v[2:3], v0, off offset:704

; #define LAS __attribute__((address_space(3)))
; __device__ __forceinline__ unsigned cvt_pk2(float lo, float hi) { f32x2c v = {lo, hi}; bf16x2c q = __builtin_convertvector(v, bf16x2c); return __builtin_bit_cast(unsigned, q); }
;     __device__ __forceinline__ void operator()(const f32x4 (&acc)[2][2][4][2], const pg8::Unit& u, int wr, int wc, int fr, int fq) const {
;         const int row0 = u.pm * 256 + wr * 64 + fr, col0 = u.pn * 128 + wc * 32 + 8 * fq;
;         const LAS float* rt = rt_.of(u.pm) + wr * 64 + fr;
; #pragma unroll
;         for (int ai = 0; ai < 2; ++ai)
; #pragma unroll
;             for (int m = 0; m < 4; ++m) { bf16_t* rowp = O + (size_t)(row0 + ai * 128 + m * 16) * FF + col0; const float r = rt[ai * 128 + m * 16];
;                 const float rl = -r * LOG2E, r2 = r * r; unsigned w[4];
; #pragma unroll
;                 for (int n = 0; n < 2; ++n)
; #pragma unroll
;                     for (int h = 0; h < 2; ++h) { const f32x2v g = {acc[ai][0][m][n][2 * h], acc[ai][0][m][n][2 * h + 1]}, uu = {acc[ai][1][m][n][2 * h], acc[ai][1][m][n][2 * h + 1]};
;                         const f32x2v t = g * rl; f32x2v d = {__builtin_amdgcn_exp2f(t.x), __builtin_amdgcn_exp2f(t.y)}; d = d + 1.0f;
;                         const f32x2v q = {__builtin_amdgcn_rcpf(d.x), __builtin_amdgcn_rcpf(d.y)}; const f32x2v o = ((g * uu) * r2) * q;
;                         w[2 * n + h] = cvt_pk2(o.x, o.y); }
;                 u32x4 wv; wv.x = w[0]; wv.y = w[1]; wv.z = w[2]; wv.w = w[3];
;                 *(u32x4*)rowp = wv; }
.LBB0_813:
	s_cmp_eq_u32 s34, s48
	s_cselect_b32 s13, s62, 0x300
	s_cmp_lg_u32 s34, s49
	s_cselect_b32 s13, s13, 0x100
	s_cmp_lg_u32 s34, s47
	s_cselect_b32 s13, s13, 0
	v_lshl_add_u32 v154, s13, 2, v148
	ds_read2_b32 v[200:201], v154 offset1:16
	ds_read2_b32 v[202:203], v154 offset0:32 offset1:48
	ds_read2_b32 v[204:205], v154 offset0:128 offset1:144
	ds_read2_b32 v[206:207], v154 offset0:160 offset1:176
	v_lshl_add_u32 v153, s34, 8, v146
	v_lshl_or_b32 v158, s64, 7, v149
	v_mov_b64_e32 v[178:179], s[40:41]
	s_mov_b32 s98, 0x1600
	v_lshlrev_b32_e32 v158, 1, v158
	v_mov_b32_e32 v159, 0
	v_mad_i64_i32 v[178:179], s[20:21], v153, s98, v[178:179]
	s_mov_b32 s98, 0x16000
	s_mov_b32 s99, 0
	s_mov_b32 s100, 0x6e000
	s_mov_b32 s101, 0
	v_lshl_add_u64 v[178:179], v[178:179], 0, v[158:159]
	s_waitcnt lgkmcnt(0)
	v_mul_f32_e32 v208, 0xbfb8aa3b, v200
	v_mul_f32_e32 v228, v200, v200
	v_mul_f32_e32 v210, 0xbfb8aa3b, v201
	v_mul_f32_e32 v230, v201, v201
	v_mul_f32_e32 v212, 0xbfb8aa3b, v202
	v_mul_f32_e32 v232, v202, v202
	v_mul_f32_e32 v214, 0xbfb8aa3b, v203
	v_mul_f32_e32 v234, v203, v203
	v_mul_f32_e32 v216, 0xbfb8aa3b, v204
	v_mul_f32_e32 v236, v204, v204
	v_mul_f32_e32 v218, 0xbfb8aa3b, v205
	v_mul_f32_e32 v238, v205, v205
	v_mul_f32_e32 v220, 0xbfb8aa3b, v206
	v_mul_f32_e32 v240, v206, v206
	v_mul_f32_e32 v222, 0xbfb8aa3b, v207
	v_mul_f32_e32 v242, v207, v207
	v_rcp_f32_e32 v228, v228
	v_rcp_f32_e32 v230, v230
	v_rcp_f32_e32 v232, v232
	v_rcp_f32_e32 v234, v234
	v_rcp_f32_e32 v236, v236
	v_rcp_f32_e32 v238, v238
	v_rcp_f32_e32 v240, v240
	v_rcp_f32_e32 v242, v242
	v_pk_mul_f32 v[154:155], v[124:125], v[208:209] op_sel_hi:[1,0]
	v_pk_mul_f32 v[156:157], v[126:127], v[208:209] op_sel_hi:[1,0]
	v_pk_mul_f32 v[158:159], v[116:117], v[208:209] op_sel_hi:[1,0]
	v_pk_mul_f32 v[160:161], v[118:119], v[208:209] op_sel_hi:[1,0]
	v_exp_f32_e32 v154, v154
	v_exp_f32_e32 v155, v155
	v_exp_f32_e32 v156, v156
	v_exp_f32_e32 v157, v157
	v_exp_f32_e32 v158, v158
	v_exp_f32_e32 v159, v159
	v_exp_f32_e32 v160, v160
	v_exp_f32_e32 v161, v161
	v_pk_mul_f32 v[162:163], v[108:109], v[210:211] op_sel_hi:[1,0]
	v_pk_mul_f32 v[164:165], v[110:111], v[210:211] op_sel_hi:[1,0]
	v_pk_mul_f32 v[166:167], v[100:101], v[210:211] op_sel_hi:[1,0]
	v_pk_mul_f32 v[168:169], v[102:103], v[210:211] op_sel_hi:[1,0]
	v_exp_f32_e32 v162, v162
	v_exp_f32_e32 v163, v163
	v_exp_f32_e32 v164, v164
	v_exp_f32_e32 v165, v165
	v_exp_f32_e32 v166, v166
	v_exp_f32_e32 v167, v167
	v_exp_f32_e32 v168, v168
	v_exp_f32_e32 v169, v169
	v_pk_mul_f32 v[120:121], v[124:125], v[120:121]
	v_pk_mul_f32 v[122:123], v[126:127], v[122:123]
	v_pk_mul_f32 v[112:113], v[116:117], v[112:113]
	v_pk_mul_f32 v[114:115], v[118:119], v[114:115]
	v_pk_fma_f32 v[154:155], v[154:155], v[228:229], v[228:229] op_sel_hi:[1,0,0]
	v_pk_fma_f32 v[156:157], v[156:157], v[228:229], v[228:229] op_sel_hi:[1,0,0]
	v_pk_fma_f32 v[158:159], v[158:159], v[228:229], v[228:229] op_sel_hi:[1,0,0]
	v_pk_fma_f32 v[160:161], v[160:161], v[228:229], v[228:229] op_sel_hi:[1,0,0]
	v_rcp_f32_e32 v154, v154
	v_rcp_f32_e32 v155, v155
	v_rcp_f32_e32 v156, v156
	v_rcp_f32_e32 v157, v157
	v_rcp_f32_e32 v158, v158
	v_rcp_f32_e32 v159, v159
	v_rcp_f32_e32 v160, v160
	v_rcp_f32_e32 v161, v161
	v_pk_mul_f32 v[170:171], v[92:93], v[212:213] op_sel_hi:[1,0]
	v_pk_mul_f32 v[172:173], v[94:95], v[212:213] op_sel_hi:[1,0]
	v_pk_mul_f32 v[174:175], v[84:85], v[212:213] op_sel_hi:[1,0]
	v_pk_mul_f32 v[176:177], v[86:87], v[212:213] op_sel_hi:[1,0]
	v_exp_f32_e32 v170, v170
	v_exp_f32_e32 v171, v171
	v_exp_f32_e32 v172, v172
	v_exp_f32_e32 v173, v173
	v_exp_f32_e32 v174, v174
	v_exp_f32_e32 v175, v175
	v_exp_f32_e32 v176, v176
	v_exp_f32_e32 v177, v177
	v_pk_mul_f32 v[104:105], v[108:109], v[104:105]
	v_pk_mul_f32 v[106:107], v[110:111], v[106:107]
	v_pk_mul_f32 v[96:97], v[100:101], v[96:97]
	v_pk_mul_f32 v[98:99], v[102:103], v[98:99]
	v_pk_fma_f32 v[162:163], v[162:163], v[230:231], v[230:231] op_sel_hi:[1,0,0]
	v_pk_fma_f32 v[164:165], v[164:165], v[230:231], v[230:231] op_sel_hi:[1,0,0]
	v_pk_fma_f32 v[166:167], v[166:167], v[230:231], v[230:231] op_sel_hi:[1,0,0]
	v_pk_fma_f32 v[168:169], v[168:169], v[230:231], v[230:231] op_sel_hi:[1,0,0]
	v_rcp_f32_e32 v162, v162
	v_rcp_f32_e32 v163, v163
	v_rcp_f32_e32 v164, v164
	v_rcp_f32_e32 v165, v165
	v_rcp_f32_e32 v166, v166
	v_rcp_f32_e32 v167, v167
	v_rcp_f32_e32 v168, v168
	v_rcp_f32_e32 v169, v169
	v_pk_mul_f32 v[120:121], v[120:121], v[154:155]
	v_pk_mul_f32 v[122:123], v[122:123], v[156:157]
	v_pk_mul_f32 v[112:113], v[112:113], v[158:159]
	v_pk_mul_f32 v[114:115], v[114:115], v[160:161]
	v_cvt_pk_bf16_f32 v154, v120, v121
	v_cvt_pk_bf16_f32 v155, v122, v123
	v_cvt_pk_bf16_f32 v156, v112, v113
	v_cvt_pk_bf16_f32 v157, v114, v115
	global_store_dwordx4 v[178:179], v[154:157], off nt
	v_lshl_add_u64 v[178:179], v[178:179], 0, s[98:99]
	s_nop 1
	v_pk_mul_f32 v[154:155], v[76:77], v[214:215] op_sel_hi:[1,0]
	v_pk_mul_f32 v[156:157], v[78:79], v[214:215] op_sel_hi:[1,0]
	v_pk_mul_f32 v[158:159], v[68:69], v[214:215] op_sel_hi:[1,0]
	v_pk_mul_f32 v[160:161], v[70:71], v[214:215] op_sel_hi:[1,0]
	v_exp_f32_e32 v154, v154
	v_exp_f32_e32 v155, v155
	v_exp_f32_e32 v156, v156
	v_exp_f32_e32 v157, v157
	v_exp_f32_e32 v158, v158
	v_exp_f32_e32 v159, v159
	v_exp_f32_e32 v160, v160
	v_exp_f32_e32 v161, v161
	v_pk_mul_f32 v[88:89], v[92:93], v[88:89]
	v_pk_mul_f32 v[90:91], v[94:95], v[90:91]
	v_pk_mul_f32 v[80:81], v[84:85], v[80:81]
	v_pk_mul_f32 v[82:83], v[86:87], v[82:83]
	v_pk_fma_f32 v[170:171], v[170:171], v[232:233], v[232:233] op_sel_hi:[1,0,0]
	v_pk_fma_f32 v[172:173], v[172:173], v[232:233], v[232:233] op_sel_hi:[1,0,0]
; __device__ __forceinline__ unsigned cvt_pk2(float lo, float hi) { f32x2c v = {lo, hi}; bf16x2c q = __builtin_convertvector(v, bf16x2c); return __builtin_bit_cast(unsigned, q); }
;     __device__ __forceinline__ void operator()(const f32x4 (&acc)[2][2][4][2], const pg8::Unit& u, int wr, int wc, int fr, int fq) const {
;     ...
;             for (int m = 0; m < 4; ++m) { bf16_t* rowp = O + (size_t)(row0 + ai * 128 + m * 16) * FF + col0; const float r = rt[ai * 128 + m * 16];
;                 const float rl = -r * LOG2E, r2 = r * r; unsigned w[4];
; #pragma unroll
;                 for (int n = 0; n < 2; ++n)
; #pragma unroll
;                     for (int h = 0; h < 2; ++h) { const f32x2v g = {acc[ai][0][m][n][2 * h], acc[ai][0][m][n][2 * h + 1]}, uu = {acc[ai][1][m][n][2 * h], acc[ai][1][m][n][2 * h + 1]};
;                         const f32x2v t = g * rl; f32x2v d = {__builtin_amdgcn_exp2f(t.x), __builtin_amdgcn_exp2f(t.y)}; d = d + 1.0f;
;                         const f32x2v q = {__builtin_amdgcn_rcpf(d.x), __builtin_amdgcn_rcpf(d.y)}; const f32x2v o = ((g * uu) * r2) * q;
;                         w[2 * n + h] = cvt_pk2(o.x, o.y); }
;                 u32x4 wv; wv.x = w[0]; wv.y = w[1]; wv.z = w[2]; wv.w = w[3];
;                 *(u32x4*)rowp = wv; }
	v_pk_fma_f32 v[174:175], v[174:175], v[232:233], v[232:233] op_sel_hi:[1,0,0]
	v_pk_fma_f32 v[176:177], v[176:177], v[232:233], v[232:233] op_sel_hi:[1,0,0]
	v_rcp_f32_e32 v170, v170
	v_rcp_f32_e32 v171, v171
	v_rcp_f32_e32 v172, v172
	v_rcp_f32_e32 v173, v173
	v_rcp_f32_e32 v174, v174
	v_rcp_f32_e32 v175, v175
	v_rcp_f32_e32 v176, v176
	v_rcp_f32_e32 v177, v177
	v_pk_mul_f32 v[104:105], v[104:105], v[162:163]
	v_pk_mul_f32 v[106:107], v[106:107], v[164:165]
	v_pk_mul_f32 v[96:97], v[96:97], v[166:167]
	v_pk_mul_f32 v[98:99], v[98:99], v[168:169]
	v_cvt_pk_bf16_f32 v162, v104, v105
	v_cvt_pk_bf16_f32 v163, v106, v107
	v_cvt_pk_bf16_f32 v164, v96, v97
	v_cvt_pk_bf16_f32 v165, v98, v99
	global_store_dwordx4 v[178:179], v[162:165], off nt
	v_lshl_add_u64 v[178:179], v[178:179], 0, s[98:99]
	s_nop 1
	v_pk_mul_f32 v[162:163], v[60:61], v[216:217] op_sel_hi:[1,0]
	v_pk_mul_f32 v[164:165], v[62:63], v[216:217] op_sel_hi:[1,0]
	v_pk_mul_f32 v[166:167], v[52:53], v[216:217] op_sel_hi:[1,0]
	v_pk_mul_f32 v[168:169], v[54:55], v[216:217] op_sel_hi:[1,0]
	v_exp_f32_e32 v162, v162
	v_exp_f32_e32 v163, v163
	v_exp_f32_e32 v164, v164
	v_exp_f32_e32 v165, v165
	v_exp_f32_e32 v166, v166
	v_exp_f32_e32 v167, v167
	v_exp_f32_e32 v168, v168
	v_exp_f32_e32 v169, v169
	v_pk_mul_f32 v[72:73], v[76:77], v[72:73]
	v_pk_mul_f32 v[74:75], v[78:79], v[74:75]
	v_pk_mul_f32 v[64:65], v[68:69], v[64:65]
	v_pk_mul_f32 v[66:67], v[70:71], v[66:67]
	v_pk_fma_f32 v[154:155], v[154:155], v[234:235], v[234:235] op_sel_hi:[1,0,0]
	v_pk_fma_f32 v[156:157], v[156:157], v[234:235], v[234:235] op_sel_hi:[1,0,0]
	v_pk_fma_f32 v[158:159], v[158:159], v[234:235], v[234:235] op_sel_hi:[1,0,0]
	v_pk_fma_f32 v[160:161], v[160:161], v[234:235], v[234:235] op_sel_hi:[1,0,0]
	v_rcp_f32_e32 v154, v154
	v_rcp_f32_e32 v155, v155
	v_rcp_f32_e32 v156, v156
	v_rcp_f32_e32 v157, v157
	v_rcp_f32_e32 v158, v158
	v_rcp_f32_e32 v159, v159
	v_rcp_f32_e32 v160, v160
	v_rcp_f32_e32 v161, v161
	v_pk_mul_f32 v[88:89], v[88:89], v[170:171]
	v_pk_mul_f32 v[90:91], v[90:91], v[172:173]
	v_pk_mul_f32 v[80:81], v[80:81], v[174:175]
	v_pk_mul_f32 v[82:83], v[82:83], v[176:177]
	v_cvt_pk_bf16_f32 v170, v88, v89
	v_cvt_pk_bf16_f32 v171, v90, v91
	v_cvt_pk_bf16_f32 v172, v80, v81
	v_cvt_pk_bf16_f32 v173, v82, v83
	global_store_dwordx4 v[178:179], v[170:173], off nt
	v_lshl_add_u64 v[178:179], v[178:179], 0, s[98:99]
	s_nop 1
	v_pk_mul_f32 v[170:171], v[44:45], v[218:219] op_sel_hi:[1,0]
	v_pk_mul_f32 v[172:173], v[46:47], v[218:219] op_sel_hi:[1,0]
	v_pk_mul_f32 v[174:175], v[36:37], v[218:219] op_sel_hi:[1,0]
	v_pk_mul_f32 v[176:177], v[38:39], v[218:219] op_sel_hi:[1,0]
	v_exp_f32_e32 v170, v170
	v_exp_f32_e32 v171, v171
	v_exp_f32_e32 v172, v172
	v_exp_f32_e32 v173, v173
	v_exp_f32_e32 v174, v174
	v_exp_f32_e32 v175, v175
	v_exp_f32_e32 v176, v176
	v_exp_f32_e32 v177, v177
	v_pk_mul_f32 v[56:57], v[60:61], v[56:57]
	v_pk_mul_f32 v[58:59], v[62:63], v[58:59]
	v_pk_mul_f32 v[48:49], v[52:53], v[48:49]
	v_pk_mul_f32 v[50:51], v[54:55], v[50:51]
	v_pk_fma_f32 v[162:163], v[162:163], v[236:237], v[236:237] op_sel_hi:[1,0,0]
	v_pk_fma_f32 v[164:165], v[164:165], v[236:237], v[236:237] op_sel_hi:[1,0,0]
	v_pk_fma_f32 v[166:167], v[166:167], v[236:237], v[236:237] op_sel_hi:[1,0,0]
	v_pk_fma_f32 v[168:169], v[168:169], v[236:237], v[236:237] op_sel_hi:[1,0,0]
	v_rcp_f32_e32 v162, v162
	v_rcp_f32_e32 v163, v163
	v_rcp_f32_e32 v164, v164
	v_rcp_f32_e32 v165, v165
	v_rcp_f32_e32 v166, v166
	v_rcp_f32_e32 v167, v167
	v_rcp_f32_e32 v168, v168
	v_rcp_f32_e32 v169, v169
	v_pk_mul_f32 v[72:73], v[72:73], v[154:155]
	v_pk_mul_f32 v[74:75], v[74:75], v[156:157]
	v_pk_mul_f32 v[64:65], v[64:65], v[158:159]
	v_pk_mul_f32 v[66:67], v[66:67], v[160:161]
	v_cvt_pk_bf16_f32 v154, v72, v73
	v_cvt_pk_bf16_f32 v155, v74, v75
	v_cvt_pk_bf16_f32 v156, v64, v65
	v_cvt_pk_bf16_f32 v157, v66, v67
	global_store_dwordx4 v[178:179], v[154:157], off nt
	v_lshl_add_u64 v[178:179], v[178:179], 0, s[100:101]
	s_nop 1
	v_pk_mul_f32 v[154:155], v[28:29], v[220:221] op_sel_hi:[1,0]
	v_pk_mul_f32 v[156:157], v[30:31], v[220:221] op_sel_hi:[1,0]
	v_pk_mul_f32 v[158:159], v[20:21], v[220:221] op_sel_hi:[1,0]
	v_pk_mul_f32 v[160:161], v[22:23], v[220:221] op_sel_hi:[1,0]
	v_exp_f32_e32 v154, v154
	v_exp_f32_e32 v155, v155
	v_exp_f32_e32 v156, v156
	v_exp_f32_e32 v157, v157
	v_exp_f32_e32 v158, v158
	v_exp_f32_e32 v159, v159
; #define PG8_BAR __builtin_amdgcn_s_barrier()
; __device__ __forceinline__ unsigned cvt_pk2(float lo, float hi) { f32x2c v = {lo, hi}; bf16x2c q = __builtin_convertvector(v, bf16x2c); return __builtin_bit_cast(unsigned, q); }
; template <class Epi, class Sched, bool ALIGN_EPI = false, bool SP2 = false>
; __device__ __forceinline__ void gemm_phase(PG8_LAS unsigned char* lds, const Gemm g, const Sched& S, const Epi& E) {
;     ...
;         if constexpr (!Epi::AFTER_DRAIN) { E(acc, cur, wr, wc, fr, fq); S.done(cur); }
;         if (!has_next) break;
; #pragma unroll
;         for (int a = 0; a < 2; ++a)
; #pragma unroll
;             for (int b = 0; b < 2; ++b)
; #pragma unroll
;                 for (int m = 0; m < 4; ++m)
; #pragma unroll
;                     for (int n = 0; n < 2; ++n) acc[a][b][m][n] = (f32x4){0.f, 0.f, 0.f, 0.f};
;         cur = nxt; cA = nA; cB = nB; ++ui;
;         if constexpr (ALIGN_EPI) { if (wr == 1) PG8_BAR; }
;     __device__ __forceinline__ void operator()(const f32x4 (&acc)[2][2][4][2], const pg8::Unit& u, int wr, int wc, int fr, int fq) const {
;     ...
;             for (int m = 0; m < 4; ++m) { bf16_t* rowp = O + (size_t)(row0 + ai * 128 + m * 16) * FF + col0; const float r = rt[ai * 128 + m * 16];
;                 const float rl = -r * LOG2E, r2 = r * r; unsigned w[4];
; #pragma unroll
;                 for (int n = 0; n < 2; ++n)
; #pragma unroll
;                     for (int h = 0; h < 2; ++h) { const f32x2v g = {acc[ai][0][m][n][2 * h], acc[ai][0][m][n][2 * h + 1]}, uu = {acc[ai][1][m][n][2 * h], acc[ai][1][m][n][2 * h + 1]};
;                         const f32x2v t = g * rl; f32x2v d = {__builtin_amdgcn_exp2f(t.x), __builtin_amdgcn_exp2f(t.y)}; d = d + 1.0f;
;                         const f32x2v q = {__builtin_amdgcn_rcpf(d.x), __builtin_amdgcn_rcpf(d.y)}; const f32x2v o = ((g * uu) * r2) * q;
;                         w[2 * n + h] = cvt_pk2(o.x, o.y); }
;                 u32x4 wv; wv.x = w[0]; wv.y = w[1]; wv.z = w[2]; wv.w = w[3];
;                 *(u32x4*)rowp = wv; }
	v_exp_f32_e32 v160, v160
	v_exp_f32_e32 v161, v161
	v_pk_mul_f32 v[40:41], v[44:45], v[40:41]
	v_pk_mul_f32 v[42:43], v[46:47], v[42:43]
	v_pk_mul_f32 v[32:33], v[36:37], v[32:33]
	v_pk_mul_f32 v[34:35], v[38:39], v[34:35]
	v_pk_fma_f32 v[170:171], v[170:171], v[238:239], v[238:239] op_sel_hi:[1,0,0]
	v_pk_fma_f32 v[172:173], v[172:173], v[238:239], v[238:239] op_sel_hi:[1,0,0]
	v_pk_fma_f32 v[174:175], v[174:175], v[238:239], v[238:239] op_sel_hi:[1,0,0]
	v_pk_fma_f32 v[176:177], v[176:177], v[238:239], v[238:239] op_sel_hi:[1,0,0]
	v_rcp_f32_e32 v170, v170
	v_rcp_f32_e32 v171, v171
	v_rcp_f32_e32 v172, v172
	v_rcp_f32_e32 v173, v173
	v_rcp_f32_e32 v174, v174
	v_rcp_f32_e32 v175, v175
	v_rcp_f32_e32 v176, v176
	v_rcp_f32_e32 v177, v177
	v_pk_mul_f32 v[56:57], v[56:57], v[162:163]
	v_pk_mul_f32 v[58:59], v[58:59], v[164:165]
	v_pk_mul_f32 v[48:49], v[48:49], v[166:167]
	v_pk_mul_f32 v[50:51], v[50:51], v[168:169]
	v_cvt_pk_bf16_f32 v162, v56, v57
	v_cvt_pk_bf16_f32 v163, v58, v59
	v_cvt_pk_bf16_f32 v164, v48, v49
	v_cvt_pk_bf16_f32 v165, v50, v51
	global_store_dwordx4 v[178:179], v[162:165], off nt
	v_lshl_add_u64 v[178:179], v[178:179], 0, s[98:99]
	s_nop 1
	v_pk_mul_f32 v[162:163], v[12:13], v[222:223] op_sel_hi:[1,0]
	v_pk_mul_f32 v[164:165], v[14:15], v[222:223] op_sel_hi:[1,0]
	v_pk_mul_f32 v[166:167], v[4:5], v[222:223] op_sel_hi:[1,0]
	v_pk_mul_f32 v[168:169], v[6:7], v[222:223] op_sel_hi:[1,0]
	v_exp_f32_e32 v162, v162
	v_exp_f32_e32 v163, v163
	v_exp_f32_e32 v164, v164
	v_exp_f32_e32 v165, v165
	v_exp_f32_e32 v166, v166
	v_exp_f32_e32 v167, v167
	v_exp_f32_e32 v168, v168
	v_exp_f32_e32 v169, v169
	v_pk_mul_f32 v[24:25], v[28:29], v[24:25]
	v_pk_mul_f32 v[26:27], v[30:31], v[26:27]
	v_pk_mul_f32 v[16:17], v[20:21], v[16:17]
	v_pk_mul_f32 v[18:19], v[22:23], v[18:19]
	v_pk_fma_f32 v[154:155], v[154:155], v[240:241], v[240:241] op_sel_hi:[1,0,0]
	v_pk_fma_f32 v[156:157], v[156:157], v[240:241], v[240:241] op_sel_hi:[1,0,0]
	v_pk_fma_f32 v[158:159], v[158:159], v[240:241], v[240:241] op_sel_hi:[1,0,0]
	v_pk_fma_f32 v[160:161], v[160:161], v[240:241], v[240:241] op_sel_hi:[1,0,0]
	v_rcp_f32_e32 v154, v154
	v_rcp_f32_e32 v155, v155
	v_rcp_f32_e32 v156, v156
	v_rcp_f32_e32 v157, v157
	v_rcp_f32_e32 v158, v158
	v_rcp_f32_e32 v159, v159
	v_rcp_f32_e32 v160, v160
	v_rcp_f32_e32 v161, v161
	v_pk_mul_f32 v[40:41], v[40:41], v[170:171]
	v_pk_mul_f32 v[42:43], v[42:43], v[172:173]
	v_pk_mul_f32 v[32:33], v[32:33], v[174:175]
	v_pk_mul_f32 v[34:35], v[34:35], v[176:177]
	v_cvt_pk_bf16_f32 v170, v40, v41
	v_cvt_pk_bf16_f32 v171, v42, v43
	v_cvt_pk_bf16_f32 v172, v32, v33
	v_cvt_pk_bf16_f32 v173, v34, v35
	global_store_dwordx4 v[178:179], v[170:173], off nt
	v_lshl_add_u64 v[178:179], v[178:179], 0, s[98:99]
	s_nop 1
	v_pk_mul_f32 v[8:9], v[12:13], v[8:9]
	v_pk_mul_f32 v[10:11], v[14:15], v[10:11]
	v_pk_mul_f32 v[0:1], v[4:5], v[0:1]
	v_pk_mul_f32 v[2:3], v[6:7], v[2:3]
	v_pk_fma_f32 v[162:163], v[162:163], v[242:243], v[242:243] op_sel_hi:[1,0,0]
	v_pk_fma_f32 v[164:165], v[164:165], v[242:243], v[242:243] op_sel_hi:[1,0,0]
	v_pk_fma_f32 v[166:167], v[166:167], v[242:243], v[242:243] op_sel_hi:[1,0,0]
	v_pk_fma_f32 v[168:169], v[168:169], v[242:243], v[242:243] op_sel_hi:[1,0,0]
	v_rcp_f32_e32 v162, v162
	v_rcp_f32_e32 v163, v163
	v_rcp_f32_e32 v164, v164
	v_rcp_f32_e32 v165, v165
	v_rcp_f32_e32 v166, v166
	v_rcp_f32_e32 v167, v167
	v_rcp_f32_e32 v168, v168
	v_rcp_f32_e32 v169, v169
	v_pk_mul_f32 v[24:25], v[24:25], v[154:155]
	v_pk_mul_f32 v[26:27], v[26:27], v[156:157]
	v_pk_mul_f32 v[16:17], v[16:17], v[158:159]
	v_pk_mul_f32 v[18:19], v[18:19], v[160:161]
	v_cvt_pk_bf16_f32 v154, v24, v25
	v_cvt_pk_bf16_f32 v155, v26, v27
	v_cvt_pk_bf16_f32 v156, v16, v17
	v_cvt_pk_bf16_f32 v157, v18, v19
	global_store_dwordx4 v[178:179], v[154:157], off nt
	v_lshl_add_u64 v[178:179], v[178:179], 0, s[98:99]
	s_nop 1
	v_pk_mul_f32 v[8:9], v[8:9], v[162:163]
	v_pk_mul_f32 v[10:11], v[10:11], v[164:165]
	v_pk_mul_f32 v[0:1], v[0:1], v[166:167]
	v_pk_mul_f32 v[2:3], v[2:3], v[168:169]
	v_cvt_pk_bf16_f32 v162, v8, v9
	v_cvt_pk_bf16_f32 v163, v10, v11
	v_cvt_pk_bf16_f32 v164, v0, v1
	v_cvt_pk_bf16_f32 v165, v2, v3
	global_store_dwordx4 v[178:179], v[162:165], off nt
	s_andn2_b64 vcc, exec, s[4:5]
	s_mov_b64 s[4:5], -1
	s_cbranch_vccnz .LBB0_806
	s_andn2_b64 vcc, exec, s[0:1]
	s_cbranch_vccnz .LBB0_805
	s_barrier
	s_branch .LBB0_805

; __device__ __forceinline__ unsigned cvt_pk_bf16(float lo, float hi) { unsigned r; asm volatile("v_cvt_pk_bf16_f32 %0, %1, %2" : "=v"(r) : "v"(lo), "v"(hi)); return r; }
;     __device__ __forceinline__ void operator()(const f32x4 (&acc)[2][2][4][2], const pg8::Unit& u, int wr, int wc, int fr, int fq) const {
;         const int row0 = u.pm * 256 + wr * 64 + fr, col0 = u.pn * 256 + wc * 32 + 8 * fq;
;         u32x4 xin[2][4][2];
; #pragma unroll
;         for (int ai = 0; ai < 2; ++ai)
; #pragma unroll
;             for (int m = 0; m < 4; ++m)
; #pragma unroll
;                 for (int bj = 0; bj < 2; ++bj) xin[ai][m][bj] = *(const u32x4*)(XB + (size_t)(row0 + ai * 128 + m * 16) * D + col0 + bj * 128);
; #pragma unroll
;         for (int ai = 0; ai < 2; ++ai)
; #pragma unroll
;             for (int m = 0; m < 4; ++m) { const size_t ro = (size_t)(row0 + ai * 128 + m * 16) * D + col0; float sq = 0.f;
; #pragma unroll
;                 for (int bj = 0; bj < 2; ++bj) { const u32x4 xb = xin[ai][m][bj];
;                     const f32x4 x0 = (f32x4){bf_lo(xb.x), bf_hi(xb.x), bf_lo(xb.y), bf_hi(xb.y)} + acc[ai][bj][m][0] * s, x1 = (f32x4){bf_lo(xb.z), bf_hi(xb.z), bf_lo(xb.w), bf_hi(xb.w)} + acc[ai][bj][m][1] * s;
;                     sq += (x0[0] * x0[0] + x0[1] * x0[1]) + (x0[2] * x0[2] + x0[3] * x0[3]) + (x1[0] * x1[0] + x1[1] * x1[1]) + (x1[2] * x1[2] + x1[3] * x1[3]);
;                     u32x4 w; w.x = cvt_pk_bf16(x0[0], x0[1]); w.y = cvt_pk_bf16(x0[2], x0[3]); w.z = cvt_pk_bf16(x1[0], x1[1]); w.w = cvt_pk_bf16(x1[2], x1[3]);
;                     *(u32x4*)(XB + ro + bj * 128) = w; }
;                 sq += __shfl_xor(sq, 16); sq += __shfl_xor(sq, 32);
;                 if (fq == 0) SSo[(size_t)(u.pn * 4 + wc) * T + row0 + ai * 128 + m * 16] = sq; }
.LBB0_898:
	v_lshl_or_b32 v204, s68, 8, v222
	v_lshl_add_u32 v202, s69, 8, v220
	v_ashrrev_i32_e32 v205, 31, v204
	v_lshlrev_b64 v[236:237], 1, v[204:205]
	v_ashrrev_i32_e32 v203, 31, v202
	v_lshl_add_u64 v[96:97], s[36:37], 0, v[236:237]
	v_lshlrev_b64 v[238:239], 11, v[202:203]
	v_lshl_add_u64 v[98:99], v[96:97], 0, v[238:239]
	global_load_dwordx4 v[228:231], v[98:99], off
	global_load_dwordx4 v[232:235], v[98:99], off offset:256
	v_or_b32_e32 v98, 16, v202
	v_or_b32_e32 v108, 32, v202
	v_or_b32_e32 v110, 48, v202
	v_ashrrev_i32_e32 v99, 31, v98
	v_ashrrev_i32_e32 v109, 31, v108
	v_ashrrev_i32_e32 v111, 31, v110
	v_lshlrev_b64 v[218:219], 11, v[98:99]
	v_lshlrev_b64 v[216:217], 11, v[108:109]
	v_lshlrev_b64 v[214:215], 11, v[110:111]
	v_lshl_add_u64 v[212:213], v[238:239], 0, s[16:17]
	v_lshl_add_u64 v[210:211], v[238:239], 0, s[18:19]
	v_lshl_add_u64 v[208:209], v[238:239], 0, s[38:39]
	v_lshl_add_u64 v[206:207], v[238:239], 0, s[44:45]
	v_lshl_add_u64 v[98:99], v[96:97], 0, v[218:219]
	v_lshl_add_u64 v[108:109], v[96:97], 0, v[216:217]
	v_lshl_add_u64 v[110:111], v[96:97], 0, v[214:215]
	v_lshl_add_u64 v[120:121], v[96:97], 0, v[212:213]
	v_lshl_add_u64 v[122:123], v[96:97], 0, v[210:211]
	v_lshl_add_u64 v[240:241], v[96:97], 0, v[208:209]
	v_lshl_add_u64 v[96:97], v[96:97], 0, v[206:207]
	global_load_dwordx4 v[180:183], v[98:99], off
	global_load_dwordx4 v[176:179], v[98:99], off offset:256
	global_load_dwordx4 v[172:175], v[108:109], off
	global_load_dwordx4 v[168:171], v[108:109], off offset:256
	global_load_dwordx4 v[164:167], v[110:111], off
	global_load_dwordx4 v[160:163], v[110:111], off offset:256
	global_load_dwordx4 v[156:159], v[120:121], off
	global_load_dwordx4 v[152:155], v[120:121], off offset:256
	global_load_dwordx4 v[148:151], v[122:123], off
	global_load_dwordx4 v[144:147], v[122:123], off offset:256
	global_load_dwordx4 v[128:131], v[240:241], off
	s_nop 0
	global_load_dwordx4 v[120:123], v[240:241], off offset:256
	global_load_dwordx4 v[108:111], v[96:97], off
	s_nop 0
	global_load_dwordx4 v[96:99], v[96:97], off offset:256
	s_lshl_b32 s20, s68, 2
	s_or_b32 s20, s20, s58
	s_ashr_i32 s21, s20, 31
	s_lshl_b64 s[20:21], s[20:21], 17
	s_waitcnt vmcnt(0)
	v_lshlrev_b32_e32 v240, 16, v228
	v_and_b32_e32 v241, 0xffff0000, v228
	v_lshlrev_b32_e32 v228, 16, v229
	v_and_b32_e32 v229, 0xffff0000, v229
	v_lshlrev_b32_e32 v242, 16, v230
	v_and_b32_e32 v243, 0xffff0000, v230
	v_lshlrev_b32_e32 v244, 16, v232
	v_and_b32_e32 v245, 0xffff0000, v232
	v_lshlrev_b32_e32 v232, 16, v233
	v_and_b32_e32 v233, 0xffff0000, v233
	v_lshlrev_b32_e32 v246, 16, v234
	v_and_b32_e32 v247, 0xffff0000, v234
	v_lshlrev_b32_e32 v234, 16, v235
	v_and_b32_e32 v235, 0xffff0000, v235
	v_pk_fma_f32 v[142:143], v[142:143], 0.5, v[228:229] op_sel_hi:[1,0,1]
	v_pk_fma_f32 v[140:141], v[140:141], 0.5, v[240:241] op_sel_hi:[1,0,1]
	v_lshlrev_b32_e32 v230, 16, v231
	v_and_b32_e32 v231, 0xffff0000, v231
	v_pk_fma_f32 v[136:137], v[136:137], 0.5, v[242:243] op_sel_hi:[1,0,1]
	v_pk_fma_f32 v[228:229], v[134:135], 0.5, v[232:233] op_sel_hi:[1,0,1]
	v_pk_fma_f32 v[232:233], v[126:127], 0.5, v[234:235] op_sel_hi:[1,0,1]
	v_pk_fma_f32 v[234:235], v[124:125], 0.5, v[246:247] op_sel_hi:[1,0,1]
	v_mul_f32_e32 v124, v141, v141
	v_mul_f32_e32 v125, v143, v143
	v_pk_fma_f32 v[138:139], v[138:139], 0.5, v[230:231] op_sel_hi:[1,0,1]
	v_pk_fma_f32 v[230:231], v[132:133], 0.5, v[244:245] op_sel_hi:[1,0,1]
	v_mul_f32_e32 v126, v137, v137
	v_fmac_f32_e32 v124, v140, v140
	v_fmac_f32_e32 v125, v142, v142
	v_mul_f32_e32 v127, v139, v139
	v_cvt_pk_bf16_f32 v132, v140, v141
	v_cvt_pk_bf16_f32 v133, v142, v143
	v_cvt_pk_bf16_f32 v134, v136, v137
	v_cvt_pk_bf16_f32 v135, v138, v139
	v_mul_f32_e32 v137, v231, v231
	v_mul_f32_e32 v139, v229, v229
	v_fmac_f32_e32 v126, v136, v136
	v_add_f32_e32 v124, v124, v125
	v_fmac_f32_e32 v137, v230, v230
	v_fmac_f32_e32 v139, v228, v228
	v_add_f32_e32 v124, v126, v124
	v_mul_f32_e32 v126, v235, v235
	v_add_f32_e32 v125, v137, v139
	v_fmac_f32_e32 v126, v234, v234
	v_add_f32_e32 v125, v126, v125
	v_mul_f32_e32 v126, v233, v233
	v_fmac_f32_e32 v127, v138, v138
	v_fmac_f32_e32 v126, v232, v232
	v_add_f32_e32 v124, v127, v124
	v_add_f32_e32 v125, v126, v125
	v_and_b32_e32 v126, 64, v226
	v_add_f32_e32 v125, v124, v125
	v_add_u32_e32 v138, 64, v126
	v_lshl_add_u64 v[126:127], s[36:37], 0, v[238:239]
	v_lshl_add_u64 v[136:137], v[126:127], 0, v[236:237]
	v_mov_b32_e32 v139, v125
	s_nop 1
	v_permlane16_swap_b32_e32 v139, v125
	global_store_dwordx4 v[136:137], v[132:135], off nt
	s_waitcnt lgkmcnt(0)
	v_add_f32_e32 v126, v125, v139
	v_cvt_pk_bf16_f32 v132, v230, v231
	v_cvt_pk_bf16_f32 v133, v228, v229
	v_cvt_pk_bf16_f32 v134, v234, v235
	v_cvt_pk_bf16_f32 v135, v232, v233
	global_store_dwordx4 v[136:137], v[132:135], off offset:256 nt
	s_nop 0
	v_mov_b32_e32 v127, v126
	s_nop 1
	v_permlane32_swap_b32_e32 v127, v126
	s_and_saveexec_b64 s[34:35], s[4:5]
	s_cbranch_execz .LBB0_900
	s_add_u32 s48, s56, s20
	s_addc_u32 s49, s57, s21
	v_lshl_add_u64 v[132:133], v[202:203], 2, s[48:49]
	s_waitcnt lgkmcnt(0)
	v_add_f32_e32 v126, v126, v127
	global_store_dword v[132:133], v126, off
; __device__ __forceinline__ unsigned cvt_pk_bf16(float lo, float hi) { unsigned r; asm volatile("v_cvt_pk_bf16_f32 %0, %1, %2" : "=v"(r) : "v"(lo), "v"(hi)); return r; }
;     __device__ __forceinline__ void operator()(const f32x4 (&acc)[2][2][4][2], const pg8::Unit& u, int wr, int wc, int fr, int fq) const {
;     ...
;             for (int m = 0; m < 4; ++m) { const size_t ro = (size_t)(row0 + ai * 128 + m * 16) * D + col0; float sq = 0.f;
; #pragma unroll
;                 for (int bj = 0; bj < 2; ++bj) { const u32x4 xb = xin[ai][m][bj];
;                     const f32x4 x0 = (f32x4){bf_lo(xb.x), bf_hi(xb.x), bf_lo(xb.y), bf_hi(xb.y)} + acc[ai][bj][m][0] * s, x1 = (f32x4){bf_lo(xb.z), bf_hi(xb.z), bf_lo(xb.w), bf_hi(xb.w)} + acc[ai][bj][m][1] * s;
;                     sq += (x0[0] * x0[0] + x0[1] * x0[1]) + (x0[2] * x0[2] + x0[3] * x0[3]) + (x1[0] * x1[0] + x1[1] * x1[1]) + (x1[2] * x1[2] + x1[3] * x1[3]);
;                     u32x4 w; w.x = cvt_pk_bf16(x0[0], x0[1]); w.y = cvt_pk_bf16(x0[2], x0[3]); w.z = cvt_pk_bf16(x1[0], x1[1]); w.w = cvt_pk_bf16(x1[2], x1[3]);
;                     *(u32x4*)(XB + ro + bj * 128) = w; }
;                 sq += __shfl_xor(sq, 16); sq += __shfl_xor(sq, 32);
;                 if (fq == 0) SSo[(size_t)(u.pn * 4 + wc) * T + row0 + ai * 128 + m * 16] = sq; }
.LBB0_900:
	s_or_b64 exec, exec, s[34:35]
	v_lshlrev_b32_e32 v126, 16, v180
	s_waitcnt lgkmcnt(0)
	v_and_b32_e32 v127, 0xffff0000, v180
	v_lshlrev_b32_e32 v132, 16, v181
	v_and_b32_e32 v133, 0xffff0000, v181
	v_pk_fma_f32 v[118:119], v[118:119], 0.5, v[132:133] op_sel_hi:[1,0,1]
	v_pk_fma_f32 v[116:117], v[116:117], 0.5, v[126:127] op_sel_hi:[1,0,1]
	v_lshlrev_b32_e32 v126, 16, v182
	v_and_b32_e32 v127, 0xffff0000, v182
	v_lshlrev_b32_e32 v132, 16, v183
	v_and_b32_e32 v133, 0xffff0000, v183
	v_pk_fma_f32 v[132:133], v[114:115], 0.5, v[132:133] op_sel_hi:[1,0,1]
	v_pk_fma_f32 v[114:115], v[112:113], 0.5, v[126:127] op_sel_hi:[1,0,1]
	v_mul_f32_e32 v112, v117, v117
	v_mul_f32_e32 v113, v119, v119
	v_fmac_f32_e32 v112, v116, v116
	v_fmac_f32_e32 v113, v118, v118
	v_add_f32_e32 v112, v112, v113
	v_mul_f32_e32 v113, v115, v115
	v_fmac_f32_e32 v113, v114, v114
	v_add_f32_e32 v112, v113, v112
	v_mul_f32_e32 v113, v133, v133
	v_fmac_f32_e32 v113, v132, v132
	v_add_f32_e32 v126, v113, v112
	v_cvt_pk_bf16_f32 v112, v116, v117
	v_cvt_pk_bf16_f32 v113, v118, v119
	v_lshlrev_b32_e32 v116, 16, v176
	v_and_b32_e32 v117, 0xffff0000, v176
	v_lshlrev_b32_e32 v118, 16, v177
	v_and_b32_e32 v119, 0xffff0000, v177
	v_pk_fma_f32 v[106:107], v[106:107], 0.5, v[118:119] op_sel_hi:[1,0,1]
	v_pk_fma_f32 v[104:105], v[104:105], 0.5, v[116:117] op_sel_hi:[1,0,1]
	v_lshlrev_b32_e32 v116, 16, v178
	v_and_b32_e32 v117, 0xffff0000, v178
	v_pk_fma_f32 v[116:117], v[100:101], 0.5, v[116:117] op_sel_hi:[1,0,1]
	v_mul_f32_e32 v100, v105, v105
	v_mul_f32_e32 v101, v107, v107
	v_fmac_f32_e32 v100, v104, v104
	v_fmac_f32_e32 v101, v106, v106
	v_lshlrev_b32_e32 v118, 16, v179
	v_and_b32_e32 v119, 0xffff0000, v179
	v_add_f32_e32 v100, v100, v101
	v_mul_f32_e32 v101, v117, v117
	v_pk_fma_f32 v[118:119], v[102:103], 0.5, v[118:119] op_sel_hi:[1,0,1]
	v_fmac_f32_e32 v101, v116, v116
	v_add_f32_e32 v100, v101, v100
	v_mul_f32_e32 v101, v119, v119
	v_fmac_f32_e32 v101, v118, v118
	v_add_f32_e32 v100, v101, v100
	v_add_f32_e32 v103, v126, v100
	v_cvt_pk_bf16_f32 v114, v114, v115
	v_cvt_pk_bf16_f32 v115, v132, v133
	v_mov_b32_e32 v132, v103
	s_nop 1
	v_permlane16_swap_b32_e32 v132, v103
	v_lshl_add_u64 v[100:101], s[36:37], 0, v[218:219]
	v_lshl_add_u64 v[126:127], v[204:205], 1, v[100:101]
	global_store_dwordx4 v[126:127], v[112:115], off nt
	v_cvt_pk_bf16_f32 v102, v104, v105
	s_waitcnt lgkmcnt(0)
	v_add_f32_e32 v100, v103, v132
	v_mov_b32_e32 v101, v100
	s_nop 1
	v_permlane32_swap_b32_e32 v101, v100
	v_cvt_pk_bf16_f32 v103, v106, v107
	v_cvt_pk_bf16_f32 v104, v116, v117
	v_cvt_pk_bf16_f32 v105, v118, v119
	global_store_dwordx4 v[126:127], v[102:105], off offset:256 nt
	s_and_saveexec_b64 s[34:35], s[4:5]
	s_cbranch_execz .LBB0_902
	s_add_u32 s48, s56, s20
	s_addc_u32 s49, s57, s21
	v_lshl_add_u64 v[102:103], v[202:203], 2, s[48:49]
	s_waitcnt lgkmcnt(0)
	v_add_f32_e32 v100, v100, v101
	global_store_dword v[102:103], v100, off offset:64
.LBB0_902:
	s_or_b64 exec, exec, s[34:35]
	v_lshlrev_b32_e32 v100, 16, v172
	s_waitcnt lgkmcnt(0)
	v_and_b32_e32 v101, 0xffff0000, v172
	v_lshlrev_b32_e32 v102, 16, v173
	v_and_b32_e32 v103, 0xffff0000, v173
	v_pk_fma_f32 v[94:95], v[94:95], 0.5, v[102:103] op_sel_hi:[1,0,1]
	v_pk_fma_f32 v[92:93], v[92:93], 0.5, v[100:101] op_sel_hi:[1,0,1]
	v_lshlrev_b32_e32 v100, 16, v174
	v_and_b32_e32 v101, 0xffff0000, v174
	v_lshlrev_b32_e32 v102, 16, v175
	v_and_b32_e32 v103, 0xffff0000, v175
	v_pk_fma_f32 v[102:103], v[90:91], 0.5, v[102:103] op_sel_hi:[1,0,1]
	v_pk_fma_f32 v[90:91], v[88:89], 0.5, v[100:101] op_sel_hi:[1,0,1]
	v_mul_f32_e32 v88, v93, v93
	v_mul_f32_e32 v89, v95, v95
	v_fmac_f32_e32 v88, v92, v92
	v_fmac_f32_e32 v89, v94, v94
	v_add_f32_e32 v88, v88, v89
	v_mul_f32_e32 v89, v91, v91
	v_fmac_f32_e32 v89, v90, v90
	v_add_f32_e32 v88, v89, v88
	v_mul_f32_e32 v89, v103, v103
	v_fmac_f32_e32 v89, v102, v102
	v_add_f32_e32 v100, v89, v88
	v_cvt_pk_bf16_f32 v88, v92, v93
	v_cvt_pk_bf16_f32 v89, v94, v95
	v_lshlrev_b32_e32 v92, 16, v168
	v_and_b32_e32 v93, 0xffff0000, v168
	v_lshlrev_b32_e32 v94, 16, v169
	v_and_b32_e32 v95, 0xffff0000, v169
	v_pk_fma_f32 v[86:87], v[86:87], 0.5, v[94:95] op_sel_hi:[1,0,1]
	v_pk_fma_f32 v[84:85], v[84:85], 0.5, v[92:93] op_sel_hi:[1,0,1]
	v_lshlrev_b32_e32 v92, 16, v170
	v_and_b32_e32 v93, 0xffff0000, v170
	v_pk_fma_f32 v[92:93], v[80:81], 0.5, v[92:93] op_sel_hi:[1,0,1]
	v_mul_f32_e32 v80, v85, v85
	v_mul_f32_e32 v81, v87, v87
	v_fmac_f32_e32 v80, v84, v84
	v_fmac_f32_e32 v81, v86, v86
	v_lshlrev_b32_e32 v94, 16, v171
	v_and_b32_e32 v95, 0xffff0000, v171
	v_add_f32_e32 v80, v80, v81
	v_mul_f32_e32 v81, v93, v93
	v_pk_fma_f32 v[94:95], v[82:83], 0.5, v[94:95] op_sel_hi:[1,0,1]
	v_fmac_f32_e32 v81, v92, v92
	v_add_f32_e32 v80, v81, v80
	v_mul_f32_e32 v81, v95, v95
	v_fmac_f32_e32 v81, v94, v94
	v_add_f32_e32 v80, v81, v80
	v_add_f32_e32 v83, v100, v80
	v_cvt_pk_bf16_f32 v90, v90, v91
	v_cvt_pk_bf16_f32 v91, v102, v103
	v_mov_b32_e32 v102, v83
	s_nop 1
	v_permlane16_swap_b32_e32 v102, v83
	v_lshl_add_u64 v[80:81], s[36:37], 0, v[216:217]
	v_lshl_add_u64 v[100:101], v[204:205], 1, v[80:81]
	global_store_dwordx4 v[100:101], v[88:91], off nt
	v_cvt_pk_bf16_f32 v82, v84, v85
	s_waitcnt lgkmcnt(0)
	v_add_f32_e32 v80, v83, v102
	v_mov_b32_e32 v81, v80
	s_nop 1
	v_permlane32_swap_b32_e32 v81, v80
	v_cvt_pk_bf16_f32 v83, v86, v87
	v_cvt_pk_bf16_f32 v84, v92, v93
	v_cvt_pk_bf16_f32 v85, v94, v95
	global_store_dwordx4 v[100:101], v[82:85], off offset:256 nt
	s_and_saveexec_b64 s[34:35], s[4:5]
	s_cbranch_execz .LBB0_904
	s_add_u32 s48, s56, s20
	s_addc_u32 s49, s57, s21
	v_lshl_add_u64 v[82:83], v[202:203], 2, s[48:49]
	s_waitcnt lgkmcnt(0)
	v_add_f32_e32 v80, v80, v81
	global_store_dword v[82:83], v80, off offset:128
; __device__ __forceinline__ unsigned cvt_pk_bf16(float lo, float hi) { unsigned r; asm volatile("v_cvt_pk_bf16_f32 %0, %1, %2" : "=v"(r) : "v"(lo), "v"(hi)); return r; }
;     __device__ __forceinline__ void operator()(const f32x4 (&acc)[2][2][4][2], const pg8::Unit& u, int wr, int wc, int fr, int fq) const {
;     ...
;             for (int m = 0; m < 4; ++m) { const size_t ro = (size_t)(row0 + ai * 128 + m * 16) * D + col0; float sq = 0.f;
; #pragma unroll
;                 for (int bj = 0; bj < 2; ++bj) { const u32x4 xb = xin[ai][m][bj];
;                     const f32x4 x0 = (f32x4){bf_lo(xb.x), bf_hi(xb.x), bf_lo(xb.y), bf_hi(xb.y)} + acc[ai][bj][m][0] * s, x1 = (f32x4){bf_lo(xb.z), bf_hi(xb.z), bf_lo(xb.w), bf_hi(xb.w)} + acc[ai][bj][m][1] * s;
;                     sq += (x0[0] * x0[0] + x0[1] * x0[1]) + (x0[2] * x0[2] + x0[3] * x0[3]) + (x1[0] * x1[0] + x1[1] * x1[1]) + (x1[2] * x1[2] + x1[3] * x1[3]);
;                     u32x4 w; w.x = cvt_pk_bf16(x0[0], x0[1]); w.y = cvt_pk_bf16(x0[2], x0[3]); w.z = cvt_pk_bf16(x1[0], x1[1]); w.w = cvt_pk_bf16(x1[2], x1[3]);
;                     *(u32x4*)(XB + ro + bj * 128) = w; }
;                 sq += __shfl_xor(sq, 16); sq += __shfl_xor(sq, 32);
;                 if (fq == 0) SSo[(size_t)(u.pn * 4 + wc) * T + row0 + ai * 128 + m * 16] = sq; }
.LBB0_904:
	s_or_b64 exec, exec, s[34:35]
	v_lshlrev_b32_e32 v80, 16, v164
	s_waitcnt lgkmcnt(0)
	v_and_b32_e32 v81, 0xffff0000, v164
	v_lshlrev_b32_e32 v82, 16, v165
	v_and_b32_e32 v83, 0xffff0000, v165
	v_pk_fma_f32 v[78:79], v[78:79], 0.5, v[82:83] op_sel_hi:[1,0,1]
	v_pk_fma_f32 v[76:77], v[76:77], 0.5, v[80:81] op_sel_hi:[1,0,1]
	v_lshlrev_b32_e32 v80, 16, v166
	v_and_b32_e32 v81, 0xffff0000, v166
	v_lshlrev_b32_e32 v82, 16, v167
	v_and_b32_e32 v83, 0xffff0000, v167
	v_pk_fma_f32 v[82:83], v[74:75], 0.5, v[82:83] op_sel_hi:[1,0,1]
	v_pk_fma_f32 v[74:75], v[72:73], 0.5, v[80:81] op_sel_hi:[1,0,1]
	v_mul_f32_e32 v72, v77, v77
	v_mul_f32_e32 v73, v79, v79
	v_fmac_f32_e32 v72, v76, v76
	v_fmac_f32_e32 v73, v78, v78
	v_add_f32_e32 v72, v72, v73
	v_mul_f32_e32 v73, v75, v75
	v_fmac_f32_e32 v73, v74, v74
	v_add_f32_e32 v72, v73, v72
	v_mul_f32_e32 v73, v83, v83
	v_fmac_f32_e32 v73, v82, v82
	v_add_f32_e32 v80, v73, v72
	v_cvt_pk_bf16_f32 v72, v76, v77
	v_cvt_pk_bf16_f32 v73, v78, v79
	v_lshlrev_b32_e32 v76, 16, v160
	v_and_b32_e32 v77, 0xffff0000, v160
	v_lshlrev_b32_e32 v78, 16, v161
	v_and_b32_e32 v79, 0xffff0000, v161
	v_pk_fma_f32 v[70:71], v[70:71], 0.5, v[78:79] op_sel_hi:[1,0,1]
	v_pk_fma_f32 v[68:69], v[68:69], 0.5, v[76:77] op_sel_hi:[1,0,1]
	v_lshlrev_b32_e32 v76, 16, v162
	v_and_b32_e32 v77, 0xffff0000, v162
	v_pk_fma_f32 v[76:77], v[64:65], 0.5, v[76:77] op_sel_hi:[1,0,1]
	v_mul_f32_e32 v64, v69, v69
	v_mul_f32_e32 v65, v71, v71
	v_fmac_f32_e32 v64, v68, v68
	v_fmac_f32_e32 v65, v70, v70
	v_lshlrev_b32_e32 v78, 16, v163
	v_and_b32_e32 v79, 0xffff0000, v163
	v_add_f32_e32 v64, v64, v65
	v_mul_f32_e32 v65, v77, v77
	v_pk_fma_f32 v[78:79], v[66:67], 0.5, v[78:79] op_sel_hi:[1,0,1]
	v_fmac_f32_e32 v65, v76, v76
	v_add_f32_e32 v64, v65, v64
	v_mul_f32_e32 v65, v79, v79
	v_fmac_f32_e32 v65, v78, v78
	v_add_f32_e32 v64, v65, v64
	v_add_f32_e32 v67, v80, v64
	v_cvt_pk_bf16_f32 v74, v74, v75
	v_cvt_pk_bf16_f32 v75, v82, v83
	v_mov_b32_e32 v82, v67
	s_nop 1
	v_permlane16_swap_b32_e32 v82, v67
	v_lshl_add_u64 v[64:65], s[36:37], 0, v[214:215]
	v_lshl_add_u64 v[80:81], v[204:205], 1, v[64:65]
	global_store_dwordx4 v[80:81], v[72:75], off nt
	v_cvt_pk_bf16_f32 v66, v68, v69
	s_waitcnt lgkmcnt(0)
	v_add_f32_e32 v64, v67, v82
	v_mov_b32_e32 v65, v64
	s_nop 1
	v_permlane32_swap_b32_e32 v65, v64
	v_cvt_pk_bf16_f32 v67, v70, v71
	v_cvt_pk_bf16_f32 v68, v76, v77
	v_cvt_pk_bf16_f32 v69, v78, v79
	global_store_dwordx4 v[80:81], v[66:69], off offset:256 nt
	s_and_saveexec_b64 s[34:35], s[4:5]
	s_cbranch_execz .LBB0_906
	s_add_u32 s48, s56, s20
	s_addc_u32 s49, s57, s21
	v_lshl_add_u64 v[66:67], v[202:203], 2, s[48:49]
	s_waitcnt lgkmcnt(0)
	v_add_f32_e32 v64, v64, v65
	global_store_dword v[66:67], v64, off offset:192
.LBB0_906:
	s_or_b64 exec, exec, s[34:35]
	v_lshlrev_b32_e32 v64, 16, v156
	s_waitcnt lgkmcnt(0)
	v_and_b32_e32 v65, 0xffff0000, v156
	v_lshlrev_b32_e32 v66, 16, v157
	v_and_b32_e32 v67, 0xffff0000, v157
	v_pk_fma_f32 v[62:63], v[62:63], 0.5, v[66:67] op_sel_hi:[1,0,1]
	v_pk_fma_f32 v[60:61], v[60:61], 0.5, v[64:65] op_sel_hi:[1,0,1]
	v_lshlrev_b32_e32 v64, 16, v158
	v_and_b32_e32 v65, 0xffff0000, v158
	v_lshlrev_b32_e32 v66, 16, v159
	v_and_b32_e32 v67, 0xffff0000, v159
	v_pk_fma_f32 v[66:67], v[58:59], 0.5, v[66:67] op_sel_hi:[1,0,1]
	v_pk_fma_f32 v[58:59], v[56:57], 0.5, v[64:65] op_sel_hi:[1,0,1]
	v_mul_f32_e32 v56, v61, v61
	v_mul_f32_e32 v57, v63, v63
	v_fmac_f32_e32 v56, v60, v60
	v_fmac_f32_e32 v57, v62, v62
	v_add_f32_e32 v56, v56, v57
	v_mul_f32_e32 v57, v59, v59
	v_fmac_f32_e32 v57, v58, v58
	v_add_f32_e32 v56, v57, v56
	v_mul_f32_e32 v57, v67, v67
	v_fmac_f32_e32 v57, v66, v66
	v_add_f32_e32 v64, v57, v56
	v_cvt_pk_bf16_f32 v56, v60, v61
	v_cvt_pk_bf16_f32 v57, v62, v63
	v_lshlrev_b32_e32 v60, 16, v152
	v_and_b32_e32 v61, 0xffff0000, v152
	v_lshlrev_b32_e32 v62, 16, v153
	v_and_b32_e32 v63, 0xffff0000, v153
	v_pk_fma_f32 v[54:55], v[54:55], 0.5, v[62:63] op_sel_hi:[1,0,1]
	v_pk_fma_f32 v[52:53], v[52:53], 0.5, v[60:61] op_sel_hi:[1,0,1]
	v_lshlrev_b32_e32 v60, 16, v154
	v_and_b32_e32 v61, 0xffff0000, v154
	v_pk_fma_f32 v[60:61], v[48:49], 0.5, v[60:61] op_sel_hi:[1,0,1]
	v_mul_f32_e32 v48, v53, v53
	v_mul_f32_e32 v49, v55, v55
	v_fmac_f32_e32 v48, v52, v52
	v_fmac_f32_e32 v49, v54, v54
	v_lshlrev_b32_e32 v62, 16, v155
	v_and_b32_e32 v63, 0xffff0000, v155
	v_add_f32_e32 v48, v48, v49
	v_mul_f32_e32 v49, v61, v61
	v_pk_fma_f32 v[62:63], v[50:51], 0.5, v[62:63] op_sel_hi:[1,0,1]
	v_fmac_f32_e32 v49, v60, v60
	v_add_f32_e32 v48, v49, v48
	v_mul_f32_e32 v49, v63, v63
	v_fmac_f32_e32 v49, v62, v62
	v_add_f32_e32 v48, v49, v48
	v_add_f32_e32 v51, v64, v48
	v_cvt_pk_bf16_f32 v58, v58, v59
	v_cvt_pk_bf16_f32 v59, v66, v67
	v_mov_b32_e32 v66, v51
	s_nop 1
	v_permlane16_swap_b32_e32 v66, v51
	v_lshl_add_u64 v[48:49], s[36:37], 0, v[212:213]
	v_lshl_add_u64 v[64:65], v[204:205], 1, v[48:49]
	global_store_dwordx4 v[64:65], v[56:59], off nt
	v_cvt_pk_bf16_f32 v50, v52, v53
	s_waitcnt lgkmcnt(0)
	v_add_f32_e32 v48, v51, v66
	v_mov_b32_e32 v49, v48
	s_nop 1
	v_permlane32_swap_b32_e32 v49, v48
	v_cvt_pk_bf16_f32 v51, v54, v55
	v_cvt_pk_bf16_f32 v52, v60, v61
	v_cvt_pk_bf16_f32 v53, v62, v63
	global_store_dwordx4 v[64:65], v[50:53], off offset:256 nt
	s_and_saveexec_b64 s[34:35], s[4:5]
	s_cbranch_execz .LBB0_908
	s_add_u32 s48, s56, s20
	s_addc_u32 s49, s57, s21
	v_lshl_add_u64 v[50:51], v[202:203], 2, s[48:49]
	s_waitcnt lgkmcnt(0)
	v_add_f32_e32 v48, v48, v49
	global_store_dword v[50:51], v48, off offset:512
; __device__ __forceinline__ unsigned cvt_pk_bf16(float lo, float hi) { unsigned r; asm volatile("v_cvt_pk_bf16_f32 %0, %1, %2" : "=v"(r) : "v"(lo), "v"(hi)); return r; }
;     __device__ __forceinline__ void operator()(const f32x4 (&acc)[2][2][4][2], const pg8::Unit& u, int wr, int wc, int fr, int fq) const {
;     ...
;             for (int m = 0; m < 4; ++m) { const size_t ro = (size_t)(row0 + ai * 128 + m * 16) * D + col0; float sq = 0.f;
; #pragma unroll
;                 for (int bj = 0; bj < 2; ++bj) { const u32x4 xb = xin[ai][m][bj];
;                     const f32x4 x0 = (f32x4){bf_lo(xb.x), bf_hi(xb.x), bf_lo(xb.y), bf_hi(xb.y)} + acc[ai][bj][m][0] * s, x1 = (f32x4){bf_lo(xb.z), bf_hi(xb.z), bf_lo(xb.w), bf_hi(xb.w)} + acc[ai][bj][m][1] * s;
;                     sq += (x0[0] * x0[0] + x0[1] * x0[1]) + (x0[2] * x0[2] + x0[3] * x0[3]) + (x1[0] * x1[0] + x1[1] * x1[1]) + (x1[2] * x1[2] + x1[3] * x1[3]);
;                     u32x4 w; w.x = cvt_pk_bf16(x0[0], x0[1]); w.y = cvt_pk_bf16(x0[2], x0[3]); w.z = cvt_pk_bf16(x1[0], x1[1]); w.w = cvt_pk_bf16(x1[2], x1[3]);
;                     *(u32x4*)(XB + ro + bj * 128) = w; }
;                 sq += __shfl_xor(sq, 16); sq += __shfl_xor(sq, 32);
;                 if (fq == 0) SSo[(size_t)(u.pn * 4 + wc) * T + row0 + ai * 128 + m * 16] = sq; }
.LBB0_908:
	s_or_b64 exec, exec, s[34:35]
	v_lshlrev_b32_e32 v48, 16, v148
	s_waitcnt lgkmcnt(0)
	v_and_b32_e32 v49, 0xffff0000, v148
	v_lshlrev_b32_e32 v50, 16, v149
	v_and_b32_e32 v51, 0xffff0000, v149
	v_pk_fma_f32 v[46:47], v[46:47], 0.5, v[50:51] op_sel_hi:[1,0,1]
	v_pk_fma_f32 v[44:45], v[44:45], 0.5, v[48:49] op_sel_hi:[1,0,1]
	v_lshlrev_b32_e32 v48, 16, v150
	v_and_b32_e32 v49, 0xffff0000, v150
	v_lshlrev_b32_e32 v50, 16, v151
	v_and_b32_e32 v51, 0xffff0000, v151
	v_pk_fma_f32 v[50:51], v[42:43], 0.5, v[50:51] op_sel_hi:[1,0,1]
	v_pk_fma_f32 v[42:43], v[40:41], 0.5, v[48:49] op_sel_hi:[1,0,1]
	v_mul_f32_e32 v40, v45, v45
	v_mul_f32_e32 v41, v47, v47
	v_fmac_f32_e32 v40, v44, v44
	v_fmac_f32_e32 v41, v46, v46
	v_add_f32_e32 v40, v40, v41
	v_mul_f32_e32 v41, v43, v43
	v_fmac_f32_e32 v41, v42, v42
	v_add_f32_e32 v40, v41, v40
	v_mul_f32_e32 v41, v51, v51
	v_fmac_f32_e32 v41, v50, v50
	v_add_f32_e32 v48, v41, v40
	v_cvt_pk_bf16_f32 v40, v44, v45
	v_cvt_pk_bf16_f32 v41, v46, v47
	v_lshlrev_b32_e32 v44, 16, v144
	v_and_b32_e32 v45, 0xffff0000, v144
	v_lshlrev_b32_e32 v46, 16, v145
	v_and_b32_e32 v47, 0xffff0000, v145
	v_pk_fma_f32 v[38:39], v[38:39], 0.5, v[46:47] op_sel_hi:[1,0,1]
	v_pk_fma_f32 v[36:37], v[36:37], 0.5, v[44:45] op_sel_hi:[1,0,1]
	v_lshlrev_b32_e32 v44, 16, v146
	v_and_b32_e32 v45, 0xffff0000, v146
	v_pk_fma_f32 v[44:45], v[32:33], 0.5, v[44:45] op_sel_hi:[1,0,1]
	v_mul_f32_e32 v32, v37, v37
	v_mul_f32_e32 v33, v39, v39
	v_fmac_f32_e32 v32, v36, v36
	v_fmac_f32_e32 v33, v38, v38
	v_lshlrev_b32_e32 v46, 16, v147
	v_and_b32_e32 v47, 0xffff0000, v147
	v_add_f32_e32 v32, v32, v33
	v_mul_f32_e32 v33, v45, v45
	v_pk_fma_f32 v[46:47], v[34:35], 0.5, v[46:47] op_sel_hi:[1,0,1]
	v_fmac_f32_e32 v33, v44, v44
	v_add_f32_e32 v32, v33, v32
	v_mul_f32_e32 v33, v47, v47
	v_fmac_f32_e32 v33, v46, v46
	v_add_f32_e32 v32, v33, v32
	v_add_f32_e32 v35, v48, v32
	v_cvt_pk_bf16_f32 v42, v42, v43
	v_cvt_pk_bf16_f32 v43, v50, v51
	v_mov_b32_e32 v50, v35
	s_nop 1
	v_permlane16_swap_b32_e32 v50, v35
	v_lshl_add_u64 v[32:33], s[36:37], 0, v[210:211]
	v_lshl_add_u64 v[48:49], v[204:205], 1, v[32:33]
	global_store_dwordx4 v[48:49], v[40:43], off nt
	v_cvt_pk_bf16_f32 v34, v36, v37
	s_waitcnt lgkmcnt(0)
	v_add_f32_e32 v32, v35, v50
	v_mov_b32_e32 v33, v32
	s_nop 1
	v_permlane32_swap_b32_e32 v33, v32
	v_cvt_pk_bf16_f32 v35, v38, v39
	v_cvt_pk_bf16_f32 v36, v44, v45
	v_cvt_pk_bf16_f32 v37, v46, v47
	global_store_dwordx4 v[48:49], v[34:37], off offset:256 nt
	s_and_saveexec_b64 s[34:35], s[4:5]
	s_cbranch_execz .LBB0_910
	s_add_u32 s48, s56, s20
	s_addc_u32 s49, s57, s21
	v_lshl_add_u64 v[34:35], v[202:203], 2, s[48:49]
	s_waitcnt lgkmcnt(0)
	v_add_f32_e32 v32, v32, v33
	global_store_dword v[34:35], v32, off offset:576
; __device__ __forceinline__ unsigned cvt_pk_bf16(float lo, float hi) { unsigned r; asm volatile("v_cvt_pk_bf16_f32 %0, %1, %2" : "=v"(r) : "v"(lo), "v"(hi)); return r; }
;     __device__ __forceinline__ void operator()(const f32x4 (&acc)[2][2][4][2], const pg8::Unit& u, int wr, int wc, int fr, int fq) const {
;     ...
;             for (int m = 0; m < 4; ++m) { const size_t ro = (size_t)(row0 + ai * 128 + m * 16) * D + col0; float sq = 0.f;
; #pragma unroll
;                 for (int bj = 0; bj < 2; ++bj) { const u32x4 xb = xin[ai][m][bj];
;                     const f32x4 x0 = (f32x4){bf_lo(xb.x), bf_hi(xb.x), bf_lo(xb.y), bf_hi(xb.y)} + acc[ai][bj][m][0] * s, x1 = (f32x4){bf_lo(xb.z), bf_hi(xb.z), bf_lo(xb.w), bf_hi(xb.w)} + acc[ai][bj][m][1] * s;
;                     sq += (x0[0] * x0[0] + x0[1] * x0[1]) + (x0[2] * x0[2] + x0[3] * x0[3]) + (x1[0] * x1[0] + x1[1] * x1[1]) + (x1[2] * x1[2] + x1[3] * x1[3]);
;                     u32x4 w; w.x = cvt_pk_bf16(x0[0], x0[1]); w.y = cvt_pk_bf16(x0[2], x0[3]); w.z = cvt_pk_bf16(x1[0], x1[1]); w.w = cvt_pk_bf16(x1[2], x1[3]);
;                     *(u32x4*)(XB + ro + bj * 128) = w; }
;                 sq += __shfl_xor(sq, 16); sq += __shfl_xor(sq, 32);
;                 if (fq == 0) SSo[(size_t)(u.pn * 4 + wc) * T + row0 + ai * 128 + m * 16] = sq; }
.LBB0_910:
	s_or_b64 exec, exec, s[34:35]
	v_lshlrev_b32_e32 v32, 16, v128
	s_waitcnt lgkmcnt(0)
	v_and_b32_e32 v33, 0xffff0000, v128
	v_lshlrev_b32_e32 v34, 16, v129
	v_and_b32_e32 v35, 0xffff0000, v129
	v_pk_fma_f32 v[30:31], v[30:31], 0.5, v[34:35] op_sel_hi:[1,0,1]
	v_pk_fma_f32 v[28:29], v[28:29], 0.5, v[32:33] op_sel_hi:[1,0,1]
	v_lshlrev_b32_e32 v32, 16, v130
	v_and_b32_e32 v33, 0xffff0000, v130
	v_lshlrev_b32_e32 v34, 16, v131
	v_and_b32_e32 v35, 0xffff0000, v131
	v_pk_fma_f32 v[34:35], v[26:27], 0.5, v[34:35] op_sel_hi:[1,0,1]
	v_pk_fma_f32 v[26:27], v[24:25], 0.5, v[32:33] op_sel_hi:[1,0,1]
	v_mul_f32_e32 v24, v29, v29
	v_mul_f32_e32 v25, v31, v31
	v_fmac_f32_e32 v24, v28, v28
	v_fmac_f32_e32 v25, v30, v30
	v_add_f32_e32 v24, v24, v25
	v_mul_f32_e32 v25, v27, v27
	v_fmac_f32_e32 v25, v26, v26
	v_add_f32_e32 v24, v25, v24
	v_mul_f32_e32 v25, v35, v35
	v_fmac_f32_e32 v25, v34, v34
	v_add_f32_e32 v32, v25, v24
	v_cvt_pk_bf16_f32 v24, v28, v29
	v_cvt_pk_bf16_f32 v25, v30, v31
	v_lshlrev_b32_e32 v28, 16, v120
	v_and_b32_e32 v29, 0xffff0000, v120
	v_lshlrev_b32_e32 v30, 16, v121
	v_and_b32_e32 v31, 0xffff0000, v121
	v_pk_fma_f32 v[22:23], v[22:23], 0.5, v[30:31] op_sel_hi:[1,0,1]
	v_pk_fma_f32 v[20:21], v[20:21], 0.5, v[28:29] op_sel_hi:[1,0,1]
	v_lshlrev_b32_e32 v28, 16, v122
	v_and_b32_e32 v29, 0xffff0000, v122
	v_pk_fma_f32 v[28:29], v[16:17], 0.5, v[28:29] op_sel_hi:[1,0,1]
	v_mul_f32_e32 v16, v21, v21
	v_mul_f32_e32 v17, v23, v23
	v_fmac_f32_e32 v16, v20, v20
	v_fmac_f32_e32 v17, v22, v22
	v_lshlrev_b32_e32 v30, 16, v123
	v_and_b32_e32 v31, 0xffff0000, v123
	v_add_f32_e32 v16, v16, v17
	v_mul_f32_e32 v17, v29, v29
	v_pk_fma_f32 v[30:31], v[18:19], 0.5, v[30:31] op_sel_hi:[1,0,1]
	v_fmac_f32_e32 v17, v28, v28
	v_add_f32_e32 v16, v17, v16
	v_mul_f32_e32 v17, v31, v31
	v_fmac_f32_e32 v17, v30, v30
	v_add_f32_e32 v16, v17, v16
	v_add_f32_e32 v19, v32, v16
	v_cvt_pk_bf16_f32 v26, v26, v27
	v_cvt_pk_bf16_f32 v27, v34, v35
	v_mov_b32_e32 v34, v19
	s_nop 1
	v_permlane16_swap_b32_e32 v34, v19
	v_lshl_add_u64 v[16:17], s[36:37], 0, v[208:209]
	v_lshl_add_u64 v[32:33], v[204:205], 1, v[16:17]
	global_store_dwordx4 v[32:33], v[24:27], off nt
	v_cvt_pk_bf16_f32 v18, v20, v21
	s_waitcnt lgkmcnt(0)
	v_add_f32_e32 v16, v19, v34
	v_mov_b32_e32 v17, v16
	s_nop 1
	v_permlane32_swap_b32_e32 v17, v16
	v_cvt_pk_bf16_f32 v19, v22, v23
	v_cvt_pk_bf16_f32 v20, v28, v29
	v_cvt_pk_bf16_f32 v21, v30, v31
	global_store_dwordx4 v[32:33], v[18:21], off offset:256 nt
	s_and_saveexec_b64 s[34:35], s[4:5]
	s_cbranch_execz .LBB0_912
	s_add_u32 s48, s56, s20
	s_addc_u32 s49, s57, s21
	v_lshl_add_u64 v[18:19], v[202:203], 2, s[48:49]
	s_waitcnt lgkmcnt(0)
	v_add_f32_e32 v16, v16, v17
	global_store_dword v[18:19], v16, off offset:640
.LBB0_912:
	s_or_b64 exec, exec, s[34:35]
	v_lshlrev_b32_e32 v16, 16, v108
	s_waitcnt lgkmcnt(0)
	v_and_b32_e32 v17, 0xffff0000, v108
	v_lshlrev_b32_e32 v18, 16, v109
	v_and_b32_e32 v19, 0xffff0000, v109
	v_pk_fma_f32 v[14:15], v[14:15], 0.5, v[18:19] op_sel_hi:[1,0,1]
	v_pk_fma_f32 v[12:13], v[12:13], 0.5, v[16:17] op_sel_hi:[1,0,1]
	v_lshlrev_b32_e32 v16, 16, v110
	v_and_b32_e32 v17, 0xffff0000, v110
	v_lshlrev_b32_e32 v18, 16, v111
	v_and_b32_e32 v19, 0xffff0000, v111
	v_pk_fma_f32 v[18:19], v[10:11], 0.5, v[18:19] op_sel_hi:[1,0,1]
	v_pk_fma_f32 v[10:11], v[8:9], 0.5, v[16:17] op_sel_hi:[1,0,1]
	v_mul_f32_e32 v8, v13, v13
	v_mul_f32_e32 v9, v15, v15
	v_fmac_f32_e32 v8, v12, v12
	v_fmac_f32_e32 v9, v14, v14
	v_add_f32_e32 v8, v8, v9
	v_mul_f32_e32 v9, v11, v11
	v_fmac_f32_e32 v9, v10, v10
	v_add_f32_e32 v8, v9, v8
	v_mul_f32_e32 v9, v19, v19
	v_fmac_f32_e32 v9, v18, v18
	v_add_f32_e32 v16, v9, v8
	v_cvt_pk_bf16_f32 v8, v12, v13
	v_cvt_pk_bf16_f32 v9, v14, v15
	v_lshlrev_b32_e32 v12, 16, v96
	v_and_b32_e32 v13, 0xffff0000, v96
	v_lshlrev_b32_e32 v14, 16, v97
	v_and_b32_e32 v15, 0xffff0000, v97
	v_pk_fma_f32 v[6:7], v[6:7], 0.5, v[14:15] op_sel_hi:[1,0,1]
	v_pk_fma_f32 v[4:5], v[4:5], 0.5, v[12:13] op_sel_hi:[1,0,1]
	v_lshlrev_b32_e32 v12, 16, v98
	v_and_b32_e32 v13, 0xffff0000, v98
	v_pk_fma_f32 v[12:13], v[0:1], 0.5, v[12:13] op_sel_hi:[1,0,1]
	v_mul_f32_e32 v0, v5, v5
	v_mul_f32_e32 v1, v7, v7
	v_fmac_f32_e32 v0, v4, v4
	v_fmac_f32_e32 v1, v6, v6
	v_lshlrev_b32_e32 v14, 16, v99
	v_and_b32_e32 v15, 0xffff0000, v99
	v_add_f32_e32 v0, v0, v1
	v_mul_f32_e32 v1, v13, v13
	v_pk_fma_f32 v[14:15], v[2:3], 0.5, v[14:15] op_sel_hi:[1,0,1]
	v_fmac_f32_e32 v1, v12, v12
	v_add_f32_e32 v0, v1, v0
	v_mul_f32_e32 v1, v15, v15
	v_fmac_f32_e32 v1, v14, v14
	v_add_f32_e32 v0, v1, v0
	v_add_f32_e32 v3, v16, v0
	v_cvt_pk_bf16_f32 v10, v10, v11
	v_cvt_pk_bf16_f32 v11, v18, v19
	v_mov_b32_e32 v18, v3
	s_nop 1
	v_permlane16_swap_b32_e32 v18, v3
	v_lshl_add_u64 v[0:1], s[36:37], 0, v[206:207]
	v_lshl_add_u64 v[16:17], v[204:205], 1, v[0:1]
	global_store_dwordx4 v[16:17], v[8:11], off nt
	v_cvt_pk_bf16_f32 v2, v4, v5
	s_waitcnt lgkmcnt(0)
	v_add_f32_e32 v0, v3, v18
	v_mov_b32_e32 v1, v0
	s_nop 1
	v_permlane32_swap_b32_e32 v1, v0
	v_cvt_pk_bf16_f32 v3, v6, v7
	v_cvt_pk_bf16_f32 v4, v12, v13
	v_cvt_pk_bf16_f32 v5, v14, v15
	global_store_dwordx4 v[16:17], v[2:5], off offset:256 nt
	s_and_saveexec_b64 s[34:35], s[4:5]
	s_cbranch_execz .LBB0_914
	s_add_u32 s20, s56, s20
	s_addc_u32 s21, s57, s21
	v_lshl_add_u64 v[2:3], v[202:203], 2, s[20:21]
	s_waitcnt lgkmcnt(0)
	v_add_f32_e32 v0, v0, v1
	global_store_dword v[2:3], v0, off offset:704

; __device__ __forceinline__ unsigned cvt_pk_bf16(float lo, float hi) { unsigned r; asm volatile("v_cvt_pk_bf16_f32 %0, %1, %2" : "=v"(r) : "v"(lo), "v"(hi)); return r; }
; #define LAS __attribute__((address_space(3)))
;     __device__ __forceinline__ void operator()(const f32x4 (&acc)[2][2][4][2], const pg8::Unit& u, int wr, int wc, int fr, int fq) const {
;         const int row0 = u.pm * 256 + wr * 64 + fr, col0 = u.pn * 256 + wc * 32 + 8 * fq; const float s = (u.pn < nscaled) ? sc : 1.f; const LAS float* rt = rt_.of(u.pm) + wr * 64 + fr;
;         f32x4 cs[2][2];
; #pragma unroll
;         for (int bj = 0; bj < 2; ++bj)
; #pragma unroll
;             for (int n = 0; n < 2; ++n) cs[bj][n] = (f32x4){0.f, 0.f, 0.f, 0.f};
; #pragma unroll
;         for (int ai = 0; ai < 2; ++ai)
; #pragma unroll
;             for (int m = 0; m < 4; ++m) { bf16_t* rowp = O + (size_t)(row0 + ai * 128 + m * 16) * ldc + col0; const float r = s * rt[ai * 128 + m * 16];
; #pragma unroll
;                 for (int bj = 0; bj < 2; ++bj) { const f32x4 v0 = acc[ai][bj][m][0] * r, v1 = acc[ai][bj][m][1] * r; cs[bj][0] += v0; cs[bj][1] += v1;
;                     u32x4 w; w.x = cvt_pk_bf16(v0[0], v0[1]); w.y = cvt_pk_bf16(v0[2], v0[3]); w.z = cvt_pk_bf16(v1[0], v1[1]); w.w = cvt_pk_bf16(v1[2], v1[3]);
;                     *(u32x4*)(rowp + bj * 128) = w; } }
.LBB0_1203:
	s_lshl_b32 s34, s0, 8
	s_cmp_lt_i32 s0, 4
	s_cselect_b64 vcc, -1, 0
	s_cmp_eq_u32 s14, s66
	s_cselect_b32 s0, s79, 0x300
	s_cmp_lg_u32 s14, s67
	s_cselect_b32 s0, s0, 0x100
	s_cmp_lg_u32 s14, s65
	s_cselect_b32 s0, s0, 0
	v_lshl_add_u32 v179, s0, 2, v162
	ds_read_b32 v128, v179
	v_lshl_add_u32 v172, s14, 8, v158
	v_or_b32_e32 v140, s34, v130
	v_ashrrev_i32_e32 v173, 31, v172
	v_cndmask_b32_e32 v178, 1.0, v166, vcc
	v_ashrrev_i32_e32 v141, 31, v140
	v_lshlrev_b64 v[142:143], 12, v[172:173]
	v_lshl_add_u64 v[142:143], s[40:41], 0, v[142:143]
	v_lshlrev_b64 v[174:175], 1, v[140:141]
	s_waitcnt lgkmcnt(0)
	v_mul_f32_e32 v128, v178, v128
	v_lshl_add_u64 v[142:143], v[142:143], 0, v[174:175]
	v_pk_mul_f32 v[126:127], v[126:127], v[128:129] op_sel_hi:[1,0]
	v_pk_mul_f32 v[124:125], v[124:125], v[128:129] op_sel_hi:[1,0]
	v_pk_mul_f32 v[122:123], v[122:123], v[128:129] op_sel_hi:[1,0]
	v_pk_mul_f32 v[120:121], v[120:121], v[128:129] op_sel_hi:[1,0]
	v_cvt_pk_bf16_f32 v168, v124, v125
	v_cvt_pk_bf16_f32 v169, v126, v127
	v_pk_mul_f32 v[118:119], v[118:119], v[128:129] op_sel_hi:[1,0]
	v_cvt_pk_bf16_f32 v170, v120, v121
	v_cvt_pk_bf16_f32 v171, v122, v123
	global_store_dwordx4 v[142:143], v[168:171], off nt
	v_pk_mul_f32 v[116:117], v[116:117], v[128:129] op_sel_hi:[1,0]
	v_pk_mul_f32 v[114:115], v[114:115], v[128:129] op_sel_hi:[1,0]
	v_pk_mul_f32 v[112:113], v[112:113], v[128:129] op_sel_hi:[1,0]
	v_cvt_pk_bf16_f32 v168, v116, v117
	v_cvt_pk_bf16_f32 v169, v118, v119
	s_nop 0
	v_cvt_pk_bf16_f32 v170, v112, v113
	v_cvt_pk_bf16_f32 v171, v114, v115
	ds_read_b32 v128, v179 offset:64
	global_store_dwordx4 v[142:143], v[168:171], off offset:256 nt
	s_waitcnt lgkmcnt(0)
	v_mul_f32_e32 v128, v178, v128
	v_or_b32_e32 v168, 16, v172
	v_ashrrev_i32_e32 v169, 31, v168
	v_lshlrev_b64 v[168:169], 12, v[168:169]
	v_lshl_add_u64 v[168:169], s[40:41], 0, v[168:169]
	v_lshl_add_u64 v[176:177], v[168:169], 0, v[174:175]
	v_pk_mul_f32 v[110:111], v[110:111], v[128:129] op_sel_hi:[1,0]
	v_pk_mul_f32 v[108:109], v[108:109], v[128:129] op_sel_hi:[1,0]
	v_pk_mul_f32 v[106:107], v[106:107], v[128:129] op_sel_hi:[1,0]
	v_pk_mul_f32 v[104:105], v[104:105], v[128:129] op_sel_hi:[1,0]
	v_cvt_pk_bf16_f32 v168, v108, v109
	v_cvt_pk_bf16_f32 v169, v110, v111
	v_pk_mul_f32 v[102:103], v[102:103], v[128:129] op_sel_hi:[1,0]
	v_cvt_pk_bf16_f32 v170, v104, v105
	v_cvt_pk_bf16_f32 v171, v106, v107
	global_store_dwordx4 v[176:177], v[168:171], off nt
	v_pk_mul_f32 v[100:101], v[100:101], v[128:129] op_sel_hi:[1,0]
	v_pk_mul_f32 v[98:99], v[98:99], v[128:129] op_sel_hi:[1,0]
	v_pk_mul_f32 v[96:97], v[96:97], v[128:129] op_sel_hi:[1,0]
	v_cvt_pk_bf16_f32 v168, v100, v101
	v_cvt_pk_bf16_f32 v169, v102, v103
	s_nop 0
	v_cvt_pk_bf16_f32 v170, v96, v97
	v_cvt_pk_bf16_f32 v171, v98, v99
	ds_read_b32 v128, v179 offset:128
	global_store_dwordx4 v[176:177], v[168:171], off offset:256 nt
	s_waitcnt lgkmcnt(0)
	v_mul_f32_e32 v128, v178, v128
	v_or_b32_e32 v168, 32, v172
	v_ashrrev_i32_e32 v169, 31, v168
	v_lshlrev_b64 v[168:169], 12, v[168:169]
	v_lshl_add_u64 v[168:169], s[40:41], 0, v[168:169]
	v_lshl_add_u64 v[176:177], v[168:169], 0, v[174:175]
	v_pk_mul_f32 v[94:95], v[94:95], v[128:129] op_sel_hi:[1,0]
	v_pk_mul_f32 v[92:93], v[92:93], v[128:129] op_sel_hi:[1,0]
	v_pk_mul_f32 v[90:91], v[90:91], v[128:129] op_sel_hi:[1,0]
	v_pk_mul_f32 v[88:89], v[88:89], v[128:129] op_sel_hi:[1,0]
	v_cvt_pk_bf16_f32 v168, v92, v93
	v_cvt_pk_bf16_f32 v169, v94, v95
	v_pk_mul_f32 v[86:87], v[86:87], v[128:129] op_sel_hi:[1,0]
	v_cvt_pk_bf16_f32 v170, v88, v89
	v_cvt_pk_bf16_f32 v171, v90, v91
	global_store_dwordx4 v[176:177], v[168:171], off nt
	v_pk_mul_f32 v[84:85], v[84:85], v[128:129] op_sel_hi:[1,0]
	v_pk_mul_f32 v[82:83], v[82:83], v[128:129] op_sel_hi:[1,0]
	v_pk_mul_f32 v[80:81], v[80:81], v[128:129] op_sel_hi:[1,0]
	v_cvt_pk_bf16_f32 v168, v84, v85
	v_cvt_pk_bf16_f32 v169, v86, v87
	s_nop 0
	v_cvt_pk_bf16_f32 v170, v80, v81
	v_cvt_pk_bf16_f32 v171, v82, v83
	ds_read_b32 v128, v179 offset:192
	global_store_dwordx4 v[176:177], v[168:171], off offset:256 nt
	s_waitcnt lgkmcnt(0)
	v_mul_f32_e32 v128, v178, v128
	v_or_b32_e32 v168, 48, v172
	v_ashrrev_i32_e32 v169, 31, v168
	v_lshlrev_b64 v[168:169], 12, v[168:169]
	v_lshl_add_u64 v[168:169], s[40:41], 0, v[168:169]
	v_lshl_add_u64 v[172:173], v[168:169], 0, v[174:175]
	v_pk_mul_f32 v[78:79], v[78:79], v[128:129] op_sel_hi:[1,0]
	v_pk_mul_f32 v[76:77], v[76:77], v[128:129] op_sel_hi:[1,0]
	v_pk_mul_f32 v[74:75], v[74:75], v[128:129] op_sel_hi:[1,0]
	v_pk_mul_f32 v[72:73], v[72:73], v[128:129] op_sel_hi:[1,0]
	v_cvt_pk_bf16_f32 v168, v76, v77
	v_cvt_pk_bf16_f32 v169, v78, v79
	v_pk_mul_f32 v[70:71], v[70:71], v[128:129] op_sel_hi:[1,0]
	v_cvt_pk_bf16_f32 v170, v72, v73
	v_cvt_pk_bf16_f32 v171, v74, v75
	global_store_dwordx4 v[172:173], v[168:171], off nt
	v_pk_mul_f32 v[68:69], v[68:69], v[128:129] op_sel_hi:[1,0]
	v_pk_mul_f32 v[66:67], v[66:67], v[128:129] op_sel_hi:[1,0]
	v_pk_mul_f32 v[64:65], v[64:65], v[128:129] op_sel_hi:[1,0]
	v_cvt_pk_bf16_f32 v168, v68, v69
	v_cvt_pk_bf16_f32 v169, v70, v71
	s_nop 0
	v_cvt_pk_bf16_f32 v170, v64, v65
	v_cvt_pk_bf16_f32 v171, v66, v67
	ds_read_b32 v128, v179 offset:512
	global_store_dwordx4 v[172:173], v[168:171], off offset:256 nt
	v_add_co_u32_e64 v172, s[0:1], s80, v142
	s_waitcnt lgkmcnt(0)
; __device__ __forceinline__ unsigned cvt_pk_bf16(float lo, float hi) { unsigned r; asm volatile("v_cvt_pk_bf16_f32 %0, %1, %2" : "=v"(r) : "v"(lo), "v"(hi)); return r; }
;     __device__ __forceinline__ void operator()(const f32x4 (&acc)[2][2][4][2], const pg8::Unit& u, int wr, int wc, int fr, int fq) const {
;     ...
;             for (int m = 0; m < 4; ++m) { bf16_t* rowp = O + (size_t)(row0 + ai * 128 + m * 16) * ldc + col0; const float r = s * rt[ai * 128 + m * 16];
; #pragma unroll
;                 for (int bj = 0; bj < 2; ++bj) { const f32x4 v0 = acc[ai][bj][m][0] * r, v1 = acc[ai][bj][m][1] * r; cs[bj][0] += v0; cs[bj][1] += v1;
;                     u32x4 w; w.x = cvt_pk_bf16(v0[0], v0[1]); w.y = cvt_pk_bf16(v0[2], v0[3]); w.z = cvt_pk_bf16(v1[0], v1[1]); w.w = cvt_pk_bf16(v1[2], v1[3]);
;                     *(u32x4*)(rowp + bj * 128) = w; } }
;         if (KMs && u.pn >= 4) {
; #pragma unroll
;             for (int bj = 0; bj < 2; ++bj)
; #pragma unroll
;                 for (int n = 0; n < 2; ++n)
; #pragma unroll
;                     for (int e = 0; e < 4; ++e) { float t = cs[bj][n][e]; t += __shfl_xor(t, 1); t += __shfl_xor(t, 2); t += __shfl_xor(t, 4); t += __shfl_xor(t, 8);
;                         if (fr == 0) { const int c = col0 + bj * 128 + 4 * n + e - 1024; unsafeAtomicAdd(KMs + ((size_t)((u.pm >> 3) * NH + (c >> 7)) * 8 + (u.pm & 7)) * HD + (c & 127), t); } }
	v_mul_f32_e32 v128, v178, v128
	v_pk_mul_f32 v[62:63], v[62:63], v[128:129] op_sel_hi:[1,0]
	v_pk_mul_f32 v[60:61], v[60:61], v[128:129] op_sel_hi:[1,0]
	v_pk_mul_f32 v[58:59], v[58:59], v[128:129] op_sel_hi:[1,0]
	v_pk_mul_f32 v[56:57], v[56:57], v[128:129] op_sel_hi:[1,0]
	v_cvt_pk_bf16_f32 v168, v60, v61
	v_cvt_pk_bf16_f32 v169, v62, v63
	v_addc_co_u32_e64 v173, s[0:1], 0, v143, s[0:1]
	v_cvt_pk_bf16_f32 v170, v56, v57
	v_cvt_pk_bf16_f32 v171, v58, v59
	global_store_dwordx4 v[172:173], v[168:171], off nt
	v_pk_mul_f32 v[54:55], v[54:55], v[128:129] op_sel_hi:[1,0]
	v_pk_mul_f32 v[52:53], v[52:53], v[128:129] op_sel_hi:[1,0]
	v_pk_mul_f32 v[46:47], v[46:47], v[128:129] op_sel_hi:[1,0]
	v_pk_mul_f32 v[44:45], v[44:45], v[128:129] op_sel_hi:[1,0]
	v_cvt_pk_bf16_f32 v168, v52, v53
	v_cvt_pk_bf16_f32 v169, v54, v55
	v_lshl_add_u64 v[172:173], v[142:143], 0, s[44:45]
	v_cvt_pk_bf16_f32 v170, v44, v45
	v_cvt_pk_bf16_f32 v171, v46, v47
	ds_read_b32 v128, v179 offset:576
	global_store_dwordx4 v[172:173], v[168:171], off offset:256 nt
	v_add_co_u32_e64 v172, s[0:1], s81, v142
	s_waitcnt lgkmcnt(0)
	v_mul_f32_e32 v128, v178, v128
	v_pk_mul_f32 v[50:51], v[50:51], v[128:129] op_sel_hi:[1,0]
	v_pk_mul_f32 v[48:49], v[48:49], v[128:129] op_sel_hi:[1,0]
	v_pk_mul_f32 v[42:43], v[42:43], v[128:129] op_sel_hi:[1,0]
	v_pk_mul_f32 v[40:41], v[40:41], v[128:129] op_sel_hi:[1,0]
	v_cvt_pk_bf16_f32 v168, v48, v49
	v_cvt_pk_bf16_f32 v169, v50, v51
	v_addc_co_u32_e64 v173, s[0:1], 0, v143, s[0:1]
	v_cvt_pk_bf16_f32 v170, v40, v41
	v_cvt_pk_bf16_f32 v171, v42, v43
	global_store_dwordx4 v[172:173], v[168:171], off nt
	v_pk_mul_f32 v[38:39], v[38:39], v[128:129] op_sel_hi:[1,0]
	v_pk_mul_f32 v[36:37], v[36:37], v[128:129] op_sel_hi:[1,0]
	v_pk_mul_f32 v[30:31], v[30:31], v[128:129] op_sel_hi:[1,0]
	v_pk_mul_f32 v[28:29], v[28:29], v[128:129] op_sel_hi:[1,0]
	v_cvt_pk_bf16_f32 v168, v36, v37
	v_cvt_pk_bf16_f32 v169, v38, v39
	v_lshl_add_u64 v[172:173], v[142:143], 0, s[46:47]
	v_cvt_pk_bf16_f32 v170, v28, v29
	v_cvt_pk_bf16_f32 v171, v30, v31
	ds_read_b32 v128, v179 offset:640
	global_store_dwordx4 v[172:173], v[168:171], off offset:256 nt
	v_add_co_u32_e64 v172, s[0:1], s82, v142
	s_waitcnt lgkmcnt(0)
	v_mul_f32_e32 v128, v178, v128
	v_pk_mul_f32 v[34:35], v[34:35], v[128:129] op_sel_hi:[1,0]
	v_pk_mul_f32 v[32:33], v[32:33], v[128:129] op_sel_hi:[1,0]
	v_pk_mul_f32 v[26:27], v[26:27], v[128:129] op_sel_hi:[1,0]
	v_pk_mul_f32 v[24:25], v[24:25], v[128:129] op_sel_hi:[1,0]
	v_cvt_pk_bf16_f32 v168, v32, v33
	v_cvt_pk_bf16_f32 v169, v34, v35
	v_addc_co_u32_e64 v173, s[0:1], 0, v143, s[0:1]
	v_cvt_pk_bf16_f32 v170, v24, v25
	v_cvt_pk_bf16_f32 v171, v26, v27
	global_store_dwordx4 v[172:173], v[168:171], off nt
	v_pk_mul_f32 v[22:23], v[22:23], v[128:129] op_sel_hi:[1,0]
	v_pk_mul_f32 v[20:21], v[20:21], v[128:129] op_sel_hi:[1,0]
	v_pk_mul_f32 v[14:15], v[14:15], v[128:129] op_sel_hi:[1,0]
	v_pk_mul_f32 v[12:13], v[12:13], v[128:129] op_sel_hi:[1,0]
	v_cvt_pk_bf16_f32 v168, v20, v21
	v_cvt_pk_bf16_f32 v169, v22, v23
	v_lshl_add_u64 v[172:173], v[142:143], 0, s[48:49]
	v_cvt_pk_bf16_f32 v170, v12, v13
	v_cvt_pk_bf16_f32 v171, v14, v15
	ds_read_b32 v128, v179 offset:704
	global_store_dwordx4 v[172:173], v[168:171], off offset:256 nt
	v_lshl_add_u64 v[172:173], v[142:143], 0, s[50:51]
	v_add_co_u32_e64 v142, s[0:1], s83, v142
	s_waitcnt lgkmcnt(0)
	v_mul_f32_e32 v128, v178, v128
	v_addc_co_u32_e64 v143, s[0:1], 0, v143, s[0:1]
	s_or_b64 s[0:1], s[52:53], vcc
	v_pk_mul_f32 v[18:19], v[18:19], v[128:129] op_sel_hi:[1,0]
	v_pk_mul_f32 v[16:17], v[16:17], v[128:129] op_sel_hi:[1,0]
	v_pk_mul_f32 v[10:11], v[10:11], v[128:129] op_sel_hi:[1,0]
	v_pk_mul_f32 v[8:9], v[8:9], v[128:129] op_sel_hi:[1,0]
	v_cvt_pk_bf16_f32 v168, v16, v17
	v_cvt_pk_bf16_f32 v169, v18, v19
	v_pk_mul_f32 v[6:7], v[6:7], v[128:129] op_sel_hi:[1,0]
	v_cvt_pk_bf16_f32 v170, v8, v9
	v_cvt_pk_bf16_f32 v171, v10, v11
	v_pk_mul_f32 v[4:5], v[4:5], v[128:129] op_sel_hi:[1,0]
	v_pk_mul_f32 v[2:3], v[2:3], v[128:129] op_sel_hi:[1,0]
	v_pk_mul_f32 v[0:1], v[0:1], v[128:129] op_sel_hi:[1,0]
	s_and_b64 vcc, exec, s[0:1]
	global_store_dwordx4 v[142:143], v[168:171], off nt
	s_nop 1
	v_cvt_pk_bf16_f32 v168, v4, v5
	v_cvt_pk_bf16_f32 v169, v6, v7
	v_cvt_pk_bf16_f32 v170, v0, v1
	v_cvt_pk_bf16_f32 v171, v2, v3
	global_store_dwordx4 v[172:173], v[168:171], off offset:256 nt
	s_cbranch_vccnz .LBB0_1237
	v_pk_add_f32 v[124:125], v[124:125], 0 op_sel_hi:[1,0]
	s_lshl_b32 s0, s14, 7
	v_pk_add_f32 v[108:109], v[124:125], v[108:109]
	s_and_b32 s35, s0, 0x380
	v_pk_add_f32 v[92:93], v[108:109], v[92:93]
	s_add_i32 s0, s34, 0xfffffc00
	v_pk_add_f32 v[76:77], v[92:93], v[76:77]
	s_and_b32 s55, s14, -8
	v_pk_add_f32 v[60:61], v[76:77], v[60:61]
	s_ashr_i32 s0, s0, 7
	v_pk_add_f32 v[48:49], v[60:61], v[48:49]
	v_xor_b32_e32 v61, 8, v167
	v_pk_add_f32 v[32:33], v[48:49], v[32:33]
	v_xor_b32_e32 v48, 4, v167
	v_pk_add_f32 v[16:17], v[32:33], v[16:17]
	v_and_b32_e32 v33, 64, v167
	v_xor_b32_e32 v32, 1, v167
	v_add_u32_e32 v49, 64, v33
	v_cmp_lt_i32_e32 vcc, v32, v49
	v_xor_b32_e32 v33, 2, v167
	s_add_i32 s0, s0, s55
	v_cndmask_b32_e32 v32, v167, v32, vcc
	v_lshlrev_b32_e32 v32, 2, v32
	ds_bpermute_b32 v60, v32, v16
	v_cmp_lt_i32_e32 vcc, v33, v49
	s_ashr_i32 s1, s0, 31
	s_lshl_b64 s[0:1], s[0:1], 12
	v_cndmask_b32_e32 v33, v167, v33, vcc
	v_lshlrev_b32_e32 v33, 2, v33
	s_waitcnt lgkmcnt(0)
	v_add_f32_e32 v16, v16, v60
	ds_bpermute_b32 v60, v33, v16
	v_cmp_lt_i32_e32 vcc, v48, v49
	v_lshlrev_b32_e32 v128, 2, v130
	s_waitcnt lgkmcnt(0)
	v_add_f32_e32 v16, v16, v60
	v_cndmask_b32_e32 v48, v167, v48, vcc
	v_lshlrev_b32_e32 v48, 2, v48
	ds_bpermute_b32 v60, v48, v16
	v_cmp_lt_i32_e32 vcc, v61, v49
	s_waitcnt lgkmcnt(0)
	v_add_f32_e32 v16, v16, v60
	v_cndmask_b32_e32 v49, v167, v61, vcc
	v_lshlrev_b32_e32 v49, 2, v49
	ds_bpermute_b32 v60, v49, v16
	s_and_saveexec_b64 s[20:21], s[6:7]
	s_cbranch_execz .LBB0_1206
	s_add_u32 s14, s28, s0
	s_addc_u32 s57, s29, s1
	s_lshl_b32 s62, s35, 2
	s_add_u32 s62, s14, s62
	s_addc_u32 s63, s57, 0
	s_waitcnt lgkmcnt(0)
	v_add_f32_e32 v16, v16, v60
	global_atomic_add_f32 v128, v16, s[62:63]

; __device__ __forceinline__ unsigned cvt_pk_bf16(float lo, float hi) { unsigned r; asm volatile("v_cvt_pk_bf16_f32 %0, %1, %2" : "=v"(r) : "v"(lo), "v"(hi)); return r; }
; #define LAS __attribute__((address_space(3)))
;     __device__ __forceinline__ void operator()(const f32x4 (&acc)[2][2][4][2], const pg8::Unit& u, int wr, int wc, int fr, int fq) const {
;         const int row0 = u.pm * 256 + wr * 64 + fr, col0 = u.pn * 256 + wc * 32 + 8 * fq;
;         f32x4 rv[2][2]; const LAS float* rt = rt_.of(u.pn) + wc * 32 + 8 * fq;
; #pragma unroll
;         for (int bj = 0; bj < 2; ++bj)
; #pragma unroll
;             for (int n = 0; n < 2; ++n) rv[bj][n] = *(const LAS f32x4*)(rt + bj * 128 + 4 * n);
; #pragma unroll
;         for (int ai = 0; ai < 2; ++ai)
; #pragma unroll
;             for (int m = 0; m < 4; ++m) { const int dg = row0 + ai * 128 + m * 16, hh = dg >> 7, d = dg & 127;
; #pragma unroll
;                 for (int bj = 0; bj < 2; ++bj) { const int tok = col0 + bj * 128, bb = tok >> 11, tl = tok & 2047;
;                     const f32x4 v0 = acc[ai][bj][m][0] * rv[bj][0], v1 = acc[ai][bj][m][1] * rv[bj][1];
;                     u32x4 w; w.x = cvt_pk_bf16(v0[0], v0[1]); w.y = cvt_pk_bf16(v0[2], v0[3]); w.z = cvt_pk_bf16(v1[0], v1[1]); w.w = cvt_pk_bf16(v1[2], v1[3]);
;                     *(u32x4*)(O + ((((size_t)(bb * 8 + hh) * 32 + (tl >> 6)) * 128 + d) * 64 + (tl & 63))) = w; } }
.LBB0_1449:
	s_cmp_eq_u32 s63, s46
	s_cselect_b32 s13, s62, 0x300
	s_cmp_lg_u32 s63, s47
	s_cselect_b32 s13, s13, 0x100
	s_cmp_lg_u32 s63, s48
	s_cselect_b32 s13, s13, 0
	s_lshl_b32 s34, s34, 8
	s_add_i32 s34, s34, s56
	v_lshl_add_u32 v128, s13, 2, v171
	s_and_b32 s38, s63, -8
	s_ashr_i32 s13, s34, 7
	s_add_i32 s20, s13, s38
	s_ashr_i32 s21, s20, 31
	s_lshl_b32 s13, s57, 1
	s_lshl_b32 s15, s63, 9
	ds_read_b128 v[140:143], v128
	ds_read_b128 v[136:139], v128 offset:16
	ds_read_b128 v[132:135], v128 offset:512
	ds_read_b128 v[128:131], v128 offset:528
	s_lshl_b64 s[20:21], s[20:21], 12
	s_or_b32 s13, s15, s13
	v_or_b32_e32 v159, s20, v152
	s_and_b32 s13, s13, 0xe80
	v_mov_b32_e32 v173, s21
	s_waitcnt lgkmcnt(0)
	v_pk_mul_f32 v[124:125], v[124:125], v[140:141]
	v_or_b32_e32 v172, s13, v159
	v_pk_mul_f32 v[174:175], v[122:123], v[138:139]
	v_pk_mul_f32 v[122:123], v[120:121], v[136:137]
	v_cvt_pk_bf16_f32 v120, v124, v125
	v_lshlrev_b64 v[124:125], 7, v[172:173]
	s_or_b32 s15, s13, 0x100
	v_pk_mul_f32 v[126:127], v[126:127], v[142:143]
	v_lshl_add_u64 v[124:125], v[160:161], 0, v[124:125]
	v_cvt_pk_bf16_f32 v121, v126, v127
	v_pk_mul_f32 v[116:117], v[116:117], v[132:133]
	v_or_b32_e32 v172, s15, v159
	v_cvt_pk_bf16_f32 v122, v122, v123
	v_cvt_pk_bf16_f32 v123, v174, v175
	global_store_dwordx4 v[124:125], v[120:123], off nt
	v_pk_mul_f32 v[118:119], v[118:119], v[134:135]
	v_pk_mul_f32 v[108:109], v[108:109], v[140:141]
	v_pk_mul_f32 v[120:121], v[114:115], v[130:131]
	v_pk_mul_f32 v[114:115], v[112:113], v[128:129]
	v_cvt_pk_bf16_f32 v112, v116, v117
	v_lshlrev_b64 v[116:117], 7, v[172:173]
	v_lshl_add_u64 v[116:117], v[160:161], 0, v[116:117]
	v_cvt_pk_bf16_f32 v113, v118, v119
	v_cvt_pk_bf16_f32 v114, v114, v115
	v_cvt_pk_bf16_f32 v115, v120, v121
	global_store_dwordx4 v[116:117], v[112:115], off nt
	v_or_b32_e32 v116, s20, v154
	v_pk_mul_f32 v[110:111], v[110:111], v[142:143]
	v_mov_b32_e32 v113, s21
	v_or_b32_e32 v112, s13, v116
	v_pk_mul_f32 v[114:115], v[106:107], v[138:139]
	v_pk_mul_f32 v[106:107], v[104:105], v[136:137]
	v_cvt_pk_bf16_f32 v104, v108, v109
	v_lshlrev_b64 v[108:109], 7, v[112:113]
	v_cvt_pk_bf16_f32 v105, v110, v111
	v_lshl_add_u64 v[108:109], v[160:161], 0, v[108:109]
	v_pk_mul_f32 v[100:101], v[100:101], v[132:133]
	v_or_b32_e32 v112, s15, v116
	v_cvt_pk_bf16_f32 v106, v106, v107
	v_cvt_pk_bf16_f32 v107, v114, v115
	global_store_dwordx4 v[108:109], v[104:107], off nt
	v_pk_mul_f32 v[102:103], v[102:103], v[134:135]
	v_pk_mul_f32 v[96:97], v[96:97], v[140:141]
	v_pk_mul_f32 v[104:105], v[94:95], v[130:131]
	v_pk_mul_f32 v[94:95], v[92:93], v[128:129]
	v_cvt_pk_bf16_f32 v92, v100, v101
	v_lshlrev_b64 v[100:101], 7, v[112:113]
	v_lshl_add_u64 v[100:101], v[160:161], 0, v[100:101]
	v_cvt_pk_bf16_f32 v93, v102, v103
	v_cvt_pk_bf16_f32 v94, v94, v95
	v_cvt_pk_bf16_f32 v95, v104, v105
	global_store_dwordx4 v[100:101], v[92:95], off nt
	v_or_b32_e32 v100, s20, v156
	v_pk_mul_f32 v[84:85], v[84:85], v[132:133]
	v_mov_b32_e32 v93, s21
	v_pk_mul_f32 v[94:95], v[98:99], v[142:143]
	v_or_b32_e32 v92, s13, v100
	v_pk_mul_f32 v[98:99], v[90:91], v[138:139]
	v_pk_mul_f32 v[90:91], v[88:89], v[136:137]
	v_cvt_pk_bf16_f32 v88, v96, v97
	v_cvt_pk_bf16_f32 v89, v94, v95
	v_lshlrev_b64 v[94:95], 7, v[92:93]
	v_lshl_add_u64 v[94:95], v[160:161], 0, v[94:95]
	v_or_b32_e32 v92, s15, v100
	v_cvt_pk_bf16_f32 v90, v90, v91
	v_cvt_pk_bf16_f32 v91, v98, v99
	global_store_dwordx4 v[94:95], v[88:91], off nt
	v_pk_mul_f32 v[86:87], v[86:87], v[134:135]
	s_addk_i32 s34, 0x80
	v_pk_mul_f32 v[88:89], v[78:79], v[130:131]
	v_pk_mul_f32 v[78:79], v[76:77], v[128:129]
	v_cvt_pk_bf16_f32 v76, v84, v85
	v_lshlrev_b64 v[84:85], 7, v[92:93]
	v_lshl_add_u64 v[84:85], v[160:161], 0, v[84:85]
	v_cvt_pk_bf16_f32 v77, v86, v87
	v_cvt_pk_bf16_f32 v78, v78, v79
	v_cvt_pk_bf16_f32 v79, v88, v89
	global_store_dwordx4 v[84:85], v[76:79], off nt
	v_or_b32_e32 v84, s20, v158
	v_pk_mul_f32 v[80:81], v[80:81], v[140:141]
	v_mov_b32_e32 v77, s21
	v_pk_mul_f32 v[78:79], v[82:83], v[142:143]
	v_or_b32_e32 v76, s13, v84
	v_pk_mul_f32 v[82:83], v[74:75], v[138:139]
	v_pk_mul_f32 v[74:75], v[72:73], v[136:137]
	v_cvt_pk_bf16_f32 v72, v80, v81
	v_cvt_pk_bf16_f32 v73, v78, v79
	v_lshlrev_b64 v[78:79], 7, v[76:77]
	s_ashr_i32 s20, s34, 7
	v_lshl_add_u64 v[78:79], v[160:161], 0, v[78:79]
	v_pk_mul_f32 v[68:69], v[68:69], v[132:133]
	v_or_b32_e32 v76, s15, v84
	s_add_i32 s20, s20, s38
	v_cvt_pk_bf16_f32 v74, v74, v75
	v_cvt_pk_bf16_f32 v75, v82, v83
	global_store_dwordx4 v[78:79], v[72:75], off nt
	s_ashr_i32 s21, s20, 31
; __device__ __forceinline__ unsigned cvt_pk_bf16(float lo, float hi) { unsigned r; asm volatile("v_cvt_pk_bf16_f32 %0, %1, %2" : "=v"(r) : "v"(lo), "v"(hi)); return r; }
;     __device__ __forceinline__ void operator()(const f32x4 (&acc)[2][2][4][2], const pg8::Unit& u, int wr, int wc, int fr, int fq) const {
;     ...
;         for (int ai = 0; ai < 2; ++ai)
; #pragma unroll
;             for (int m = 0; m < 4; ++m) { const int dg = row0 + ai * 128 + m * 16, hh = dg >> 7, d = dg & 127;
; #pragma unroll
;                 for (int bj = 0; bj < 2; ++bj) { const int tok = col0 + bj * 128, bb = tok >> 11, tl = tok & 2047;
;                     const f32x4 v0 = acc[ai][bj][m][0] * rv[bj][0], v1 = acc[ai][bj][m][1] * rv[bj][1];
;                     u32x4 w; w.x = cvt_pk_bf16(v0[0], v0[1]); w.y = cvt_pk_bf16(v0[2], v0[3]); w.z = cvt_pk_bf16(v1[0], v1[1]); w.w = cvt_pk_bf16(v1[2], v1[3]);
;                     *(u32x4*)(O + ((((size_t)(bb * 8 + hh) * 32 + (tl >> 6)) * 128 + d) * 64 + (tl & 63))) = w; } }
	s_lshl_b64 s[20:21], s[20:21], 12
	v_pk_mul_f32 v[72:73], v[66:67], v[130:131]
	v_pk_mul_f32 v[66:67], v[64:65], v[128:129]
	v_cvt_pk_bf16_f32 v64, v68, v69
	v_lshlrev_b64 v[68:69], 7, v[76:77]
	v_lshl_add_u64 v[68:69], v[160:161], 0, v[68:69]
	v_pk_mul_f32 v[70:71], v[70:71], v[134:135]
	v_pk_mul_f32 v[60:61], v[60:61], v[140:141]
	v_cvt_pk_bf16_f32 v65, v70, v71
	v_cvt_pk_bf16_f32 v66, v66, v67
	v_cvt_pk_bf16_f32 v67, v72, v73
	global_store_dwordx4 v[68:69], v[64:67], off nt
	v_or_b32_e32 v68, s20, v152
	v_pk_mul_f32 v[62:63], v[62:63], v[142:143]
	v_mov_b32_e32 v65, s21
	v_or_b32_e32 v64, s13, v68
	v_pk_mul_f32 v[66:67], v[58:59], v[138:139]
	v_pk_mul_f32 v[58:59], v[56:57], v[136:137]
	v_cvt_pk_bf16_f32 v56, v60, v61
	v_lshlrev_b64 v[60:61], 7, v[64:65]
	v_cvt_pk_bf16_f32 v57, v62, v63
	v_lshl_add_u64 v[60:61], v[160:161], 0, v[60:61]
	v_pk_mul_f32 v[52:53], v[52:53], v[132:133]
	v_or_b32_e32 v64, s15, v68
	v_cvt_pk_bf16_f32 v58, v58, v59
	v_cvt_pk_bf16_f32 v59, v66, v67
	global_store_dwordx4 v[60:61], v[56:59], off nt
	v_pk_mul_f32 v[54:55], v[54:55], v[134:135]
	v_pk_mul_f32 v[48:49], v[48:49], v[140:141]
	v_pk_mul_f32 v[56:57], v[46:47], v[130:131]
	v_pk_mul_f32 v[46:47], v[44:45], v[128:129]
	v_cvt_pk_bf16_f32 v44, v52, v53
	v_lshlrev_b64 v[52:53], 7, v[64:65]
	v_lshl_add_u64 v[52:53], v[160:161], 0, v[52:53]
	v_cvt_pk_bf16_f32 v45, v54, v55
	v_cvt_pk_bf16_f32 v46, v46, v47
	v_cvt_pk_bf16_f32 v47, v56, v57
	global_store_dwordx4 v[52:53], v[44:47], off nt
	v_or_b32_e32 v52, s20, v154
	v_pk_mul_f32 v[36:37], v[36:37], v[132:133]
	v_mov_b32_e32 v45, s21
	v_pk_mul_f32 v[46:47], v[50:51], v[142:143]
	v_or_b32_e32 v44, s13, v52
	v_pk_mul_f32 v[50:51], v[42:43], v[138:139]
	v_pk_mul_f32 v[42:43], v[40:41], v[136:137]
	v_cvt_pk_bf16_f32 v40, v48, v49
	v_cvt_pk_bf16_f32 v41, v46, v47
	v_lshlrev_b64 v[46:47], 7, v[44:45]
	v_lshl_add_u64 v[46:47], v[160:161], 0, v[46:47]
	v_or_b32_e32 v44, s15, v52
	v_cvt_pk_bf16_f32 v42, v42, v43
	v_cvt_pk_bf16_f32 v43, v50, v51
	global_store_dwordx4 v[46:47], v[40:43], off nt
	v_pk_mul_f32 v[38:39], v[38:39], v[134:135]
	v_pk_mul_f32 v[32:33], v[32:33], v[140:141]
	v_pk_mul_f32 v[40:41], v[30:31], v[130:131]
	v_pk_mul_f32 v[30:31], v[28:29], v[128:129]
	v_cvt_pk_bf16_f32 v28, v36, v37
	v_lshlrev_b64 v[36:37], 7, v[44:45]
	v_lshl_add_u64 v[36:37], v[160:161], 0, v[36:37]
	v_cvt_pk_bf16_f32 v29, v38, v39
	v_cvt_pk_bf16_f32 v30, v30, v31
	v_cvt_pk_bf16_f32 v31, v40, v41
	global_store_dwordx4 v[36:37], v[28:31], off nt
	v_or_b32_e32 v36, s20, v156
	v_pk_mul_f32 v[20:21], v[20:21], v[132:133]
	v_mov_b32_e32 v29, s21
	v_pk_mul_f32 v[30:31], v[34:35], v[142:143]
	v_or_b32_e32 v28, s13, v36
	v_pk_mul_f32 v[34:35], v[26:27], v[138:139]
	v_pk_mul_f32 v[26:27], v[24:25], v[136:137]
	v_cvt_pk_bf16_f32 v24, v32, v33
	v_cvt_pk_bf16_f32 v25, v30, v31
	v_lshlrev_b64 v[30:31], 7, v[28:29]
	v_lshl_add_u64 v[30:31], v[160:161], 0, v[30:31]
	v_or_b32_e32 v28, s15, v36
	v_cvt_pk_bf16_f32 v26, v26, v27
	v_cvt_pk_bf16_f32 v27, v34, v35
	global_store_dwordx4 v[30:31], v[24:27], off nt
	v_pk_mul_f32 v[22:23], v[22:23], v[134:135]
	v_pk_mul_f32 v[16:17], v[16:17], v[140:141]
	v_pk_mul_f32 v[24:25], v[14:15], v[130:131]
	v_pk_mul_f32 v[14:15], v[12:13], v[128:129]
	v_cvt_pk_bf16_f32 v12, v20, v21
	v_lshlrev_b64 v[20:21], 7, v[28:29]
	v_lshl_add_u64 v[20:21], v[160:161], 0, v[20:21]
	v_cvt_pk_bf16_f32 v13, v22, v23
	v_cvt_pk_bf16_f32 v14, v14, v15
	v_cvt_pk_bf16_f32 v15, v24, v25
	global_store_dwordx4 v[20:21], v[12:15], off nt
	v_or_b32_e32 v20, s20, v158
	v_pk_mul_f32 v[4:5], v[4:5], v[132:133]
	v_mov_b32_e32 v13, s21
	v_pk_mul_f32 v[14:15], v[18:19], v[142:143]
	v_or_b32_e32 v12, s13, v20
	v_pk_mul_f32 v[18:19], v[10:11], v[138:139]
	v_pk_mul_f32 v[10:11], v[8:9], v[136:137]
	v_cvt_pk_bf16_f32 v8, v16, v17
	v_cvt_pk_bf16_f32 v9, v14, v15
	v_lshlrev_b64 v[14:15], 7, v[12:13]
	v_lshl_add_u64 v[14:15], v[160:161], 0, v[14:15]
	v_or_b32_e32 v12, s15, v20
	v_cvt_pk_bf16_f32 v10, v10, v11
	v_cvt_pk_bf16_f32 v11, v18, v19
	global_store_dwordx4 v[14:15], v[8:11], off nt
	s_andn2_b64 vcc, exec, s[4:5]
	s_mov_b64 s[4:5], -1
	v_pk_mul_f32 v[8:9], v[2:3], v[130:131]
	v_pk_mul_f32 v[2:3], v[0:1], v[128:129]
	v_cvt_pk_bf16_f32 v0, v4, v5
	v_lshlrev_b64 v[4:5], 7, v[12:13]
	v_lshl_add_u64 v[4:5], v[160:161], 0, v[4:5]
	v_pk_mul_f32 v[6:7], v[6:7], v[134:135]
	s_nop 0
	v_cvt_pk_bf16_f32 v1, v6, v7
	v_cvt_pk_bf16_f32 v2, v2, v3
	v_cvt_pk_bf16_f32 v3, v8, v9
	global_store_dwordx4 v[4:5], v[0:3], off nt
	s_cbranch_vccnz .LBB0_1438
	s_andn2_b64 vcc, exec, s[0:1]
	s_cbranch_vccnz .LBB0_1437
	s_barrier
	s_branch .LBB0_1437

; __device__ __forceinline__ unsigned cvt_pk_bf16(float lo, float hi) { unsigned r; asm volatile("v_cvt_pk_bf16_f32 %0, %1, %2" : "=v"(r) : "v"(lo), "v"(hi)); return r; }
;     __device__ __forceinline__ void operator()(const f32x4 (&acc)[2][2][4][2], const pg8::Unit& u, int wr, int wc, int fr, int fq) const {
;         const int row0 = u.pm * 256 + wr * 64 + fr, col0 = u.pn * 256 + wc * 32 + 8 * fq;
;         u32x4 xin[2][4][2];
; #pragma unroll
;         for (int ai = 0; ai < 2; ++ai)
; #pragma unroll
;             for (int m = 0; m < 4; ++m)
; #pragma unroll
;                 for (int bj = 0; bj < 2; ++bj) xin[ai][m][bj] = *(const u32x4*)(XB + (size_t)(row0 + ai * 128 + m * 16) * D + col0 + bj * 128);
; #pragma unroll
;         for (int ai = 0; ai < 2; ++ai)
; #pragma unroll
;             for (int m = 0; m < 4; ++m) { const size_t ro = (size_t)(row0 + ai * 128 + m * 16) * D + col0; float sq = 0.f;
; #pragma unroll
;                 for (int bj = 0; bj < 2; ++bj) { const u32x4 xb = xin[ai][m][bj];
;                     const f32x4 x0 = (f32x4){bf_lo(xb.x), bf_hi(xb.x), bf_lo(xb.y), bf_hi(xb.y)} + acc[ai][bj][m][0] * s, x1 = (f32x4){bf_lo(xb.z), bf_hi(xb.z), bf_lo(xb.w), bf_hi(xb.w)} + acc[ai][bj][m][1] * s;
;                     sq += (x0[0] * x0[0] + x0[1] * x0[1]) + (x0[2] * x0[2] + x0[3] * x0[3]) + (x1[0] * x1[0] + x1[1] * x1[1]) + (x1[2] * x1[2] + x1[3] * x1[3]);
;                     u32x4 w; w.x = cvt_pk_bf16(x0[0], x0[1]); w.y = cvt_pk_bf16(x0[2], x0[3]); w.z = cvt_pk_bf16(x1[0], x1[1]); w.w = cvt_pk_bf16(x1[2], x1[3]);
;                     *(u32x4*)(XB + ro + bj * 128) = w; }
;                 sq += __shfl_xor(sq, 16); sq += __shfl_xor(sq, 32);
;                 if (fq == 0) SSo[(size_t)(u.pn * 4 + wc) * T + row0 + ai * 128 + m * 16] = sq; }
.LBB0_1638:
	v_lshl_or_b32 v204, s34, 8, v222
	v_lshl_add_u32 v202, s52, 8, v220
	v_ashrrev_i32_e32 v205, 31, v204
	v_lshlrev_b64 v[236:237], 1, v[204:205]
	v_ashrrev_i32_e32 v203, 31, v202
	v_lshl_add_u64 v[96:97], s[36:37], 0, v[236:237]
	v_lshlrev_b64 v[238:239], 11, v[202:203]
	v_lshl_add_u64 v[98:99], v[96:97], 0, v[238:239]
	global_load_dwordx4 v[228:231], v[98:99], off
	global_load_dwordx4 v[232:235], v[98:99], off offset:256
	v_or_b32_e32 v98, 16, v202
	v_or_b32_e32 v108, 32, v202
	v_or_b32_e32 v110, 48, v202
	v_ashrrev_i32_e32 v99, 31, v98
	v_ashrrev_i32_e32 v109, 31, v108
	v_ashrrev_i32_e32 v111, 31, v110
	v_lshlrev_b64 v[218:219], 11, v[98:99]
	v_lshlrev_b64 v[216:217], 11, v[108:109]
	v_lshlrev_b64 v[214:215], 11, v[110:111]
	v_lshl_add_u64 v[212:213], v[238:239], 0, s[8:9]
	v_lshl_add_u64 v[210:211], v[238:239], 0, s[16:17]
	v_lshl_add_u64 v[208:209], v[238:239], 0, s[38:39]
	v_lshl_add_u64 v[206:207], v[238:239], 0, s[42:43]
	v_lshl_add_u64 v[98:99], v[96:97], 0, v[218:219]
	v_lshl_add_u64 v[108:109], v[96:97], 0, v[216:217]
	v_lshl_add_u64 v[110:111], v[96:97], 0, v[214:215]
	v_lshl_add_u64 v[120:121], v[96:97], 0, v[212:213]
	v_lshl_add_u64 v[122:123], v[96:97], 0, v[210:211]
	v_lshl_add_u64 v[240:241], v[96:97], 0, v[208:209]
	v_lshl_add_u64 v[96:97], v[96:97], 0, v[206:207]
	global_load_dwordx4 v[180:183], v[98:99], off
	global_load_dwordx4 v[176:179], v[98:99], off offset:256
	global_load_dwordx4 v[172:175], v[108:109], off
	global_load_dwordx4 v[168:171], v[108:109], off offset:256
	global_load_dwordx4 v[164:167], v[110:111], off
	global_load_dwordx4 v[160:163], v[110:111], off offset:256
	global_load_dwordx4 v[156:159], v[120:121], off
	global_load_dwordx4 v[152:155], v[120:121], off offset:256
	global_load_dwordx4 v[148:151], v[122:123], off
	global_load_dwordx4 v[144:147], v[122:123], off offset:256
	global_load_dwordx4 v[128:131], v[240:241], off
	s_nop 0
	global_load_dwordx4 v[120:123], v[240:241], off offset:256
	global_load_dwordx4 v[108:111], v[96:97], off
	s_nop 0
	global_load_dwordx4 v[96:99], v[96:97], off offset:256
	s_lshl_b32 s20, s34, 2
	s_or_b32 s20, s20, s65
	s_ashr_i32 s21, s20, 31
	s_lshl_b64 s[20:21], s[20:21], 17
	s_waitcnt vmcnt(0)
	v_lshlrev_b32_e32 v240, 16, v228
	v_and_b32_e32 v241, 0xffff0000, v228
	v_lshlrev_b32_e32 v228, 16, v229
	v_and_b32_e32 v229, 0xffff0000, v229
	v_lshlrev_b32_e32 v242, 16, v230
	v_and_b32_e32 v243, 0xffff0000, v230
	v_lshlrev_b32_e32 v244, 16, v232
	v_and_b32_e32 v245, 0xffff0000, v232
	v_lshlrev_b32_e32 v232, 16, v233
	v_and_b32_e32 v233, 0xffff0000, v233
	v_lshlrev_b32_e32 v246, 16, v234
	v_and_b32_e32 v247, 0xffff0000, v234
	v_lshlrev_b32_e32 v234, 16, v235
	v_and_b32_e32 v235, 0xffff0000, v235
	v_pk_add_f32 v[142:143], v[142:143], v[228:229]
	v_pk_add_f32 v[140:141], v[140:141], v[240:241]
	v_lshlrev_b32_e32 v230, 16, v231
	v_and_b32_e32 v231, 0xffff0000, v231
	v_pk_add_f32 v[136:137], v[136:137], v[242:243]
	v_pk_add_f32 v[228:229], v[134:135], v[232:233]
	v_pk_add_f32 v[232:233], v[126:127], v[234:235]
	v_pk_add_f32 v[234:235], v[124:125], v[246:247]
	v_mul_f32_e32 v124, v141, v141
	v_mul_f32_e32 v125, v143, v143
	v_pk_add_f32 v[138:139], v[138:139], v[230:231]
	v_pk_add_f32 v[230:231], v[132:133], v[244:245]
	v_mul_f32_e32 v126, v137, v137
	v_fmac_f32_e32 v124, v140, v140
	v_fmac_f32_e32 v125, v142, v142
	v_mul_f32_e32 v127, v139, v139
	v_cvt_pk_bf16_f32 v132, v140, v141
	v_cvt_pk_bf16_f32 v133, v142, v143
	v_cvt_pk_bf16_f32 v134, v136, v137
	v_cvt_pk_bf16_f32 v135, v138, v139
	v_mul_f32_e32 v137, v231, v231
	v_mul_f32_e32 v139, v229, v229
	v_fmac_f32_e32 v126, v136, v136
	v_add_f32_e32 v124, v124, v125
	v_fmac_f32_e32 v137, v230, v230
	v_fmac_f32_e32 v139, v228, v228
	v_add_f32_e32 v124, v126, v124
	v_mul_f32_e32 v126, v235, v235
	v_add_f32_e32 v125, v137, v139
	v_fmac_f32_e32 v126, v234, v234
	v_add_f32_e32 v125, v126, v125
	v_mul_f32_e32 v126, v233, v233
	v_fmac_f32_e32 v127, v138, v138
	v_fmac_f32_e32 v126, v232, v232
	v_add_f32_e32 v124, v127, v124
	v_add_f32_e32 v125, v126, v125
	v_and_b32_e32 v126, 64, v226
	v_add_f32_e32 v125, v124, v125
	v_add_u32_e32 v138, 64, v126
	v_lshl_add_u64 v[126:127], s[36:37], 0, v[238:239]
	v_lshl_add_u64 v[136:137], v[126:127], 0, v[236:237]
	v_mov_b32_e32 v139, v125
	s_nop 1
	v_permlane16_swap_b32_e32 v139, v125
	global_store_dwordx4 v[136:137], v[132:135], off nt
	s_waitcnt lgkmcnt(0)
	v_add_f32_e32 v126, v125, v139
	v_cvt_pk_bf16_f32 v132, v230, v231
	v_cvt_pk_bf16_f32 v133, v228, v229
	v_cvt_pk_bf16_f32 v134, v234, v235
	v_cvt_pk_bf16_f32 v135, v232, v233
	global_store_dwordx4 v[136:137], v[132:135], off offset:256 nt
	s_nop 0
	v_mov_b32_e32 v127, v126
	s_nop 1
	v_permlane32_swap_b32_e32 v127, v126
	s_and_saveexec_b64 s[34:35], s[4:5]
	s_cbranch_execz .LBB0_1640
	s_add_u32 s54, s63, s20
	s_addc_u32 s55, s64, s21
	v_lshl_add_u64 v[132:133], v[202:203], 2, s[54:55]
	s_waitcnt lgkmcnt(0)
	v_add_f32_e32 v126, v126, v127
	global_store_dword v[132:133], v126, off

; #define LAS __attribute__((address_space(3)))
; __device__ __forceinline__ unsigned cvt_pk2(float lo, float hi) { f32x2c v = {lo, hi}; bf16x2c q = __builtin_convertvector(v, bf16x2c); return __builtin_bit_cast(unsigned, q); }
;     __device__ __forceinline__ void operator()(const f32x4 (&acc)[2][2][4][2], const pg8::Unit& u, int wr, int wc, int fr, int fq) const {
;         const int row0 = u.pm * 256 + wr * 64 + fr, col0 = u.pn * 128 + wc * 32 + 8 * fq;
;         const LAS float* rt = rt_.of(u.pm) + wr * 64 + fr;
; #pragma unroll
;         for (int ai = 0; ai < 2; ++ai)
; #pragma unroll
;             for (int m = 0; m < 4; ++m) { bf16_t* rowp = O + (size_t)(row0 + ai * 128 + m * 16) * FF + col0; const float r = rt[ai * 128 + m * 16];
;                 const float rl = -r * LOG2E, r2 = r * r; unsigned w[4];
; #pragma unroll
;                 for (int n = 0; n < 2; ++n)
; #pragma unroll
;                     for (int h = 0; h < 2; ++h) { const f32x2v g = {acc[ai][0][m][n][2 * h], acc[ai][0][m][n][2 * h + 1]}, uu = {acc[ai][1][m][n][2 * h], acc[ai][1][m][n][2 * h + 1]};
;                         const f32x2v t = g * rl; f32x2v d = {__builtin_amdgcn_exp2f(t.x), __builtin_amdgcn_exp2f(t.y)}; d = d + 1.0f;
;                         const f32x2v q = {__builtin_amdgcn_rcpf(d.x), __builtin_amdgcn_rcpf(d.y)}; const f32x2v o = ((g * uu) * r2) * q;
;                         w[2 * n + h] = cvt_pk2(o.x, o.y); }
;                 u32x4 wv; wv.x = w[0]; wv.y = w[1]; wv.z = w[2]; wv.w = w[3];
;                 *(u32x4*)rowp = wv; }
.LBB0_1743:
	s_cmp_eq_u32 s34, s45
	s_cselect_b32 s13, s60, 0x300
	s_cmp_lg_u32 s34, s46
	s_cselect_b32 s13, s13, 0x100
	s_cmp_lg_u32 s34, s47
	s_cselect_b32 s13, s13, 0
	v_lshl_add_u32 v154, s13, 2, v148
	ds_read2_b32 v[200:201], v154 offset1:16
	ds_read2_b32 v[202:203], v154 offset0:32 offset1:48
	ds_read2_b32 v[204:205], v154 offset0:128 offset1:144
	ds_read2_b32 v[206:207], v154 offset0:160 offset1:176
	v_lshl_add_u32 v153, s34, 8, v146
	v_lshl_or_b32 v158, s62, 7, v149
	v_mov_b64_e32 v[178:179], s[40:41]
	s_mov_b32 s98, 0x1600
	v_lshlrev_b32_e32 v158, 1, v158
	v_mov_b32_e32 v159, 0
	v_mad_i64_i32 v[178:179], s[20:21], v153, s98, v[178:179]
	s_mov_b32 s98, 0x16000
	s_mov_b32 s99, 0
	s_mov_b32 s100, 0x6e000
	s_mov_b32 s101, 0
	v_lshl_add_u64 v[178:179], v[178:179], 0, v[158:159]
	s_waitcnt lgkmcnt(0)
	v_mul_f32_e32 v208, 0xbfb8aa3b, v200
	v_mul_f32_e32 v228, v200, v200
	v_mul_f32_e32 v210, 0xbfb8aa3b, v201
	v_mul_f32_e32 v230, v201, v201
	v_mul_f32_e32 v212, 0xbfb8aa3b, v202
	v_mul_f32_e32 v232, v202, v202
	v_mul_f32_e32 v214, 0xbfb8aa3b, v203
	v_mul_f32_e32 v234, v203, v203
	v_mul_f32_e32 v216, 0xbfb8aa3b, v204
	v_mul_f32_e32 v236, v204, v204
	v_mul_f32_e32 v218, 0xbfb8aa3b, v205
	v_mul_f32_e32 v238, v205, v205
	v_mul_f32_e32 v220, 0xbfb8aa3b, v206
	v_mul_f32_e32 v240, v206, v206
	v_mul_f32_e32 v222, 0xbfb8aa3b, v207
	v_mul_f32_e32 v242, v207, v207
	v_rcp_f32_e32 v228, v228
	v_rcp_f32_e32 v230, v230
	v_rcp_f32_e32 v232, v232
	v_rcp_f32_e32 v234, v234
	v_rcp_f32_e32 v236, v236
	v_rcp_f32_e32 v238, v238
	v_rcp_f32_e32 v240, v240
	v_rcp_f32_e32 v242, v242
	v_pk_mul_f32 v[154:155], v[124:125], v[208:209] op_sel_hi:[1,0]
	v_pk_mul_f32 v[156:157], v[126:127], v[208:209] op_sel_hi:[1,0]
	v_pk_mul_f32 v[158:159], v[116:117], v[208:209] op_sel_hi:[1,0]
	v_pk_mul_f32 v[160:161], v[118:119], v[208:209] op_sel_hi:[1,0]
	v_exp_f32_e32 v154, v154
	v_exp_f32_e32 v155, v155
	v_exp_f32_e32 v156, v156
	v_exp_f32_e32 v157, v157
	v_exp_f32_e32 v158, v158
	v_exp_f32_e32 v159, v159
	v_exp_f32_e32 v160, v160
	v_exp_f32_e32 v161, v161
	v_pk_mul_f32 v[162:163], v[108:109], v[210:211] op_sel_hi:[1,0]
	v_pk_mul_f32 v[164:165], v[110:111], v[210:211] op_sel_hi:[1,0]
	v_pk_mul_f32 v[166:167], v[100:101], v[210:211] op_sel_hi:[1,0]
	v_pk_mul_f32 v[168:169], v[102:103], v[210:211] op_sel_hi:[1,0]
	v_exp_f32_e32 v162, v162
	v_exp_f32_e32 v163, v163
	v_exp_f32_e32 v164, v164
	v_exp_f32_e32 v165, v165
	v_exp_f32_e32 v166, v166
	v_exp_f32_e32 v167, v167
	v_exp_f32_e32 v168, v168
	v_exp_f32_e32 v169, v169
	v_pk_mul_f32 v[120:121], v[124:125], v[120:121]
	v_pk_mul_f32 v[122:123], v[126:127], v[122:123]
	v_pk_mul_f32 v[112:113], v[116:117], v[112:113]
	v_pk_mul_f32 v[114:115], v[118:119], v[114:115]
	v_pk_fma_f32 v[154:155], v[154:155], v[228:229], v[228:229] op_sel_hi:[1,0,0]
	v_pk_fma_f32 v[156:157], v[156:157], v[228:229], v[228:229] op_sel_hi:[1,0,0]
	v_pk_fma_f32 v[158:159], v[158:159], v[228:229], v[228:229] op_sel_hi:[1,0,0]
	v_pk_fma_f32 v[160:161], v[160:161], v[228:229], v[228:229] op_sel_hi:[1,0,0]
	v_rcp_f32_e32 v154, v154
	v_rcp_f32_e32 v155, v155
	v_rcp_f32_e32 v156, v156
	v_rcp_f32_e32 v157, v157
	v_rcp_f32_e32 v158, v158
	v_rcp_f32_e32 v159, v159
	v_rcp_f32_e32 v160, v160
	v_rcp_f32_e32 v161, v161
	v_pk_mul_f32 v[170:171], v[92:93], v[212:213] op_sel_hi:[1,0]
	v_pk_mul_f32 v[172:173], v[94:95], v[212:213] op_sel_hi:[1,0]
	v_pk_mul_f32 v[174:175], v[84:85], v[212:213] op_sel_hi:[1,0]
	v_pk_mul_f32 v[176:177], v[86:87], v[212:213] op_sel_hi:[1,0]
	v_exp_f32_e32 v170, v170
	v_exp_f32_e32 v171, v171
	v_exp_f32_e32 v172, v172
	v_exp_f32_e32 v173, v173
	v_exp_f32_e32 v174, v174
	v_exp_f32_e32 v175, v175
	v_exp_f32_e32 v176, v176
	v_exp_f32_e32 v177, v177
	v_pk_mul_f32 v[104:105], v[108:109], v[104:105]
	v_pk_mul_f32 v[106:107], v[110:111], v[106:107]
	v_pk_mul_f32 v[96:97], v[100:101], v[96:97]
	v_pk_mul_f32 v[98:99], v[102:103], v[98:99]
	v_pk_fma_f32 v[162:163], v[162:163], v[230:231], v[230:231] op_sel_hi:[1,0,0]
	v_pk_fma_f32 v[164:165], v[164:165], v[230:231], v[230:231] op_sel_hi:[1,0,0]
	v_pk_fma_f32 v[166:167], v[166:167], v[230:231], v[230:231] op_sel_hi:[1,0,0]
	v_pk_fma_f32 v[168:169], v[168:169], v[230:231], v[230:231] op_sel_hi:[1,0,0]
	v_rcp_f32_e32 v162, v162
	v_rcp_f32_e32 v163, v163
	v_rcp_f32_e32 v164, v164
	v_rcp_f32_e32 v165, v165
	v_rcp_f32_e32 v166, v166
	v_rcp_f32_e32 v167, v167
	v_rcp_f32_e32 v168, v168
	v_rcp_f32_e32 v169, v169
	v_pk_mul_f32 v[120:121], v[120:121], v[154:155]
	v_pk_mul_f32 v[122:123], v[122:123], v[156:157]
	v_pk_mul_f32 v[112:113], v[112:113], v[158:159]
	v_pk_mul_f32 v[114:115], v[114:115], v[160:161]
	v_cvt_pk_bf16_f32 v154, v120, v121
	v_cvt_pk_bf16_f32 v155, v122, v123
	v_cvt_pk_bf16_f32 v156, v112, v113
	v_cvt_pk_bf16_f32 v157, v114, v115
	global_store_dwordx4 v[178:179], v[154:157], off nt
	v_lshl_add_u64 v[178:179], v[178:179], 0, s[98:99]
	s_nop 1
	v_pk_mul_f32 v[154:155], v[76:77], v[214:215] op_sel_hi:[1,0]
	v_pk_mul_f32 v[156:157], v[78:79], v[214:215] op_sel_hi:[1,0]
	v_pk_mul_f32 v[158:159], v[68:69], v[214:215] op_sel_hi:[1,0]
	v_pk_mul_f32 v[160:161], v[70:71], v[214:215] op_sel_hi:[1,0]
	v_exp_f32_e32 v154, v154
	v_exp_f32_e32 v155, v155
	v_exp_f32_e32 v156, v156
	v_exp_f32_e32 v157, v157
	v_exp_f32_e32 v158, v158
	v_exp_f32_e32 v159, v159
	v_exp_f32_e32 v160, v160
	v_exp_f32_e32 v161, v161
	v_pk_mul_f32 v[88:89], v[92:93], v[88:89]
	v_pk_mul_f32 v[90:91], v[94:95], v[90:91]
	v_pk_mul_f32 v[80:81], v[84:85], v[80:81]
	v_pk_mul_f32 v[82:83], v[86:87], v[82:83]
	v_pk_fma_f32 v[170:171], v[170:171], v[232:233], v[232:233] op_sel_hi:[1,0,0]
	v_pk_fma_f32 v[172:173], v[172:173], v[232:233], v[232:233] op_sel_hi:[1,0,0]
; __device__ __forceinline__ unsigned cvt_pk2(float lo, float hi) { f32x2c v = {lo, hi}; bf16x2c q = __builtin_convertvector(v, bf16x2c); return __builtin_bit_cast(unsigned, q); }
;     __device__ __forceinline__ void operator()(const f32x4 (&acc)[2][2][4][2], const pg8::Unit& u, int wr, int wc, int fr, int fq) const {
;     ...
;             for (int m = 0; m < 4; ++m) { bf16_t* rowp = O + (size_t)(row0 + ai * 128 + m * 16) * FF + col0; const float r = rt[ai * 128 + m * 16];
;                 const float rl = -r * LOG2E, r2 = r * r; unsigned w[4];
; #pragma unroll
;                 for (int n = 0; n < 2; ++n)
; #pragma unroll
;                     for (int h = 0; h < 2; ++h) { const f32x2v g = {acc[ai][0][m][n][2 * h], acc[ai][0][m][n][2 * h + 1]}, uu = {acc[ai][1][m][n][2 * h], acc[ai][1][m][n][2 * h + 1]};
;                         const f32x2v t = g * rl; f32x2v d = {__builtin_amdgcn_exp2f(t.x), __builtin_amdgcn_exp2f(t.y)}; d = d + 1.0f;
;                         const f32x2v q = {__builtin_amdgcn_rcpf(d.x), __builtin_amdgcn_rcpf(d.y)}; const f32x2v o = ((g * uu) * r2) * q;
;                         w[2 * n + h] = cvt_pk2(o.x, o.y); }
;                 u32x4 wv; wv.x = w[0]; wv.y = w[1]; wv.z = w[2]; wv.w = w[3];
;                 *(u32x4*)rowp = wv; }
	v_pk_fma_f32 v[174:175], v[174:175], v[232:233], v[232:233] op_sel_hi:[1,0,0]
	v_pk_fma_f32 v[176:177], v[176:177], v[232:233], v[232:233] op_sel_hi:[1,0,0]
	v_rcp_f32_e32 v170, v170
	v_rcp_f32_e32 v171, v171
	v_rcp_f32_e32 v172, v172
	v_rcp_f32_e32 v173, v173
	v_rcp_f32_e32 v174, v174
	v_rcp_f32_e32 v175, v175
	v_rcp_f32_e32 v176, v176
	v_rcp_f32_e32 v177, v177
	v_pk_mul_f32 v[104:105], v[104:105], v[162:163]
	v_pk_mul_f32 v[106:107], v[106:107], v[164:165]
	v_pk_mul_f32 v[96:97], v[96:97], v[166:167]
	v_pk_mul_f32 v[98:99], v[98:99], v[168:169]
	v_cvt_pk_bf16_f32 v162, v104, v105
	v_cvt_pk_bf16_f32 v163, v106, v107
	v_cvt_pk_bf16_f32 v164, v96, v97
	v_cvt_pk_bf16_f32 v165, v98, v99
	global_store_dwordx4 v[178:179], v[162:165], off nt
	v_lshl_add_u64 v[178:179], v[178:179], 0, s[98:99]
	s_nop 1
	v_pk_mul_f32 v[162:163], v[60:61], v[216:217] op_sel_hi:[1,0]
	v_pk_mul_f32 v[164:165], v[62:63], v[216:217] op_sel_hi:[1,0]
	v_pk_mul_f32 v[166:167], v[52:53], v[216:217] op_sel_hi:[1,0]
	v_pk_mul_f32 v[168:169], v[54:55], v[216:217] op_sel_hi:[1,0]
	v_exp_f32_e32 v162, v162
	v_exp_f32_e32 v163, v163
	v_exp_f32_e32 v164, v164
	v_exp_f32_e32 v165, v165
	v_exp_f32_e32 v166, v166
	v_exp_f32_e32 v167, v167
	v_exp_f32_e32 v168, v168
	v_exp_f32_e32 v169, v169
	v_pk_mul_f32 v[72:73], v[76:77], v[72:73]
	v_pk_mul_f32 v[74:75], v[78:79], v[74:75]
	v_pk_mul_f32 v[64:65], v[68:69], v[64:65]
	v_pk_mul_f32 v[66:67], v[70:71], v[66:67]
	v_pk_fma_f32 v[154:155], v[154:155], v[234:235], v[234:235] op_sel_hi:[1,0,0]
	v_pk_fma_f32 v[156:157], v[156:157], v[234:235], v[234:235] op_sel_hi:[1,0,0]
	v_pk_fma_f32 v[158:159], v[158:159], v[234:235], v[234:235] op_sel_hi:[1,0,0]
	v_pk_fma_f32 v[160:161], v[160:161], v[234:235], v[234:235] op_sel_hi:[1,0,0]
	v_rcp_f32_e32 v154, v154
	v_rcp_f32_e32 v155, v155
	v_rcp_f32_e32 v156, v156
	v_rcp_f32_e32 v157, v157
	v_rcp_f32_e32 v158, v158
	v_rcp_f32_e32 v159, v159
	v_rcp_f32_e32 v160, v160
	v_rcp_f32_e32 v161, v161
	v_pk_mul_f32 v[88:89], v[88:89], v[170:171]
	v_pk_mul_f32 v[90:91], v[90:91], v[172:173]
	v_pk_mul_f32 v[80:81], v[80:81], v[174:175]
	v_pk_mul_f32 v[82:83], v[82:83], v[176:177]
	v_cvt_pk_bf16_f32 v170, v88, v89
	v_cvt_pk_bf16_f32 v171, v90, v91
	v_cvt_pk_bf16_f32 v172, v80, v81
	v_cvt_pk_bf16_f32 v173, v82, v83
	global_store_dwordx4 v[178:179], v[170:173], off nt
	v_lshl_add_u64 v[178:179], v[178:179], 0, s[98:99]
	s_nop 1
	v_pk_mul_f32 v[170:171], v[44:45], v[218:219] op_sel_hi:[1,0]
	v_pk_mul_f32 v[172:173], v[46:47], v[218:219] op_sel_hi:[1,0]
	v_pk_mul_f32 v[174:175], v[36:37], v[218:219] op_sel_hi:[1,0]
	v_pk_mul_f32 v[176:177], v[38:39], v[218:219] op_sel_hi:[1,0]
	v_exp_f32_e32 v170, v170
	v_exp_f32_e32 v171, v171
	v_exp_f32_e32 v172, v172
	v_exp_f32_e32 v173, v173
	v_exp_f32_e32 v174, v174
	v_exp_f32_e32 v175, v175
	v_exp_f32_e32 v176, v176
	v_exp_f32_e32 v177, v177
	v_pk_mul_f32 v[56:57], v[60:61], v[56:57]
	v_pk_mul_f32 v[58:59], v[62:63], v[58:59]
	v_pk_mul_f32 v[48:49], v[52:53], v[48:49]
	v_pk_mul_f32 v[50:51], v[54:55], v[50:51]
	v_pk_fma_f32 v[162:163], v[162:163], v[236:237], v[236:237] op_sel_hi:[1,0,0]
	v_pk_fma_f32 v[164:165], v[164:165], v[236:237], v[236:237] op_sel_hi:[1,0,0]
	v_pk_fma_f32 v[166:167], v[166:167], v[236:237], v[236:237] op_sel_hi:[1,0,0]
	v_pk_fma_f32 v[168:169], v[168:169], v[236:237], v[236:237] op_sel_hi:[1,0,0]
	v_rcp_f32_e32 v162, v162
	v_rcp_f32_e32 v163, v163
	v_rcp_f32_e32 v164, v164
	v_rcp_f32_e32 v165, v165
	v_rcp_f32_e32 v166, v166
	v_rcp_f32_e32 v167, v167
	v_rcp_f32_e32 v168, v168
	v_rcp_f32_e32 v169, v169
	v_pk_mul_f32 v[72:73], v[72:73], v[154:155]
	v_pk_mul_f32 v[74:75], v[74:75], v[156:157]
	v_pk_mul_f32 v[64:65], v[64:65], v[158:159]
	v_pk_mul_f32 v[66:67], v[66:67], v[160:161]
	v_cvt_pk_bf16_f32 v154, v72, v73
	v_cvt_pk_bf16_f32 v155, v74, v75
	v_cvt_pk_bf16_f32 v156, v64, v65
	v_cvt_pk_bf16_f32 v157, v66, v67
	global_store_dwordx4 v[178:179], v[154:157], off nt
	v_lshl_add_u64 v[178:179], v[178:179], 0, s[100:101]
	s_nop 1
	v_pk_mul_f32 v[154:155], v[28:29], v[220:221] op_sel_hi:[1,0]
	v_pk_mul_f32 v[156:157], v[30:31], v[220:221] op_sel_hi:[1,0]
	v_pk_mul_f32 v[158:159], v[20:21], v[220:221] op_sel_hi:[1,0]
	v_pk_mul_f32 v[160:161], v[22:23], v[220:221] op_sel_hi:[1,0]
	v_exp_f32_e32 v154, v154
	v_exp_f32_e32 v155, v155
	v_exp_f32_e32 v156, v156
	v_exp_f32_e32 v157, v157
	v_exp_f32_e32 v158, v158
	v_exp_f32_e32 v159, v159
; #define PG8_BAR __builtin_amdgcn_s_barrier()
; __device__ __forceinline__ unsigned cvt_pk2(float lo, float hi) { f32x2c v = {lo, hi}; bf16x2c q = __builtin_convertvector(v, bf16x2c); return __builtin_bit_cast(unsigned, q); }
; template <class Epi, class Sched, bool ALIGN_EPI = false, bool SP2 = false>
; __device__ __forceinline__ void gemm_phase(PG8_LAS unsigned char* lds, const Gemm g, const Sched& S, const Epi& E) {
;     ...
;         if constexpr (!Epi::AFTER_DRAIN) { E(acc, cur, wr, wc, fr, fq); S.done(cur); }
;         if (!has_next) break;
; #pragma unroll
;         for (int a = 0; a < 2; ++a)
; #pragma unroll
;             for (int b = 0; b < 2; ++b)
; #pragma unroll
;                 for (int m = 0; m < 4; ++m)
; #pragma unroll
;                     for (int n = 0; n < 2; ++n) acc[a][b][m][n] = (f32x4){0.f, 0.f, 0.f, 0.f};
;         cur = nxt; cA = nA; cB = nB; ++ui;
;         if constexpr (ALIGN_EPI) { if (wr == 1) PG8_BAR; }
;     __device__ __forceinline__ void operator()(const f32x4 (&acc)[2][2][4][2], const pg8::Unit& u, int wr, int wc, int fr, int fq) const {
;     ...
;             for (int m = 0; m < 4; ++m) { bf16_t* rowp = O + (size_t)(row0 + ai * 128 + m * 16) * FF + col0; const float r = rt[ai * 128 + m * 16];
;                 const float rl = -r * LOG2E, r2 = r * r; unsigned w[4];
; #pragma unroll
;                 for (int n = 0; n < 2; ++n)
; #pragma unroll
;                     for (int h = 0; h < 2; ++h) { const f32x2v g = {acc[ai][0][m][n][2 * h], acc[ai][0][m][n][2 * h + 1]}, uu = {acc[ai][1][m][n][2 * h], acc[ai][1][m][n][2 * h + 1]};
;                         const f32x2v t = g * rl; f32x2v d = {__builtin_amdgcn_exp2f(t.x), __builtin_amdgcn_exp2f(t.y)}; d = d + 1.0f;
;                         const f32x2v q = {__builtin_amdgcn_rcpf(d.x), __builtin_amdgcn_rcpf(d.y)}; const f32x2v o = ((g * uu) * r2) * q;
;                         w[2 * n + h] = cvt_pk2(o.x, o.y); }
;                 u32x4 wv; wv.x = w[0]; wv.y = w[1]; wv.z = w[2]; wv.w = w[3];
;                 *(u32x4*)rowp = wv; }
	v_exp_f32_e32 v160, v160
	v_exp_f32_e32 v161, v161
	v_pk_mul_f32 v[40:41], v[44:45], v[40:41]
	v_pk_mul_f32 v[42:43], v[46:47], v[42:43]
	v_pk_mul_f32 v[32:33], v[36:37], v[32:33]
	v_pk_mul_f32 v[34:35], v[38:39], v[34:35]
	v_pk_fma_f32 v[170:171], v[170:171], v[238:239], v[238:239] op_sel_hi:[1,0,0]
	v_pk_fma_f32 v[172:173], v[172:173], v[238:239], v[238:239] op_sel_hi:[1,0,0]
	v_pk_fma_f32 v[174:175], v[174:175], v[238:239], v[238:239] op_sel_hi:[1,0,0]
	v_pk_fma_f32 v[176:177], v[176:177], v[238:239], v[238:239] op_sel_hi:[1,0,0]
	v_rcp_f32_e32 v170, v170
	v_rcp_f32_e32 v171, v171
	v_rcp_f32_e32 v172, v172
	v_rcp_f32_e32 v173, v173
	v_rcp_f32_e32 v174, v174
	v_rcp_f32_e32 v175, v175
	v_rcp_f32_e32 v176, v176
	v_rcp_f32_e32 v177, v177
	v_pk_mul_f32 v[56:57], v[56:57], v[162:163]
	v_pk_mul_f32 v[58:59], v[58:59], v[164:165]
	v_pk_mul_f32 v[48:49], v[48:49], v[166:167]
	v_pk_mul_f32 v[50:51], v[50:51], v[168:169]
	v_cvt_pk_bf16_f32 v162, v56, v57
	v_cvt_pk_bf16_f32 v163, v58, v59
	v_cvt_pk_bf16_f32 v164, v48, v49
	v_cvt_pk_bf16_f32 v165, v50, v51
	global_store_dwordx4 v[178:179], v[162:165], off nt
	v_lshl_add_u64 v[178:179], v[178:179], 0, s[98:99]
	s_nop 1
	v_pk_mul_f32 v[162:163], v[12:13], v[222:223] op_sel_hi:[1,0]
	v_pk_mul_f32 v[164:165], v[14:15], v[222:223] op_sel_hi:[1,0]
	v_pk_mul_f32 v[166:167], v[4:5], v[222:223] op_sel_hi:[1,0]
	v_pk_mul_f32 v[168:169], v[6:7], v[222:223] op_sel_hi:[1,0]
	v_exp_f32_e32 v162, v162
	v_exp_f32_e32 v163, v163
	v_exp_f32_e32 v164, v164
	v_exp_f32_e32 v165, v165
	v_exp_f32_e32 v166, v166
	v_exp_f32_e32 v167, v167
	v_exp_f32_e32 v168, v168
	v_exp_f32_e32 v169, v169
	v_pk_mul_f32 v[24:25], v[28:29], v[24:25]
	v_pk_mul_f32 v[26:27], v[30:31], v[26:27]
	v_pk_mul_f32 v[16:17], v[20:21], v[16:17]
	v_pk_mul_f32 v[18:19], v[22:23], v[18:19]
	v_pk_fma_f32 v[154:155], v[154:155], v[240:241], v[240:241] op_sel_hi:[1,0,0]
	v_pk_fma_f32 v[156:157], v[156:157], v[240:241], v[240:241] op_sel_hi:[1,0,0]
	v_pk_fma_f32 v[158:159], v[158:159], v[240:241], v[240:241] op_sel_hi:[1,0,0]
	v_pk_fma_f32 v[160:161], v[160:161], v[240:241], v[240:241] op_sel_hi:[1,0,0]
	v_rcp_f32_e32 v154, v154
	v_rcp_f32_e32 v155, v155
	v_rcp_f32_e32 v156, v156
	v_rcp_f32_e32 v157, v157
	v_rcp_f32_e32 v158, v158
	v_rcp_f32_e32 v159, v159
	v_rcp_f32_e32 v160, v160
	v_rcp_f32_e32 v161, v161
	v_pk_mul_f32 v[40:41], v[40:41], v[170:171]
	v_pk_mul_f32 v[42:43], v[42:43], v[172:173]
	v_pk_mul_f32 v[32:33], v[32:33], v[174:175]
	v_pk_mul_f32 v[34:35], v[34:35], v[176:177]
	v_cvt_pk_bf16_f32 v170, v40, v41
	v_cvt_pk_bf16_f32 v171, v42, v43
	v_cvt_pk_bf16_f32 v172, v32, v33
	v_cvt_pk_bf16_f32 v173, v34, v35
	global_store_dwordx4 v[178:179], v[170:173], off nt
	v_lshl_add_u64 v[178:179], v[178:179], 0, s[98:99]
	s_nop 1
	v_pk_mul_f32 v[8:9], v[12:13], v[8:9]
	v_pk_mul_f32 v[10:11], v[14:15], v[10:11]
	v_pk_mul_f32 v[0:1], v[4:5], v[0:1]
	v_pk_mul_f32 v[2:3], v[6:7], v[2:3]
	v_pk_fma_f32 v[162:163], v[162:163], v[242:243], v[242:243] op_sel_hi:[1,0,0]
	v_pk_fma_f32 v[164:165], v[164:165], v[242:243], v[242:243] op_sel_hi:[1,0,0]
	v_pk_fma_f32 v[166:167], v[166:167], v[242:243], v[242:243] op_sel_hi:[1,0,0]
	v_pk_fma_f32 v[168:169], v[168:169], v[242:243], v[242:243] op_sel_hi:[1,0,0]
	v_rcp_f32_e32 v162, v162
	v_rcp_f32_e32 v163, v163
	v_rcp_f32_e32 v164, v164
	v_rcp_f32_e32 v165, v165
	v_rcp_f32_e32 v166, v166
	v_rcp_f32_e32 v167, v167
	v_rcp_f32_e32 v168, v168
	v_rcp_f32_e32 v169, v169
	v_pk_mul_f32 v[24:25], v[24:25], v[154:155]
	v_pk_mul_f32 v[26:27], v[26:27], v[156:157]
	v_pk_mul_f32 v[16:17], v[16:17], v[158:159]
	v_pk_mul_f32 v[18:19], v[18:19], v[160:161]
	v_cvt_pk_bf16_f32 v154, v24, v25
	v_cvt_pk_bf16_f32 v155, v26, v27
	v_cvt_pk_bf16_f32 v156, v16, v17
	v_cvt_pk_bf16_f32 v157, v18, v19
	global_store_dwordx4 v[178:179], v[154:157], off nt
	v_lshl_add_u64 v[178:179], v[178:179], 0, s[98:99]
	s_nop 1
	v_pk_mul_f32 v[8:9], v[8:9], v[162:163]
	v_pk_mul_f32 v[10:11], v[10:11], v[164:165]
	v_pk_mul_f32 v[0:1], v[0:1], v[166:167]
	v_pk_mul_f32 v[2:3], v[2:3], v[168:169]
	v_cvt_pk_bf16_f32 v162, v8, v9
	v_cvt_pk_bf16_f32 v163, v10, v11
	v_cvt_pk_bf16_f32 v164, v0, v1
	v_cvt_pk_bf16_f32 v165, v2, v3
	global_store_dwordx4 v[178:179], v[162:165], off nt
	s_andn2_b64 vcc, exec, s[4:5]
	s_mov_b64 s[4:5], -1
	s_cbranch_vccnz .LBB0_1736
	s_andn2_b64 vcc, exec, s[0:1]
	s_cbranch_vccnz .LBB0_1735
	s_barrier
	s_branch .LBB0_1735

; __device__ __forceinline__ unsigned cvt_pk_bf16(float lo, float hi) { unsigned r; asm volatile("v_cvt_pk_bf16_f32 %0, %1, %2" : "=v"(r) : "v"(lo), "v"(hi)); return r; }
;     __device__ __forceinline__ void operator()(const f32x4 (&acc)[2][2][4][2], const pg8::Unit& u, int wr, int wc, int fr, int fq) const {
;         const int row0 = u.pm * 256 + wr * 64 + fr, col0 = u.pn * 256 + wc * 32 + 8 * fq;
;         u32x4 xin[2][4][2];
; #pragma unroll
;         for (int ai = 0; ai < 2; ++ai)
; #pragma unroll
;             for (int m = 0; m < 4; ++m)
; #pragma unroll
;                 for (int bj = 0; bj < 2; ++bj) xin[ai][m][bj] = *(const u32x4*)(XB + (size_t)(row0 + ai * 128 + m * 16) * D + col0 + bj * 128);
; #pragma unroll
;         for (int ai = 0; ai < 2; ++ai)
; #pragma unroll
;             for (int m = 0; m < 4; ++m) { const size_t ro = (size_t)(row0 + ai * 128 + m * 16) * D + col0; float sq = 0.f;
; #pragma unroll
;                 for (int bj = 0; bj < 2; ++bj) { const u32x4 xb = xin[ai][m][bj];
;                     const f32x4 x0 = (f32x4){bf_lo(xb.x), bf_hi(xb.x), bf_lo(xb.y), bf_hi(xb.y)} + acc[ai][bj][m][0] * s, x1 = (f32x4){bf_lo(xb.z), bf_hi(xb.z), bf_lo(xb.w), bf_hi(xb.w)} + acc[ai][bj][m][1] * s;
;                     sq += (x0[0] * x0[0] + x0[1] * x0[1]) + (x0[2] * x0[2] + x0[3] * x0[3]) + (x1[0] * x1[0] + x1[1] * x1[1]) + (x1[2] * x1[2] + x1[3] * x1[3]);
;                     u32x4 w; w.x = cvt_pk_bf16(x0[0], x0[1]); w.y = cvt_pk_bf16(x0[2], x0[3]); w.z = cvt_pk_bf16(x1[0], x1[1]); w.w = cvt_pk_bf16(x1[2], x1[3]);
;                     *(u32x4*)(XB + ro + bj * 128) = w; }
;                 sq += __shfl_xor(sq, 16); sq += __shfl_xor(sq, 32);
;                 if (fq == 0) SSo[(size_t)(u.pn * 4 + wc) * T + row0 + ai * 128 + m * 16] = sq; }
.LBB0_1828:
	v_lshl_or_b32 v204, s66, 8, v221
	v_lshl_add_u32 v202, s67, 8, v220
	v_ashrrev_i32_e32 v205, 31, v204
	v_lshlrev_b64 v[234:235], 1, v[204:205]
	v_ashrrev_i32_e32 v203, 31, v202
	v_lshl_add_u64 v[96:97], s[36:37], 0, v[234:235]
	v_lshlrev_b64 v[236:237], 11, v[202:203]
	v_lshl_add_u64 v[98:99], v[96:97], 0, v[236:237]
	global_load_dwordx4 v[226:229], v[98:99], off
	global_load_dwordx4 v[230:233], v[98:99], off offset:256
	v_or_b32_e32 v98, 16, v202
	v_or_b32_e32 v108, 32, v202
	v_or_b32_e32 v110, 48, v202
	v_ashrrev_i32_e32 v99, 31, v98
	v_ashrrev_i32_e32 v109, 31, v108
	v_ashrrev_i32_e32 v111, 31, v110
	v_lshlrev_b64 v[218:219], 11, v[98:99]
	v_lshlrev_b64 v[216:217], 11, v[108:109]
	v_lshlrev_b64 v[214:215], 11, v[110:111]
	v_lshl_add_u64 v[212:213], v[236:237], 0, s[16:17]
	v_lshl_add_u64 v[210:211], v[236:237], 0, s[18:19]
	v_lshl_add_u64 v[208:209], v[236:237], 0, s[38:39]
	v_lshl_add_u64 v[206:207], v[236:237], 0, s[42:43]
	v_lshl_add_u64 v[98:99], v[96:97], 0, v[218:219]
	v_lshl_add_u64 v[108:109], v[96:97], 0, v[216:217]
	v_lshl_add_u64 v[110:111], v[96:97], 0, v[214:215]
	v_lshl_add_u64 v[120:121], v[96:97], 0, v[212:213]
	v_lshl_add_u64 v[122:123], v[96:97], 0, v[210:211]
	v_lshl_add_u64 v[238:239], v[96:97], 0, v[208:209]
	v_lshl_add_u64 v[96:97], v[96:97], 0, v[206:207]
	global_load_dwordx4 v[180:183], v[98:99], off
	global_load_dwordx4 v[176:179], v[98:99], off offset:256
	global_load_dwordx4 v[172:175], v[108:109], off
	global_load_dwordx4 v[168:171], v[108:109], off offset:256
	global_load_dwordx4 v[164:167], v[110:111], off
	global_load_dwordx4 v[160:163], v[110:111], off offset:256
	global_load_dwordx4 v[156:159], v[120:121], off
	global_load_dwordx4 v[152:155], v[120:121], off offset:256
	global_load_dwordx4 v[148:151], v[122:123], off
	global_load_dwordx4 v[144:147], v[122:123], off offset:256
	global_load_dwordx4 v[128:131], v[238:239], off
	s_nop 0
	global_load_dwordx4 v[120:123], v[238:239], off offset:256
	global_load_dwordx4 v[108:111], v[96:97], off
	s_nop 0
	global_load_dwordx4 v[96:99], v[96:97], off offset:256
	s_lshl_b32 s20, s66, 2
	s_or_b32 s20, s20, s56
	s_ashr_i32 s21, s20, 31
	s_lshl_b64 s[20:21], s[20:21], 17
	s_waitcnt vmcnt(0)
	v_lshlrev_b32_e32 v238, 16, v226
	v_and_b32_e32 v239, 0xffff0000, v226
	v_lshlrev_b32_e32 v226, 16, v227
	v_and_b32_e32 v227, 0xffff0000, v227
	v_lshlrev_b32_e32 v240, 16, v228
	v_and_b32_e32 v241, 0xffff0000, v228
	v_lshlrev_b32_e32 v242, 16, v230
	v_and_b32_e32 v243, 0xffff0000, v230
	v_lshlrev_b32_e32 v230, 16, v231
	v_and_b32_e32 v231, 0xffff0000, v231
	v_lshlrev_b32_e32 v244, 16, v232
	v_and_b32_e32 v245, 0xffff0000, v232
	v_lshlrev_b32_e32 v232, 16, v233
	v_and_b32_e32 v233, 0xffff0000, v233
	v_pk_fma_f32 v[142:143], v[142:143], 0.5, v[226:227] op_sel_hi:[1,0,1]
	v_pk_fma_f32 v[140:141], v[140:141], 0.5, v[238:239] op_sel_hi:[1,0,1]
	v_lshlrev_b32_e32 v228, 16, v229
	v_and_b32_e32 v229, 0xffff0000, v229
	v_pk_fma_f32 v[136:137], v[136:137], 0.5, v[240:241] op_sel_hi:[1,0,1]
	v_pk_fma_f32 v[226:227], v[134:135], 0.5, v[230:231] op_sel_hi:[1,0,1]
	v_pk_fma_f32 v[230:231], v[126:127], 0.5, v[232:233] op_sel_hi:[1,0,1]
	v_pk_fma_f32 v[232:233], v[124:125], 0.5, v[244:245] op_sel_hi:[1,0,1]
	v_mul_f32_e32 v124, v141, v141
	v_mul_f32_e32 v125, v143, v143
	v_pk_fma_f32 v[138:139], v[138:139], 0.5, v[228:229] op_sel_hi:[1,0,1]
	v_pk_fma_f32 v[228:229], v[132:133], 0.5, v[242:243] op_sel_hi:[1,0,1]
	v_mul_f32_e32 v126, v137, v137
	v_fmac_f32_e32 v124, v140, v140
	v_fmac_f32_e32 v125, v142, v142
	v_mul_f32_e32 v127, v139, v139
	v_cvt_pk_bf16_f32 v132, v140, v141
	v_cvt_pk_bf16_f32 v133, v142, v143
	v_cvt_pk_bf16_f32 v134, v136, v137
	v_cvt_pk_bf16_f32 v135, v138, v139
	v_mul_f32_e32 v137, v229, v229
	v_mul_f32_e32 v139, v227, v227
	v_fmac_f32_e32 v126, v136, v136
	v_add_f32_e32 v124, v124, v125
	v_fmac_f32_e32 v137, v228, v228
	v_fmac_f32_e32 v139, v226, v226
	v_add_f32_e32 v124, v126, v124
	v_mul_f32_e32 v126, v233, v233
	v_add_f32_e32 v125, v137, v139
	v_fmac_f32_e32 v126, v232, v232
	v_add_f32_e32 v125, v126, v125
	v_mul_f32_e32 v126, v231, v231
	v_fmac_f32_e32 v127, v138, v138
	v_fmac_f32_e32 v126, v230, v230
	v_add_f32_e32 v124, v127, v124
	v_add_f32_e32 v125, v126, v125
	v_and_b32_e32 v126, 64, v225
	v_add_f32_e32 v125, v124, v125
	v_add_u32_e32 v138, 64, v126
	v_lshl_add_u64 v[126:127], s[36:37], 0, v[236:237]
	v_lshl_add_u64 v[136:137], v[126:127], 0, v[234:235]
	v_mov_b32_e32 v139, v125
	s_nop 1
	v_permlane16_swap_b32_e32 v139, v125
	global_store_dwordx4 v[136:137], v[132:135], off nt
	s_waitcnt lgkmcnt(0)
	v_add_f32_e32 v126, v125, v139
	v_cvt_pk_bf16_f32 v132, v228, v229
	v_cvt_pk_bf16_f32 v133, v226, v227
	v_cvt_pk_bf16_f32 v134, v232, v233
	v_cvt_pk_bf16_f32 v135, v230, v231
	global_store_dwordx4 v[136:137], v[132:135], off offset:256 nt
	s_nop 0
	v_mov_b32_e32 v127, v126
	s_nop 1
	v_permlane32_swap_b32_e32 v127, v126
	s_and_saveexec_b64 s[34:35], s[4:5]
	s_cbranch_execz .LBB0_1830
	s_add_u32 s46, s54, s20
	s_addc_u32 s47, s55, s21
	v_lshl_add_u64 v[132:133], v[202:203], 2, s[46:47]
	s_waitcnt lgkmcnt(0)
	v_add_f32_e32 v126, v126, v127
	global_store_dword v[132:133], v126, off
; __device__ __forceinline__ unsigned cvt_pk_bf16(float lo, float hi) { unsigned r; asm volatile("v_cvt_pk_bf16_f32 %0, %1, %2" : "=v"(r) : "v"(lo), "v"(hi)); return r; }
;     __device__ __forceinline__ void operator()(const f32x4 (&acc)[2][2][4][2], const pg8::Unit& u, int wr, int wc, int fr, int fq) const {
;     ...
;             for (int m = 0; m < 4; ++m) { const size_t ro = (size_t)(row0 + ai * 128 + m * 16) * D + col0; float sq = 0.f;
; #pragma unroll
;                 for (int bj = 0; bj < 2; ++bj) { const u32x4 xb = xin[ai][m][bj];
;                     const f32x4 x0 = (f32x4){bf_lo(xb.x), bf_hi(xb.x), bf_lo(xb.y), bf_hi(xb.y)} + acc[ai][bj][m][0] * s, x1 = (f32x4){bf_lo(xb.z), bf_hi(xb.z), bf_lo(xb.w), bf_hi(xb.w)} + acc[ai][bj][m][1] * s;
;                     sq += (x0[0] * x0[0] + x0[1] * x0[1]) + (x0[2] * x0[2] + x0[3] * x0[3]) + (x1[0] * x1[0] + x1[1] * x1[1]) + (x1[2] * x1[2] + x1[3] * x1[3]);
;                     u32x4 w; w.x = cvt_pk_bf16(x0[0], x0[1]); w.y = cvt_pk_bf16(x0[2], x0[3]); w.z = cvt_pk_bf16(x1[0], x1[1]); w.w = cvt_pk_bf16(x1[2], x1[3]);
;                     *(u32x4*)(XB + ro + bj * 128) = w; }
;                 sq += __shfl_xor(sq, 16); sq += __shfl_xor(sq, 32);
;                 if (fq == 0) SSo[(size_t)(u.pn * 4 + wc) * T + row0 + ai * 128 + m * 16] = sq; }
.LBB0_1830:
	s_or_b64 exec, exec, s[34:35]
	v_lshlrev_b32_e32 v126, 16, v180
	s_waitcnt lgkmcnt(0)
	v_and_b32_e32 v127, 0xffff0000, v180
	v_lshlrev_b32_e32 v132, 16, v181
	v_and_b32_e32 v133, 0xffff0000, v181
	v_pk_fma_f32 v[118:119], v[118:119], 0.5, v[132:133] op_sel_hi:[1,0,1]
	v_pk_fma_f32 v[116:117], v[116:117], 0.5, v[126:127] op_sel_hi:[1,0,1]
	v_lshlrev_b32_e32 v126, 16, v182
	v_and_b32_e32 v127, 0xffff0000, v182
	v_lshlrev_b32_e32 v132, 16, v183
	v_and_b32_e32 v133, 0xffff0000, v183
	v_pk_fma_f32 v[132:133], v[114:115], 0.5, v[132:133] op_sel_hi:[1,0,1]
	v_pk_fma_f32 v[114:115], v[112:113], 0.5, v[126:127] op_sel_hi:[1,0,1]
	v_mul_f32_e32 v112, v117, v117
	v_mul_f32_e32 v113, v119, v119
	v_fmac_f32_e32 v112, v116, v116
	v_fmac_f32_e32 v113, v118, v118
	v_add_f32_e32 v112, v112, v113
	v_mul_f32_e32 v113, v115, v115
	v_fmac_f32_e32 v113, v114, v114
	v_add_f32_e32 v112, v113, v112
	v_mul_f32_e32 v113, v133, v133
	v_fmac_f32_e32 v113, v132, v132
	v_add_f32_e32 v126, v113, v112
	v_cvt_pk_bf16_f32 v112, v116, v117
	v_cvt_pk_bf16_f32 v113, v118, v119
	v_lshlrev_b32_e32 v116, 16, v176
	v_and_b32_e32 v117, 0xffff0000, v176
	v_lshlrev_b32_e32 v118, 16, v177
	v_and_b32_e32 v119, 0xffff0000, v177
	v_pk_fma_f32 v[106:107], v[106:107], 0.5, v[118:119] op_sel_hi:[1,0,1]
	v_pk_fma_f32 v[104:105], v[104:105], 0.5, v[116:117] op_sel_hi:[1,0,1]
	v_lshlrev_b32_e32 v116, 16, v178
	v_and_b32_e32 v117, 0xffff0000, v178
	v_pk_fma_f32 v[116:117], v[100:101], 0.5, v[116:117] op_sel_hi:[1,0,1]
	v_mul_f32_e32 v100, v105, v105
	v_mul_f32_e32 v101, v107, v107
	v_fmac_f32_e32 v100, v104, v104
	v_fmac_f32_e32 v101, v106, v106
	v_lshlrev_b32_e32 v118, 16, v179
	v_and_b32_e32 v119, 0xffff0000, v179
	v_add_f32_e32 v100, v100, v101
	v_mul_f32_e32 v101, v117, v117
	v_pk_fma_f32 v[118:119], v[102:103], 0.5, v[118:119] op_sel_hi:[1,0,1]
	v_fmac_f32_e32 v101, v116, v116
	v_add_f32_e32 v100, v101, v100
	v_mul_f32_e32 v101, v119, v119
	v_fmac_f32_e32 v101, v118, v118
	v_add_f32_e32 v100, v101, v100
	v_add_f32_e32 v103, v126, v100
	v_cvt_pk_bf16_f32 v114, v114, v115
	v_cvt_pk_bf16_f32 v115, v132, v133
	v_mov_b32_e32 v132, v103
	s_nop 1
	v_permlane16_swap_b32_e32 v132, v103
	v_lshl_add_u64 v[100:101], s[36:37], 0, v[218:219]
	v_lshl_add_u64 v[126:127], v[204:205], 1, v[100:101]
	global_store_dwordx4 v[126:127], v[112:115], off nt
	v_cvt_pk_bf16_f32 v102, v104, v105
	s_waitcnt lgkmcnt(0)
	v_add_f32_e32 v100, v103, v132
	v_mov_b32_e32 v101, v100
	s_nop 1
	v_permlane32_swap_b32_e32 v101, v100
	v_cvt_pk_bf16_f32 v103, v106, v107
	v_cvt_pk_bf16_f32 v104, v116, v117
	v_cvt_pk_bf16_f32 v105, v118, v119
	global_store_dwordx4 v[126:127], v[102:105], off offset:256 nt
	s_and_saveexec_b64 s[34:35], s[4:5]
	s_cbranch_execz .LBB0_1832
	s_add_u32 s46, s54, s20
	s_addc_u32 s47, s55, s21
	v_lshl_add_u64 v[102:103], v[202:203], 2, s[46:47]
	s_waitcnt lgkmcnt(0)
	v_add_f32_e32 v100, v100, v101
	global_store_dword v[102:103], v100, off offset:64
.LBB0_1832:
	s_or_b64 exec, exec, s[34:35]
	v_lshlrev_b32_e32 v100, 16, v172
	s_waitcnt lgkmcnt(0)
	v_and_b32_e32 v101, 0xffff0000, v172
	v_lshlrev_b32_e32 v102, 16, v173
	v_and_b32_e32 v103, 0xffff0000, v173
	v_pk_fma_f32 v[94:95], v[94:95], 0.5, v[102:103] op_sel_hi:[1,0,1]
	v_pk_fma_f32 v[92:93], v[92:93], 0.5, v[100:101] op_sel_hi:[1,0,1]
	v_lshlrev_b32_e32 v100, 16, v174
	v_and_b32_e32 v101, 0xffff0000, v174
	v_lshlrev_b32_e32 v102, 16, v175
	v_and_b32_e32 v103, 0xffff0000, v175
	v_pk_fma_f32 v[102:103], v[90:91], 0.5, v[102:103] op_sel_hi:[1,0,1]
	v_pk_fma_f32 v[90:91], v[88:89], 0.5, v[100:101] op_sel_hi:[1,0,1]
	v_mul_f32_e32 v88, v93, v93
	v_mul_f32_e32 v89, v95, v95
	v_fmac_f32_e32 v88, v92, v92
	v_fmac_f32_e32 v89, v94, v94
	v_add_f32_e32 v88, v88, v89
	v_mul_f32_e32 v89, v91, v91
	v_fmac_f32_e32 v89, v90, v90
	v_add_f32_e32 v88, v89, v88
	v_mul_f32_e32 v89, v103, v103
	v_fmac_f32_e32 v89, v102, v102
	v_add_f32_e32 v100, v89, v88
	v_cvt_pk_bf16_f32 v88, v92, v93
	v_cvt_pk_bf16_f32 v89, v94, v95
	v_lshlrev_b32_e32 v92, 16, v168
	v_and_b32_e32 v93, 0xffff0000, v168
	v_lshlrev_b32_e32 v94, 16, v169
	v_and_b32_e32 v95, 0xffff0000, v169
	v_pk_fma_f32 v[86:87], v[86:87], 0.5, v[94:95] op_sel_hi:[1,0,1]
	v_pk_fma_f32 v[84:85], v[84:85], 0.5, v[92:93] op_sel_hi:[1,0,1]
	v_lshlrev_b32_e32 v92, 16, v170
	v_and_b32_e32 v93, 0xffff0000, v170
	v_pk_fma_f32 v[92:93], v[80:81], 0.5, v[92:93] op_sel_hi:[1,0,1]
	v_mul_f32_e32 v80, v85, v85
	v_mul_f32_e32 v81, v87, v87
	v_fmac_f32_e32 v80, v84, v84
	v_fmac_f32_e32 v81, v86, v86
	v_lshlrev_b32_e32 v94, 16, v171
	v_and_b32_e32 v95, 0xffff0000, v171
	v_add_f32_e32 v80, v80, v81
	v_mul_f32_e32 v81, v93, v93
	v_pk_fma_f32 v[94:95], v[82:83], 0.5, v[94:95] op_sel_hi:[1,0,1]
	v_fmac_f32_e32 v81, v92, v92
	v_add_f32_e32 v80, v81, v80
	v_mul_f32_e32 v81, v95, v95
	v_fmac_f32_e32 v81, v94, v94
	v_add_f32_e32 v80, v81, v80
	v_add_f32_e32 v83, v100, v80
	v_cvt_pk_bf16_f32 v90, v90, v91
	v_cvt_pk_bf16_f32 v91, v102, v103
	v_mov_b32_e32 v102, v83
	s_nop 1
	v_permlane16_swap_b32_e32 v102, v83
	v_lshl_add_u64 v[80:81], s[36:37], 0, v[216:217]
	v_lshl_add_u64 v[100:101], v[204:205], 1, v[80:81]
	global_store_dwordx4 v[100:101], v[88:91], off nt
	v_cvt_pk_bf16_f32 v82, v84, v85
	s_waitcnt lgkmcnt(0)
	v_add_f32_e32 v80, v83, v102
	v_mov_b32_e32 v81, v80
	s_nop 1
	v_permlane32_swap_b32_e32 v81, v80
	v_cvt_pk_bf16_f32 v83, v86, v87
	v_cvt_pk_bf16_f32 v84, v92, v93
	v_cvt_pk_bf16_f32 v85, v94, v95
	global_store_dwordx4 v[100:101], v[82:85], off offset:256 nt
	s_and_saveexec_b64 s[34:35], s[4:5]
	s_cbranch_execz .LBB0_1834
	s_add_u32 s46, s54, s20
	s_addc_u32 s47, s55, s21
	v_lshl_add_u64 v[82:83], v[202:203], 2, s[46:47]
	s_waitcnt lgkmcnt(0)
	v_add_f32_e32 v80, v80, v81
	global_store_dword v[82:83], v80, off offset:128
; __device__ __forceinline__ unsigned cvt_pk_bf16(float lo, float hi) { unsigned r; asm volatile("v_cvt_pk_bf16_f32 %0, %1, %2" : "=v"(r) : "v"(lo), "v"(hi)); return r; }
;     __device__ __forceinline__ void operator()(const f32x4 (&acc)[2][2][4][2], const pg8::Unit& u, int wr, int wc, int fr, int fq) const {
;     ...
;             for (int m = 0; m < 4; ++m) { const size_t ro = (size_t)(row0 + ai * 128 + m * 16) * D + col0; float sq = 0.f;
; #pragma unroll
;                 for (int bj = 0; bj < 2; ++bj) { const u32x4 xb = xin[ai][m][bj];
;                     const f32x4 x0 = (f32x4){bf_lo(xb.x), bf_hi(xb.x), bf_lo(xb.y), bf_hi(xb.y)} + acc[ai][bj][m][0] * s, x1 = (f32x4){bf_lo(xb.z), bf_hi(xb.z), bf_lo(xb.w), bf_hi(xb.w)} + acc[ai][bj][m][1] * s;
;                     sq += (x0[0] * x0[0] + x0[1] * x0[1]) + (x0[2] * x0[2] + x0[3] * x0[3]) + (x1[0] * x1[0] + x1[1] * x1[1]) + (x1[2] * x1[2] + x1[3] * x1[3]);
;                     u32x4 w; w.x = cvt_pk_bf16(x0[0], x0[1]); w.y = cvt_pk_bf16(x0[2], x0[3]); w.z = cvt_pk_bf16(x1[0], x1[1]); w.w = cvt_pk_bf16(x1[2], x1[3]);
;                     *(u32x4*)(XB + ro + bj * 128) = w; }
;                 sq += __shfl_xor(sq, 16); sq += __shfl_xor(sq, 32);
;                 if (fq == 0) SSo[(size_t)(u.pn * 4 + wc) * T + row0 + ai * 128 + m * 16] = sq; }
.LBB0_1834:
	s_or_b64 exec, exec, s[34:35]
	v_lshlrev_b32_e32 v80, 16, v164
	s_waitcnt lgkmcnt(0)
	v_and_b32_e32 v81, 0xffff0000, v164
	v_lshlrev_b32_e32 v82, 16, v165
	v_and_b32_e32 v83, 0xffff0000, v165
	v_pk_fma_f32 v[78:79], v[78:79], 0.5, v[82:83] op_sel_hi:[1,0,1]
	v_pk_fma_f32 v[76:77], v[76:77], 0.5, v[80:81] op_sel_hi:[1,0,1]
	v_lshlrev_b32_e32 v80, 16, v166
	v_and_b32_e32 v81, 0xffff0000, v166
	v_lshlrev_b32_e32 v82, 16, v167
	v_and_b32_e32 v83, 0xffff0000, v167
	v_pk_fma_f32 v[82:83], v[74:75], 0.5, v[82:83] op_sel_hi:[1,0,1]
	v_pk_fma_f32 v[74:75], v[72:73], 0.5, v[80:81] op_sel_hi:[1,0,1]
	v_mul_f32_e32 v72, v77, v77
	v_mul_f32_e32 v73, v79, v79
	v_fmac_f32_e32 v72, v76, v76
	v_fmac_f32_e32 v73, v78, v78
	v_add_f32_e32 v72, v72, v73
	v_mul_f32_e32 v73, v75, v75
	v_fmac_f32_e32 v73, v74, v74
	v_add_f32_e32 v72, v73, v72
	v_mul_f32_e32 v73, v83, v83
	v_fmac_f32_e32 v73, v82, v82
	v_add_f32_e32 v80, v73, v72
	v_cvt_pk_bf16_f32 v72, v76, v77
	v_cvt_pk_bf16_f32 v73, v78, v79
	v_lshlrev_b32_e32 v76, 16, v160
	v_and_b32_e32 v77, 0xffff0000, v160
	v_lshlrev_b32_e32 v78, 16, v161
	v_and_b32_e32 v79, 0xffff0000, v161
	v_pk_fma_f32 v[70:71], v[70:71], 0.5, v[78:79] op_sel_hi:[1,0,1]
	v_pk_fma_f32 v[68:69], v[68:69], 0.5, v[76:77] op_sel_hi:[1,0,1]
	v_lshlrev_b32_e32 v76, 16, v162
	v_and_b32_e32 v77, 0xffff0000, v162
	v_pk_fma_f32 v[76:77], v[64:65], 0.5, v[76:77] op_sel_hi:[1,0,1]
	v_mul_f32_e32 v64, v69, v69
	v_mul_f32_e32 v65, v71, v71
	v_fmac_f32_e32 v64, v68, v68
	v_fmac_f32_e32 v65, v70, v70
	v_lshlrev_b32_e32 v78, 16, v163
	v_and_b32_e32 v79, 0xffff0000, v163
	v_add_f32_e32 v64, v64, v65
	v_mul_f32_e32 v65, v77, v77
	v_pk_fma_f32 v[78:79], v[66:67], 0.5, v[78:79] op_sel_hi:[1,0,1]
	v_fmac_f32_e32 v65, v76, v76
	v_add_f32_e32 v64, v65, v64
	v_mul_f32_e32 v65, v79, v79
	v_fmac_f32_e32 v65, v78, v78
	v_add_f32_e32 v64, v65, v64
	v_add_f32_e32 v67, v80, v64
	v_cvt_pk_bf16_f32 v74, v74, v75
	v_cvt_pk_bf16_f32 v75, v82, v83
	v_mov_b32_e32 v82, v67
	s_nop 1
	v_permlane16_swap_b32_e32 v82, v67
	v_lshl_add_u64 v[64:65], s[36:37], 0, v[214:215]
	v_lshl_add_u64 v[80:81], v[204:205], 1, v[64:65]
	global_store_dwordx4 v[80:81], v[72:75], off nt
	v_cvt_pk_bf16_f32 v66, v68, v69
	s_waitcnt lgkmcnt(0)
	v_add_f32_e32 v64, v67, v82
	v_mov_b32_e32 v65, v64
	s_nop 1
	v_permlane32_swap_b32_e32 v65, v64
	v_cvt_pk_bf16_f32 v67, v70, v71
	v_cvt_pk_bf16_f32 v68, v76, v77
	v_cvt_pk_bf16_f32 v69, v78, v79
	global_store_dwordx4 v[80:81], v[66:69], off offset:256 nt
	s_and_saveexec_b64 s[34:35], s[4:5]
	s_cbranch_execz .LBB0_1836
	s_add_u32 s46, s54, s20
	s_addc_u32 s47, s55, s21
	v_lshl_add_u64 v[66:67], v[202:203], 2, s[46:47]
	s_waitcnt lgkmcnt(0)
	v_add_f32_e32 v64, v64, v65
	global_store_dword v[66:67], v64, off offset:192
.LBB0_1836:
	s_or_b64 exec, exec, s[34:35]
	v_lshlrev_b32_e32 v64, 16, v156
	s_waitcnt lgkmcnt(0)
	v_and_b32_e32 v65, 0xffff0000, v156
	v_lshlrev_b32_e32 v66, 16, v157
	v_and_b32_e32 v67, 0xffff0000, v157
	v_pk_fma_f32 v[62:63], v[62:63], 0.5, v[66:67] op_sel_hi:[1,0,1]
	v_pk_fma_f32 v[60:61], v[60:61], 0.5, v[64:65] op_sel_hi:[1,0,1]
	v_lshlrev_b32_e32 v64, 16, v158
	v_and_b32_e32 v65, 0xffff0000, v158
	v_lshlrev_b32_e32 v66, 16, v159
	v_and_b32_e32 v67, 0xffff0000, v159
	v_pk_fma_f32 v[66:67], v[58:59], 0.5, v[66:67] op_sel_hi:[1,0,1]
	v_pk_fma_f32 v[58:59], v[56:57], 0.5, v[64:65] op_sel_hi:[1,0,1]
	v_mul_f32_e32 v56, v61, v61
	v_mul_f32_e32 v57, v63, v63
	v_fmac_f32_e32 v56, v60, v60
	v_fmac_f32_e32 v57, v62, v62
	v_add_f32_e32 v56, v56, v57
	v_mul_f32_e32 v57, v59, v59
	v_fmac_f32_e32 v57, v58, v58
	v_add_f32_e32 v56, v57, v56
	v_mul_f32_e32 v57, v67, v67
	v_fmac_f32_e32 v57, v66, v66
	v_add_f32_e32 v64, v57, v56
	v_cvt_pk_bf16_f32 v56, v60, v61
	v_cvt_pk_bf16_f32 v57, v62, v63
	v_lshlrev_b32_e32 v60, 16, v152
	v_and_b32_e32 v61, 0xffff0000, v152
	v_lshlrev_b32_e32 v62, 16, v153
	v_and_b32_e32 v63, 0xffff0000, v153
	v_pk_fma_f32 v[54:55], v[54:55], 0.5, v[62:63] op_sel_hi:[1,0,1]
	v_pk_fma_f32 v[52:53], v[52:53], 0.5, v[60:61] op_sel_hi:[1,0,1]
	v_lshlrev_b32_e32 v60, 16, v154
	v_and_b32_e32 v61, 0xffff0000, v154
	v_pk_fma_f32 v[60:61], v[48:49], 0.5, v[60:61] op_sel_hi:[1,0,1]
	v_mul_f32_e32 v48, v53, v53
	v_mul_f32_e32 v49, v55, v55
	v_fmac_f32_e32 v48, v52, v52
	v_fmac_f32_e32 v49, v54, v54
	v_lshlrev_b32_e32 v62, 16, v155
	v_and_b32_e32 v63, 0xffff0000, v155
	v_add_f32_e32 v48, v48, v49
	v_mul_f32_e32 v49, v61, v61
	v_pk_fma_f32 v[62:63], v[50:51], 0.5, v[62:63] op_sel_hi:[1,0,1]
	v_fmac_f32_e32 v49, v60, v60
	v_add_f32_e32 v48, v49, v48
	v_mul_f32_e32 v49, v63, v63
	v_fmac_f32_e32 v49, v62, v62
	v_add_f32_e32 v48, v49, v48
	v_add_f32_e32 v51, v64, v48
	v_cvt_pk_bf16_f32 v58, v58, v59
	v_cvt_pk_bf16_f32 v59, v66, v67
	v_mov_b32_e32 v66, v51
	s_nop 1
	v_permlane16_swap_b32_e32 v66, v51
	v_lshl_add_u64 v[48:49], s[36:37], 0, v[212:213]
	v_lshl_add_u64 v[64:65], v[204:205], 1, v[48:49]
	global_store_dwordx4 v[64:65], v[56:59], off nt
	v_cvt_pk_bf16_f32 v50, v52, v53
	s_waitcnt lgkmcnt(0)
	v_add_f32_e32 v48, v51, v66
	v_mov_b32_e32 v49, v48
	s_nop 1
	v_permlane32_swap_b32_e32 v49, v48
	v_cvt_pk_bf16_f32 v51, v54, v55
	v_cvt_pk_bf16_f32 v52, v60, v61
	v_cvt_pk_bf16_f32 v53, v62, v63
	global_store_dwordx4 v[64:65], v[50:53], off offset:256 nt
	s_and_saveexec_b64 s[34:35], s[4:5]
	s_cbranch_execz .LBB0_1838
	s_add_u32 s46, s54, s20
	s_addc_u32 s47, s55, s21
	v_lshl_add_u64 v[50:51], v[202:203], 2, s[46:47]
	s_waitcnt lgkmcnt(0)
	v_add_f32_e32 v48, v48, v49
	global_store_dword v[50:51], v48, off offset:512
; __device__ __forceinline__ unsigned cvt_pk_bf16(float lo, float hi) { unsigned r; asm volatile("v_cvt_pk_bf16_f32 %0, %1, %2" : "=v"(r) : "v"(lo), "v"(hi)); return r; }
;     __device__ __forceinline__ void operator()(const f32x4 (&acc)[2][2][4][2], const pg8::Unit& u, int wr, int wc, int fr, int fq) const {
;     ...
;             for (int m = 0; m < 4; ++m) { const size_t ro = (size_t)(row0 + ai * 128 + m * 16) * D + col0; float sq = 0.f;
; #pragma unroll
;                 for (int bj = 0; bj < 2; ++bj) { const u32x4 xb = xin[ai][m][bj];
;                     const f32x4 x0 = (f32x4){bf_lo(xb.x), bf_hi(xb.x), bf_lo(xb.y), bf_hi(xb.y)} + acc[ai][bj][m][0] * s, x1 = (f32x4){bf_lo(xb.z), bf_hi(xb.z), bf_lo(xb.w), bf_hi(xb.w)} + acc[ai][bj][m][1] * s;
;                     sq += (x0[0] * x0[0] + x0[1] * x0[1]) + (x0[2] * x0[2] + x0[3] * x0[3]) + (x1[0] * x1[0] + x1[1] * x1[1]) + (x1[2] * x1[2] + x1[3] * x1[3]);
;                     u32x4 w; w.x = cvt_pk_bf16(x0[0], x0[1]); w.y = cvt_pk_bf16(x0[2], x0[3]); w.z = cvt_pk_bf16(x1[0], x1[1]); w.w = cvt_pk_bf16(x1[2], x1[3]);
;                     *(u32x4*)(XB + ro + bj * 128) = w; }
;                 sq += __shfl_xor(sq, 16); sq += __shfl_xor(sq, 32);
;                 if (fq == 0) SSo[(size_t)(u.pn * 4 + wc) * T + row0 + ai * 128 + m * 16] = sq; }
.LBB0_1838:
	s_or_b64 exec, exec, s[34:35]
	v_lshlrev_b32_e32 v48, 16, v148
	s_waitcnt lgkmcnt(0)
	v_and_b32_e32 v49, 0xffff0000, v148
	v_lshlrev_b32_e32 v50, 16, v149
	v_and_b32_e32 v51, 0xffff0000, v149
	v_pk_fma_f32 v[46:47], v[46:47], 0.5, v[50:51] op_sel_hi:[1,0,1]
	v_pk_fma_f32 v[44:45], v[44:45], 0.5, v[48:49] op_sel_hi:[1,0,1]
	v_lshlrev_b32_e32 v48, 16, v150
	v_and_b32_e32 v49, 0xffff0000, v150
	v_lshlrev_b32_e32 v50, 16, v151
	v_and_b32_e32 v51, 0xffff0000, v151
	v_pk_fma_f32 v[50:51], v[42:43], 0.5, v[50:51] op_sel_hi:[1,0,1]
	v_pk_fma_f32 v[42:43], v[40:41], 0.5, v[48:49] op_sel_hi:[1,0,1]
	v_mul_f32_e32 v40, v45, v45
	v_mul_f32_e32 v41, v47, v47
	v_fmac_f32_e32 v40, v44, v44
	v_fmac_f32_e32 v41, v46, v46
	v_add_f32_e32 v40, v40, v41
	v_mul_f32_e32 v41, v43, v43
	v_fmac_f32_e32 v41, v42, v42
	v_add_f32_e32 v40, v41, v40
	v_mul_f32_e32 v41, v51, v51
	v_fmac_f32_e32 v41, v50, v50
	v_add_f32_e32 v48, v41, v40
	v_cvt_pk_bf16_f32 v40, v44, v45
	v_cvt_pk_bf16_f32 v41, v46, v47
	v_lshlrev_b32_e32 v44, 16, v144
	v_and_b32_e32 v45, 0xffff0000, v144
	v_lshlrev_b32_e32 v46, 16, v145
	v_and_b32_e32 v47, 0xffff0000, v145
	v_pk_fma_f32 v[38:39], v[38:39], 0.5, v[46:47] op_sel_hi:[1,0,1]
	v_pk_fma_f32 v[36:37], v[36:37], 0.5, v[44:45] op_sel_hi:[1,0,1]
	v_lshlrev_b32_e32 v44, 16, v146
	v_and_b32_e32 v45, 0xffff0000, v146
	v_pk_fma_f32 v[44:45], v[32:33], 0.5, v[44:45] op_sel_hi:[1,0,1]
	v_mul_f32_e32 v32, v37, v37
	v_mul_f32_e32 v33, v39, v39
	v_fmac_f32_e32 v32, v36, v36
	v_fmac_f32_e32 v33, v38, v38
	v_lshlrev_b32_e32 v46, 16, v147
	v_and_b32_e32 v47, 0xffff0000, v147
	v_add_f32_e32 v32, v32, v33
	v_mul_f32_e32 v33, v45, v45
	v_pk_fma_f32 v[46:47], v[34:35], 0.5, v[46:47] op_sel_hi:[1,0,1]
	v_fmac_f32_e32 v33, v44, v44
	v_add_f32_e32 v32, v33, v32
	v_mul_f32_e32 v33, v47, v47
	v_fmac_f32_e32 v33, v46, v46
	v_add_f32_e32 v32, v33, v32
	v_add_f32_e32 v35, v48, v32
	v_cvt_pk_bf16_f32 v42, v42, v43
	v_cvt_pk_bf16_f32 v43, v50, v51
	v_mov_b32_e32 v50, v35
	s_nop 1
	v_permlane16_swap_b32_e32 v50, v35
	v_lshl_add_u64 v[32:33], s[36:37], 0, v[210:211]
	v_lshl_add_u64 v[48:49], v[204:205], 1, v[32:33]
	global_store_dwordx4 v[48:49], v[40:43], off nt
	v_cvt_pk_bf16_f32 v34, v36, v37
	s_waitcnt lgkmcnt(0)
	v_add_f32_e32 v32, v35, v50
	v_mov_b32_e32 v33, v32
	s_nop 1
	v_permlane32_swap_b32_e32 v33, v32
	v_cvt_pk_bf16_f32 v35, v38, v39
	v_cvt_pk_bf16_f32 v36, v44, v45
	v_cvt_pk_bf16_f32 v37, v46, v47
	global_store_dwordx4 v[48:49], v[34:37], off offset:256 nt
	s_and_saveexec_b64 s[34:35], s[4:5]
	s_cbranch_execz .LBB0_1840
	s_add_u32 s46, s54, s20
	s_addc_u32 s47, s55, s21
	v_lshl_add_u64 v[34:35], v[202:203], 2, s[46:47]
	s_waitcnt lgkmcnt(0)
	v_add_f32_e32 v32, v32, v33
	global_store_dword v[34:35], v32, off offset:576
; __device__ __forceinline__ unsigned cvt_pk_bf16(float lo, float hi) { unsigned r; asm volatile("v_cvt_pk_bf16_f32 %0, %1, %2" : "=v"(r) : "v"(lo), "v"(hi)); return r; }
;     __device__ __forceinline__ void operator()(const f32x4 (&acc)[2][2][4][2], const pg8::Unit& u, int wr, int wc, int fr, int fq) const {
;     ...
;             for (int m = 0; m < 4; ++m) { const size_t ro = (size_t)(row0 + ai * 128 + m * 16) * D + col0; float sq = 0.f;
; #pragma unroll
;                 for (int bj = 0; bj < 2; ++bj) { const u32x4 xb = xin[ai][m][bj];
;                     const f32x4 x0 = (f32x4){bf_lo(xb.x), bf_hi(xb.x), bf_lo(xb.y), bf_hi(xb.y)} + acc[ai][bj][m][0] * s, x1 = (f32x4){bf_lo(xb.z), bf_hi(xb.z), bf_lo(xb.w), bf_hi(xb.w)} + acc[ai][bj][m][1] * s;
;                     sq += (x0[0] * x0[0] + x0[1] * x0[1]) + (x0[2] * x0[2] + x0[3] * x0[3]) + (x1[0] * x1[0] + x1[1] * x1[1]) + (x1[2] * x1[2] + x1[3] * x1[3]);
;                     u32x4 w; w.x = cvt_pk_bf16(x0[0], x0[1]); w.y = cvt_pk_bf16(x0[2], x0[3]); w.z = cvt_pk_bf16(x1[0], x1[1]); w.w = cvt_pk_bf16(x1[2], x1[3]);
;                     *(u32x4*)(XB + ro + bj * 128) = w; }
;                 sq += __shfl_xor(sq, 16); sq += __shfl_xor(sq, 32);
;                 if (fq == 0) SSo[(size_t)(u.pn * 4 + wc) * T + row0 + ai * 128 + m * 16] = sq; }
.LBB0_1840:
	s_or_b64 exec, exec, s[34:35]
	v_lshlrev_b32_e32 v32, 16, v128
	s_waitcnt lgkmcnt(0)
	v_and_b32_e32 v33, 0xffff0000, v128
	v_lshlrev_b32_e32 v34, 16, v129
	v_and_b32_e32 v35, 0xffff0000, v129
	v_pk_fma_f32 v[30:31], v[30:31], 0.5, v[34:35] op_sel_hi:[1,0,1]
	v_pk_fma_f32 v[28:29], v[28:29], 0.5, v[32:33] op_sel_hi:[1,0,1]
	v_lshlrev_b32_e32 v32, 16, v130
	v_and_b32_e32 v33, 0xffff0000, v130
	v_lshlrev_b32_e32 v34, 16, v131
	v_and_b32_e32 v35, 0xffff0000, v131
	v_pk_fma_f32 v[34:35], v[26:27], 0.5, v[34:35] op_sel_hi:[1,0,1]
	v_pk_fma_f32 v[26:27], v[24:25], 0.5, v[32:33] op_sel_hi:[1,0,1]
	v_mul_f32_e32 v24, v29, v29
	v_mul_f32_e32 v25, v31, v31
	v_fmac_f32_e32 v24, v28, v28
	v_fmac_f32_e32 v25, v30, v30
	v_add_f32_e32 v24, v24, v25
	v_mul_f32_e32 v25, v27, v27
	v_fmac_f32_e32 v25, v26, v26
	v_add_f32_e32 v24, v25, v24
	v_mul_f32_e32 v25, v35, v35
	v_fmac_f32_e32 v25, v34, v34
	v_add_f32_e32 v32, v25, v24
	v_cvt_pk_bf16_f32 v24, v28, v29
	v_cvt_pk_bf16_f32 v25, v30, v31
	v_lshlrev_b32_e32 v28, 16, v120
	v_and_b32_e32 v29, 0xffff0000, v120
	v_lshlrev_b32_e32 v30, 16, v121
	v_and_b32_e32 v31, 0xffff0000, v121
	v_pk_fma_f32 v[22:23], v[22:23], 0.5, v[30:31] op_sel_hi:[1,0,1]
	v_pk_fma_f32 v[20:21], v[20:21], 0.5, v[28:29] op_sel_hi:[1,0,1]
	v_lshlrev_b32_e32 v28, 16, v122
	v_and_b32_e32 v29, 0xffff0000, v122
	v_pk_fma_f32 v[28:29], v[16:17], 0.5, v[28:29] op_sel_hi:[1,0,1]
	v_mul_f32_e32 v16, v21, v21
	v_mul_f32_e32 v17, v23, v23
	v_fmac_f32_e32 v16, v20, v20
	v_fmac_f32_e32 v17, v22, v22
	v_lshlrev_b32_e32 v30, 16, v123
	v_and_b32_e32 v31, 0xffff0000, v123
	v_add_f32_e32 v16, v16, v17
	v_mul_f32_e32 v17, v29, v29
	v_pk_fma_f32 v[30:31], v[18:19], 0.5, v[30:31] op_sel_hi:[1,0,1]
	v_fmac_f32_e32 v17, v28, v28
	v_add_f32_e32 v16, v17, v16
	v_mul_f32_e32 v17, v31, v31
	v_fmac_f32_e32 v17, v30, v30
	v_add_f32_e32 v16, v17, v16
	v_add_f32_e32 v19, v32, v16
	v_cvt_pk_bf16_f32 v26, v26, v27
	v_cvt_pk_bf16_f32 v27, v34, v35
	v_mov_b32_e32 v34, v19
	s_nop 1
	v_permlane16_swap_b32_e32 v34, v19
	v_lshl_add_u64 v[16:17], s[36:37], 0, v[208:209]
	v_lshl_add_u64 v[32:33], v[204:205], 1, v[16:17]
	global_store_dwordx4 v[32:33], v[24:27], off nt
	v_cvt_pk_bf16_f32 v18, v20, v21
	s_waitcnt lgkmcnt(0)
	v_add_f32_e32 v16, v19, v34
	v_mov_b32_e32 v17, v16
	s_nop 1
	v_permlane32_swap_b32_e32 v17, v16
	v_cvt_pk_bf16_f32 v19, v22, v23
	v_cvt_pk_bf16_f32 v20, v28, v29
	v_cvt_pk_bf16_f32 v21, v30, v31
	global_store_dwordx4 v[32:33], v[18:21], off offset:256 nt
	s_and_saveexec_b64 s[34:35], s[4:5]
	s_cbranch_execz .LBB0_1842
	s_add_u32 s46, s54, s20
	s_addc_u32 s47, s55, s21
	v_lshl_add_u64 v[18:19], v[202:203], 2, s[46:47]
	s_waitcnt lgkmcnt(0)
	v_add_f32_e32 v16, v16, v17
	global_store_dword v[18:19], v16, off offset:640
.LBB0_1842:
	s_or_b64 exec, exec, s[34:35]
	v_lshlrev_b32_e32 v16, 16, v108
	s_waitcnt lgkmcnt(0)
	v_and_b32_e32 v17, 0xffff0000, v108
	v_lshlrev_b32_e32 v18, 16, v109
	v_and_b32_e32 v19, 0xffff0000, v109
	v_pk_fma_f32 v[14:15], v[14:15], 0.5, v[18:19] op_sel_hi:[1,0,1]
	v_pk_fma_f32 v[12:13], v[12:13], 0.5, v[16:17] op_sel_hi:[1,0,1]
	v_lshlrev_b32_e32 v16, 16, v110
	v_and_b32_e32 v17, 0xffff0000, v110
	v_lshlrev_b32_e32 v18, 16, v111
	v_and_b32_e32 v19, 0xffff0000, v111
	v_pk_fma_f32 v[18:19], v[10:11], 0.5, v[18:19] op_sel_hi:[1,0,1]
	v_pk_fma_f32 v[10:11], v[8:9], 0.5, v[16:17] op_sel_hi:[1,0,1]
	v_mul_f32_e32 v8, v13, v13
	v_mul_f32_e32 v9, v15, v15
	v_fmac_f32_e32 v8, v12, v12
	v_fmac_f32_e32 v9, v14, v14
	v_add_f32_e32 v8, v8, v9
	v_mul_f32_e32 v9, v11, v11
	v_fmac_f32_e32 v9, v10, v10
	v_add_f32_e32 v8, v9, v8
	v_mul_f32_e32 v9, v19, v19
	v_fmac_f32_e32 v9, v18, v18
	v_add_f32_e32 v16, v9, v8
	v_cvt_pk_bf16_f32 v8, v12, v13
	v_cvt_pk_bf16_f32 v9, v14, v15
	v_lshlrev_b32_e32 v12, 16, v96
	v_and_b32_e32 v13, 0xffff0000, v96
	v_lshlrev_b32_e32 v14, 16, v97
	v_and_b32_e32 v15, 0xffff0000, v97
	v_pk_fma_f32 v[6:7], v[6:7], 0.5, v[14:15] op_sel_hi:[1,0,1]
	v_pk_fma_f32 v[4:5], v[4:5], 0.5, v[12:13] op_sel_hi:[1,0,1]
	v_lshlrev_b32_e32 v12, 16, v98
	v_and_b32_e32 v13, 0xffff0000, v98
	v_pk_fma_f32 v[12:13], v[0:1], 0.5, v[12:13] op_sel_hi:[1,0,1]
	v_mul_f32_e32 v0, v5, v5
	v_mul_f32_e32 v1, v7, v7
	v_fmac_f32_e32 v0, v4, v4
	v_fmac_f32_e32 v1, v6, v6
	v_lshlrev_b32_e32 v14, 16, v99
	v_and_b32_e32 v15, 0xffff0000, v99
	v_add_f32_e32 v0, v0, v1
	v_mul_f32_e32 v1, v13, v13
	v_pk_fma_f32 v[14:15], v[2:3], 0.5, v[14:15] op_sel_hi:[1,0,1]
	v_fmac_f32_e32 v1, v12, v12
	v_add_f32_e32 v0, v1, v0
	v_mul_f32_e32 v1, v15, v15
	v_fmac_f32_e32 v1, v14, v14
	v_add_f32_e32 v0, v1, v0
	v_add_f32_e32 v3, v16, v0
	v_cvt_pk_bf16_f32 v10, v10, v11
	v_cvt_pk_bf16_f32 v11, v18, v19
	v_mov_b32_e32 v18, v3
	s_nop 1
	v_permlane16_swap_b32_e32 v18, v3
	v_lshl_add_u64 v[0:1], s[36:37], 0, v[206:207]
	v_lshl_add_u64 v[16:17], v[204:205], 1, v[0:1]
	global_store_dwordx4 v[16:17], v[8:11], off nt
	v_cvt_pk_bf16_f32 v2, v4, v5
	s_waitcnt lgkmcnt(0)
	v_add_f32_e32 v0, v3, v18
	v_mov_b32_e32 v1, v0
	s_nop 1
	v_permlane32_swap_b32_e32 v1, v0
	v_cvt_pk_bf16_f32 v3, v6, v7
	v_cvt_pk_bf16_f32 v4, v12, v13
	v_cvt_pk_bf16_f32 v5, v14, v15
	global_store_dwordx4 v[16:17], v[2:5], off offset:256 nt
	s_and_saveexec_b64 s[34:35], s[4:5]
	s_cbranch_execz .LBB0_1844
	s_add_u32 s20, s54, s20
	s_addc_u32 s21, s55, s21
	v_lshl_add_u64 v[2:3], v[202:203], 2, s[20:21]
	s_waitcnt lgkmcnt(0)
	v_add_f32_e32 v0, v0, v1
	global_store_dword v[2:3], v0, off offset:704
